# speedup vs baseline: 1.0026x; 1.0026x over previous
; __device__ __forceinline__ int opaque_tid() { int t = threadIdx.x; asm volatile("" : "+v"(t)); return t; }
; __device__ __forceinline__ void transpose_job(char* shm, const float* __restrict__ src, u16* __restrict__ dst,
;                                               int K, int N, const float* __restrict__ g, const float* __restrict__ cs,
;                                               int perm) {
;   float* sT = (float*)shm;
;   const int tid = opaque_tid();
;   const int tk = K >> 6, tn = N >> 6, nt = tk * tn;
;   for (int t = blockIdx.x; t < nt; t += gridDim.x) {
;     const int k0 = (t / tn) << 6, n0 = (t % tn) << 6;
; #pragma unroll
;     for (int i = 0; i < 2; ++i) {
;       int idx = tid + i * 512, kk = idx >> 4, c4 = idx & 15;
; __global__ void __launch_bounds__(NTHREADS, 2) mega_kernel(Params p) {
;   __shared__ __attribute__((aligned(1024))) char shm[LDS_BYTES];
;   cg::grid_group grid = cg::this_grid();
;   run_phase(0, shm, p); grid.sync();
_Z11mega_kernel6Params:
	s_load_dwordx2 s[56:57], s[0:1], 0xb0
	s_load_dwordx16 s[36:51], s[0:1], 0x0
	s_add_u32 s96, s0, 0xb8
	s_addc_u32 s97, s1, 0
	s_load_dword s33, s[0:1], 0xb8
	s_waitcnt lgkmcnt(0)
	v_readfirstlane_b32 s3, v0
	s_nop 3
	s_and_b32 s3, s3, 0x3ff
	s_cmpk_lt_u32 s3, 0x100
	s_cbranch_scc1 .Lprio_done
	s_setprio 1
.Lprio_done:
	s_add_u32 s10, s56, 0x30100000
	s_addc_u32 s11, s57, 0
	s_cmpk_lt_i32 s2, 0x1600
	s_cselect_b64 s[4:5], -1, 0
	v_and_b32_e32 v217, 0x3ff, v0
	v_writelane_b32 v254, s4, 0
	v_mov_b32_e32 v2, v217
	s_cmpk_gt_i32 s2, 0x15ff
	v_writelane_b32 v254, s5, 1
	s_movk_i32 s3, 0x1600
	s_cbranch_scc1 .LBB0_7
	v_lshlrev_b32_e32 v1, 4, v2
	v_and_b32_e32 v10, 0xf0, v1
	s_cmp_lg_u64 s[40:41], 0
	v_ashrrev_i32_e32 v1, 3, v2
	v_lshlrev_b32_e32 v3, 3, v2
	v_ashrrev_i32_e32 v15, 4, v2
	v_add_u32_e32 v2, 0x200, v2
	s_cselect_b64 s[4:5], -1, 0
	v_and_b32_e32 v4, 56, v3
	s_movk_i32 s6, 0x104
	v_ashrrev_i32_e32 v17, 4, v2
	v_lshlrev_b32_e32 v5, 2, v1
	v_mov_b32_e32 v11, 0
	v_mul_lo_u32 v3, v15, s6
	v_mul_lo_u32 v2, v17, s6
	v_mad_u32_u24 v20, v4, s6, v5
	v_cndmask_b32_e64 v5, 0, 1, s[4:5]
	v_lshl_add_u64 v[12:13], s[42:43], 0, v[10:11]
	s_lshl_b32 s12, s2, 6
	s_lshl_b32 s13, s33, 6
	s_mov_b32 s14, 0xb000
	v_add_u32_e32 v21, v10, v3
	v_add_u32_e32 v22, v10, v2
	v_lshlrev_b32_e32 v10, 1, v4
	v_cmp_ne_u32_e64 s[4:5], 1, v5
	v_add_u32_e32 v23, 0x400, v20
	s_mov_b32 s15, s2
	s_branch .LBB0_3

; #define SCHED() __builtin_amdgcn_sched_barrier(0)
; #define LGKM(n) asm volatile("s_waitcnt lgkmcnt(%0)" ::"n"(n) : "memory")
; #define STAGE_A(b, h, kt) STAGE_AX(Ag, b, h, kt)
; #define STAGE_B(b, h, kt) STAGE_BX(Bg, b, h, kt)
; #define LDA(b, h) do { const unsigned pa_ = lds0 + SLOTA(b, h) + wr * 8192 + laneoff; _Pragma("unroll") for (int m = 0; m < 4; ++m)   \
;       _Pragma("unroll") for (int k = 0; k < 2; ++k) DSR(At[m][k], pa_, m * 2048 + k * 1024); } while (0)
; #define LDB(dst, b, h) do { const unsigned pb_ = lds0 + SLOTB(b, h) + wc * 4096 + laneoff; _Pragma("unroll") for (int n = 0; n < 2; ++n) \
;       _Pragma("unroll") for (int k = 0; k < 2; ++k) DSR(dst[n][k], pb_, n * 2048 + k * 1024); } while (0)
; #define BAR __builtin_amdgcn_s_barrier()
; #define LGKM(n) asm volatile("s_waitcnt lgkmcnt(%0)" ::"n"(n) : "memory")
; template <int EPI, bool SWP> ...
;     ...
;   for (int t = 0; t < nt - 2; t += 2) {
;     LDB(B0, 0, 0); LDA(0, 0); STAGE_A(1, 1, t + 1);
;     LGKM(8); BAR; LGKM(0); SCHED(); MMA(0, 0, B0); BAR; SCHED();
;     LDB(B1, 0, 1); STAGE_B(0, 0, t + 2);
;     BAR; LGKM(0); SCHED(); MMA(0, 1, B1); BAR; SCHED();
;     LDA(0, 1); STAGE_A(0, 0, t + 2);
;     BAR; LGKM(0); SCHED(); MMA(1, 0, B0); BAR; SCHED();
.LBB0_81:
	ds_read_b128 v[128:131], v219 offset:0
	ds_read_b128 v[132:135], v219 offset:0x400
	ds_read_b128 v[136:139], v219 offset:0x800
	ds_read_b128 v[140:143], v219 offset:0xc00
	ds_read_b128 v[144:147], v220 offset:0
	ds_read_b128 v[148:151], v220 offset:0x400
	ds_read_b128 v[152:155], v220 offset:0x800
	ds_read_b128 v[156:159], v220 offset:0xc00
	ds_read_b128 v[160:163], v220 offset:0x1000
	ds_read_b128 v[164:167], v220 offset:0x1400
	ds_read_b128 v[168:171], v220 offset:0x1800
	v_lshl_add_u64 v[192:193], s[76:77], 0, v[210:211]
	s_mov_b32 m0, s79
	ds_read_b128 v[172:175], v220 offset:0x1c00
	v_lshl_add_u64 v[176:177], v[192:193], 0, s[44:45]
	global_load_lds_dwordx4 v[176:177], off
	v_lshl_add_u64 v[176:177], v[192:193], 0, s[48:49]
	s_mov_b32 m0, s80
	s_nop 0
	global_load_lds_dwordx4 v[176:177], off
	s_waitcnt lgkmcnt(8)
	s_barrier
	s_waitcnt lgkmcnt(0)
	v_mfma_f32_16x16x32_bf16 v[124:127], v[128:131], v[144:147], v[124:127]
	v_mfma_f32_16x16x32_bf16 v[120:123], v[136:139], v[144:147], v[120:123]
	v_mfma_f32_16x16x32_bf16 v[116:119], v[128:131], v[152:155], v[116:119]
	v_mfma_f32_16x16x32_bf16 v[112:115], v[136:139], v[152:155], v[112:115]
	v_mfma_f32_16x16x32_bf16 v[108:111], v[128:131], v[160:163], v[108:111]
	v_mfma_f32_16x16x32_bf16 v[104:107], v[136:139], v[160:163], v[104:107]
	v_mfma_f32_16x16x32_bf16 v[100:103], v[128:131], v[168:171], v[100:103]
	v_mfma_f32_16x16x32_bf16 v[96:99], v[136:139], v[168:171], v[96:99]
	v_mfma_f32_16x16x32_bf16 v[124:127], v[132:135], v[148:151], v[124:127]
	v_mfma_f32_16x16x32_bf16 v[120:123], v[140:143], v[148:151], v[120:123]
	v_mfma_f32_16x16x32_bf16 v[116:119], v[132:135], v[156:159], v[116:119]
	v_mfma_f32_16x16x32_bf16 v[112:115], v[140:143], v[156:159], v[112:115]
	v_mfma_f32_16x16x32_bf16 v[108:111], v[132:135], v[164:167], v[108:111]
	v_mfma_f32_16x16x32_bf16 v[104:107], v[140:143], v[164:167], v[104:107]
	v_mfma_f32_16x16x32_bf16 v[100:103], v[132:135], v[172:175], v[100:103]
	v_mfma_f32_16x16x32_bf16 v[96:99], v[140:143], v[172:175], v[96:99]
	s_barrier
	ds_read_b128 v[176:179], v221 offset:0
	ds_read_b128 v[180:183], v221 offset:0x400
	ds_read_b128 v[184:187], v221 offset:0x800
	v_lshl_add_u64 v[194:195], s[74:75], 0, v[210:211]
	s_mov_b64 s[84:85], 0x30100100
	s_mov_b32 m0, s19
	ds_read_b128 v[188:191], v221 offset:0xc00
	v_lshl_add_u64 v[196:197], v[194:195], 0, s[84:85]
	s_mov_b64 s[84:85], 0x30140100
	global_load_lds_dwordx4 v[196:197], off
	v_lshl_add_u64 v[196:197], v[194:195], 0, s[84:85]
	s_mov_b32 m0, s30
	s_nop 0
	global_load_lds_dwordx4 v[196:197], off
	s_barrier
	s_waitcnt lgkmcnt(0)
	v_mfma_f32_16x16x32_bf16 v[92:95], v[176:179], v[144:147], v[92:95]
	v_mfma_f32_16x16x32_bf16 v[88:91], v[184:187], v[144:147], v[88:91]
	v_mfma_f32_16x16x32_bf16 v[84:87], v[176:179], v[152:155], v[84:87]
	v_mfma_f32_16x16x32_bf16 v[80:83], v[184:187], v[152:155], v[80:83]
	v_mfma_f32_16x16x32_bf16 v[76:79], v[176:179], v[160:163], v[76:79]
	v_mfma_f32_16x16x32_bf16 v[72:75], v[184:187], v[160:163], v[72:75]
	v_mfma_f32_16x16x32_bf16 v[68:71], v[176:179], v[168:171], v[68:71]
	v_mfma_f32_16x16x32_bf16 v[64:67], v[184:187], v[168:171], v[64:67]
	v_mfma_f32_16x16x32_bf16 v[92:95], v[180:183], v[148:151], v[92:95]
	v_mfma_f32_16x16x32_bf16 v[88:91], v[188:191], v[148:151], v[88:91]
	v_mfma_f32_16x16x32_bf16 v[84:87], v[180:183], v[156:159], v[84:87]
	v_mfma_f32_16x16x32_bf16 v[80:83], v[188:191], v[156:159], v[80:83]
	v_mfma_f32_16x16x32_bf16 v[76:79], v[180:183], v[164:167], v[76:79]
	v_mfma_f32_16x16x32_bf16 v[72:75], v[188:191], v[164:167], v[72:75]
	v_mfma_f32_16x16x32_bf16 v[68:71], v[180:183], v[172:175], v[68:71]
	v_mfma_f32_16x16x32_bf16 v[64:67], v[188:191], v[172:175], v[64:67]
	s_barrier
	ds_read_b128 v[144:147], v222 offset:0
	ds_read_b128 v[148:151], v222 offset:0x400
	ds_read_b128 v[152:155], v222 offset:0x800
	ds_read_b128 v[156:159], v222 offset:0xc00
	ds_read_b128 v[160:163], v222 offset:0x1000
	ds_read_b128 v[164:167], v222 offset:0x1400
	ds_read_b128 v[168:171], v222 offset:0x1800
	s_mov_b64 s[84:85], 0x100
	s_mov_b32 m0, s3
	ds_read_b128 v[172:175], v222 offset:0x1c00
	v_lshl_add_u64 v[196:197], v[192:193], 0, s[84:85]
	s_mov_b64 s[84:85], 0x40100
	global_load_lds_dwordx4 v[196:197], off
	v_lshl_add_u64 v[196:197], v[192:193], 0, s[84:85]
	s_mov_b32 m0, s31
	s_nop 0
	global_load_lds_dwordx4 v[196:197], off
	s_barrier
	s_waitcnt lgkmcnt(0)
	v_mfma_f32_16x16x32_bf16 v[60:63], v[128:131], v[144:147], v[60:63]
	v_mfma_f32_16x16x32_bf16 v[56:59], v[136:139], v[144:147], v[56:59]
	v_mfma_f32_16x16x32_bf16 v[52:55], v[128:131], v[152:155], v[52:55]
	v_mfma_f32_16x16x32_bf16 v[48:51], v[136:139], v[152:155], v[48:51]
	v_mfma_f32_16x16x32_bf16 v[44:47], v[128:131], v[160:163], v[44:47]
	v_mfma_f32_16x16x32_bf16 v[40:43], v[136:139], v[160:163], v[40:43]
	v_mfma_f32_16x16x32_bf16 v[36:39], v[128:131], v[168:171], v[36:39]
	v_mfma_f32_16x16x32_bf16 v[32:35], v[136:139], v[168:171], v[32:35]
	v_mfma_f32_16x16x32_bf16 v[60:63], v[132:135], v[148:151], v[60:63]
	v_mfma_f32_16x16x32_bf16 v[56:59], v[140:143], v[148:151], v[56:59]
	v_mfma_f32_16x16x32_bf16 v[52:55], v[132:135], v[156:159], v[52:55]
	v_mfma_f32_16x16x32_bf16 v[48:51], v[140:143], v[156:159], v[48:51]
	v_mfma_f32_16x16x32_bf16 v[44:47], v[132:135], v[164:167], v[44:47]
	v_mfma_f32_16x16x32_bf16 v[40:43], v[140:143], v[164:167], v[40:43]
	v_mfma_f32_16x16x32_bf16 v[36:39], v[132:135], v[172:175], v[36:39]
	v_mfma_f32_16x16x32_bf16 v[32:35], v[140:143], v[172:175], v[32:35]
	s_barrier
; #define WAIT_V(n) asm volatile("s_waitcnt vmcnt(%0)" ::"n"(n) : "memory")
; #define SCHED() __builtin_amdgcn_sched_barrier(0)
; #define LGKM(n) asm volatile("s_waitcnt lgkmcnt(%0)" ::"n"(n) : "memory")
; #define STAGE_A(b, h, kt) STAGE_AX(Ag, b, h, kt)
; #define STAGE_B(b, h, kt) STAGE_BX(Bg, b, h, kt)
; #define LDA(b, h) do { const unsigned pa_ = lds0 + SLOTA(b, h) + wr * 8192 + laneoff; _Pragma("unroll") for (int m = 0; m < 4; ++m)   \
;       _Pragma("unroll") for (int k = 0; k < 2; ++k) DSR(At[m][k], pa_, m * 2048 + k * 1024); } while (0)
; #define LDB(dst, b, h) do { const unsigned pb_ = lds0 + SLOTB(b, h) + wc * 4096 + laneoff; _Pragma("unroll") for (int n = 0; n < 2; ++n) \
;       _Pragma("unroll") for (int k = 0; k < 2; ++k) DSR(dst[n][k], pb_, n * 2048 + k * 1024); } while (0)
; #define BAR __builtin_amdgcn_s_barrier()
; #define LGKM(n) asm volatile("s_waitcnt lgkmcnt(%0)" ::"n"(n) : "memory")
; template <int EPI, bool SWP> ...
;     ...
;     LDA(0, 1); STAGE_A(0, 0, t + 2);
;     BAR; LGKM(0); SCHED(); MMA(1, 0, B0); BAR; SCHED();
;     STAGE_B(0, 1, t + 2);
;     WAIT_V(6); BAR; SCHED(); MMA(1, 1, B1); BAR; SCHED();
;     LDB(B0, 1, 0); LDA(1, 0); STAGE_A(0, 1, t + 2);
;     LGKM(8); BAR; LGKM(0); SCHED(); MMA(0, 0, B0); BAR; SCHED();
;     LDB(B1, 1, 1); STAGE_B(1, 0, t + 3);
;     BAR; LGKM(0); SCHED(); MMA(0, 1, B1); BAR; SCHED();
;     LDA(1, 1); STAGE_A(1, 0, t + 3);
	s_mov_b64 s[84:85], 0x30180100
	s_mov_b32 m0, s50
	v_lshl_add_u64 v[128:129], v[194:195], 0, s[84:85]
	s_mov_b64 s[84:85], 0x301c0100
	global_load_lds_dwordx4 v[128:129], off
	v_lshl_add_u64 v[128:129], v[194:195], 0, s[84:85]
	s_mov_b32 m0, s51
	s_nop 0
	global_load_lds_dwordx4 v[128:129], off
	s_waitcnt vmcnt(6)
	s_barrier
	v_mfma_f32_16x16x32_bf16 v[28:31], v[176:179], v[144:147], v[28:31]
	v_mfma_f32_16x16x32_bf16 v[24:27], v[184:187], v[144:147], v[24:27]
	v_mfma_f32_16x16x32_bf16 v[20:23], v[176:179], v[152:155], v[20:23]
	v_mfma_f32_16x16x32_bf16 v[16:19], v[184:187], v[152:155], v[16:19]
	v_mfma_f32_16x16x32_bf16 v[12:15], v[176:179], v[160:163], v[12:15]
	v_mfma_f32_16x16x32_bf16 v[8:11], v[184:187], v[160:163], v[8:11]
	v_mfma_f32_16x16x32_bf16 v[4:7], v[176:179], v[168:171], v[4:7]
	v_mfma_f32_16x16x32_bf16 v[0:3], v[184:187], v[168:171], v[0:3]
	v_mfma_f32_16x16x32_bf16 v[28:31], v[180:183], v[148:151], v[28:31]
	v_mfma_f32_16x16x32_bf16 v[24:27], v[188:191], v[148:151], v[24:27]
	v_mfma_f32_16x16x32_bf16 v[20:23], v[180:183], v[156:159], v[20:23]
	v_mfma_f32_16x16x32_bf16 v[16:19], v[188:191], v[156:159], v[16:19]
	v_mfma_f32_16x16x32_bf16 v[12:15], v[180:183], v[164:167], v[12:15]
	v_mfma_f32_16x16x32_bf16 v[8:11], v[188:191], v[164:167], v[8:11]
	v_mfma_f32_16x16x32_bf16 v[4:7], v[180:183], v[172:175], v[4:7]
	v_mfma_f32_16x16x32_bf16 v[0:3], v[188:191], v[172:175], v[0:3]
	s_barrier
	ds_read_b128 v[128:131], v223 offset:0
	ds_read_b128 v[132:135], v223 offset:0x400
	ds_read_b128 v[136:139], v223 offset:0x800
	ds_read_b128 v[140:143], v223 offset:0xc00
	ds_read_b128 v[144:147], v224 offset:0
	ds_read_b128 v[148:151], v224 offset:0x400
	ds_read_b128 v[152:155], v224 offset:0x800
	ds_read_b128 v[156:159], v224 offset:0xc00
	ds_read_b128 v[160:163], v224 offset:0x1000
	ds_read_b128 v[164:167], v224 offset:0x1400
	ds_read_b128 v[168:171], v224 offset:0x1800
	s_mov_b64 s[84:85], 0x80100
	s_mov_b32 m0, s64
	ds_read_b128 v[172:175], v224 offset:0x1c00
	v_lshl_add_u64 v[176:177], v[192:193], 0, s[84:85]
	s_mov_b64 s[84:85], 0xc0100
	global_load_lds_dwordx4 v[176:177], off
	v_lshl_add_u64 v[176:177], v[192:193], 0, s[84:85]
	s_mov_b32 m0, s65
	s_nop 0
	global_load_lds_dwordx4 v[176:177], off
	s_waitcnt lgkmcnt(8)
	s_barrier
	s_waitcnt lgkmcnt(0)
	v_mfma_f32_16x16x32_bf16 v[124:127], v[128:131], v[144:147], v[124:127]
	v_mfma_f32_16x16x32_bf16 v[120:123], v[136:139], v[144:147], v[120:123]
	v_mfma_f32_16x16x32_bf16 v[116:119], v[128:131], v[152:155], v[116:119]
	v_mfma_f32_16x16x32_bf16 v[112:115], v[136:139], v[152:155], v[112:115]
	v_mfma_f32_16x16x32_bf16 v[108:111], v[128:131], v[160:163], v[108:111]
	v_mfma_f32_16x16x32_bf16 v[104:107], v[136:139], v[160:163], v[104:107]
	v_mfma_f32_16x16x32_bf16 v[100:103], v[128:131], v[168:171], v[100:103]
	v_mfma_f32_16x16x32_bf16 v[96:99], v[136:139], v[168:171], v[96:99]
	v_mfma_f32_16x16x32_bf16 v[124:127], v[132:135], v[148:151], v[124:127]
	v_mfma_f32_16x16x32_bf16 v[120:123], v[140:143], v[148:151], v[120:123]
	v_mfma_f32_16x16x32_bf16 v[116:119], v[132:135], v[156:159], v[116:119]
	v_mfma_f32_16x16x32_bf16 v[112:115], v[140:143], v[156:159], v[112:115]
	v_mfma_f32_16x16x32_bf16 v[108:111], v[132:135], v[164:167], v[108:111]
	v_mfma_f32_16x16x32_bf16 v[104:107], v[140:143], v[164:167], v[104:107]
	v_mfma_f32_16x16x32_bf16 v[100:103], v[132:135], v[172:175], v[100:103]
	v_mfma_f32_16x16x32_bf16 v[96:99], v[140:143], v[172:175], v[96:99]
	s_barrier
	ds_read_b128 v[176:179], v225 offset:0
	ds_read_b128 v[180:183], v225 offset:0x400
	ds_read_b128 v[184:187], v225 offset:0x800
	s_mov_b64 s[84:85], 0x30100180
	s_add_i32 s83, s3, 0x18000
	ds_read_b128 v[188:191], v225 offset:0xc00
	v_lshl_add_u64 v[196:197], v[194:195], 0, s[84:85]
	s_mov_b32 m0, s83
	s_mov_b64 s[84:85], 0x30140180
	global_load_lds_dwordx4 v[196:197], off
	v_lshl_add_u64 v[196:197], v[194:195], 0, s[84:85]
	s_mov_b32 m0, s66
	s_nop 0
	global_load_lds_dwordx4 v[196:197], off
	s_barrier
	s_waitcnt lgkmcnt(0)
	v_mfma_f32_16x16x32_bf16 v[92:95], v[176:179], v[144:147], v[92:95]
	v_mfma_f32_16x16x32_bf16 v[88:91], v[184:187], v[144:147], v[88:91]
	v_mfma_f32_16x16x32_bf16 v[84:87], v[176:179], v[152:155], v[84:87]
	v_mfma_f32_16x16x32_bf16 v[80:83], v[184:187], v[152:155], v[80:83]
	v_mfma_f32_16x16x32_bf16 v[76:79], v[176:179], v[160:163], v[76:79]
	v_mfma_f32_16x16x32_bf16 v[72:75], v[184:187], v[160:163], v[72:75]
	v_mfma_f32_16x16x32_bf16 v[68:71], v[176:179], v[168:171], v[68:71]
	v_mfma_f32_16x16x32_bf16 v[64:67], v[184:187], v[168:171], v[64:67]
	v_mfma_f32_16x16x32_bf16 v[92:95], v[180:183], v[148:151], v[92:95]
	v_mfma_f32_16x16x32_bf16 v[88:91], v[188:191], v[148:151], v[88:91]
	v_mfma_f32_16x16x32_bf16 v[84:87], v[180:183], v[156:159], v[84:87]
	v_mfma_f32_16x16x32_bf16 v[80:83], v[188:191], v[156:159], v[80:83]
	v_mfma_f32_16x16x32_bf16 v[76:79], v[180:183], v[164:167], v[76:79]
	v_mfma_f32_16x16x32_bf16 v[72:75], v[188:191], v[164:167], v[72:75]
	v_mfma_f32_16x16x32_bf16 v[68:71], v[180:183], v[172:175], v[68:71]
	v_mfma_f32_16x16x32_bf16 v[64:67], v[188:191], v[172:175], v[64:67]
	s_barrier
	ds_read_b128 v[144:147], v226 offset:0
	ds_read_b128 v[148:151], v226 offset:0x400
	ds_read_b128 v[152:155], v226 offset:0x800
	ds_read_b128 v[156:159], v226 offset:0xc00
	ds_read_b128 v[160:163], v226 offset:0x1000
	ds_read_b128 v[164:167], v226 offset:0x1400
	s_mov_b64 s[84:85], 0x180
	ds_read_b128 v[168:171], v226 offset:0x1800
	v_lshl_add_u64 v[196:197], v[192:193], 0, s[84:85]
	s_add_i32 s84, s3, 0x8000
	ds_read_b128 v[172:175], v226 offset:0x1c00
	s_mov_b32 m0, s84
	s_mov_b64 s[86:87], 0x40180
	global_load_lds_dwordx4 v[196:197], off
	v_lshl_add_u64 v[192:193], v[192:193], 0, s[86:87]
	s_mov_b32 m0, s67
	s_nop 0
	global_load_lds_dwordx4 v[192:193], off
	s_barrier
; #define WAIT_V(n) asm volatile("s_waitcnt vmcnt(%0)" ::"n"(n) : "memory")
; #define SCHED() __builtin_amdgcn_sched_barrier(0)
; #define LGKM(n) asm volatile("s_waitcnt lgkmcnt(%0)" ::"n"(n) : "memory")
; #define STAGE_A(b, h, kt) STAGE_AX(Ag, b, h, kt)
; #define STAGE_B(b, h, kt) STAGE_BX(Bg, b, h, kt)
; #define LDA(b, h) do { const unsigned pa_ = lds0 + SLOTA(b, h) + wr * 8192 + laneoff; _Pragma("unroll") for (int m = 0; m < 4; ++m)   \
;       _Pragma("unroll") for (int k = 0; k < 2; ++k) DSR(At[m][k], pa_, m * 2048 + k * 1024); } while (0)
; #define LDB(dst, b, h) do { const unsigned pb_ = lds0 + SLOTB(b, h) + wc * 4096 + laneoff; _Pragma("unroll") for (int n = 0; n < 2; ++n) \
;       _Pragma("unroll") for (int k = 0; k < 2; ++k) DSR(dst[n][k], pb_, n * 2048 + k * 1024); } while (0)
; #define BAR __builtin_amdgcn_s_barrier()
; #define LGKM(n) asm volatile("s_waitcnt lgkmcnt(%0)" ::"n"(n) : "memory")
; template <int EPI, bool SWP> ...
;     ...
;     LDB(B1, 1, 1); STAGE_B(1, 0, t + 3);
;     BAR; LGKM(0); SCHED(); MMA(0, 1, B1); BAR; SCHED();
;     LDA(1, 1); STAGE_A(1, 0, t + 3);
;     BAR; LGKM(0); SCHED(); MMA(1, 0, B0); BAR; SCHED();
;     STAGE_B(1, 1, t + 3);
;     WAIT_V(6); BAR; SCHED(); MMA(1, 1, B1); BAR; SCHED();
;   }
;   { LDB(B0, 0, 0); LDA(0, 0); STAGE_A(1, 1, nt - 1);
;     BAR; LGKM(0); SCHED(); MMA(0, 0, B0); BAR; SCHED();
	s_waitcnt lgkmcnt(0)
	v_mfma_f32_16x16x32_bf16 v[60:63], v[128:131], v[144:147], v[60:63]
	v_mfma_f32_16x16x32_bf16 v[56:59], v[136:139], v[144:147], v[56:59]
	v_mfma_f32_16x16x32_bf16 v[52:55], v[128:131], v[152:155], v[52:55]
	v_mfma_f32_16x16x32_bf16 v[48:51], v[136:139], v[152:155], v[48:51]
	v_mfma_f32_16x16x32_bf16 v[44:47], v[128:131], v[160:163], v[44:47]
	v_mfma_f32_16x16x32_bf16 v[40:43], v[136:139], v[160:163], v[40:43]
	v_mfma_f32_16x16x32_bf16 v[36:39], v[128:131], v[168:171], v[36:39]
	v_mfma_f32_16x16x32_bf16 v[32:35], v[136:139], v[168:171], v[32:35]
	v_mfma_f32_16x16x32_bf16 v[60:63], v[132:135], v[148:151], v[60:63]
	v_mfma_f32_16x16x32_bf16 v[56:59], v[140:143], v[148:151], v[56:59]
	v_mfma_f32_16x16x32_bf16 v[52:55], v[132:135], v[156:159], v[52:55]
	v_mfma_f32_16x16x32_bf16 v[48:51], v[140:143], v[156:159], v[48:51]
	v_mfma_f32_16x16x32_bf16 v[44:47], v[132:135], v[164:167], v[44:47]
	v_mfma_f32_16x16x32_bf16 v[40:43], v[140:143], v[164:167], v[40:43]
	v_mfma_f32_16x16x32_bf16 v[36:39], v[132:135], v[172:175], v[36:39]
	v_mfma_f32_16x16x32_bf16 v[32:35], v[140:143], v[172:175], v[32:35]
	s_barrier
	s_mov_b64 s[86:87], 0x30180180
	s_add_i32 s85, s3, 0x1c000
	v_lshl_add_u64 v[128:129], v[194:195], 0, s[86:87]
	s_mov_b32 m0, s85
	s_mov_b64 s[86:87], 0x301c0180
	global_load_lds_dwordx4 v[128:129], off
	v_lshl_add_u64 v[128:129], v[194:195], 0, s[86:87]
	s_mov_b32 m0, s78
	s_nop 0
	global_load_lds_dwordx4 v[128:129], off
	s_waitcnt vmcnt(6)
	s_barrier
	v_mfma_f32_16x16x32_bf16 v[28:31], v[176:179], v[144:147], v[28:31]
	v_mfma_f32_16x16x32_bf16 v[24:27], v[184:187], v[144:147], v[24:27]
	v_mfma_f32_16x16x32_bf16 v[20:23], v[176:179], v[152:155], v[20:23]
	v_mfma_f32_16x16x32_bf16 v[16:19], v[184:187], v[152:155], v[16:19]
	v_mfma_f32_16x16x32_bf16 v[12:15], v[176:179], v[160:163], v[12:15]
	v_mfma_f32_16x16x32_bf16 v[8:11], v[184:187], v[160:163], v[8:11]
	v_mfma_f32_16x16x32_bf16 v[4:7], v[176:179], v[168:171], v[4:7]
	v_mfma_f32_16x16x32_bf16 v[0:3], v[184:187], v[168:171], v[0:3]
	v_mfma_f32_16x16x32_bf16 v[28:31], v[180:183], v[148:151], v[28:31]
	v_mfma_f32_16x16x32_bf16 v[24:27], v[188:191], v[148:151], v[24:27]
	v_mfma_f32_16x16x32_bf16 v[20:23], v[180:183], v[156:159], v[20:23]
	v_mfma_f32_16x16x32_bf16 v[16:19], v[188:191], v[156:159], v[16:19]
	v_mfma_f32_16x16x32_bf16 v[12:15], v[180:183], v[164:167], v[12:15]
	v_mfma_f32_16x16x32_bf16 v[8:11], v[188:191], v[164:167], v[8:11]
	v_mfma_f32_16x16x32_bf16 v[4:7], v[180:183], v[172:175], v[4:7]
	v_mfma_f32_16x16x32_bf16 v[0:3], v[188:191], v[172:175], v[0:3]
	s_barrier
	s_add_i32 s15, s15, 2
	s_add_u32 s74, s74, 0x100
	s_addc_u32 s75, s75, 0
	s_add_u32 s76, s76, 0x100
	s_addc_u32 s77, s77, 0
	s_cmp_gt_u32 s15, 27
	s_cbranch_scc0 .LBB0_81
	ds_read_b128 v[136:139], v219 offset:0
	ds_read_b128 v[140:143], v219 offset:0x400
	ds_read_b128 v[144:147], v219 offset:0x800
	ds_read_b128 v[148:151], v219 offset:0xc00
	ds_read_b128 v[128:131], v220 offset:0
	ds_read_b128 v[132:135], v220 offset:0x400
	ds_read_b128 v[152:155], v220 offset:0x800
	ds_read_b128 v[156:159], v220 offset:0xc00
	ds_read_b128 v[160:163], v220 offset:0x1000
	ds_read_b128 v[164:167], v220 offset:0x1400
	v_lshl_add_u64 v[176:177], s[72:73], 0, v[208:209]
	ds_read_b128 v[168:171], v220 offset:0x1800
	s_mov_b64 s[72:73], 0x80f80
	s_mov_b32 m0, s79
	ds_read_b128 v[172:175], v220 offset:0x1c00
	v_lshl_add_u64 v[178:179], v[176:177], 0, s[72:73]
	s_mov_b64 s[72:73], 0xc0f80
	global_load_lds_dwordx4 v[178:179], off
	v_lshl_add_u64 v[176:177], v[176:177], 0, s[72:73]
	s_mov_b32 m0, s80
	s_ashr_i32 s15, s14, 31
	global_load_lds_dwordx4 v[176:177], off
	s_lshl_b64 s[72:73], s[14:15], 20
	s_add_u32 s72, s56, s72
	s_addc_u32 s73, s57, s73
	s_ashr_i32 s61, s60, 31
	s_barrier
	s_waitcnt lgkmcnt(0)
	s_lshl_b64 s[74:75], s[60:61], 20
	s_add_u32 s74, s10, s74
	s_addc_u32 s75, s11, s75
	v_mfma_f32_16x16x32_bf16 v[124:127], v[136:139], v[128:131], v[124:127]
	v_mfma_f32_16x16x32_bf16 v[120:123], v[144:147], v[128:131], v[120:123]
	v_mfma_f32_16x16x32_bf16 v[116:119], v[136:139], v[152:155], v[116:119]
	v_mfma_f32_16x16x32_bf16 v[112:115], v[144:147], v[152:155], v[112:115]
	v_mfma_f32_16x16x32_bf16 v[108:111], v[136:139], v[160:163], v[108:111]
	v_mfma_f32_16x16x32_bf16 v[104:107], v[144:147], v[160:163], v[104:107]
	v_mfma_f32_16x16x32_bf16 v[100:103], v[136:139], v[168:171], v[100:103]
	v_mfma_f32_16x16x32_bf16 v[96:99], v[144:147], v[168:171], v[96:99]
	v_mfma_f32_16x16x32_bf16 v[124:127], v[140:143], v[132:135], v[124:127]
	v_mfma_f32_16x16x32_bf16 v[120:123], v[148:151], v[132:135], v[120:123]
	v_mfma_f32_16x16x32_bf16 v[116:119], v[140:143], v[156:159], v[116:119]
	v_mfma_f32_16x16x32_bf16 v[112:115], v[148:151], v[156:159], v[112:115]
	v_mfma_f32_16x16x32_bf16 v[176:179], v[140:143], v[164:167], v[108:111]
	v_mfma_f32_16x16x32_bf16 v[180:183], v[148:151], v[164:167], v[104:107]
	v_mfma_f32_16x16x32_bf16 v[100:103], v[140:143], v[172:175], v[100:103]
	v_mfma_f32_16x16x32_bf16 v[96:99], v[148:151], v[172:175], v[96:99]
	s_barrier
	ds_read_b128 v[104:107], v221 offset:0
	ds_read_b128 v[108:111], v221 offset:0x400
	ds_read_b128 v[184:187], v221 offset:0x800
	ds_read_b128 v[188:191], v221 offset:0xc00
	s_barrier
; #define WAIT_V(n) asm volatile("s_waitcnt vmcnt(%0)" ::"n"(n) : "memory")
; #define SCHED() __builtin_amdgcn_sched_barrier(0)
; #define LGKM(n) asm volatile("s_waitcnt lgkmcnt(%0)" ::"n"(n) : "memory")
; #define STAGE_A(b, h, kt) STAGE_AX(Ag, b, h, kt)
; #define LDA(b, h) do { const unsigned pa_ = lds0 + SLOTA(b, h) + wr * 8192 + laneoff; _Pragma("unroll") for (int m = 0; m < 4; ++m)   \
;       _Pragma("unroll") for (int k = 0; k < 2; ++k) DSR(At[m][k], pa_, m * 2048 + k * 1024); } while (0)
; #define LDB(dst, b, h) do { const unsigned pb_ = lds0 + SLOTB(b, h) + wc * 4096 + laneoff; _Pragma("unroll") for (int n = 0; n < 2; ++n) \
;       _Pragma("unroll") for (int k = 0; k < 2; ++k) DSR(dst[n][k], pb_, n * 2048 + k * 1024); } while (0)
; #define BAR __builtin_amdgcn_s_barrier()
; #define LGKM(n) asm volatile("s_waitcnt lgkmcnt(%0)" ::"n"(n) : "memory")
; template <int EPI, bool SWP> ...
;     ...
;   { LDB(B0, 0, 0); LDA(0, 0); STAGE_A(1, 1, nt - 1);
;     BAR; LGKM(0); SCHED(); MMA(0, 0, B0); BAR; SCHED();
;     LDB(B1, 0, 1); BAR; LGKM(0); SCHED(); MMA(0, 1, B1); BAR; SCHED();
;     LDA(0, 1); WAIT_V(4); BAR; LGKM(0); SCHED(); MMA(1, 0, B0); MMA(1, 1, B1); BAR; SCHED(); }
;   { LDB(B0, 1, 0); LDA(1, 0); WAIT_V(2); BAR; LGKM(0); SCHED(); MMA(0, 0, B0); BAR; SCHED();
	s_waitcnt lgkmcnt(0)
	v_mfma_f32_16x16x32_bf16 v[92:95], v[104:107], v[128:131], v[92:95]
	v_mfma_f32_16x16x32_bf16 v[88:91], v[184:187], v[128:131], v[88:91]
	v_mfma_f32_16x16x32_bf16 v[84:87], v[104:107], v[152:155], v[84:87]
	v_mfma_f32_16x16x32_bf16 v[80:83], v[184:187], v[152:155], v[80:83]
	v_mfma_f32_16x16x32_bf16 v[76:79], v[104:107], v[160:163], v[76:79]
	v_mfma_f32_16x16x32_bf16 v[72:75], v[184:187], v[160:163], v[72:75]
	v_mfma_f32_16x16x32_bf16 v[68:71], v[104:107], v[168:171], v[68:71]
	v_mfma_f32_16x16x32_bf16 v[64:67], v[184:187], v[168:171], v[64:67]
	v_mfma_f32_16x16x32_bf16 v[192:195], v[108:111], v[132:135], v[92:95]
	v_mfma_f32_16x16x32_bf16 v[196:199], v[188:191], v[132:135], v[88:91]
	v_mfma_f32_16x16x32_bf16 v[84:87], v[108:111], v[156:159], v[84:87]
	v_mfma_f32_16x16x32_bf16 v[80:83], v[188:191], v[156:159], v[80:83]
	v_mfma_f32_16x16x32_bf16 v[200:203], v[108:111], v[164:167], v[76:79]
	v_mfma_f32_16x16x32_bf16 v[204:207], v[188:191], v[164:167], v[72:75]
	v_mfma_f32_16x16x32_bf16 v[68:71], v[108:111], v[172:175], v[68:71]
	v_mfma_f32_16x16x32_bf16 v[64:67], v[188:191], v[172:175], v[64:67]
	s_barrier
	ds_read_b128 v[72:75], v222 offset:0
	ds_read_b128 v[76:79], v222 offset:0x400
	ds_read_b128 v[88:91], v222 offset:0x800
	ds_read_b128 v[92:95], v222 offset:0xc00
	ds_read_b128 v[152:155], v222 offset:0x1000
	ds_read_b128 v[156:159], v222 offset:0x1400
	ds_read_b128 v[160:163], v222 offset:0x1800
	ds_read_b128 v[164:167], v222 offset:0x1c00
	s_waitcnt vmcnt(4)
	s_barrier
	s_waitcnt lgkmcnt(0)
	v_mfma_f32_16x16x32_bf16 v[60:63], v[136:139], v[72:75], v[60:63]
	v_mfma_f32_16x16x32_bf16 v[56:59], v[144:147], v[72:75], v[56:59]
	v_mfma_f32_16x16x32_bf16 v[52:55], v[136:139], v[88:91], v[52:55]
	v_mfma_f32_16x16x32_bf16 v[48:51], v[144:147], v[88:91], v[48:51]
	v_mfma_f32_16x16x32_bf16 v[44:47], v[136:139], v[152:155], v[44:47]
	v_mfma_f32_16x16x32_bf16 v[40:43], v[144:147], v[152:155], v[40:43]
	v_mfma_f32_16x16x32_bf16 v[36:39], v[136:139], v[160:163], v[36:39]
	v_mfma_f32_16x16x32_bf16 v[32:35], v[144:147], v[160:163], v[32:35]
	v_mfma_f32_16x16x32_bf16 v[60:63], v[140:143], v[76:79], v[60:63]
	v_mfma_f32_16x16x32_bf16 v[56:59], v[148:151], v[76:79], v[56:59]
	v_mfma_f32_16x16x32_bf16 v[52:55], v[140:143], v[92:95], v[52:55]
	v_mfma_f32_16x16x32_bf16 v[48:51], v[148:151], v[92:95], v[48:51]
	v_mfma_f32_16x16x32_bf16 v[128:131], v[140:143], v[156:159], v[44:47]
	v_mfma_f32_16x16x32_bf16 v[132:135], v[148:151], v[156:159], v[40:43]
	v_mfma_f32_16x16x32_bf16 v[36:39], v[140:143], v[164:167], v[36:39]
	v_mfma_f32_16x16x32_bf16 v[32:35], v[148:151], v[164:167], v[32:35]
	v_mfma_f32_16x16x32_bf16 v[28:31], v[104:107], v[72:75], v[28:31]
	v_mfma_f32_16x16x32_bf16 v[24:27], v[184:187], v[72:75], v[24:27]
	v_mfma_f32_16x16x32_bf16 v[20:23], v[104:107], v[88:91], v[20:23]
	v_mfma_f32_16x16x32_bf16 v[16:19], v[184:187], v[88:91], v[16:19]
	v_mfma_f32_16x16x32_bf16 v[12:15], v[104:107], v[152:155], v[12:15]
	v_mfma_f32_16x16x32_bf16 v[8:11], v[184:187], v[152:155], v[8:11]
	v_mfma_f32_16x16x32_bf16 v[4:7], v[104:107], v[160:163], v[4:7]
	v_mfma_f32_16x16x32_bf16 v[0:3], v[184:187], v[160:163], v[0:3]
	v_mfma_f32_16x16x32_bf16 v[136:139], v[108:111], v[76:79], v[28:31]
	v_mfma_f32_16x16x32_bf16 v[140:143], v[188:191], v[76:79], v[24:27]
	v_mfma_f32_16x16x32_bf16 v[20:23], v[108:111], v[92:95], v[20:23]
	v_mfma_f32_16x16x32_bf16 v[16:19], v[188:191], v[92:95], v[16:19]
	v_mfma_f32_16x16x32_bf16 v[144:147], v[108:111], v[156:159], v[12:15]
	v_mfma_f32_16x16x32_bf16 v[148:151], v[188:191], v[156:159], v[8:11]
	v_mfma_f32_16x16x32_bf16 v[4:7], v[108:111], v[164:167], v[4:7]
	v_mfma_f32_16x16x32_bf16 v[0:3], v[188:191], v[164:167], v[0:3]
	s_barrier
	ds_read_b128 v[8:11], v223 offset:0
	ds_read_b128 v[12:15], v223 offset:0x400
	ds_read_b128 v[152:155], v223 offset:0x800
	ds_read_b128 v[156:159], v223 offset:0xc00
	ds_read_b128 v[24:27], v224 offset:0
	ds_read_b128 v[28:31], v224 offset:0x400
	ds_read_b128 v[40:43], v224 offset:0x800
	ds_read_b128 v[44:47], v224 offset:0xc00
	ds_read_b128 v[184:187], v224 offset:0x1000
	ds_read_b128 v[188:191], v224 offset:0x1400
	ds_read_b128 v[212:215], v224 offset:0x1800
	ds_read_b128 v[236:239], v224 offset:0x1c00
	s_waitcnt vmcnt(2)
	s_barrier
	s_waitcnt lgkmcnt(0)
	v_mfma_f32_16x16x32_bf16 v[72:75], v[8:11], v[24:27], v[124:127]
	v_mfma_f32_16x16x32_bf16 v[124:127], v[12:15], v[28:31], v[72:75]
	v_mfma_f32_16x16x32_bf16 v[72:75], v[152:155], v[24:27], v[120:123]
	v_mfma_f32_16x16x32_bf16 v[120:123], v[156:159], v[28:31], v[72:75]
	v_mfma_f32_16x16x32_bf16 v[72:75], v[8:11], v[40:43], v[116:119]
	v_mfma_f32_16x16x32_bf16 v[108:111], v[12:15], v[44:47], v[72:75]
	v_mfma_f32_16x16x32_bf16 v[72:75], v[152:155], v[40:43], v[112:115]
	v_mfma_f32_16x16x32_bf16 v[104:107], v[156:159], v[44:47], v[72:75]
	v_mfma_f32_16x16x32_bf16 v[72:75], v[8:11], v[184:187], v[176:179]
	v_mfma_f32_16x16x32_bf16 v[92:95], v[12:15], v[188:191], v[72:75]
	v_mfma_f32_16x16x32_bf16 v[72:75], v[152:155], v[184:187], v[180:183]
	v_mfma_f32_16x16x32_bf16 v[88:91], v[156:159], v[188:191], v[72:75]
	v_mfma_f32_16x16x32_bf16 v[72:75], v[8:11], v[212:215], v[100:103]
	v_mfma_f32_16x16x32_bf16 v[76:79], v[12:15], v[236:239], v[72:75]
	v_mfma_f32_16x16x32_bf16 v[72:75], v[152:155], v[212:215], v[96:99]
	v_mfma_f32_16x16x32_bf16 v[72:75], v[156:159], v[236:239], v[72:75]
	s_barrier
; #define WAIT_V(n) asm volatile("s_waitcnt vmcnt(%0)" ::"n"(n) : "memory")
; #define SCHED() __builtin_amdgcn_sched_barrier(0)
; #define LGKM(n) asm volatile("s_waitcnt lgkmcnt(%0)" ::"n"(n) : "memory")
; #define STAGE_AX(AG, b, h, kt) do { _Pragma("unroll") for (int i = 0; i < 2; ++i)                                    \
;       __builtin_amdgcn_global_load_lds((const unsigned*)(((AG) + ((size_t)(kt) * (BK * 2) + (size_t)((h) * 2 + i) * 128 * lda)) + aoff), \
;                                        (unsigned*)(shm + SLOTA(b, h) + wid * 1024 + i * 8192), 16, 0, 0); } while (0)
; #define STAGE_BX(BG, b, h, kt) do { _Pragma("unroll") for (int i = 0; i < 2; ++i)                                    \
;       __builtin_amdgcn_global_load_lds((const unsigned*)(((BG) + ((size_t)(kt) * (BK * 2) + (size_t)((h) * 2 + i) * 128 * K)) + boff),   \
;                                        (unsigned*)(shm + SLOTB(b, h) + wid * 1024 + i * 8192), 16, 0, 0); } while (0)
; #define LDA(b, h) do { const unsigned pa_ = lds0 + SLOTA(b, h) + wr * 8192 + laneoff; _Pragma("unroll") for (int m = 0; m < 4; ++m)   \
;       _Pragma("unroll") for (int k = 0; k < 2; ++k) DSR(At[m][k], pa_, m * 2048 + k * 1024); } while (0)
; #define LDB(dst, b, h) do { const unsigned pb_ = lds0 + SLOTB(b, h) + wc * 4096 + laneoff; _Pragma("unroll") for (int n = 0; n < 2; ++n) \
;       _Pragma("unroll") for (int k = 0; k < 2; ++k) DSR(dst[n][k], pb_, n * 2048 + k * 1024); } while (0)
; #define BAR __builtin_amdgcn_s_barrier()
; #define LGKM(n) asm volatile("s_waitcnt lgkmcnt(%0)" ::"n"(n) : "memory")
; template <int EPI, bool SWP> ...
;     ...
;   { LDB(B0, 1, 0); LDA(1, 0); WAIT_V(2); BAR; LGKM(0); SCHED(); MMA(0, 0, B0); BAR; SCHED();
;     LDB(B1, 1, 1); WAIT_V(0); BAR; LGKM(0); SCHED(); MMA(0, 1, B1); BAR; SCHED();
;     LDA(1, 1);
;     if (has_next) { STAGE_BX(Bg_n, 0, 0, 0); STAGE_AX(Ag_n, 0, 0, 0); STAGE_BX(Bg_n, 0, 1, 0); STAGE_AX(Ag_n, 0, 1, 0); }
;     BAR; LGKM(0); SCHED(); MMA(1, 0, B0); MMA(1, 1, B1); BAR; SCHED(); }
;   if (wr == 0) BAR;
	ds_read_b128 v[160:163], v225 offset:0
	ds_read_b128 v[164:167], v225 offset:0x400
	ds_read_b128 v[168:171], v225 offset:0x800
	ds_read_b128 v[172:175], v225 offset:0xc00
	s_waitcnt vmcnt(0)
	s_barrier
	s_waitcnt lgkmcnt(0)
	v_mfma_f32_16x16x32_bf16 v[96:99], v[160:163], v[24:27], v[192:195]
	v_mfma_f32_16x16x32_bf16 v[24:27], v[168:171], v[24:27], v[196:199]
	v_mfma_f32_16x16x32_bf16 v[112:115], v[172:175], v[28:31], v[24:27]
	v_mfma_f32_16x16x32_bf16 v[24:27], v[160:163], v[40:43], v[84:87]
	v_mfma_f32_16x16x32_bf16 v[100:103], v[164:167], v[44:47], v[24:27]
	v_mfma_f32_16x16x32_bf16 v[24:27], v[168:171], v[40:43], v[80:83]
	v_mfma_f32_16x16x32_bf16 v[116:119], v[164:167], v[28:31], v[96:99]
	v_mfma_f32_16x16x32_bf16 v[96:99], v[172:175], v[44:47], v[24:27]
	v_mfma_f32_16x16x32_bf16 v[24:27], v[160:163], v[184:187], v[200:203]
	v_mfma_f32_16x16x32_bf16 v[84:87], v[164:167], v[188:191], v[24:27]
	v_mfma_f32_16x16x32_bf16 v[24:27], v[168:171], v[184:187], v[204:207]
	v_mfma_f32_16x16x32_bf16 v[80:83], v[172:175], v[188:191], v[24:27]
	v_mfma_f32_16x16x32_bf16 v[24:27], v[160:163], v[212:215], v[68:71]
	v_mfma_f32_16x16x32_bf16 v[68:71], v[164:167], v[236:239], v[24:27]
	v_mfma_f32_16x16x32_bf16 v[24:27], v[168:171], v[212:215], v[64:67]
	v_mfma_f32_16x16x32_bf16 v[64:67], v[172:175], v[236:239], v[24:27]
	s_barrier
	ds_read_b128 v[200:203], v226 offset:0
	ds_read_b128 v[204:207], v226 offset:0x400
	ds_read_b128 v[192:195], v226 offset:0x800
	ds_read_b128 v[196:199], v226 offset:0xc00
	ds_read_b128 v[184:187], v226 offset:0x1000
	ds_read_b128 v[188:191], v226 offset:0x1400
	ds_read_b128 v[176:179], v226 offset:0x1800
	ds_read_b128 v[180:183], v226 offset:0x1c00
	s_and_b64 vcc, exec, s[70:71]
	v_lshl_add_u64 v[212:213], s[74:75], 0, v[208:209]
	v_lshl_add_u64 v[214:215], s[72:73], 0, v[208:209]
	s_cbranch_vccz .LBB0_84
	s_mov_b32 m0, s19
	v_lshl_add_u64 v[24:25], v[212:213], 0, s[22:23]
	global_load_lds_dwordx4 v[212:213], off
	s_mov_b32 m0, s30
	s_nop 0
	global_load_lds_dwordx4 v[24:25], off
	s_mov_b32 m0, s3
	v_lshl_add_u64 v[24:25], v[214:215], 0, s[22:23]
	global_load_lds_dwordx4 v[214:215], off
	s_mov_b32 m0, s31
	s_nop 0
	global_load_lds_dwordx4 v[24:25], off
	v_lshl_add_u64 v[24:25], v[212:213], 0, s[24:25]
	s_mov_b32 m0, s50
	s_nop 0
	global_load_lds_dwordx4 v[24:25], off
	v_lshl_add_u64 v[24:25], v[212:213], 0, s[26:27]
	s_mov_b32 m0, s51
	s_nop 0
	global_load_lds_dwordx4 v[24:25], off
	v_lshl_add_u64 v[24:25], v[214:215], 0, s[24:25]
	s_mov_b32 m0, s64
	s_nop 0
	global_load_lds_dwordx4 v[24:25], off
	v_lshl_add_u64 v[24:25], v[214:215], 0, s[26:27]
	s_mov_b32 m0, s65
	s_nop 0
	global_load_lds_dwordx4 v[24:25], off
.LBB0_84:
	s_barrier
	s_waitcnt lgkmcnt(0)
	v_mfma_f32_16x16x32_bf16 v[24:27], v[8:11], v[200:203], v[60:63]
	v_mfma_f32_16x16x32_bf16 v[60:63], v[12:15], v[204:207], v[24:27]
	v_mfma_f32_16x16x32_bf16 v[24:27], v[152:155], v[200:203], v[56:59]
	v_mfma_f32_16x16x32_bf16 v[56:59], v[156:159], v[204:207], v[24:27]
	v_mfma_f32_16x16x32_bf16 v[24:27], v[8:11], v[192:195], v[52:55]
	v_mfma_f32_16x16x32_bf16 v[44:47], v[12:15], v[196:199], v[24:27]
	v_mfma_f32_16x16x32_bf16 v[24:27], v[152:155], v[192:195], v[48:51]
	v_mfma_f32_16x16x32_bf16 v[40:43], v[156:159], v[196:199], v[24:27]
	v_mfma_f32_16x16x32_bf16 v[24:27], v[8:11], v[184:187], v[128:131]
	v_mfma_f32_16x16x32_bf16 v[8:11], v[8:11], v[176:179], v[36:39]
	v_mfma_f32_16x16x32_bf16 v[28:31], v[12:15], v[188:191], v[24:27]
	v_mfma_f32_16x16x32_bf16 v[24:27], v[152:155], v[184:187], v[132:135]
	v_mfma_f32_16x16x32_bf16 v[12:15], v[12:15], v[180:183], v[8:11]
	v_mfma_f32_16x16x32_bf16 v[8:11], v[152:155], v[176:179], v[32:35]
	v_mfma_f32_16x16x32_bf16 v[24:27], v[156:159], v[188:191], v[24:27]
	v_mfma_f32_16x16x32_bf16 v[8:11], v[156:159], v[180:183], v[8:11]
	v_mfma_f32_16x16x32_bf16 v[32:35], v[160:163], v[200:203], v[136:139]
	v_mfma_f32_16x16x32_bf16 v[52:55], v[164:167], v[204:207], v[32:35]
	v_mfma_f32_16x16x32_bf16 v[32:35], v[168:171], v[200:203], v[140:143]
	v_mfma_f32_16x16x32_bf16 v[16:19], v[168:171], v[192:195], v[16:19]
	v_mfma_f32_16x16x32_bf16 v[48:51], v[172:175], v[204:207], v[32:35]
	v_mfma_f32_16x16x32_bf16 v[20:23], v[160:163], v[192:195], v[20:23]
	v_mfma_f32_16x16x32_bf16 v[32:35], v[172:175], v[196:199], v[16:19]
	v_mfma_f32_16x16x32_bf16 v[16:19], v[160:163], v[184:187], v[144:147]
	v_mfma_f32_16x16x32_bf16 v[36:39], v[164:167], v[196:199], v[20:23]
	v_mfma_f32_16x16x32_bf16 v[20:23], v[164:167], v[188:191], v[16:19]
	v_mfma_f32_16x16x32_bf16 v[16:19], v[168:171], v[184:187], v[148:151]
	v_mfma_f32_16x16x32_bf16 v[4:7], v[160:163], v[176:179], v[4:7]
	v_mfma_f32_16x16x32_bf16 v[0:3], v[168:171], v[176:179], v[0:3]
	v_mfma_f32_16x16x32_bf16 v[16:19], v[172:175], v[188:191], v[16:19]
	v_mfma_f32_16x16x32_bf16 v[4:7], v[164:167], v[180:183], v[4:7]
	v_mfma_f32_16x16x32_bf16 v[0:3], v[172:175], v[180:183], v[0:3]
	s_barrier
	s_andn2_b64 vcc, exec, s[20:21]
	s_cbranch_vccnz .LBB0_86
	s_barrier

; #define SCHED() __builtin_amdgcn_sched_barrier(0)
; #define LGKM(n) asm volatile("s_waitcnt lgkmcnt(%0)" ::"n"(n) : "memory")
; #define STAGE_A(b, h, kt) STAGE_AX(Ag, b, h, kt)
; #define STAGE_B(b, h, kt) STAGE_BX(Bg, b, h, kt)
; #define LDA(b, h) do { const unsigned pa_ = lds0 + SLOTA(b, h) + wr * 8192 + laneoff; _Pragma("unroll") for (int m = 0; m < 4; ++m)   \
;       _Pragma("unroll") for (int k = 0; k < 2; ++k) DSR(At[m][k], pa_, m * 2048 + k * 1024); } while (0)
; #define LDB(dst, b, h) do { const unsigned pb_ = lds0 + SLOTB(b, h) + wc * 4096 + laneoff; _Pragma("unroll") for (int n = 0; n < 2; ++n) \
;       _Pragma("unroll") for (int k = 0; k < 2; ++k) DSR(dst[n][k], pb_, n * 2048 + k * 1024); } while (0)
; #define BAR __builtin_amdgcn_s_barrier()
; #define LGKM(n) asm volatile("s_waitcnt lgkmcnt(%0)" ::"n"(n) : "memory")
; template <int EPI, bool SWP> ...
;     ...
;   for (int t = 0; t < nt - 2; t += 2) {
;     LDB(B0, 0, 0); LDA(0, 0); STAGE_A(1, 1, t + 1);
;     LGKM(8); BAR; LGKM(0); SCHED(); MMA(0, 0, B0); BAR; SCHED();
;     LDB(B1, 0, 1); STAGE_B(0, 0, t + 2);
;     BAR; LGKM(0); SCHED(); MMA(0, 1, B1); BAR; SCHED();
;     LDA(0, 1); STAGE_A(0, 0, t + 2);
;     BAR; LGKM(0); SCHED(); MMA(1, 0, B0); BAR; SCHED();
.LBB0_123:
	ds_read_b128 v[130:133], v201 offset:0
	ds_read_b128 v[134:137], v201 offset:0x400
	ds_read_b128 v[138:141], v201 offset:0x800
	ds_read_b128 v[142:145], v201 offset:0xc00
	ds_read_b128 v[146:149], v202 offset:0
	ds_read_b128 v[150:153], v202 offset:0x400
	ds_read_b128 v[154:157], v202 offset:0x800
	ds_read_b128 v[158:161], v202 offset:0xc00
	ds_read_b128 v[162:165], v202 offset:0x1000
	ds_read_b128 v[166:169], v202 offset:0x1400
	ds_read_b128 v[170:173], v202 offset:0x1800
	v_lshl_add_u64 v[190:191], s[58:59], 0, v[194:195]
	s_mov_b64 s[70:71], 0xf260080
	s_add_i32 s74, s3, 0xc000
	ds_read_b128 v[174:177], v202 offset:0x1c00
	v_lshl_add_u64 v[178:179], v[190:191], 0, s[70:71]
	s_mov_b32 m0, s74
	s_mov_b64 s[70:71], 0xf310080
	global_load_lds_dwordx4 v[178:179], off
	v_lshl_add_u64 v[178:179], v[190:191], 0, s[70:71]
	s_mov_b32 m0, s61
	s_nop 0
	global_load_lds_dwordx4 v[178:179], off
	s_waitcnt lgkmcnt(8)
	s_barrier
	s_waitcnt lgkmcnt(0)
	v_mfma_f32_16x16x32_bf16 v[124:127], v[130:133], v[146:149], v[124:127]
	v_mfma_f32_16x16x32_bf16 v[120:123], v[138:141], v[146:149], v[120:123]
	v_mfma_f32_16x16x32_bf16 v[116:119], v[130:133], v[154:157], v[116:119]
	v_mfma_f32_16x16x32_bf16 v[112:115], v[138:141], v[154:157], v[112:115]
	v_mfma_f32_16x16x32_bf16 v[108:111], v[130:133], v[162:165], v[108:111]
	v_mfma_f32_16x16x32_bf16 v[104:107], v[138:141], v[162:165], v[104:107]
	v_mfma_f32_16x16x32_bf16 v[100:103], v[130:133], v[170:173], v[100:103]
	v_mfma_f32_16x16x32_bf16 v[96:99], v[138:141], v[170:173], v[96:99]
	v_mfma_f32_16x16x32_bf16 v[124:127], v[134:137], v[150:153], v[124:127]
	v_mfma_f32_16x16x32_bf16 v[120:123], v[142:145], v[150:153], v[120:123]
	v_mfma_f32_16x16x32_bf16 v[116:119], v[134:137], v[158:161], v[116:119]
	v_mfma_f32_16x16x32_bf16 v[112:115], v[142:145], v[158:161], v[112:115]
	v_mfma_f32_16x16x32_bf16 v[108:111], v[134:137], v[166:169], v[108:111]
	v_mfma_f32_16x16x32_bf16 v[104:107], v[142:145], v[166:169], v[104:107]
	v_mfma_f32_16x16x32_bf16 v[100:103], v[134:137], v[174:177], v[100:103]
	v_mfma_f32_16x16x32_bf16 v[96:99], v[142:145], v[174:177], v[96:99]
	s_barrier
	ds_read_b128 v[178:181], v203 offset:0
	ds_read_b128 v[182:185], v203 offset:0x400
	ds_read_b128 v[186:189], v203 offset:0x800
	v_lshl_add_u64 v[220:221], s[10:11], 0, v[194:195]
	s_mov_b64 s[70:71], 0x32d00100
	s_mov_b32 m0, s17
	ds_read_b128 v[196:199], v203 offset:0xc00
	v_lshl_add_u64 v[222:223], v[220:221], 0, s[70:71]
	s_mov_b64 s[70:71], 0x32db0100
	global_load_lds_dwordx4 v[222:223], off
	v_lshl_add_u64 v[222:223], v[220:221], 0, s[70:71]
	s_mov_b32 m0, s18
	s_nop 0
	global_load_lds_dwordx4 v[222:223], off
	s_barrier
	s_waitcnt lgkmcnt(0)
	v_mfma_f32_16x16x32_bf16 v[92:95], v[178:181], v[146:149], v[92:95]
	v_mfma_f32_16x16x32_bf16 v[88:91], v[186:189], v[146:149], v[88:91]
	v_mfma_f32_16x16x32_bf16 v[84:87], v[178:181], v[154:157], v[84:87]
	v_mfma_f32_16x16x32_bf16 v[80:83], v[186:189], v[154:157], v[80:83]
	v_mfma_f32_16x16x32_bf16 v[76:79], v[178:181], v[162:165], v[76:79]
	v_mfma_f32_16x16x32_bf16 v[72:75], v[186:189], v[162:165], v[72:75]
	v_mfma_f32_16x16x32_bf16 v[68:71], v[178:181], v[170:173], v[68:71]
	v_mfma_f32_16x16x32_bf16 v[64:67], v[186:189], v[170:173], v[64:67]
	v_mfma_f32_16x16x32_bf16 v[92:95], v[182:185], v[150:153], v[92:95]
	v_mfma_f32_16x16x32_bf16 v[88:91], v[196:199], v[150:153], v[88:91]
	v_mfma_f32_16x16x32_bf16 v[84:87], v[182:185], v[158:161], v[84:87]
	v_mfma_f32_16x16x32_bf16 v[80:83], v[196:199], v[158:161], v[80:83]
	v_mfma_f32_16x16x32_bf16 v[76:79], v[182:185], v[166:169], v[76:79]
	v_mfma_f32_16x16x32_bf16 v[72:75], v[196:199], v[166:169], v[72:75]
	v_mfma_f32_16x16x32_bf16 v[68:71], v[182:185], v[174:177], v[68:71]
	v_mfma_f32_16x16x32_bf16 v[64:67], v[196:199], v[174:177], v[64:67]
	s_barrier
	ds_read_b128 v[146:149], v204 offset:0
	ds_read_b128 v[150:153], v204 offset:0x400
	ds_read_b128 v[154:157], v204 offset:0x800
	ds_read_b128 v[158:161], v204 offset:0xc00
	ds_read_b128 v[162:165], v204 offset:0x1000
	ds_read_b128 v[166:169], v204 offset:0x1400
	ds_read_b128 v[170:173], v204 offset:0x1800
	s_mov_b64 s[70:71], 0xf100100
	s_mov_b32 m0, s3
	ds_read_b128 v[174:177], v204 offset:0x1c00
	v_lshl_add_u64 v[222:223], v[190:191], 0, s[70:71]
	s_mov_b64 s[70:71], 0xf1b0100
	global_load_lds_dwordx4 v[222:223], off
	v_lshl_add_u64 v[222:223], v[190:191], 0, s[70:71]
	s_mov_b32 m0, s19
	s_nop 0
	global_load_lds_dwordx4 v[222:223], off
	s_barrier
	s_waitcnt lgkmcnt(0)
	v_mfma_f32_16x16x32_bf16 v[60:63], v[130:133], v[146:149], v[60:63]
	v_mfma_f32_16x16x32_bf16 v[56:59], v[138:141], v[146:149], v[56:59]
	v_mfma_f32_16x16x32_bf16 v[52:55], v[130:133], v[154:157], v[52:55]
	v_mfma_f32_16x16x32_bf16 v[48:51], v[138:141], v[154:157], v[48:51]
	v_mfma_f32_16x16x32_bf16 v[44:47], v[130:133], v[162:165], v[44:47]
	v_mfma_f32_16x16x32_bf16 v[40:43], v[138:141], v[162:165], v[40:43]
	v_mfma_f32_16x16x32_bf16 v[36:39], v[130:133], v[170:173], v[36:39]
	v_mfma_f32_16x16x32_bf16 v[32:35], v[138:141], v[170:173], v[32:35]
	v_mfma_f32_16x16x32_bf16 v[60:63], v[134:137], v[150:153], v[60:63]
	v_mfma_f32_16x16x32_bf16 v[56:59], v[142:145], v[150:153], v[56:59]
	v_mfma_f32_16x16x32_bf16 v[52:55], v[134:137], v[158:161], v[52:55]
	v_mfma_f32_16x16x32_bf16 v[48:51], v[142:145], v[158:161], v[48:51]
	v_mfma_f32_16x16x32_bf16 v[44:47], v[134:137], v[166:169], v[44:47]
	v_mfma_f32_16x16x32_bf16 v[40:43], v[142:145], v[166:169], v[40:43]
	v_mfma_f32_16x16x32_bf16 v[36:39], v[134:137], v[174:177], v[36:39]
	v_mfma_f32_16x16x32_bf16 v[32:35], v[142:145], v[174:177], v[32:35]
	s_barrier
; #define WAIT_V(n) asm volatile("s_waitcnt vmcnt(%0)" ::"n"(n) : "memory")
; #define SCHED() __builtin_amdgcn_sched_barrier(0)
; #define LGKM(n) asm volatile("s_waitcnt lgkmcnt(%0)" ::"n"(n) : "memory")
; #define STAGE_A(b, h, kt) STAGE_AX(Ag, b, h, kt)
; #define STAGE_B(b, h, kt) STAGE_BX(Bg, b, h, kt)
; #define LDA(b, h) do { const unsigned pa_ = lds0 + SLOTA(b, h) + wr * 8192 + laneoff; _Pragma("unroll") for (int m = 0; m < 4; ++m)   \
;       _Pragma("unroll") for (int k = 0; k < 2; ++k) DSR(At[m][k], pa_, m * 2048 + k * 1024); } while (0)
; #define LDB(dst, b, h) do { const unsigned pb_ = lds0 + SLOTB(b, h) + wc * 4096 + laneoff; _Pragma("unroll") for (int n = 0; n < 2; ++n) \
;       _Pragma("unroll") for (int k = 0; k < 2; ++k) DSR(dst[n][k], pb_, n * 2048 + k * 1024); } while (0)
; #define BAR __builtin_amdgcn_s_barrier()
; #define LGKM(n) asm volatile("s_waitcnt lgkmcnt(%0)" ::"n"(n) : "memory")
; template <int EPI, bool SWP> ...
;     ...
;     LDA(0, 1); STAGE_A(0, 0, t + 2);
;     BAR; LGKM(0); SCHED(); MMA(1, 0, B0); BAR; SCHED();
;     STAGE_B(0, 1, t + 2);
;     WAIT_V(6); BAR; SCHED(); MMA(1, 1, B1); BAR; SCHED();
;     LDB(B0, 1, 0); LDA(1, 0); STAGE_A(0, 1, t + 2);
;     LGKM(8); BAR; LGKM(0); SCHED(); MMA(0, 0, B0); BAR; SCHED();
;     LDB(B1, 1, 1); STAGE_B(1, 0, t + 3);
;     BAR; LGKM(0); SCHED(); MMA(0, 1, B1); BAR; SCHED();
;     LDA(1, 1); STAGE_A(1, 0, t + 3);
	s_mov_b64 s[70:71], 0x32e60100
	s_add_i32 s69, s3, 0x14000
	v_lshl_add_u64 v[130:131], v[220:221], 0, s[70:71]
	s_mov_b32 m0, s69
	s_mov_b64 s[70:71], 0x32f10100
	global_load_lds_dwordx4 v[130:131], off
	v_lshl_add_u64 v[130:131], v[220:221], 0, s[70:71]
	s_mov_b32 m0, s30
	s_nop 0
	global_load_lds_dwordx4 v[130:131], off
	s_waitcnt vmcnt(6)
	s_barrier
	v_mfma_f32_16x16x32_bf16 v[28:31], v[178:181], v[146:149], v[28:31]
	v_mfma_f32_16x16x32_bf16 v[24:27], v[186:189], v[146:149], v[24:27]
	v_mfma_f32_16x16x32_bf16 v[20:23], v[178:181], v[154:157], v[20:23]
	v_mfma_f32_16x16x32_bf16 v[16:19], v[186:189], v[154:157], v[16:19]
	v_mfma_f32_16x16x32_bf16 v[12:15], v[178:181], v[162:165], v[12:15]
	v_mfma_f32_16x16x32_bf16 v[8:11], v[186:189], v[162:165], v[8:11]
	v_mfma_f32_16x16x32_bf16 v[4:7], v[178:181], v[170:173], v[4:7]
	v_mfma_f32_16x16x32_bf16 v[0:3], v[186:189], v[170:173], v[0:3]
	v_mfma_f32_16x16x32_bf16 v[28:31], v[182:185], v[150:153], v[28:31]
	v_mfma_f32_16x16x32_bf16 v[24:27], v[196:199], v[150:153], v[24:27]
	v_mfma_f32_16x16x32_bf16 v[20:23], v[182:185], v[158:161], v[20:23]
	v_mfma_f32_16x16x32_bf16 v[16:19], v[196:199], v[158:161], v[16:19]
	v_mfma_f32_16x16x32_bf16 v[12:15], v[182:185], v[166:169], v[12:15]
	v_mfma_f32_16x16x32_bf16 v[8:11], v[196:199], v[166:169], v[8:11]
	v_mfma_f32_16x16x32_bf16 v[4:7], v[182:185], v[174:177], v[4:7]
	v_mfma_f32_16x16x32_bf16 v[0:3], v[196:199], v[174:177], v[0:3]
	s_barrier
	ds_read_b128 v[130:133], v205 offset:0
	ds_read_b128 v[134:137], v205 offset:0x400
	ds_read_b128 v[138:141], v205 offset:0x800
	ds_read_b128 v[142:145], v205 offset:0xc00
	ds_read_b128 v[146:149], v206 offset:0
	ds_read_b128 v[150:153], v206 offset:0x400
	ds_read_b128 v[154:157], v206 offset:0x800
	ds_read_b128 v[158:161], v206 offset:0xc00
	ds_read_b128 v[162:165], v206 offset:0x1000
	ds_read_b128 v[166:169], v206 offset:0x1400
	s_mov_b64 s[70:71], 0xf260100
	ds_read_b128 v[170:173], v206 offset:0x1800
	v_lshl_add_u64 v[178:179], v[190:191], 0, s[70:71]
	s_add_i32 s71, s3, 0x4000
	ds_read_b128 v[174:177], v206 offset:0x1c00
	s_mov_b32 m0, s71
	s_mov_b64 s[72:73], 0xf310100
	global_load_lds_dwordx4 v[178:179], off
	v_lshl_add_u64 v[178:179], v[190:191], 0, s[72:73]
	s_mov_b32 m0, s31
	s_nop 0
	global_load_lds_dwordx4 v[178:179], off
	s_waitcnt lgkmcnt(8)
	s_barrier
	s_waitcnt lgkmcnt(0)
	v_mfma_f32_16x16x32_bf16 v[124:127], v[130:133], v[146:149], v[124:127]
	v_mfma_f32_16x16x32_bf16 v[120:123], v[138:141], v[146:149], v[120:123]
	v_mfma_f32_16x16x32_bf16 v[116:119], v[130:133], v[154:157], v[116:119]
	v_mfma_f32_16x16x32_bf16 v[112:115], v[138:141], v[154:157], v[112:115]
	v_mfma_f32_16x16x32_bf16 v[108:111], v[130:133], v[162:165], v[108:111]
	v_mfma_f32_16x16x32_bf16 v[104:107], v[138:141], v[162:165], v[104:107]
	v_mfma_f32_16x16x32_bf16 v[100:103], v[130:133], v[170:173], v[100:103]
	v_mfma_f32_16x16x32_bf16 v[96:99], v[138:141], v[170:173], v[96:99]
	v_mfma_f32_16x16x32_bf16 v[124:127], v[134:137], v[150:153], v[124:127]
	v_mfma_f32_16x16x32_bf16 v[120:123], v[142:145], v[150:153], v[120:123]
	v_mfma_f32_16x16x32_bf16 v[116:119], v[134:137], v[158:161], v[116:119]
	v_mfma_f32_16x16x32_bf16 v[112:115], v[142:145], v[158:161], v[112:115]
	v_mfma_f32_16x16x32_bf16 v[108:111], v[134:137], v[166:169], v[108:111]
	v_mfma_f32_16x16x32_bf16 v[104:107], v[142:145], v[166:169], v[104:107]
	v_mfma_f32_16x16x32_bf16 v[100:103], v[134:137], v[174:177], v[100:103]
	v_mfma_f32_16x16x32_bf16 v[96:99], v[142:145], v[174:177], v[96:99]
	s_barrier
	ds_read_b128 v[178:181], v207 offset:0
	ds_read_b128 v[182:185], v207 offset:0x400
	ds_read_b128 v[186:189], v207 offset:0x800
	s_mov_b64 s[72:73], 0x32d00180
	s_add_i32 s70, s3, 0x18000
	ds_read_b128 v[196:199], v207 offset:0xc00
	v_lshl_add_u64 v[222:223], v[220:221], 0, s[72:73]
	s_mov_b32 m0, s70
	s_mov_b64 s[72:73], 0x32db0180
	global_load_lds_dwordx4 v[222:223], off
	v_lshl_add_u64 v[222:223], v[220:221], 0, s[72:73]
	s_mov_b32 m0, s50
	s_nop 0
	global_load_lds_dwordx4 v[222:223], off
	s_barrier
	s_waitcnt lgkmcnt(0)
	v_mfma_f32_16x16x32_bf16 v[92:95], v[178:181], v[146:149], v[92:95]
	v_mfma_f32_16x16x32_bf16 v[88:91], v[186:189], v[146:149], v[88:91]
	v_mfma_f32_16x16x32_bf16 v[84:87], v[178:181], v[154:157], v[84:87]
	v_mfma_f32_16x16x32_bf16 v[80:83], v[186:189], v[154:157], v[80:83]
	v_mfma_f32_16x16x32_bf16 v[76:79], v[178:181], v[162:165], v[76:79]
	v_mfma_f32_16x16x32_bf16 v[72:75], v[186:189], v[162:165], v[72:75]
	v_mfma_f32_16x16x32_bf16 v[68:71], v[178:181], v[170:173], v[68:71]
	v_mfma_f32_16x16x32_bf16 v[64:67], v[186:189], v[170:173], v[64:67]
	v_mfma_f32_16x16x32_bf16 v[92:95], v[182:185], v[150:153], v[92:95]
	v_mfma_f32_16x16x32_bf16 v[88:91], v[196:199], v[150:153], v[88:91]
	v_mfma_f32_16x16x32_bf16 v[84:87], v[182:185], v[158:161], v[84:87]
	v_mfma_f32_16x16x32_bf16 v[80:83], v[196:199], v[158:161], v[80:83]
	v_mfma_f32_16x16x32_bf16 v[76:79], v[182:185], v[166:169], v[76:79]
	v_mfma_f32_16x16x32_bf16 v[72:75], v[196:199], v[166:169], v[72:75]
	v_mfma_f32_16x16x32_bf16 v[68:71], v[182:185], v[174:177], v[68:71]
	v_mfma_f32_16x16x32_bf16 v[64:67], v[196:199], v[174:177], v[64:67]
	s_barrier
	ds_read_b128 v[146:149], v208 offset:0
	ds_read_b128 v[150:153], v208 offset:0x400
	ds_read_b128 v[154:157], v208 offset:0x800
	ds_read_b128 v[158:161], v208 offset:0xc00
	ds_read_b128 v[162:165], v208 offset:0x1000
	ds_read_b128 v[166:169], v208 offset:0x1400
	s_mov_b64 s[72:73], 0xf100180
	ds_read_b128 v[170:173], v208 offset:0x1800
	v_lshl_add_u64 v[222:223], v[190:191], 0, s[72:73]
	s_add_i32 s72, s3, 0x8000
	ds_read_b128 v[174:177], v208 offset:0x1c00
	s_mov_b32 m0, s72
	s_mov_b64 s[76:77], 0xf1b0180
	global_load_lds_dwordx4 v[222:223], off
	v_lshl_add_u64 v[190:191], v[190:191], 0, s[76:77]
	s_mov_b32 m0, s51
	s_nop 0
	global_load_lds_dwordx4 v[190:191], off
	s_barrier
; #define WAIT_V(n) asm volatile("s_waitcnt vmcnt(%0)" ::"n"(n) : "memory")
; #define SCHED() __builtin_amdgcn_sched_barrier(0)
; #define LGKM(n) asm volatile("s_waitcnt lgkmcnt(%0)" ::"n"(n) : "memory")
; #define STAGE_A(b, h, kt) STAGE_AX(Ag, b, h, kt)
; #define STAGE_B(b, h, kt) STAGE_BX(Bg, b, h, kt)
; #define LDA(b, h) do { const unsigned pa_ = lds0 + SLOTA(b, h) + wr * 8192 + laneoff; _Pragma("unroll") for (int m = 0; m < 4; ++m)   \
;       _Pragma("unroll") for (int k = 0; k < 2; ++k) DSR(At[m][k], pa_, m * 2048 + k * 1024); } while (0)
; #define LDB(dst, b, h) do { const unsigned pb_ = lds0 + SLOTB(b, h) + wc * 4096 + laneoff; _Pragma("unroll") for (int n = 0; n < 2; ++n) \
;       _Pragma("unroll") for (int k = 0; k < 2; ++k) DSR(dst[n][k], pb_, n * 2048 + k * 1024); } while (0)
; #define BAR __builtin_amdgcn_s_barrier()
; #define LGKM(n) asm volatile("s_waitcnt lgkmcnt(%0)" ::"n"(n) : "memory")
; template <int EPI, bool SWP> ...
;     ...
;     BAR; LGKM(0); SCHED(); MMA(0, 1, B1); BAR; SCHED();
;     LDA(1, 1); STAGE_A(1, 0, t + 3);
;     BAR; LGKM(0); SCHED(); MMA(1, 0, B0); BAR; SCHED();
;     STAGE_B(1, 1, t + 3);
;     WAIT_V(6); BAR; SCHED(); MMA(1, 1, B1); BAR; SCHED();
;   }
;   { LDB(B0, 0, 0); LDA(0, 0); STAGE_A(1, 1, nt - 1);
;     BAR; LGKM(0); SCHED(); MMA(0, 0, B0); BAR; SCHED();
	s_waitcnt lgkmcnt(0)
	v_mfma_f32_16x16x32_bf16 v[60:63], v[130:133], v[146:149], v[60:63]
	v_mfma_f32_16x16x32_bf16 v[56:59], v[138:141], v[146:149], v[56:59]
	v_mfma_f32_16x16x32_bf16 v[52:55], v[130:133], v[154:157], v[52:55]
	v_mfma_f32_16x16x32_bf16 v[48:51], v[138:141], v[154:157], v[48:51]
	v_mfma_f32_16x16x32_bf16 v[44:47], v[130:133], v[162:165], v[44:47]
	v_mfma_f32_16x16x32_bf16 v[40:43], v[138:141], v[162:165], v[40:43]
	v_mfma_f32_16x16x32_bf16 v[36:39], v[130:133], v[170:173], v[36:39]
	v_mfma_f32_16x16x32_bf16 v[32:35], v[138:141], v[170:173], v[32:35]
	v_mfma_f32_16x16x32_bf16 v[60:63], v[134:137], v[150:153], v[60:63]
	v_mfma_f32_16x16x32_bf16 v[56:59], v[142:145], v[150:153], v[56:59]
	v_mfma_f32_16x16x32_bf16 v[52:55], v[134:137], v[158:161], v[52:55]
	v_mfma_f32_16x16x32_bf16 v[48:51], v[142:145], v[158:161], v[48:51]
	v_mfma_f32_16x16x32_bf16 v[44:47], v[134:137], v[166:169], v[44:47]
	v_mfma_f32_16x16x32_bf16 v[40:43], v[142:145], v[166:169], v[40:43]
	v_mfma_f32_16x16x32_bf16 v[36:39], v[134:137], v[174:177], v[36:39]
	v_mfma_f32_16x16x32_bf16 v[32:35], v[142:145], v[174:177], v[32:35]
	s_barrier
	s_mov_b64 s[76:77], 0x32e60180
	s_add_i32 s73, s3, 0x1c000
	v_lshl_add_u64 v[130:131], v[220:221], 0, s[76:77]
	s_mov_b32 m0, s73
	s_mov_b64 s[76:77], 0x32f10180
	global_load_lds_dwordx4 v[130:131], off
	v_lshl_add_u64 v[130:131], v[220:221], 0, s[76:77]
	s_mov_b32 m0, s60
	s_nop 0
	global_load_lds_dwordx4 v[130:131], off
	s_waitcnt vmcnt(6)
	s_barrier
	v_mfma_f32_16x16x32_bf16 v[28:31], v[178:181], v[146:149], v[28:31]
	v_mfma_f32_16x16x32_bf16 v[24:27], v[186:189], v[146:149], v[24:27]
	v_mfma_f32_16x16x32_bf16 v[20:23], v[178:181], v[154:157], v[20:23]
	v_mfma_f32_16x16x32_bf16 v[16:19], v[186:189], v[154:157], v[16:19]
	v_mfma_f32_16x16x32_bf16 v[12:15], v[178:181], v[162:165], v[12:15]
	v_mfma_f32_16x16x32_bf16 v[8:11], v[186:189], v[162:165], v[8:11]
	v_mfma_f32_16x16x32_bf16 v[4:7], v[178:181], v[170:173], v[4:7]
	v_mfma_f32_16x16x32_bf16 v[0:3], v[186:189], v[170:173], v[0:3]
	v_mfma_f32_16x16x32_bf16 v[28:31], v[182:185], v[150:153], v[28:31]
	v_mfma_f32_16x16x32_bf16 v[24:27], v[196:199], v[150:153], v[24:27]
	v_mfma_f32_16x16x32_bf16 v[20:23], v[182:185], v[158:161], v[20:23]
	v_mfma_f32_16x16x32_bf16 v[16:19], v[196:199], v[158:161], v[16:19]
	v_mfma_f32_16x16x32_bf16 v[12:15], v[182:185], v[166:169], v[12:15]
	v_mfma_f32_16x16x32_bf16 v[8:11], v[196:199], v[166:169], v[8:11]
	v_mfma_f32_16x16x32_bf16 v[4:7], v[182:185], v[174:177], v[4:7]
	v_mfma_f32_16x16x32_bf16 v[0:3], v[196:199], v[174:177], v[0:3]
	s_barrier
	s_add_i32 s68, s68, 2
	s_add_u32 s10, s10, 0x100
	s_addc_u32 s11, s11, 0
	s_add_u32 s58, s58, 0x100
	s_addc_u32 s59, s59, 0
	s_cmpk_gt_u32 s68, 0x53
	s_cbranch_scc0 .LBB0_123
	ds_read_b128 v[130:133], v201 offset:0
	ds_read_b128 v[134:137], v201 offset:0x400
	ds_read_b128 v[138:141], v201 offset:0x800
	ds_read_b128 v[142:145], v201 offset:0xc00
	ds_read_b128 v[146:149], v202 offset:0
	ds_read_b128 v[150:153], v202 offset:0x400
	ds_read_b128 v[154:157], v202 offset:0x800
	ds_read_b128 v[158:161], v202 offset:0xc00
	ds_read_b128 v[162:165], v202 offset:0x1000
	ds_read_b128 v[166:169], v202 offset:0x1400
	ds_read_b128 v[170:173], v202 offset:0x1800
	s_mov_b64 s[10:11], 0x162b80
	s_mov_b32 m0, s74
	ds_read_b128 v[174:177], v202 offset:0x1c00
	v_lshl_add_u64 v[178:179], v[128:129], 0, s[10:11]
	s_mov_b64 s[10:11], 0x212b80
	global_load_lds_dwordx4 v[178:179], off
	v_lshl_add_u64 v[128:129], v[128:129], 0, s[10:11]
	s_mov_b32 m0, s61
	s_mul_i32 s10, s63, 0x2c0000
	global_load_lds_dwordx4 v[128:129], off
	s_mul_hi_i32 s11, s63, 0x2c0000
	s_add_u32 s10, s46, s10
	s_barrier
	s_waitcnt lgkmcnt(0)
	s_addc_u32 s11, s47, s11
	s_mul_i32 s58, s64, 0x2c0000
	s_mul_hi_i32 s59, s64, 0x2c0000
	s_add_u32 s58, s12, s58
	s_addc_u32 s59, s13, s59
	v_mfma_f32_16x16x32_bf16 v[124:127], v[130:133], v[146:149], v[124:127]
	v_mfma_f32_16x16x32_bf16 v[120:123], v[138:141], v[146:149], v[120:123]
	v_mfma_f32_16x16x32_bf16 v[116:119], v[130:133], v[154:157], v[116:119]
	v_mfma_f32_16x16x32_bf16 v[112:115], v[138:141], v[154:157], v[112:115]
	v_mfma_f32_16x16x32_bf16 v[108:111], v[130:133], v[162:165], v[108:111]
	v_mfma_f32_16x16x32_bf16 v[104:107], v[138:141], v[162:165], v[104:107]
	v_mfma_f32_16x16x32_bf16 v[100:103], v[130:133], v[170:173], v[100:103]
	v_mfma_f32_16x16x32_bf16 v[96:99], v[138:141], v[170:173], v[96:99]
	v_mfma_f32_16x16x32_bf16 v[124:127], v[134:137], v[150:153], v[124:127]
	v_mfma_f32_16x16x32_bf16 v[120:123], v[142:145], v[150:153], v[120:123]
	v_mfma_f32_16x16x32_bf16 v[116:119], v[134:137], v[158:161], v[116:119]
	v_mfma_f32_16x16x32_bf16 v[112:115], v[142:145], v[158:161], v[112:115]
	v_mfma_f32_16x16x32_bf16 v[108:111], v[134:137], v[166:169], v[108:111]
	v_mfma_f32_16x16x32_bf16 v[104:107], v[142:145], v[166:169], v[104:107]
	v_mfma_f32_16x16x32_bf16 v[100:103], v[134:137], v[174:177], v[100:103]
	v_mfma_f32_16x16x32_bf16 v[96:99], v[142:145], v[174:177], v[96:99]
	s_barrier
	ds_read_b128 v[178:181], v203 offset:0
	ds_read_b128 v[182:185], v203 offset:0x400
	ds_read_b128 v[186:189], v203 offset:0x800
	ds_read_b128 v[196:199], v203 offset:0xc00
	s_barrier
; #define WAIT_V(n) asm volatile("s_waitcnt vmcnt(%0)" ::"n"(n) : "memory")
; #define SCHED() __builtin_amdgcn_sched_barrier(0)
; #define LGKM(n) asm volatile("s_waitcnt lgkmcnt(%0)" ::"n"(n) : "memory")
; #define LDA(b, h) do { const unsigned pa_ = lds0 + SLOTA(b, h) + wr * 8192 + laneoff; _Pragma("unroll") for (int m = 0; m < 4; ++m)   \
;       _Pragma("unroll") for (int k = 0; k < 2; ++k) DSR(At[m][k], pa_, m * 2048 + k * 1024); } while (0)
; #define LDB(dst, b, h) do { const unsigned pb_ = lds0 + SLOTB(b, h) + wc * 4096 + laneoff; _Pragma("unroll") for (int n = 0; n < 2; ++n) \
;       _Pragma("unroll") for (int k = 0; k < 2; ++k) DSR(dst[n][k], pb_, n * 2048 + k * 1024); } while (0)
; #define BAR __builtin_amdgcn_s_barrier()
; #define LGKM(n) asm volatile("s_waitcnt lgkmcnt(%0)" ::"n"(n) : "memory")
; template <int EPI, bool SWP> ...
;     ...
;     LDB(B1, 0, 1); BAR; LGKM(0); SCHED(); MMA(0, 1, B1); BAR; SCHED();
;     LDA(0, 1); WAIT_V(4); BAR; LGKM(0); SCHED(); MMA(1, 0, B0); MMA(1, 1, B1); BAR; SCHED(); }
;   { LDB(B0, 1, 0); LDA(1, 0); WAIT_V(2); BAR; LGKM(0); SCHED(); MMA(0, 0, B0); BAR; SCHED();
	s_waitcnt lgkmcnt(0)
	v_mfma_f32_16x16x32_bf16 v[92:95], v[178:181], v[146:149], v[92:95]
	v_mfma_f32_16x16x32_bf16 v[88:91], v[186:189], v[146:149], v[88:91]
	v_mfma_f32_16x16x32_bf16 v[84:87], v[178:181], v[154:157], v[84:87]
	v_mfma_f32_16x16x32_bf16 v[80:83], v[186:189], v[154:157], v[80:83]
	v_mfma_f32_16x16x32_bf16 v[76:79], v[178:181], v[162:165], v[76:79]
	v_mfma_f32_16x16x32_bf16 v[72:75], v[186:189], v[162:165], v[72:75]
	v_mfma_f32_16x16x32_bf16 v[68:71], v[178:181], v[170:173], v[68:71]
	v_mfma_f32_16x16x32_bf16 v[64:67], v[186:189], v[170:173], v[64:67]
	v_mfma_f32_16x16x32_bf16 v[92:95], v[182:185], v[150:153], v[92:95]
	v_mfma_f32_16x16x32_bf16 v[88:91], v[196:199], v[150:153], v[88:91]
	v_mfma_f32_16x16x32_bf16 v[84:87], v[182:185], v[158:161], v[84:87]
	v_mfma_f32_16x16x32_bf16 v[80:83], v[196:199], v[158:161], v[80:83]
	v_mfma_f32_16x16x32_bf16 v[76:79], v[182:185], v[166:169], v[76:79]
	v_mfma_f32_16x16x32_bf16 v[72:75], v[196:199], v[166:169], v[72:75]
	v_mfma_f32_16x16x32_bf16 v[68:71], v[182:185], v[174:177], v[68:71]
	v_mfma_f32_16x16x32_bf16 v[64:67], v[196:199], v[174:177], v[64:67]
	s_barrier
	ds_read_b128 v[146:149], v204 offset:0
	ds_read_b128 v[150:153], v204 offset:0x400
	ds_read_b128 v[154:157], v204 offset:0x800
	ds_read_b128 v[158:161], v204 offset:0xc00
	ds_read_b128 v[162:165], v204 offset:0x1000
	ds_read_b128 v[166:169], v204 offset:0x1400
	ds_read_b128 v[170:173], v204 offset:0x1800
	ds_read_b128 v[174:177], v204 offset:0x1c00
	s_waitcnt vmcnt(4)
	s_barrier
	s_waitcnt lgkmcnt(0)
	v_mfma_f32_16x16x32_bf16 v[60:63], v[130:133], v[146:149], v[60:63]
	v_mfma_f32_16x16x32_bf16 v[56:59], v[138:141], v[146:149], v[56:59]
	v_mfma_f32_16x16x32_bf16 v[52:55], v[130:133], v[154:157], v[52:55]
	v_mfma_f32_16x16x32_bf16 v[48:51], v[138:141], v[154:157], v[48:51]
	v_mfma_f32_16x16x32_bf16 v[44:47], v[130:133], v[162:165], v[44:47]
	v_mfma_f32_16x16x32_bf16 v[40:43], v[138:141], v[162:165], v[40:43]
	v_mfma_f32_16x16x32_bf16 v[36:39], v[130:133], v[170:173], v[36:39]
	v_mfma_f32_16x16x32_bf16 v[32:35], v[138:141], v[170:173], v[32:35]
	v_mfma_f32_16x16x32_bf16 v[60:63], v[134:137], v[150:153], v[60:63]
	v_mfma_f32_16x16x32_bf16 v[56:59], v[142:145], v[150:153], v[56:59]
	v_mfma_f32_16x16x32_bf16 v[52:55], v[134:137], v[158:161], v[52:55]
	v_mfma_f32_16x16x32_bf16 v[48:51], v[142:145], v[158:161], v[48:51]
	v_mfma_f32_16x16x32_bf16 v[44:47], v[134:137], v[166:169], v[44:47]
	v_mfma_f32_16x16x32_bf16 v[40:43], v[142:145], v[166:169], v[40:43]
	v_mfma_f32_16x16x32_bf16 v[36:39], v[134:137], v[174:177], v[36:39]
	v_mfma_f32_16x16x32_bf16 v[32:35], v[142:145], v[174:177], v[32:35]
	v_mfma_f32_16x16x32_bf16 v[28:31], v[178:181], v[146:149], v[28:31]
	v_mfma_f32_16x16x32_bf16 v[24:27], v[186:189], v[146:149], v[24:27]
	v_mfma_f32_16x16x32_bf16 v[20:23], v[178:181], v[154:157], v[20:23]
	v_mfma_f32_16x16x32_bf16 v[16:19], v[186:189], v[154:157], v[16:19]
	v_mfma_f32_16x16x32_bf16 v[12:15], v[178:181], v[162:165], v[12:15]
	v_mfma_f32_16x16x32_bf16 v[8:11], v[186:189], v[162:165], v[8:11]
	v_mfma_f32_16x16x32_bf16 v[4:7], v[178:181], v[170:173], v[4:7]
	v_mfma_f32_16x16x32_bf16 v[0:3], v[186:189], v[170:173], v[0:3]
	v_mfma_f32_16x16x32_bf16 v[28:31], v[182:185], v[150:153], v[28:31]
	v_mfma_f32_16x16x32_bf16 v[24:27], v[196:199], v[150:153], v[24:27]
	v_mfma_f32_16x16x32_bf16 v[20:23], v[182:185], v[158:161], v[20:23]
	v_mfma_f32_16x16x32_bf16 v[16:19], v[196:199], v[158:161], v[16:19]
	v_mfma_f32_16x16x32_bf16 v[12:15], v[182:185], v[166:169], v[12:15]
	v_mfma_f32_16x16x32_bf16 v[8:11], v[196:199], v[166:169], v[8:11]
	v_mfma_f32_16x16x32_bf16 v[4:7], v[182:185], v[174:177], v[4:7]
	v_mfma_f32_16x16x32_bf16 v[0:3], v[196:199], v[174:177], v[0:3]
	s_barrier
	ds_read_b128 v[128:131], v205 offset:0
	ds_read_b128 v[132:135], v205 offset:0x400
	ds_read_b128 v[136:139], v205 offset:0x800
	ds_read_b128 v[140:143], v205 offset:0xc00
	ds_read_b128 v[160:163], v206 offset:0
	ds_read_b128 v[164:167], v206 offset:0x400
	ds_read_b128 v[168:171], v206 offset:0x800
	ds_read_b128 v[172:175], v206 offset:0xc00
	ds_read_b128 v[176:179], v206 offset:0x1000
	ds_read_b128 v[180:183], v206 offset:0x1400
	ds_read_b128 v[184:187], v206 offset:0x1800
	ds_read_b128 v[188:191], v206 offset:0x1c00
	s_waitcnt vmcnt(2)
	s_barrier
	s_waitcnt lgkmcnt(0)
	v_mfma_f32_16x16x32_bf16 v[124:127], v[128:131], v[160:163], v[124:127]
	v_mfma_f32_16x16x32_bf16 v[120:123], v[136:139], v[160:163], v[120:123]
	v_mfma_f32_16x16x32_bf16 v[116:119], v[128:131], v[168:171], v[116:119]
	v_mfma_f32_16x16x32_bf16 v[112:115], v[136:139], v[168:171], v[112:115]
	v_mfma_f32_16x16x32_bf16 v[108:111], v[128:131], v[176:179], v[108:111]
	v_mfma_f32_16x16x32_bf16 v[104:107], v[136:139], v[176:179], v[104:107]
	v_mfma_f32_16x16x32_bf16 v[100:103], v[128:131], v[184:187], v[100:103]
	v_mfma_f32_16x16x32_bf16 v[96:99], v[136:139], v[184:187], v[96:99]
	v_mfma_f32_16x16x32_bf16 v[124:127], v[132:135], v[164:167], v[124:127]
	v_mfma_f32_16x16x32_bf16 v[120:123], v[140:143], v[164:167], v[120:123]
	v_mfma_f32_16x16x32_bf16 v[116:119], v[132:135], v[172:175], v[116:119]
	v_mfma_f32_16x16x32_bf16 v[112:115], v[140:143], v[172:175], v[112:115]
	v_mfma_f32_16x16x32_bf16 v[108:111], v[132:135], v[180:183], v[108:111]
	v_mfma_f32_16x16x32_bf16 v[104:107], v[140:143], v[180:183], v[104:107]
	v_mfma_f32_16x16x32_bf16 v[100:103], v[132:135], v[188:191], v[100:103]
	v_mfma_f32_16x16x32_bf16 v[96:99], v[140:143], v[188:191], v[96:99]
	s_barrier
; #define WAIT_V(n) asm volatile("s_waitcnt vmcnt(%0)" ::"n"(n) : "memory")
; #define SCHED() __builtin_amdgcn_sched_barrier(0)
; #define LGKM(n) asm volatile("s_waitcnt lgkmcnt(%0)" ::"n"(n) : "memory")
; #define STAGE_AX(AG, b, h, kt) do { _Pragma("unroll") for (int i = 0; i < 2; ++i)                                    \
;       __builtin_amdgcn_global_load_lds((const unsigned*)(((AG) + ((size_t)(kt) * (BK * 2) + (size_t)((h) * 2 + i) * 128 * lda)) + aoff), \
;                                        (unsigned*)(shm + SLOTA(b, h) + wid * 1024 + i * 8192), 16, 0, 0); } while (0)
; #define STAGE_BX(BG, b, h, kt) do { _Pragma("unroll") for (int i = 0; i < 2; ++i)                                    \
;       __builtin_amdgcn_global_load_lds((const unsigned*)(((BG) + ((size_t)(kt) * (BK * 2) + (size_t)((h) * 2 + i) * 128 * K)) + boff),   \
;                                        (unsigned*)(shm + SLOTB(b, h) + wid * 1024 + i * 8192), 16, 0, 0); } while (0)
; #define LDA(b, h) do { const unsigned pa_ = lds0 + SLOTA(b, h) + wr * 8192 + laneoff; _Pragma("unroll") for (int m = 0; m < 4; ++m)   \
;       _Pragma("unroll") for (int k = 0; k < 2; ++k) DSR(At[m][k], pa_, m * 2048 + k * 1024); } while (0)
; #define LDB(dst, b, h) do { const unsigned pb_ = lds0 + SLOTB(b, h) + wc * 4096 + laneoff; _Pragma("unroll") for (int n = 0; n < 2; ++n) \
;       _Pragma("unroll") for (int k = 0; k < 2; ++k) DSR(dst[n][k], pb_, n * 2048 + k * 1024); } while (0)
; #define BAR __builtin_amdgcn_s_barrier()
; #define LGKM(n) asm volatile("s_waitcnt lgkmcnt(%0)" ::"n"(n) : "memory")
; template <int EPI, bool SWP> ...
;     ...
;   { LDB(B0, 1, 0); LDA(1, 0); WAIT_V(2); BAR; LGKM(0); SCHED(); MMA(0, 0, B0); BAR; SCHED();
;     LDB(B1, 1, 1); WAIT_V(0); BAR; LGKM(0); SCHED(); MMA(0, 1, B1); BAR; SCHED();
;     LDA(1, 1);
;     if (has_next) { STAGE_BX(Bg_n, 0, 0, 0); STAGE_AX(Ag_n, 0, 0, 0); STAGE_BX(Bg_n, 0, 1, 0); STAGE_AX(Ag_n, 0, 1, 0); }
;     BAR; LGKM(0); SCHED(); MMA(1, 0, B0); MMA(1, 1, B1); BAR; SCHED(); }
;   if (wr == 0) BAR;
	ds_read_b128 v[144:147], v207 offset:0
	ds_read_b128 v[148:151], v207 offset:0x400
	ds_read_b128 v[152:155], v207 offset:0x800
	ds_read_b128 v[156:159], v207 offset:0xc00
	s_waitcnt vmcnt(0)
	s_barrier
	s_waitcnt lgkmcnt(0)
	v_mfma_f32_16x16x32_bf16 v[92:95], v[144:147], v[160:163], v[92:95]
	v_mfma_f32_16x16x32_bf16 v[88:91], v[152:155], v[160:163], v[88:91]
	v_mfma_f32_16x16x32_bf16 v[84:87], v[144:147], v[168:171], v[84:87]
	v_mfma_f32_16x16x32_bf16 v[80:83], v[152:155], v[168:171], v[80:83]
	v_mfma_f32_16x16x32_bf16 v[76:79], v[144:147], v[176:179], v[76:79]
	v_mfma_f32_16x16x32_bf16 v[72:75], v[152:155], v[176:179], v[72:75]
	v_mfma_f32_16x16x32_bf16 v[68:71], v[144:147], v[184:187], v[68:71]
	v_mfma_f32_16x16x32_bf16 v[64:67], v[152:155], v[184:187], v[64:67]
	v_mfma_f32_16x16x32_bf16 v[92:95], v[148:151], v[164:167], v[92:95]
	v_mfma_f32_16x16x32_bf16 v[88:91], v[156:159], v[164:167], v[88:91]
	v_mfma_f32_16x16x32_bf16 v[84:87], v[148:151], v[172:175], v[84:87]
	v_mfma_f32_16x16x32_bf16 v[80:83], v[156:159], v[172:175], v[80:83]
	v_mfma_f32_16x16x32_bf16 v[76:79], v[148:151], v[180:183], v[76:79]
	v_mfma_f32_16x16x32_bf16 v[72:75], v[156:159], v[180:183], v[72:75]
	v_mfma_f32_16x16x32_bf16 v[68:71], v[148:151], v[188:191], v[68:71]
	v_mfma_f32_16x16x32_bf16 v[64:67], v[156:159], v[188:191], v[64:67]
	s_barrier
	ds_read_b128 v[184:187], v208 offset:0
	ds_read_b128 v[188:191], v208 offset:0x400
	ds_read_b128 v[176:179], v208 offset:0x800
	ds_read_b128 v[180:183], v208 offset:0xc00
	ds_read_b128 v[168:171], v208 offset:0x1000
	ds_read_b128 v[172:175], v208 offset:0x1400
	ds_read_b128 v[160:163], v208 offset:0x1800
	ds_read_b128 v[164:167], v208 offset:0x1c00
	s_and_b64 vcc, exec, s[48:49]
	v_lshl_add_u64 v[196:197], s[58:59], 0, v[192:193]
	v_lshl_add_u64 v[198:199], s[10:11], 0, v[192:193]
	s_cbranch_vccz .LBB0_126
	s_mov_b32 m0, s17
	v_lshl_add_u64 v[220:221], v[196:197], 0, s[14:15]
	global_load_lds_dwordx4 v[196:197], off
	s_mov_b32 m0, s18
	s_nop 0
	global_load_lds_dwordx4 v[220:221], off
	s_mov_b32 m0, s3
	v_lshl_add_u64 v[220:221], v[198:199], 0, s[14:15]
	global_load_lds_dwordx4 v[198:199], off
	s_mov_b32 m0, s19
	s_nop 0
	global_load_lds_dwordx4 v[220:221], off
	v_lshl_add_u64 v[220:221], v[196:197], 0, s[20:21]
	s_mov_b32 m0, s69
	s_nop 0
	global_load_lds_dwordx4 v[220:221], off
	v_lshl_add_u64 v[220:221], v[196:197], 0, s[22:23]
	s_mov_b32 m0, s30
	s_nop 0
	global_load_lds_dwordx4 v[220:221], off
	v_lshl_add_u64 v[220:221], v[198:199], 0, s[20:21]
	s_mov_b32 m0, s71
	s_nop 0
	global_load_lds_dwordx4 v[220:221], off
	v_lshl_add_u64 v[220:221], v[198:199], 0, s[22:23]
	s_mov_b32 m0, s31
	s_nop 0
	global_load_lds_dwordx4 v[220:221], off
.LBB0_126:
	s_barrier
	s_waitcnt lgkmcnt(0)
	v_mfma_f32_16x16x32_bf16 v[60:63], v[128:131], v[184:187], v[60:63]
	v_mfma_f32_16x16x32_bf16 v[56:59], v[136:139], v[184:187], v[56:59]
	v_mfma_f32_16x16x32_bf16 v[52:55], v[128:131], v[176:179], v[52:55]
	v_mfma_f32_16x16x32_bf16 v[48:51], v[136:139], v[176:179], v[48:51]
	v_mfma_f32_16x16x32_bf16 v[44:47], v[128:131], v[168:171], v[44:47]
	v_mfma_f32_16x16x32_bf16 v[40:43], v[136:139], v[168:171], v[40:43]
	v_mfma_f32_16x16x32_bf16 v[36:39], v[128:131], v[160:163], v[36:39]
	v_mfma_f32_16x16x32_bf16 v[32:35], v[136:139], v[160:163], v[32:35]
	v_mfma_f32_16x16x32_bf16 v[60:63], v[132:135], v[188:191], v[60:63]
	v_mfma_f32_16x16x32_bf16 v[56:59], v[140:143], v[188:191], v[56:59]
	v_mfma_f32_16x16x32_bf16 v[52:55], v[132:135], v[180:183], v[52:55]
	v_mfma_f32_16x16x32_bf16 v[48:51], v[140:143], v[180:183], v[48:51]
	v_mfma_f32_16x16x32_bf16 v[44:47], v[132:135], v[172:175], v[44:47]
	v_mfma_f32_16x16x32_bf16 v[40:43], v[140:143], v[172:175], v[40:43]
	v_mfma_f32_16x16x32_bf16 v[36:39], v[132:135], v[164:167], v[36:39]
	v_mfma_f32_16x16x32_bf16 v[32:35], v[140:143], v[164:167], v[32:35]
	v_mfma_f32_16x16x32_bf16 v[28:31], v[144:147], v[184:187], v[28:31]
	v_mfma_f32_16x16x32_bf16 v[24:27], v[152:155], v[184:187], v[24:27]
	v_mfma_f32_16x16x32_bf16 v[20:23], v[144:147], v[176:179], v[20:23]
	v_mfma_f32_16x16x32_bf16 v[16:19], v[152:155], v[176:179], v[16:19]
	v_mfma_f32_16x16x32_bf16 v[12:15], v[144:147], v[168:171], v[12:15]
	v_mfma_f32_16x16x32_bf16 v[8:11], v[152:155], v[168:171], v[8:11]
	v_mfma_f32_16x16x32_bf16 v[4:7], v[144:147], v[160:163], v[4:7]
	v_mfma_f32_16x16x32_bf16 v[0:3], v[152:155], v[160:163], v[0:3]
	v_mfma_f32_16x16x32_bf16 v[28:31], v[148:151], v[188:191], v[28:31]
	v_mfma_f32_16x16x32_bf16 v[24:27], v[156:159], v[188:191], v[24:27]
	v_mfma_f32_16x16x32_bf16 v[20:23], v[148:151], v[180:183], v[20:23]
	v_mfma_f32_16x16x32_bf16 v[16:19], v[156:159], v[180:183], v[16:19]
	v_mfma_f32_16x16x32_bf16 v[12:15], v[148:151], v[172:175], v[12:15]
	v_mfma_f32_16x16x32_bf16 v[8:11], v[156:159], v[172:175], v[8:11]
	v_mfma_f32_16x16x32_bf16 v[4:7], v[148:151], v[164:167], v[4:7]
	v_mfma_f32_16x16x32_bf16 v[0:3], v[156:159], v[164:167], v[0:3]
	s_barrier
	s_andn2_b64 vcc, exec, s[4:5]
	s_cbranch_vccnz .LBB0_128
	s_barrier

; #define WAIT_V(n) asm volatile("s_waitcnt vmcnt(%0)" ::"n"(n) : "memory")
; #define SCHED() __builtin_amdgcn_sched_barrier(0)
; #define LGKM(n) asm volatile("s_waitcnt lgkmcnt(%0)" ::"n"(n) : "memory")
; #define STAGE_A(b, h, kt) STAGE_AX(Ag, b, h, kt)
; #define STAGE_B(b, h, kt) STAGE_BX(Bg, b, h, kt)
; #define LDA(b, h) do { const unsigned pa_ = lds0 + SLOTA(b, h) + wr * 8192 + laneoff; _Pragma("unroll") for (int m = 0; m < 4; ++m)   \
;       _Pragma("unroll") for (int k = 0; k < 2; ++k) DSR(At[m][k], pa_, m * 2048 + k * 1024); } while (0)
; #define LDB(dst, b, h) do { const unsigned pb_ = lds0 + SLOTB(b, h) + wc * 4096 + laneoff; _Pragma("unroll") for (int n = 0; n < 2; ++n) \
;       _Pragma("unroll") for (int k = 0; k < 2; ++k) DSR(dst[n][k], pb_, n * 2048 + k * 1024); } while (0)
; #define BAR __builtin_amdgcn_s_barrier()
; #define LGKM(n) asm volatile("s_waitcnt lgkmcnt(%0)" ::"n"(n) : "memory")
; template <int EPI, bool SWP> ...
;     ...
;   for (int t = 0; t < nt - 2; t += 2) {
;     LDB(B0, 0, 0); LDA(0, 0); STAGE_A(1, 1, t + 1);
;     LGKM(8); BAR; LGKM(0); SCHED(); MMA(0, 0, B0); BAR; SCHED();
;     LDB(B1, 0, 1); STAGE_B(0, 0, t + 2);
;     BAR; LGKM(0); SCHED(); MMA(0, 1, B1); BAR; SCHED();
;     LDA(0, 1); STAGE_A(0, 0, t + 2);
;     BAR; LGKM(0); SCHED(); MMA(1, 0, B0); BAR; SCHED();
;     STAGE_B(0, 1, t + 2);
;     WAIT_V(6); BAR; SCHED(); MMA(1, 1, B1); BAR; SCHED();
.LBB0_197:
	ds_read_b128 v[128:131], v203 offset:0
	ds_read_b128 v[132:135], v203 offset:0x400
	ds_read_b128 v[136:139], v203 offset:0x800
	ds_read_b128 v[140:143], v203 offset:0xc00
	ds_read_b128 v[144:147], v204 offset:0
	ds_read_b128 v[148:151], v204 offset:0x400
	ds_read_b128 v[152:155], v204 offset:0x800
	ds_read_b128 v[156:159], v204 offset:0xc00
	ds_read_b128 v[160:163], v204 offset:0x1000
	ds_read_b128 v[164:167], v204 offset:0x1400
	ds_read_b128 v[168:171], v204 offset:0x1800
	v_lshl_add_u64 v[200:201], s[12:13], 0, v[196:197]
	s_add_i32 vcc_lo, s69, 0xc000
	ds_read_b128 v[172:175], v204 offset:0x1c00
	v_lshl_add_u64 v[176:177], v[200:201], 0, s[80:81]
	s_mov_b32 m0, vcc_lo
	s_nop 0
	global_load_lds_dwordx4 v[176:177], off
	v_lshl_add_u64 v[176:177], v[200:201], 0, s[82:83]
	s_mov_b32 m0, s17
	s_nop 0
	global_load_lds_dwordx4 v[176:177], off
	s_waitcnt lgkmcnt(8)
	s_barrier
	s_waitcnt lgkmcnt(0)
	v_mfma_f32_16x16x32_bf16 v[124:127], v[128:131], v[144:147], v[124:127]
	v_mfma_f32_16x16x32_bf16 v[120:123], v[136:139], v[144:147], v[120:123]
	v_mfma_f32_16x16x32_bf16 v[116:119], v[128:131], v[152:155], v[116:119]
	v_mfma_f32_16x16x32_bf16 v[112:115], v[136:139], v[152:155], v[112:115]
	v_mfma_f32_16x16x32_bf16 v[108:111], v[128:131], v[160:163], v[108:111]
	v_mfma_f32_16x16x32_bf16 v[104:107], v[136:139], v[160:163], v[104:107]
	v_mfma_f32_16x16x32_bf16 v[100:103], v[128:131], v[168:171], v[100:103]
	v_mfma_f32_16x16x32_bf16 v[96:99], v[136:139], v[168:171], v[96:99]
	v_mfma_f32_16x16x32_bf16 v[124:127], v[132:135], v[148:151], v[124:127]
	v_mfma_f32_16x16x32_bf16 v[120:123], v[140:143], v[148:151], v[120:123]
	v_mfma_f32_16x16x32_bf16 v[116:119], v[132:135], v[156:159], v[116:119]
	v_mfma_f32_16x16x32_bf16 v[112:115], v[140:143], v[156:159], v[112:115]
	v_mfma_f32_16x16x32_bf16 v[108:111], v[132:135], v[164:167], v[108:111]
	v_mfma_f32_16x16x32_bf16 v[104:107], v[140:143], v[164:167], v[104:107]
	v_mfma_f32_16x16x32_bf16 v[100:103], v[132:135], v[172:175], v[100:103]
	v_mfma_f32_16x16x32_bf16 v[96:99], v[140:143], v[172:175], v[96:99]
	s_barrier
	ds_read_b128 v[176:179], v205 offset:0
	ds_read_b128 v[180:183], v205 offset:0x400
	ds_read_b128 v[184:187], v205 offset:0x800
	v_lshl_add_u64 v[224:225], s[6:7], 0, v[196:197]
	s_mov_b32 m0, s68
	ds_read_b128 v[188:191], v205 offset:0xc00
	v_lshl_add_u64 v[226:227], v[224:225], 0, s[84:85]
	global_load_lds_dwordx4 v[226:227], off
	v_lshl_add_u64 v[226:227], v[224:225], 0, s[86:87]
	s_mov_b32 m0, s64
	s_nop 0
	global_load_lds_dwordx4 v[226:227], off
	s_barrier
	s_waitcnt lgkmcnt(0)
	v_mfma_f32_16x16x32_bf16 v[92:95], v[176:179], v[144:147], v[92:95]
	v_mfma_f32_16x16x32_bf16 v[88:91], v[184:187], v[144:147], v[88:91]
	v_mfma_f32_16x16x32_bf16 v[84:87], v[176:179], v[152:155], v[84:87]
	v_mfma_f32_16x16x32_bf16 v[80:83], v[184:187], v[152:155], v[80:83]
	v_mfma_f32_16x16x32_bf16 v[76:79], v[176:179], v[160:163], v[76:79]
	v_mfma_f32_16x16x32_bf16 v[72:75], v[184:187], v[160:163], v[72:75]
	v_mfma_f32_16x16x32_bf16 v[68:71], v[176:179], v[168:171], v[68:71]
	v_mfma_f32_16x16x32_bf16 v[64:67], v[184:187], v[168:171], v[64:67]
	v_mfma_f32_16x16x32_bf16 v[92:95], v[180:183], v[148:151], v[92:95]
	v_mfma_f32_16x16x32_bf16 v[88:91], v[188:191], v[148:151], v[88:91]
	v_mfma_f32_16x16x32_bf16 v[84:87], v[180:183], v[156:159], v[84:87]
	v_mfma_f32_16x16x32_bf16 v[80:83], v[188:191], v[156:159], v[80:83]
	v_mfma_f32_16x16x32_bf16 v[76:79], v[180:183], v[164:167], v[76:79]
	v_mfma_f32_16x16x32_bf16 v[72:75], v[188:191], v[164:167], v[72:75]
	v_mfma_f32_16x16x32_bf16 v[68:71], v[180:183], v[172:175], v[68:71]
	v_mfma_f32_16x16x32_bf16 v[64:67], v[188:191], v[172:175], v[64:67]
	s_barrier
	ds_read_b128 v[144:147], v206 offset:0
	ds_read_b128 v[148:151], v206 offset:0x400
	ds_read_b128 v[152:155], v206 offset:0x800
	ds_read_b128 v[156:159], v206 offset:0xc00
	ds_read_b128 v[160:163], v206 offset:0x1000
	ds_read_b128 v[164:167], v206 offset:0x1400
	ds_read_b128 v[168:171], v206 offset:0x1800
	s_mov_b32 m0, s69
	ds_read_b128 v[172:175], v206 offset:0x1c00
	v_lshl_add_u64 v[226:227], v[200:201], 0, s[88:89]
	global_load_lds_dwordx4 v[226:227], off
	v_lshl_add_u64 v[226:227], v[200:201], 0, s[90:91]
	s_mov_b32 m0, s65
	s_nop 0
	global_load_lds_dwordx4 v[226:227], off
	s_barrier
	s_waitcnt lgkmcnt(0)
	v_mfma_f32_16x16x32_bf16 v[60:63], v[128:131], v[144:147], v[60:63]
	v_mfma_f32_16x16x32_bf16 v[56:59], v[136:139], v[144:147], v[56:59]
	v_mfma_f32_16x16x32_bf16 v[52:55], v[128:131], v[152:155], v[52:55]
	v_mfma_f32_16x16x32_bf16 v[48:51], v[136:139], v[152:155], v[48:51]
	v_mfma_f32_16x16x32_bf16 v[44:47], v[128:131], v[160:163], v[44:47]
	v_mfma_f32_16x16x32_bf16 v[40:43], v[136:139], v[160:163], v[40:43]
	v_mfma_f32_16x16x32_bf16 v[36:39], v[128:131], v[168:171], v[36:39]
	v_mfma_f32_16x16x32_bf16 v[32:35], v[136:139], v[168:171], v[32:35]
	v_mfma_f32_16x16x32_bf16 v[60:63], v[132:135], v[148:151], v[60:63]
	v_mfma_f32_16x16x32_bf16 v[56:59], v[140:143], v[148:151], v[56:59]
	v_mfma_f32_16x16x32_bf16 v[52:55], v[132:135], v[156:159], v[52:55]
	v_mfma_f32_16x16x32_bf16 v[48:51], v[140:143], v[156:159], v[48:51]
	v_mfma_f32_16x16x32_bf16 v[44:47], v[132:135], v[164:167], v[44:47]
	v_mfma_f32_16x16x32_bf16 v[40:43], v[140:143], v[164:167], v[40:43]
	v_mfma_f32_16x16x32_bf16 v[36:39], v[132:135], v[172:175], v[36:39]
	v_mfma_f32_16x16x32_bf16 v[32:35], v[140:143], v[172:175], v[32:35]
	s_barrier
	s_add_i32 s23, s69, 0x14000
	v_lshl_add_u64 v[128:129], v[224:225], 0, s[92:93]
	s_mov_b32 m0, s23
	s_nop 0
	global_load_lds_dwordx4 v[128:129], off
	v_lshl_add_u64 v[128:129], v[224:225], 0, s[94:95]
	s_mov_b32 m0, s50
	s_nop 0
	global_load_lds_dwordx4 v[128:129], off
	s_waitcnt vmcnt(6)
	s_barrier
; #define WAIT_V(n) asm volatile("s_waitcnt vmcnt(%0)" ::"n"(n) : "memory")
; #define SCHED() __builtin_amdgcn_sched_barrier(0)
; #define LGKM(n) asm volatile("s_waitcnt lgkmcnt(%0)" ::"n"(n) : "memory")
; #define STAGE_A(b, h, kt) STAGE_AX(Ag, b, h, kt)
; #define STAGE_B(b, h, kt) STAGE_BX(Bg, b, h, kt)
; #define LDA(b, h) do { const unsigned pa_ = lds0 + SLOTA(b, h) + wr * 8192 + laneoff; _Pragma("unroll") for (int m = 0; m < 4; ++m)   \
;       _Pragma("unroll") for (int k = 0; k < 2; ++k) DSR(At[m][k], pa_, m * 2048 + k * 1024); } while (0)
; #define LDB(dst, b, h) do { const unsigned pb_ = lds0 + SLOTB(b, h) + wc * 4096 + laneoff; _Pragma("unroll") for (int n = 0; n < 2; ++n) \
;       _Pragma("unroll") for (int k = 0; k < 2; ++k) DSR(dst[n][k], pb_, n * 2048 + k * 1024); } while (0)
; #define BAR __builtin_amdgcn_s_barrier()
; #define LGKM(n) asm volatile("s_waitcnt lgkmcnt(%0)" ::"n"(n) : "memory")
; template <int EPI, bool SWP> ...
;     ...
;     STAGE_B(0, 1, t + 2);
;     WAIT_V(6); BAR; SCHED(); MMA(1, 1, B1); BAR; SCHED();
;     LDB(B0, 1, 0); LDA(1, 0); STAGE_A(0, 1, t + 2);
;     LGKM(8); BAR; LGKM(0); SCHED(); MMA(0, 0, B0); BAR; SCHED();
;     LDB(B1, 1, 1); STAGE_B(1, 0, t + 3);
;     BAR; LGKM(0); SCHED(); MMA(0, 1, B1); BAR; SCHED();
;     LDA(1, 1); STAGE_A(1, 0, t + 3);
	v_mfma_f32_16x16x32_bf16 v[28:31], v[176:179], v[144:147], v[28:31]
	v_mfma_f32_16x16x32_bf16 v[24:27], v[184:187], v[144:147], v[24:27]
	v_mfma_f32_16x16x32_bf16 v[20:23], v[176:179], v[152:155], v[20:23]
	v_mfma_f32_16x16x32_bf16 v[16:19], v[184:187], v[152:155], v[16:19]
	v_mfma_f32_16x16x32_bf16 v[12:15], v[176:179], v[160:163], v[12:15]
	v_mfma_f32_16x16x32_bf16 v[8:11], v[184:187], v[160:163], v[8:11]
	v_mfma_f32_16x16x32_bf16 v[4:7], v[176:179], v[168:171], v[4:7]
	v_mfma_f32_16x16x32_bf16 v[0:3], v[184:187], v[168:171], v[0:3]
	v_mfma_f32_16x16x32_bf16 v[28:31], v[180:183], v[148:151], v[28:31]
	v_mfma_f32_16x16x32_bf16 v[24:27], v[188:191], v[148:151], v[24:27]
	v_mfma_f32_16x16x32_bf16 v[20:23], v[180:183], v[156:159], v[20:23]
	v_mfma_f32_16x16x32_bf16 v[16:19], v[188:191], v[156:159], v[16:19]
	v_mfma_f32_16x16x32_bf16 v[12:15], v[180:183], v[164:167], v[12:15]
	v_mfma_f32_16x16x32_bf16 v[8:11], v[188:191], v[164:167], v[8:11]
	v_mfma_f32_16x16x32_bf16 v[4:7], v[180:183], v[172:175], v[4:7]
	v_mfma_f32_16x16x32_bf16 v[0:3], v[188:191], v[172:175], v[0:3]
	s_barrier
	ds_read_b128 v[128:131], v207 offset:0
	ds_read_b128 v[132:135], v207 offset:0x400
	ds_read_b128 v[136:139], v207 offset:0x800
	ds_read_b128 v[140:143], v207 offset:0xc00
	ds_read_b128 v[144:147], v208 offset:0
	ds_read_b128 v[148:151], v208 offset:0x400
	ds_read_b128 v[152:155], v208 offset:0x800
	ds_read_b128 v[156:159], v208 offset:0xc00
	ds_read_b128 v[160:163], v208 offset:0x1000
	ds_read_b128 v[164:167], v208 offset:0x1400
	ds_read_b128 v[168:171], v208 offset:0x1800
	s_add_i32 s29, s69, 0x4000
	ds_read_b128 v[172:175], v208 offset:0x1c00
	v_lshl_add_u64 v[176:177], v[200:201], 0, s[96:97]
	s_mov_b32 m0, s29
	s_nop 0
	global_load_lds_dwordx4 v[176:177], off
	v_lshl_add_u64 v[176:177], v[200:201], 0, s[44:45]
	s_mov_b32 m0, s51
	s_nop 0
	global_load_lds_dwordx4 v[176:177], off
	s_waitcnt lgkmcnt(8)
	s_barrier
	s_waitcnt lgkmcnt(0)
	v_mfma_f32_16x16x32_bf16 v[124:127], v[128:131], v[144:147], v[124:127]
	v_mfma_f32_16x16x32_bf16 v[120:123], v[136:139], v[144:147], v[120:123]
	v_mfma_f32_16x16x32_bf16 v[116:119], v[128:131], v[152:155], v[116:119]
	v_mfma_f32_16x16x32_bf16 v[112:115], v[136:139], v[152:155], v[112:115]
	v_mfma_f32_16x16x32_bf16 v[108:111], v[128:131], v[160:163], v[108:111]
	v_mfma_f32_16x16x32_bf16 v[104:107], v[136:139], v[160:163], v[104:107]
	v_mfma_f32_16x16x32_bf16 v[100:103], v[128:131], v[168:171], v[100:103]
	v_mfma_f32_16x16x32_bf16 v[96:99], v[136:139], v[168:171], v[96:99]
	v_mfma_f32_16x16x32_bf16 v[124:127], v[132:135], v[148:151], v[124:127]
	v_mfma_f32_16x16x32_bf16 v[120:123], v[140:143], v[148:151], v[120:123]
	v_mfma_f32_16x16x32_bf16 v[116:119], v[132:135], v[156:159], v[116:119]
	v_mfma_f32_16x16x32_bf16 v[112:115], v[140:143], v[156:159], v[112:115]
	v_mfma_f32_16x16x32_bf16 v[108:111], v[132:135], v[164:167], v[108:111]
	v_mfma_f32_16x16x32_bf16 v[104:107], v[140:143], v[164:167], v[104:107]
	v_mfma_f32_16x16x32_bf16 v[100:103], v[132:135], v[172:175], v[100:103]
	v_mfma_f32_16x16x32_bf16 v[96:99], v[140:143], v[172:175], v[96:99]
	s_barrier
	ds_read_b128 v[176:179], v209 offset:0
	ds_read_b128 v[180:183], v209 offset:0x400
	ds_read_b128 v[184:187], v209 offset:0x800
	s_add_i32 s25, s69, 0x18000
	ds_read_b128 v[188:191], v209 offset:0xc00
	v_lshl_add_u64 v[226:227], v[224:225], 0, s[58:59]
	s_mov_b32 m0, s25
	s_nop 0
	global_load_lds_dwordx4 v[226:227], off
	v_lshl_add_u64 v[226:227], v[224:225], 0, s[60:61]
	s_mov_b32 m0, s66
	s_nop 0
	global_load_lds_dwordx4 v[226:227], off
	s_barrier
	s_waitcnt lgkmcnt(0)
	v_mfma_f32_16x16x32_bf16 v[92:95], v[176:179], v[144:147], v[92:95]
	v_mfma_f32_16x16x32_bf16 v[88:91], v[184:187], v[144:147], v[88:91]
	v_mfma_f32_16x16x32_bf16 v[84:87], v[176:179], v[152:155], v[84:87]
	v_mfma_f32_16x16x32_bf16 v[80:83], v[184:187], v[152:155], v[80:83]
	v_mfma_f32_16x16x32_bf16 v[76:79], v[176:179], v[160:163], v[76:79]
	v_mfma_f32_16x16x32_bf16 v[72:75], v[184:187], v[160:163], v[72:75]
	v_mfma_f32_16x16x32_bf16 v[68:71], v[176:179], v[168:171], v[68:71]
	v_mfma_f32_16x16x32_bf16 v[64:67], v[184:187], v[168:171], v[64:67]
	v_mfma_f32_16x16x32_bf16 v[92:95], v[180:183], v[148:151], v[92:95]
	v_mfma_f32_16x16x32_bf16 v[88:91], v[188:191], v[148:151], v[88:91]
	v_mfma_f32_16x16x32_bf16 v[84:87], v[180:183], v[156:159], v[84:87]
	v_mfma_f32_16x16x32_bf16 v[80:83], v[188:191], v[156:159], v[80:83]
	v_mfma_f32_16x16x32_bf16 v[76:79], v[180:183], v[164:167], v[76:79]
	v_mfma_f32_16x16x32_bf16 v[72:75], v[188:191], v[164:167], v[72:75]
	v_mfma_f32_16x16x32_bf16 v[68:71], v[180:183], v[172:175], v[68:71]
	v_mfma_f32_16x16x32_bf16 v[64:67], v[188:191], v[172:175], v[64:67]
	s_barrier
	ds_read_b128 v[144:147], v210 offset:0
	ds_read_b128 v[148:151], v210 offset:0x400
	ds_read_b128 v[152:155], v210 offset:0x800
	ds_read_b128 v[156:159], v210 offset:0xc00
	ds_read_b128 v[160:163], v210 offset:0x1000
	ds_read_b128 v[164:167], v210 offset:0x1400
	ds_read_b128 v[168:171], v210 offset:0x1800
	s_add_i32 s48, s69, 0x8000
	ds_read_b128 v[172:175], v210 offset:0x1c00
	v_lshl_add_u64 v[226:227], v[200:201], 0, s[0:1]
	s_mov_b32 m0, s48
	v_lshl_add_u64 v[200:201], v[200:201], 0, s[4:5]
	global_load_lds_dwordx4 v[226:227], off
	s_mov_b32 m0, s67
	s_nop 0
	global_load_lds_dwordx4 v[200:201], off
	s_barrier
; #define WAIT_V(n) asm volatile("s_waitcnt vmcnt(%0)" ::"n"(n) : "memory")
; #define SCHED() __builtin_amdgcn_sched_barrier(0)
; #define LGKM(n) asm volatile("s_waitcnt lgkmcnt(%0)" ::"n"(n) : "memory")
; #define STAGE_A(b, h, kt) STAGE_AX(Ag, b, h, kt)
; #define STAGE_B(b, h, kt) STAGE_BX(Bg, b, h, kt)
; #define LDA(b, h) do { const unsigned pa_ = lds0 + SLOTA(b, h) + wr * 8192 + laneoff; _Pragma("unroll") for (int m = 0; m < 4; ++m)   \
;       _Pragma("unroll") for (int k = 0; k < 2; ++k) DSR(At[m][k], pa_, m * 2048 + k * 1024); } while (0)
; #define LDB(dst, b, h) do { const unsigned pb_ = lds0 + SLOTB(b, h) + wc * 4096 + laneoff; _Pragma("unroll") for (int n = 0; n < 2; ++n) \
;       _Pragma("unroll") for (int k = 0; k < 2; ++k) DSR(dst[n][k], pb_, n * 2048 + k * 1024); } while (0)
; #define BAR __builtin_amdgcn_s_barrier()
; #define LGKM(n) asm volatile("s_waitcnt lgkmcnt(%0)" ::"n"(n) : "memory")
; template <int EPI, bool SWP> ...
;     ...
;     BAR; LGKM(0); SCHED(); MMA(1, 0, B0); BAR; SCHED();
;     STAGE_B(1, 1, t + 3);
;     WAIT_V(6); BAR; SCHED(); MMA(1, 1, B1); BAR; SCHED();
;   }
;   { LDB(B0, 0, 0); LDA(0, 0); STAGE_A(1, 1, nt - 1);
;     BAR; LGKM(0); SCHED(); MMA(0, 0, B0); BAR; SCHED();
;     LDB(B1, 0, 1); BAR; LGKM(0); SCHED(); MMA(0, 1, B1); BAR; SCHED();
	s_waitcnt lgkmcnt(0)
	v_mfma_f32_16x16x32_bf16 v[60:63], v[128:131], v[144:147], v[60:63]
	v_mfma_f32_16x16x32_bf16 v[56:59], v[136:139], v[144:147], v[56:59]
	v_mfma_f32_16x16x32_bf16 v[52:55], v[128:131], v[152:155], v[52:55]
	v_mfma_f32_16x16x32_bf16 v[48:51], v[136:139], v[152:155], v[48:51]
	v_mfma_f32_16x16x32_bf16 v[44:47], v[128:131], v[160:163], v[44:47]
	v_mfma_f32_16x16x32_bf16 v[40:43], v[136:139], v[160:163], v[40:43]
	v_mfma_f32_16x16x32_bf16 v[36:39], v[128:131], v[168:171], v[36:39]
	v_mfma_f32_16x16x32_bf16 v[32:35], v[136:139], v[168:171], v[32:35]
	v_mfma_f32_16x16x32_bf16 v[60:63], v[132:135], v[148:151], v[60:63]
	v_mfma_f32_16x16x32_bf16 v[56:59], v[140:143], v[148:151], v[56:59]
	v_mfma_f32_16x16x32_bf16 v[52:55], v[132:135], v[156:159], v[52:55]
	v_mfma_f32_16x16x32_bf16 v[48:51], v[140:143], v[156:159], v[48:51]
	v_mfma_f32_16x16x32_bf16 v[44:47], v[132:135], v[164:167], v[44:47]
	v_mfma_f32_16x16x32_bf16 v[40:43], v[140:143], v[164:167], v[40:43]
	v_mfma_f32_16x16x32_bf16 v[36:39], v[132:135], v[172:175], v[36:39]
	v_mfma_f32_16x16x32_bf16 v[32:35], v[140:143], v[172:175], v[32:35]
	s_barrier
	s_add_i32 s49, s69, 0x1c000
	v_lshl_add_u64 v[128:129], v[224:225], 0, s[34:35]
	s_mov_b32 m0, s49
	s_nop 0
	global_load_lds_dwordx4 v[128:129], off
	v_lshl_add_u64 v[128:129], v[224:225], 0, s[14:15]
	s_mov_b32 m0, s16
	s_nop 0
	global_load_lds_dwordx4 v[128:129], off
	s_waitcnt vmcnt(6)
	s_barrier
	v_mfma_f32_16x16x32_bf16 v[28:31], v[176:179], v[144:147], v[28:31]
	v_mfma_f32_16x16x32_bf16 v[24:27], v[184:187], v[144:147], v[24:27]
	v_mfma_f32_16x16x32_bf16 v[20:23], v[176:179], v[152:155], v[20:23]
	v_mfma_f32_16x16x32_bf16 v[16:19], v[184:187], v[152:155], v[16:19]
	v_mfma_f32_16x16x32_bf16 v[12:15], v[176:179], v[160:163], v[12:15]
	v_mfma_f32_16x16x32_bf16 v[8:11], v[184:187], v[160:163], v[8:11]
	v_mfma_f32_16x16x32_bf16 v[4:7], v[176:179], v[168:171], v[4:7]
	v_mfma_f32_16x16x32_bf16 v[0:3], v[184:187], v[168:171], v[0:3]
	v_mfma_f32_16x16x32_bf16 v[28:31], v[180:183], v[148:151], v[28:31]
	v_mfma_f32_16x16x32_bf16 v[24:27], v[188:191], v[148:151], v[24:27]
	v_mfma_f32_16x16x32_bf16 v[20:23], v[180:183], v[156:159], v[20:23]
	v_mfma_f32_16x16x32_bf16 v[16:19], v[188:191], v[156:159], v[16:19]
	v_mfma_f32_16x16x32_bf16 v[12:15], v[180:183], v[164:167], v[12:15]
	v_mfma_f32_16x16x32_bf16 v[8:11], v[188:191], v[164:167], v[8:11]
	v_mfma_f32_16x16x32_bf16 v[4:7], v[180:183], v[172:175], v[4:7]
	v_mfma_f32_16x16x32_bf16 v[0:3], v[188:191], v[172:175], v[0:3]
	s_barrier
	s_add_i32 s9, s9, 2
	s_add_u32 s6, s6, 0x100
	s_addc_u32 s7, s7, 0
	s_add_u32 s12, s12, 0x100
	s_addc_u32 s13, s13, 0
	s_cmp_gt_u32 s9, 27
	s_cbranch_scc0 .LBB0_197
	ds_read_b128 v[128:131], v203 offset:0
	ds_read_b128 v[132:135], v203 offset:0x400
	ds_read_b128 v[136:139], v203 offset:0x800
	ds_read_b128 v[140:143], v203 offset:0xc00
	ds_read_b128 v[144:147], v204 offset:0
	ds_read_b128 v[148:151], v204 offset:0x400
	ds_read_b128 v[152:155], v204 offset:0x800
	ds_read_b128 v[156:159], v204 offset:0xc00
	ds_read_b128 v[160:163], v204 offset:0x1000
	ds_read_b128 v[164:167], v204 offset:0x1400
	v_lshl_add_u64 v[176:177], s[76:77], 0, v[192:193]
	ds_read_b128 v[168:171], v204 offset:0x1800
	s_mov_b64 s[6:7], 0x80f80
	s_mov_b32 m0, vcc_lo
	ds_read_b128 v[172:175], v204 offset:0x1c00
	v_lshl_add_u64 v[178:179], v[176:177], 0, s[6:7]
	s_mov_b64 s[6:7], 0xc0f80
	global_load_lds_dwordx4 v[178:179], off
	v_lshl_add_u64 v[176:177], v[176:177], 0, s[6:7]
	s_mov_b32 m0, s17
	s_nop 0
	global_load_lds_dwordx4 v[176:177], off
	s_barrier
	s_waitcnt lgkmcnt(0)
	v_mfma_f32_16x16x32_bf16 v[124:127], v[128:131], v[144:147], v[124:127]
	v_mfma_f32_16x16x32_bf16 v[120:123], v[136:139], v[144:147], v[120:123]
	v_mfma_f32_16x16x32_bf16 v[116:119], v[128:131], v[152:155], v[116:119]
	v_mfma_f32_16x16x32_bf16 v[112:115], v[136:139], v[152:155], v[112:115]
	v_mfma_f32_16x16x32_bf16 v[108:111], v[128:131], v[160:163], v[108:111]
	v_mfma_f32_16x16x32_bf16 v[104:107], v[136:139], v[160:163], v[104:107]
	v_mfma_f32_16x16x32_bf16 v[100:103], v[128:131], v[168:171], v[100:103]
	v_mfma_f32_16x16x32_bf16 v[96:99], v[136:139], v[168:171], v[96:99]
	v_mfma_f32_16x16x32_bf16 v[124:127], v[132:135], v[148:151], v[124:127]
	v_mfma_f32_16x16x32_bf16 v[120:123], v[140:143], v[148:151], v[120:123]
	v_mfma_f32_16x16x32_bf16 v[116:119], v[132:135], v[156:159], v[116:119]
	v_mfma_f32_16x16x32_bf16 v[112:115], v[140:143], v[156:159], v[112:115]
	v_mfma_f32_16x16x32_bf16 v[108:111], v[132:135], v[164:167], v[108:111]
	v_mfma_f32_16x16x32_bf16 v[104:107], v[140:143], v[164:167], v[104:107]
	v_mfma_f32_16x16x32_bf16 v[100:103], v[132:135], v[172:175], v[100:103]
	v_mfma_f32_16x16x32_bf16 v[96:99], v[140:143], v[172:175], v[96:99]
	s_barrier
	ds_read_b128 v[176:179], v205 offset:0
	ds_read_b128 v[180:183], v205 offset:0x400
	ds_read_b128 v[184:187], v205 offset:0x800
	ds_read_b128 v[188:191], v205 offset:0xc00
	s_barrier
	s_waitcnt lgkmcnt(0)
	v_mfma_f32_16x16x32_bf16 v[92:95], v[176:179], v[144:147], v[92:95]
	v_mfma_f32_16x16x32_bf16 v[88:91], v[184:187], v[144:147], v[88:91]
	v_mfma_f32_16x16x32_bf16 v[84:87], v[176:179], v[152:155], v[84:87]
	v_mfma_f32_16x16x32_bf16 v[80:83], v[184:187], v[152:155], v[80:83]
	v_mfma_f32_16x16x32_bf16 v[76:79], v[176:179], v[160:163], v[76:79]
	v_mfma_f32_16x16x32_bf16 v[72:75], v[184:187], v[160:163], v[72:75]
	v_mfma_f32_16x16x32_bf16 v[68:71], v[176:179], v[168:171], v[68:71]
	v_mfma_f32_16x16x32_bf16 v[64:67], v[184:187], v[168:171], v[64:67]
	v_mfma_f32_16x16x32_bf16 v[92:95], v[180:183], v[148:151], v[92:95]
	v_mfma_f32_16x16x32_bf16 v[88:91], v[188:191], v[148:151], v[88:91]
	v_mfma_f32_16x16x32_bf16 v[84:87], v[180:183], v[156:159], v[84:87]
	v_mfma_f32_16x16x32_bf16 v[80:83], v[188:191], v[156:159], v[80:83]
	v_mfma_f32_16x16x32_bf16 v[76:79], v[180:183], v[164:167], v[76:79]
	v_mfma_f32_16x16x32_bf16 v[72:75], v[188:191], v[164:167], v[72:75]
	v_mfma_f32_16x16x32_bf16 v[68:71], v[180:183], v[172:175], v[68:71]
	v_mfma_f32_16x16x32_bf16 v[64:67], v[188:191], v[172:175], v[64:67]
	s_barrier
; #define WAIT_V(n) asm volatile("s_waitcnt vmcnt(%0)" ::"n"(n) : "memory")
; #define SCHED() __builtin_amdgcn_sched_barrier(0)
; #define LGKM(n) asm volatile("s_waitcnt lgkmcnt(%0)" ::"n"(n) : "memory")
; #define LDA(b, h) do { const unsigned pa_ = lds0 + SLOTA(b, h) + wr * 8192 + laneoff; _Pragma("unroll") for (int m = 0; m < 4; ++m)   \
;       _Pragma("unroll") for (int k = 0; k < 2; ++k) DSR(At[m][k], pa_, m * 2048 + k * 1024); } while (0)
; #define LDB(dst, b, h) do { const unsigned pb_ = lds0 + SLOTB(b, h) + wc * 4096 + laneoff; _Pragma("unroll") for (int n = 0; n < 2; ++n) \
;       _Pragma("unroll") for (int k = 0; k < 2; ++k) DSR(dst[n][k], pb_, n * 2048 + k * 1024); } while (0)
; #define BAR __builtin_amdgcn_s_barrier()
; #define LGKM(n) asm volatile("s_waitcnt lgkmcnt(%0)" ::"n"(n) : "memory")
; template <int EPI, bool SWP> ...
;     ...
;     LDA(0, 1); WAIT_V(4); BAR; LGKM(0); SCHED(); MMA(1, 0, B0); MMA(1, 1, B1); BAR; SCHED(); }
;   { LDB(B0, 1, 0); LDA(1, 0); WAIT_V(2); BAR; LGKM(0); SCHED(); MMA(0, 0, B0); BAR; SCHED();
	ds_read_b128 v[144:147], v206 offset:0
	ds_read_b128 v[148:151], v206 offset:0x400
	ds_read_b128 v[152:155], v206 offset:0x800
	ds_read_b128 v[156:159], v206 offset:0xc00
	ds_read_b128 v[160:163], v206 offset:0x1000
	ds_read_b128 v[164:167], v206 offset:0x1400
	ds_read_b128 v[168:171], v206 offset:0x1800
	ds_read_b128 v[172:175], v206 offset:0x1c00
	s_waitcnt vmcnt(4)
	s_barrier
	s_waitcnt lgkmcnt(0)
	v_mfma_f32_16x16x32_bf16 v[60:63], v[128:131], v[144:147], v[60:63]
	v_mfma_f32_16x16x32_bf16 v[56:59], v[136:139], v[144:147], v[56:59]
	v_mfma_f32_16x16x32_bf16 v[52:55], v[128:131], v[152:155], v[52:55]
	v_mfma_f32_16x16x32_bf16 v[48:51], v[136:139], v[152:155], v[48:51]
	v_mfma_f32_16x16x32_bf16 v[44:47], v[128:131], v[160:163], v[44:47]
	v_mfma_f32_16x16x32_bf16 v[40:43], v[136:139], v[160:163], v[40:43]
	v_mfma_f32_16x16x32_bf16 v[36:39], v[128:131], v[168:171], v[36:39]
	v_mfma_f32_16x16x32_bf16 v[32:35], v[136:139], v[168:171], v[32:35]
	v_mfma_f32_16x16x32_bf16 v[60:63], v[132:135], v[148:151], v[60:63]
	v_mfma_f32_16x16x32_bf16 v[56:59], v[140:143], v[148:151], v[56:59]
	v_mfma_f32_16x16x32_bf16 v[52:55], v[132:135], v[156:159], v[52:55]
	v_mfma_f32_16x16x32_bf16 v[48:51], v[140:143], v[156:159], v[48:51]
	v_mfma_f32_16x16x32_bf16 v[44:47], v[132:135], v[164:167], v[44:47]
	v_mfma_f32_16x16x32_bf16 v[40:43], v[140:143], v[164:167], v[40:43]
	v_mfma_f32_16x16x32_bf16 v[36:39], v[132:135], v[172:175], v[36:39]
	v_mfma_f32_16x16x32_bf16 v[32:35], v[140:143], v[172:175], v[32:35]
	v_mfma_f32_16x16x32_bf16 v[28:31], v[176:179], v[144:147], v[28:31]
	v_mfma_f32_16x16x32_bf16 v[24:27], v[184:187], v[144:147], v[24:27]
	v_mfma_f32_16x16x32_bf16 v[20:23], v[176:179], v[152:155], v[20:23]
	v_mfma_f32_16x16x32_bf16 v[16:19], v[184:187], v[152:155], v[16:19]
	v_mfma_f32_16x16x32_bf16 v[12:15], v[176:179], v[160:163], v[12:15]
	v_mfma_f32_16x16x32_bf16 v[8:11], v[184:187], v[160:163], v[8:11]
	v_mfma_f32_16x16x32_bf16 v[4:7], v[176:179], v[168:171], v[4:7]
	v_mfma_f32_16x16x32_bf16 v[0:3], v[184:187], v[168:171], v[0:3]
	v_mfma_f32_16x16x32_bf16 v[28:31], v[180:183], v[148:151], v[28:31]
	v_mfma_f32_16x16x32_bf16 v[24:27], v[188:191], v[148:151], v[24:27]
	v_mfma_f32_16x16x32_bf16 v[20:23], v[180:183], v[156:159], v[20:23]
	v_mfma_f32_16x16x32_bf16 v[16:19], v[188:191], v[156:159], v[16:19]
	v_mfma_f32_16x16x32_bf16 v[12:15], v[180:183], v[164:167], v[12:15]
	v_mfma_f32_16x16x32_bf16 v[8:11], v[188:191], v[164:167], v[8:11]
	v_mfma_f32_16x16x32_bf16 v[4:7], v[180:183], v[172:175], v[4:7]
	v_mfma_f32_16x16x32_bf16 v[0:3], v[188:191], v[172:175], v[0:3]
	s_barrier
	ds_read_b128 v[128:131], v207 offset:0
	ds_read_b128 v[132:135], v207 offset:0x400
	ds_read_b128 v[136:139], v207 offset:0x800
	ds_read_b128 v[140:143], v207 offset:0xc00
	ds_read_b128 v[160:163], v208 offset:0
	ds_read_b128 v[164:167], v208 offset:0x400
	ds_read_b128 v[168:171], v208 offset:0x800
	ds_read_b128 v[172:175], v208 offset:0xc00
	ds_read_b128 v[176:179], v208 offset:0x1000
	ds_read_b128 v[180:183], v208 offset:0x1400
	ds_read_b128 v[184:187], v208 offset:0x1800
	ds_read_b128 v[188:191], v208 offset:0x1c00
	s_waitcnt vmcnt(2)
	s_barrier
	s_waitcnt lgkmcnt(0)
	v_mfma_f32_16x16x32_bf16 v[124:127], v[128:131], v[160:163], v[124:127]
	v_mfma_f32_16x16x32_bf16 v[120:123], v[136:139], v[160:163], v[120:123]
	v_mfma_f32_16x16x32_bf16 v[116:119], v[128:131], v[168:171], v[116:119]
	v_mfma_f32_16x16x32_bf16 v[112:115], v[136:139], v[168:171], v[112:115]
	v_mfma_f32_16x16x32_bf16 v[108:111], v[128:131], v[176:179], v[108:111]
	v_mfma_f32_16x16x32_bf16 v[104:107], v[136:139], v[176:179], v[104:107]
	v_mfma_f32_16x16x32_bf16 v[100:103], v[128:131], v[184:187], v[100:103]
	v_mfma_f32_16x16x32_bf16 v[96:99], v[136:139], v[184:187], v[96:99]
	v_mfma_f32_16x16x32_bf16 v[124:127], v[132:135], v[164:167], v[124:127]
	v_mfma_f32_16x16x32_bf16 v[120:123], v[140:143], v[164:167], v[120:123]
	v_mfma_f32_16x16x32_bf16 v[116:119], v[132:135], v[172:175], v[116:119]
	v_mfma_f32_16x16x32_bf16 v[112:115], v[140:143], v[172:175], v[112:115]
	v_mfma_f32_16x16x32_bf16 v[108:111], v[132:135], v[180:183], v[108:111]
	v_mfma_f32_16x16x32_bf16 v[104:107], v[140:143], v[180:183], v[104:107]
	v_mfma_f32_16x16x32_bf16 v[100:103], v[132:135], v[188:191], v[100:103]
	v_mfma_f32_16x16x32_bf16 v[96:99], v[140:143], v[188:191], v[96:99]
	s_barrier
	ds_read_b128 v[144:147], v209 offset:0
	ds_read_b128 v[148:151], v209 offset:0x400
	ds_read_b128 v[152:155], v209 offset:0x800
	ds_read_b128 v[156:159], v209 offset:0xc00
	s_waitcnt vmcnt(0)
	s_barrier
; #define WAIT_V(n) asm volatile("s_waitcnt vmcnt(%0)" ::"n"(n) : "memory")
; #define SCHED() __builtin_amdgcn_sched_barrier(0)
; #define LGKM(n) asm volatile("s_waitcnt lgkmcnt(%0)" ::"n"(n) : "memory")
; #define STAGE_AX(AG, b, h, kt) do { _Pragma("unroll") for (int i = 0; i < 2; ++i)                                    \
;       __builtin_amdgcn_global_load_lds((const unsigned*)(((AG) + ((size_t)(kt) * (BK * 2) + (size_t)((h) * 2 + i) * 128 * lda)) + aoff), \
;                                        (unsigned*)(shm + SLOTA(b, h) + wid * 1024 + i * 8192), 16, 0, 0); } while (0)
; #define STAGE_BX(BG, b, h, kt) do { _Pragma("unroll") for (int i = 0; i < 2; ++i)                                    \
;       __builtin_amdgcn_global_load_lds((const unsigned*)(((BG) + ((size_t)(kt) * (BK * 2) + (size_t)((h) * 2 + i) * 128 * K)) + boff),   \
;                                        (unsigned*)(shm + SLOTB(b, h) + wid * 1024 + i * 8192), 16, 0, 0); } while (0)
; #define LDA(b, h) do { const unsigned pa_ = lds0 + SLOTA(b, h) + wr * 8192 + laneoff; _Pragma("unroll") for (int m = 0; m < 4; ++m)   \
;       _Pragma("unroll") for (int k = 0; k < 2; ++k) DSR(At[m][k], pa_, m * 2048 + k * 1024); } while (0)
; #define LDB(dst, b, h) do { const unsigned pb_ = lds0 + SLOTB(b, h) + wc * 4096 + laneoff; _Pragma("unroll") for (int n = 0; n < 2; ++n) \
;       _Pragma("unroll") for (int k = 0; k < 2; ++k) DSR(dst[n][k], pb_, n * 2048 + k * 1024); } while (0)
; #define BAR __builtin_amdgcn_s_barrier()
; #define LGKM(n) asm volatile("s_waitcnt lgkmcnt(%0)" ::"n"(n) : "memory")
; template <int EPI, bool SWP> ...
;     ...
;   { LDB(B0, 1, 0); LDA(1, 0); WAIT_V(2); BAR; LGKM(0); SCHED(); MMA(0, 0, B0); BAR; SCHED();
;     LDB(B1, 1, 1); WAIT_V(0); BAR; LGKM(0); SCHED(); MMA(0, 1, B1); BAR; SCHED();
;     LDA(1, 1);
;     if (has_next) { STAGE_BX(Bg_n, 0, 0, 0); STAGE_AX(Ag_n, 0, 0, 0); STAGE_BX(Bg_n, 0, 1, 0); STAGE_AX(Ag_n, 0, 1, 0); }
;     BAR; LGKM(0); SCHED(); MMA(1, 0, B0); MMA(1, 1, B1); BAR; SCHED(); }
;   if (wr == 0) BAR;
	s_waitcnt lgkmcnt(0)
	v_mfma_f32_16x16x32_bf16 v[92:95], v[144:147], v[160:163], v[92:95]
	v_mfma_f32_16x16x32_bf16 v[88:91], v[152:155], v[160:163], v[88:91]
	v_mfma_f32_16x16x32_bf16 v[84:87], v[144:147], v[168:171], v[84:87]
	v_mfma_f32_16x16x32_bf16 v[80:83], v[152:155], v[168:171], v[80:83]
	v_mfma_f32_16x16x32_bf16 v[76:79], v[144:147], v[176:179], v[76:79]
	v_mfma_f32_16x16x32_bf16 v[72:75], v[152:155], v[176:179], v[72:75]
	v_mfma_f32_16x16x32_bf16 v[68:71], v[144:147], v[184:187], v[68:71]
	v_mfma_f32_16x16x32_bf16 v[64:67], v[152:155], v[184:187], v[64:67]
	v_mfma_f32_16x16x32_bf16 v[92:95], v[148:151], v[164:167], v[92:95]
	v_mfma_f32_16x16x32_bf16 v[88:91], v[156:159], v[164:167], v[88:91]
	v_mfma_f32_16x16x32_bf16 v[84:87], v[148:151], v[172:175], v[84:87]
	v_mfma_f32_16x16x32_bf16 v[80:83], v[156:159], v[172:175], v[80:83]
	v_mfma_f32_16x16x32_bf16 v[76:79], v[148:151], v[180:183], v[76:79]
	v_mfma_f32_16x16x32_bf16 v[72:75], v[156:159], v[180:183], v[72:75]
	v_mfma_f32_16x16x32_bf16 v[68:71], v[148:151], v[188:191], v[68:71]
	v_mfma_f32_16x16x32_bf16 v[64:67], v[156:159], v[188:191], v[64:67]
	s_barrier
	ds_read_b128 v[184:187], v210 offset:0
	ds_read_b128 v[188:191], v210 offset:0x400
	ds_read_b128 v[176:179], v210 offset:0x800
	ds_read_b128 v[180:183], v210 offset:0xc00
	ds_read_b128 v[168:171], v210 offset:0x1000
	ds_read_b128 v[172:175], v210 offset:0x1400
	ds_read_b128 v[160:163], v210 offset:0x1800
	ds_read_b128 v[164:167], v210 offset:0x1c00
	s_and_b64 vcc, exec, s[70:71]
	s_cbranch_vccz .LBB0_200
	s_mov_b32 m0, s68
	v_lshl_add_u64 v[200:201], s[74:75], 0, v[192:193]
	s_mov_b64 s[6:7], 0x40000
	global_load_lds_dwordx4 v[200:201], off
	v_lshl_add_u64 v[224:225], v[200:201], 0, s[6:7]
	s_mov_b32 m0, s64
	s_mov_b64 s[12:13], 0xc0000
	global_load_lds_dwordx4 v[224:225], off
	v_lshl_add_u64 v[224:225], s[72:73], 0, v[192:193]
	s_mov_b32 m0, s69
	v_lshl_add_u64 v[226:227], v[224:225], 0, s[6:7]
	global_load_lds_dwordx4 v[224:225], off
	s_mov_b32 m0, s65
	s_mov_b64 s[6:7], 0x80000
	global_load_lds_dwordx4 v[226:227], off
	v_lshl_add_u64 v[226:227], v[200:201], 0, s[6:7]
	s_mov_b32 m0, s23
	v_lshl_add_u64 v[200:201], v[200:201], 0, s[12:13]
	global_load_lds_dwordx4 v[226:227], off
	s_mov_b32 m0, s50
	s_nop 0
	global_load_lds_dwordx4 v[200:201], off
	v_lshl_add_u64 v[200:201], v[224:225], 0, s[6:7]
	s_mov_b32 m0, s29
	s_nop 0
	global_load_lds_dwordx4 v[200:201], off
	v_lshl_add_u64 v[200:201], v[224:225], 0, s[12:13]
	s_mov_b32 m0, s51
	s_nop 0
	global_load_lds_dwordx4 v[200:201], off
.LBB0_200:
	s_barrier
	s_waitcnt lgkmcnt(0)
	v_mfma_f32_16x16x32_bf16 v[60:63], v[128:131], v[184:187], v[60:63]
	v_mfma_f32_16x16x32_bf16 v[56:59], v[136:139], v[184:187], v[56:59]
	v_mfma_f32_16x16x32_bf16 v[52:55], v[128:131], v[176:179], v[52:55]
	v_mfma_f32_16x16x32_bf16 v[48:51], v[136:139], v[176:179], v[48:51]
	v_mfma_f32_16x16x32_bf16 v[44:47], v[128:131], v[168:171], v[44:47]
	v_mfma_f32_16x16x32_bf16 v[40:43], v[136:139], v[168:171], v[40:43]
	v_mfma_f32_16x16x32_bf16 v[36:39], v[128:131], v[160:163], v[36:39]
	v_mfma_f32_16x16x32_bf16 v[32:35], v[136:139], v[160:163], v[32:35]
	v_mfma_f32_16x16x32_bf16 v[60:63], v[132:135], v[188:191], v[60:63]
	v_mfma_f32_16x16x32_bf16 v[56:59], v[140:143], v[188:191], v[56:59]
	v_mfma_f32_16x16x32_bf16 v[52:55], v[132:135], v[180:183], v[52:55]
	v_mfma_f32_16x16x32_bf16 v[48:51], v[140:143], v[180:183], v[48:51]
	v_mfma_f32_16x16x32_bf16 v[44:47], v[132:135], v[172:175], v[44:47]
	v_mfma_f32_16x16x32_bf16 v[40:43], v[140:143], v[172:175], v[40:43]
	v_mfma_f32_16x16x32_bf16 v[36:39], v[132:135], v[164:167], v[36:39]
	v_mfma_f32_16x16x32_bf16 v[32:35], v[140:143], v[164:167], v[32:35]
	v_mfma_f32_16x16x32_bf16 v[28:31], v[144:147], v[184:187], v[28:31]
	v_mfma_f32_16x16x32_bf16 v[24:27], v[152:155], v[184:187], v[24:27]
	v_mfma_f32_16x16x32_bf16 v[20:23], v[144:147], v[176:179], v[20:23]
	v_mfma_f32_16x16x32_bf16 v[16:19], v[152:155], v[176:179], v[16:19]
	v_mfma_f32_16x16x32_bf16 v[12:15], v[144:147], v[168:171], v[12:15]
	v_mfma_f32_16x16x32_bf16 v[8:11], v[152:155], v[168:171], v[8:11]
	v_mfma_f32_16x16x32_bf16 v[4:7], v[144:147], v[160:163], v[4:7]
	v_mfma_f32_16x16x32_bf16 v[0:3], v[152:155], v[160:163], v[0:3]
	v_mfma_f32_16x16x32_bf16 v[28:31], v[148:151], v[188:191], v[28:31]
	v_mfma_f32_16x16x32_bf16 v[24:27], v[156:159], v[188:191], v[24:27]
	v_mfma_f32_16x16x32_bf16 v[20:23], v[148:151], v[180:183], v[20:23]
	v_mfma_f32_16x16x32_bf16 v[16:19], v[156:159], v[180:183], v[16:19]
	v_mfma_f32_16x16x32_bf16 v[12:15], v[148:151], v[172:175], v[12:15]
	v_mfma_f32_16x16x32_bf16 v[8:11], v[156:159], v[172:175], v[8:11]
	v_mfma_f32_16x16x32_bf16 v[4:7], v[148:151], v[164:167], v[4:7]
	v_mfma_f32_16x16x32_bf16 v[0:3], v[156:159], v[164:167], v[0:3]
	s_barrier
	v_readlane_b32 s6, v255, 0
	v_readlane_b32 s7, v255, 1
	s_andn2_b64 vcc, exec, s[6:7]
	s_cbranch_vccnz .LBB0_202
	s_barrier

; #define WAIT_V(n) asm volatile("s_waitcnt vmcnt(%0)" ::"n"(n) : "memory")
; #define SCHED() __builtin_amdgcn_sched_barrier(0)
; #define LGKM(n) asm volatile("s_waitcnt lgkmcnt(%0)" ::"n"(n) : "memory")
; #define STAGE_A(b, h, kt) STAGE_AX(Ag, b, h, kt)
; #define STAGE_B(b, h, kt) STAGE_BX(Bg, b, h, kt)
; #define LDA(b, h) do { const unsigned pa_ = lds0 + SLOTA(b, h) + wr * 8192 + laneoff; _Pragma("unroll") for (int m = 0; m < 4; ++m)   \
;       _Pragma("unroll") for (int k = 0; k < 2; ++k) DSR(At[m][k], pa_, m * 2048 + k * 1024); } while (0)
; #define LDB(dst, b, h) do { const unsigned pb_ = lds0 + SLOTB(b, h) + wc * 4096 + laneoff; _Pragma("unroll") for (int n = 0; n < 2; ++n) \
;       _Pragma("unroll") for (int k = 0; k < 2; ++k) DSR(dst[n][k], pb_, n * 2048 + k * 1024); } while (0)
; #define BAR __builtin_amdgcn_s_barrier()
; #define LGKM(n) asm volatile("s_waitcnt lgkmcnt(%0)" ::"n"(n) : "memory")
; template <int EPI, bool SWP> ...
;     ...
;   for (int t = 0; t < nt - 2; t += 2) {
;     LDB(B0, 0, 0); LDA(0, 0); STAGE_A(1, 1, t + 1);
;     LGKM(8); BAR; LGKM(0); SCHED(); MMA(0, 0, B0); BAR; SCHED();
;     LDB(B1, 0, 1); STAGE_B(0, 0, t + 2);
;     BAR; LGKM(0); SCHED(); MMA(0, 1, B1); BAR; SCHED();
;     LDA(0, 1); STAGE_A(0, 0, t + 2);
;     BAR; LGKM(0); SCHED(); MMA(1, 0, B0); BAR; SCHED();
;     STAGE_B(0, 1, t + 2);
;     WAIT_V(6); BAR; SCHED(); MMA(1, 1, B1); BAR; SCHED();
.LBB0_269:
	ds_read_b128 v[128:131], v203 offset:0
	ds_read_b128 v[132:135], v203 offset:0x400
	ds_read_b128 v[136:139], v203 offset:0x800
	ds_read_b128 v[140:143], v203 offset:0xc00
	ds_read_b128 v[144:147], v204 offset:0
	ds_read_b128 v[148:151], v204 offset:0x400
	ds_read_b128 v[152:155], v204 offset:0x800
	ds_read_b128 v[156:159], v204 offset:0xc00
	ds_read_b128 v[160:163], v204 offset:0x1000
	ds_read_b128 v[164:167], v204 offset:0x1400
	ds_read_b128 v[168:171], v204 offset:0x1800
	v_lshl_add_u64 v[198:199], s[10:11], 0, v[196:197]
	s_add_i32 s29, s69, 0xc000
	ds_read_b128 v[172:175], v204 offset:0x1c00
	v_lshl_add_u64 v[176:177], v[198:199], 0, s[80:81]
	s_mov_b32 m0, s29
	s_nop 0
	global_load_lds_dwordx4 v[176:177], off
	v_lshl_add_u64 v[176:177], v[198:199], 0, s[82:83]
	s_mov_b32 m0, s17
	s_nop 0
	global_load_lds_dwordx4 v[176:177], off
	s_waitcnt lgkmcnt(8)
	s_barrier
	s_waitcnt lgkmcnt(0)
	v_mfma_f32_16x16x32_bf16 v[124:127], v[144:147], v[128:131], v[124:127]
	v_mfma_f32_16x16x32_bf16 v[120:123], v[144:147], v[136:139], v[120:123]
	v_mfma_f32_16x16x32_bf16 v[116:119], v[152:155], v[128:131], v[116:119]
	v_mfma_f32_16x16x32_bf16 v[112:115], v[152:155], v[136:139], v[112:115]
	v_mfma_f32_16x16x32_bf16 v[108:111], v[160:163], v[128:131], v[108:111]
	v_mfma_f32_16x16x32_bf16 v[104:107], v[160:163], v[136:139], v[104:107]
	v_mfma_f32_16x16x32_bf16 v[100:103], v[168:171], v[128:131], v[100:103]
	v_mfma_f32_16x16x32_bf16 v[96:99], v[168:171], v[136:139], v[96:99]
	v_mfma_f32_16x16x32_bf16 v[124:127], v[148:151], v[132:135], v[124:127]
	v_mfma_f32_16x16x32_bf16 v[120:123], v[148:151], v[140:143], v[120:123]
	v_mfma_f32_16x16x32_bf16 v[116:119], v[156:159], v[132:135], v[116:119]
	v_mfma_f32_16x16x32_bf16 v[112:115], v[156:159], v[140:143], v[112:115]
	v_mfma_f32_16x16x32_bf16 v[108:111], v[164:167], v[132:135], v[108:111]
	v_mfma_f32_16x16x32_bf16 v[104:107], v[164:167], v[140:143], v[104:107]
	v_mfma_f32_16x16x32_bf16 v[100:103], v[172:175], v[132:135], v[100:103]
	v_mfma_f32_16x16x32_bf16 v[96:99], v[172:175], v[140:143], v[96:99]
	s_barrier
	ds_read_b128 v[176:179], v205 offset:0
	ds_read_b128 v[180:183], v205 offset:0x400
	ds_read_b128 v[184:187], v205 offset:0x800
	v_lshl_add_u64 v[200:201], s[6:7], 0, v[196:197]
	s_mov_b32 m0, s68
	ds_read_b128 v[188:191], v205 offset:0xc00
	v_lshl_add_u64 v[226:227], v[200:201], 0, s[84:85]
	global_load_lds_dwordx4 v[226:227], off
	v_lshl_add_u64 v[226:227], v[200:201], 0, s[86:87]
	s_mov_b32 m0, s64
	s_nop 0
	global_load_lds_dwordx4 v[226:227], off
	s_barrier
	s_waitcnt lgkmcnt(0)
	v_mfma_f32_16x16x32_bf16 v[92:95], v[144:147], v[176:179], v[92:95]
	v_mfma_f32_16x16x32_bf16 v[88:91], v[144:147], v[184:187], v[88:91]
	v_mfma_f32_16x16x32_bf16 v[84:87], v[152:155], v[176:179], v[84:87]
	v_mfma_f32_16x16x32_bf16 v[80:83], v[152:155], v[184:187], v[80:83]
	v_mfma_f32_16x16x32_bf16 v[76:79], v[160:163], v[176:179], v[76:79]
	v_mfma_f32_16x16x32_bf16 v[72:75], v[160:163], v[184:187], v[72:75]
	v_mfma_f32_16x16x32_bf16 v[68:71], v[168:171], v[176:179], v[68:71]
	v_mfma_f32_16x16x32_bf16 v[64:67], v[168:171], v[184:187], v[64:67]
	v_mfma_f32_16x16x32_bf16 v[92:95], v[148:151], v[180:183], v[92:95]
	v_mfma_f32_16x16x32_bf16 v[88:91], v[148:151], v[188:191], v[88:91]
	v_mfma_f32_16x16x32_bf16 v[84:87], v[156:159], v[180:183], v[84:87]
	v_mfma_f32_16x16x32_bf16 v[80:83], v[156:159], v[188:191], v[80:83]
	v_mfma_f32_16x16x32_bf16 v[76:79], v[164:167], v[180:183], v[76:79]
	v_mfma_f32_16x16x32_bf16 v[72:75], v[164:167], v[188:191], v[72:75]
	v_mfma_f32_16x16x32_bf16 v[68:71], v[172:175], v[180:183], v[68:71]
	v_mfma_f32_16x16x32_bf16 v[64:67], v[172:175], v[188:191], v[64:67]
	s_barrier
	ds_read_b128 v[144:147], v206 offset:0
	ds_read_b128 v[148:151], v206 offset:0x400
	ds_read_b128 v[152:155], v206 offset:0x800
	ds_read_b128 v[156:159], v206 offset:0xc00
	ds_read_b128 v[160:163], v206 offset:0x1000
	ds_read_b128 v[164:167], v206 offset:0x1400
	ds_read_b128 v[168:171], v206 offset:0x1800
	s_mov_b32 m0, s69
	ds_read_b128 v[172:175], v206 offset:0x1c00
	v_lshl_add_u64 v[226:227], v[198:199], 0, s[88:89]
	global_load_lds_dwordx4 v[226:227], off
	v_lshl_add_u64 v[226:227], v[198:199], 0, s[90:91]
	s_mov_b32 m0, s65
	s_nop 0
	global_load_lds_dwordx4 v[226:227], off
	s_barrier
	s_waitcnt lgkmcnt(0)
	v_mfma_f32_16x16x32_bf16 v[60:63], v[144:147], v[128:131], v[60:63]
	v_mfma_f32_16x16x32_bf16 v[56:59], v[144:147], v[136:139], v[56:59]
	v_mfma_f32_16x16x32_bf16 v[52:55], v[152:155], v[128:131], v[52:55]
	v_mfma_f32_16x16x32_bf16 v[48:51], v[152:155], v[136:139], v[48:51]
	v_mfma_f32_16x16x32_bf16 v[44:47], v[160:163], v[128:131], v[44:47]
	v_mfma_f32_16x16x32_bf16 v[40:43], v[160:163], v[136:139], v[40:43]
	v_mfma_f32_16x16x32_bf16 v[36:39], v[168:171], v[128:131], v[36:39]
	v_mfma_f32_16x16x32_bf16 v[32:35], v[168:171], v[136:139], v[32:35]
	v_mfma_f32_16x16x32_bf16 v[60:63], v[148:151], v[132:135], v[60:63]
	v_mfma_f32_16x16x32_bf16 v[56:59], v[148:151], v[140:143], v[56:59]
	v_mfma_f32_16x16x32_bf16 v[52:55], v[156:159], v[132:135], v[52:55]
	v_mfma_f32_16x16x32_bf16 v[48:51], v[156:159], v[140:143], v[48:51]
	v_mfma_f32_16x16x32_bf16 v[44:47], v[164:167], v[132:135], v[44:47]
	v_mfma_f32_16x16x32_bf16 v[40:43], v[164:167], v[140:143], v[40:43]
	v_mfma_f32_16x16x32_bf16 v[36:39], v[172:175], v[132:135], v[36:39]
	v_mfma_f32_16x16x32_bf16 v[32:35], v[172:175], v[140:143], v[32:35]
	s_barrier
	s_add_i32 s9, s69, 0x14000
	v_lshl_add_u64 v[128:129], v[200:201], 0, s[92:93]
	s_mov_b32 m0, s9
	s_nop 0
	global_load_lds_dwordx4 v[128:129], off
	v_lshl_add_u64 v[128:129], v[200:201], 0, s[94:95]
	s_mov_b32 m0, s50
	s_nop 0
	global_load_lds_dwordx4 v[128:129], off
	s_waitcnt vmcnt(6)
	s_barrier
; #define WAIT_V(n) asm volatile("s_waitcnt vmcnt(%0)" ::"n"(n) : "memory")
; #define SCHED() __builtin_amdgcn_sched_barrier(0)
; #define LGKM(n) asm volatile("s_waitcnt lgkmcnt(%0)" ::"n"(n) : "memory")
; #define STAGE_A(b, h, kt) STAGE_AX(Ag, b, h, kt)
; #define STAGE_B(b, h, kt) STAGE_BX(Bg, b, h, kt)
; #define LDA(b, h) do { const unsigned pa_ = lds0 + SLOTA(b, h) + wr * 8192 + laneoff; _Pragma("unroll") for (int m = 0; m < 4; ++m)   \
;       _Pragma("unroll") for (int k = 0; k < 2; ++k) DSR(At[m][k], pa_, m * 2048 + k * 1024); } while (0)
; #define LDB(dst, b, h) do { const unsigned pb_ = lds0 + SLOTB(b, h) + wc * 4096 + laneoff; _Pragma("unroll") for (int n = 0; n < 2; ++n) \
;       _Pragma("unroll") for (int k = 0; k < 2; ++k) DSR(dst[n][k], pb_, n * 2048 + k * 1024); } while (0)
; #define BAR __builtin_amdgcn_s_barrier()
; #define LGKM(n) asm volatile("s_waitcnt lgkmcnt(%0)" ::"n"(n) : "memory")
; template <int EPI, bool SWP> ...
;     ...
;     STAGE_B(0, 1, t + 2);
;     WAIT_V(6); BAR; SCHED(); MMA(1, 1, B1); BAR; SCHED();
;     LDB(B0, 1, 0); LDA(1, 0); STAGE_A(0, 1, t + 2);
;     LGKM(8); BAR; LGKM(0); SCHED(); MMA(0, 0, B0); BAR; SCHED();
;     LDB(B1, 1, 1); STAGE_B(1, 0, t + 3);
;     BAR; LGKM(0); SCHED(); MMA(0, 1, B1); BAR; SCHED();
;     LDA(1, 1); STAGE_A(1, 0, t + 3);
	v_mfma_f32_16x16x32_bf16 v[28:31], v[144:147], v[176:179], v[28:31]
	v_mfma_f32_16x16x32_bf16 v[24:27], v[144:147], v[184:187], v[24:27]
	v_mfma_f32_16x16x32_bf16 v[20:23], v[152:155], v[176:179], v[20:23]
	v_mfma_f32_16x16x32_bf16 v[16:19], v[152:155], v[184:187], v[16:19]
	v_mfma_f32_16x16x32_bf16 v[12:15], v[160:163], v[176:179], v[12:15]
	v_mfma_f32_16x16x32_bf16 v[8:11], v[160:163], v[184:187], v[8:11]
	v_mfma_f32_16x16x32_bf16 v[4:7], v[168:171], v[176:179], v[4:7]
	v_mfma_f32_16x16x32_bf16 v[0:3], v[168:171], v[184:187], v[0:3]
	v_mfma_f32_16x16x32_bf16 v[28:31], v[148:151], v[180:183], v[28:31]
	v_mfma_f32_16x16x32_bf16 v[24:27], v[148:151], v[188:191], v[24:27]
	v_mfma_f32_16x16x32_bf16 v[20:23], v[156:159], v[180:183], v[20:23]
	v_mfma_f32_16x16x32_bf16 v[16:19], v[156:159], v[188:191], v[16:19]
	v_mfma_f32_16x16x32_bf16 v[12:15], v[164:167], v[180:183], v[12:15]
	v_mfma_f32_16x16x32_bf16 v[8:11], v[164:167], v[188:191], v[8:11]
	v_mfma_f32_16x16x32_bf16 v[4:7], v[172:175], v[180:183], v[4:7]
	v_mfma_f32_16x16x32_bf16 v[0:3], v[172:175], v[188:191], v[0:3]
	s_barrier
	ds_read_b128 v[128:131], v207 offset:0
	ds_read_b128 v[132:135], v207 offset:0x400
	ds_read_b128 v[136:139], v207 offset:0x800
	ds_read_b128 v[140:143], v207 offset:0xc00
	ds_read_b128 v[144:147], v208 offset:0
	ds_read_b128 v[148:151], v208 offset:0x400
	ds_read_b128 v[152:155], v208 offset:0x800
	ds_read_b128 v[156:159], v208 offset:0xc00
	ds_read_b128 v[160:163], v208 offset:0x1000
	ds_read_b128 v[164:167], v208 offset:0x1400
	ds_read_b128 v[168:171], v208 offset:0x1800
	s_add_i32 s13, s69, 0x4000
	ds_read_b128 v[172:175], v208 offset:0x1c00
	v_lshl_add_u64 v[176:177], v[198:199], 0, s[96:97]
	s_mov_b32 m0, s13
	s_nop 0
	global_load_lds_dwordx4 v[176:177], off
	v_lshl_add_u64 v[176:177], v[198:199], 0, s[44:45]
	s_mov_b32 m0, s51
	s_nop 0
	global_load_lds_dwordx4 v[176:177], off
	s_waitcnt lgkmcnt(8)
	s_barrier
	s_waitcnt lgkmcnt(0)
	v_mfma_f32_16x16x32_bf16 v[124:127], v[144:147], v[128:131], v[124:127]
	v_mfma_f32_16x16x32_bf16 v[120:123], v[144:147], v[136:139], v[120:123]
	v_mfma_f32_16x16x32_bf16 v[116:119], v[152:155], v[128:131], v[116:119]
	v_mfma_f32_16x16x32_bf16 v[112:115], v[152:155], v[136:139], v[112:115]
	v_mfma_f32_16x16x32_bf16 v[108:111], v[160:163], v[128:131], v[108:111]
	v_mfma_f32_16x16x32_bf16 v[104:107], v[160:163], v[136:139], v[104:107]
	v_mfma_f32_16x16x32_bf16 v[100:103], v[168:171], v[128:131], v[100:103]
	v_mfma_f32_16x16x32_bf16 v[96:99], v[168:171], v[136:139], v[96:99]
	v_mfma_f32_16x16x32_bf16 v[124:127], v[148:151], v[132:135], v[124:127]
	v_mfma_f32_16x16x32_bf16 v[120:123], v[148:151], v[140:143], v[120:123]
	v_mfma_f32_16x16x32_bf16 v[116:119], v[156:159], v[132:135], v[116:119]
	v_mfma_f32_16x16x32_bf16 v[112:115], v[156:159], v[140:143], v[112:115]
	v_mfma_f32_16x16x32_bf16 v[108:111], v[164:167], v[132:135], v[108:111]
	v_mfma_f32_16x16x32_bf16 v[104:107], v[164:167], v[140:143], v[104:107]
	v_mfma_f32_16x16x32_bf16 v[100:103], v[172:175], v[132:135], v[100:103]
	v_mfma_f32_16x16x32_bf16 v[96:99], v[172:175], v[140:143], v[96:99]
	s_barrier
	ds_read_b128 v[176:179], v209 offset:0
	ds_read_b128 v[180:183], v209 offset:0x400
	ds_read_b128 v[184:187], v209 offset:0x800
	s_add_i32 s12, s69, 0x18000
	ds_read_b128 v[188:191], v209 offset:0xc00
	v_lshl_add_u64 v[226:227], v[200:201], 0, s[58:59]
	s_mov_b32 m0, s12
	s_nop 0
	global_load_lds_dwordx4 v[226:227], off
	v_lshl_add_u64 v[226:227], v[200:201], 0, s[60:61]
	s_mov_b32 m0, s66
	s_nop 0
	global_load_lds_dwordx4 v[226:227], off
	s_barrier
	s_waitcnt lgkmcnt(0)
	v_mfma_f32_16x16x32_bf16 v[92:95], v[144:147], v[176:179], v[92:95]
	v_mfma_f32_16x16x32_bf16 v[88:91], v[144:147], v[184:187], v[88:91]
	v_mfma_f32_16x16x32_bf16 v[84:87], v[152:155], v[176:179], v[84:87]
	v_mfma_f32_16x16x32_bf16 v[80:83], v[152:155], v[184:187], v[80:83]
	v_mfma_f32_16x16x32_bf16 v[76:79], v[160:163], v[176:179], v[76:79]
	v_mfma_f32_16x16x32_bf16 v[72:75], v[160:163], v[184:187], v[72:75]
	v_mfma_f32_16x16x32_bf16 v[68:71], v[168:171], v[176:179], v[68:71]
	v_mfma_f32_16x16x32_bf16 v[64:67], v[168:171], v[184:187], v[64:67]
	v_mfma_f32_16x16x32_bf16 v[92:95], v[148:151], v[180:183], v[92:95]
	v_mfma_f32_16x16x32_bf16 v[88:91], v[148:151], v[188:191], v[88:91]
	v_mfma_f32_16x16x32_bf16 v[84:87], v[156:159], v[180:183], v[84:87]
	v_mfma_f32_16x16x32_bf16 v[80:83], v[156:159], v[188:191], v[80:83]
	v_mfma_f32_16x16x32_bf16 v[76:79], v[164:167], v[180:183], v[76:79]
	v_mfma_f32_16x16x32_bf16 v[72:75], v[164:167], v[188:191], v[72:75]
	v_mfma_f32_16x16x32_bf16 v[68:71], v[172:175], v[180:183], v[68:71]
	v_mfma_f32_16x16x32_bf16 v[64:67], v[172:175], v[188:191], v[64:67]
	s_barrier
	ds_read_b128 v[144:147], v210 offset:0
	ds_read_b128 v[148:151], v210 offset:0x400
	ds_read_b128 v[152:155], v210 offset:0x800
	ds_read_b128 v[156:159], v210 offset:0xc00
	ds_read_b128 v[160:163], v210 offset:0x1000
	ds_read_b128 v[164:167], v210 offset:0x1400
	ds_read_b128 v[168:171], v210 offset:0x1800
	s_add_i32 s23, s69, 0x8000
	ds_read_b128 v[172:175], v210 offset:0x1c00
	v_lshl_add_u64 v[226:227], v[198:199], 0, s[0:1]
	s_mov_b32 m0, s23
	v_lshl_add_u64 v[198:199], v[198:199], 0, s[4:5]
	global_load_lds_dwordx4 v[226:227], off
	s_mov_b32 m0, s67
	s_nop 0
	global_load_lds_dwordx4 v[198:199], off
	s_barrier
; #define WAIT_V(n) asm volatile("s_waitcnt vmcnt(%0)" ::"n"(n) : "memory")
; #define SCHED() __builtin_amdgcn_sched_barrier(0)
; #define LGKM(n) asm volatile("s_waitcnt lgkmcnt(%0)" ::"n"(n) : "memory")
; #define STAGE_A(b, h, kt) STAGE_AX(Ag, b, h, kt)
; #define STAGE_B(b, h, kt) STAGE_BX(Bg, b, h, kt)
; #define LDA(b, h) do { const unsigned pa_ = lds0 + SLOTA(b, h) + wr * 8192 + laneoff; _Pragma("unroll") for (int m = 0; m < 4; ++m)   \
;       _Pragma("unroll") for (int k = 0; k < 2; ++k) DSR(At[m][k], pa_, m * 2048 + k * 1024); } while (0)
; #define LDB(dst, b, h) do { const unsigned pb_ = lds0 + SLOTB(b, h) + wc * 4096 + laneoff; _Pragma("unroll") for (int n = 0; n < 2; ++n) \
;       _Pragma("unroll") for (int k = 0; k < 2; ++k) DSR(dst[n][k], pb_, n * 2048 + k * 1024); } while (0)
; #define BAR __builtin_amdgcn_s_barrier()
; #define LGKM(n) asm volatile("s_waitcnt lgkmcnt(%0)" ::"n"(n) : "memory")
; template <int EPI, bool SWP> ...
;     ...
;     BAR; LGKM(0); SCHED(); MMA(1, 0, B0); BAR; SCHED();
;     STAGE_B(1, 1, t + 3);
;     WAIT_V(6); BAR; SCHED(); MMA(1, 1, B1); BAR; SCHED();
;   }
;   { LDB(B0, 0, 0); LDA(0, 0); STAGE_A(1, 1, nt - 1);
;     BAR; LGKM(0); SCHED(); MMA(0, 0, B0); BAR; SCHED();
;     LDB(B1, 0, 1); BAR; LGKM(0); SCHED(); MMA(0, 1, B1); BAR; SCHED();
	s_waitcnt lgkmcnt(0)
	v_mfma_f32_16x16x32_bf16 v[60:63], v[144:147], v[128:131], v[60:63]
	v_mfma_f32_16x16x32_bf16 v[56:59], v[144:147], v[136:139], v[56:59]
	v_mfma_f32_16x16x32_bf16 v[52:55], v[152:155], v[128:131], v[52:55]
	v_mfma_f32_16x16x32_bf16 v[48:51], v[152:155], v[136:139], v[48:51]
	v_mfma_f32_16x16x32_bf16 v[44:47], v[160:163], v[128:131], v[44:47]
	v_mfma_f32_16x16x32_bf16 v[40:43], v[160:163], v[136:139], v[40:43]
	v_mfma_f32_16x16x32_bf16 v[36:39], v[168:171], v[128:131], v[36:39]
	v_mfma_f32_16x16x32_bf16 v[32:35], v[168:171], v[136:139], v[32:35]
	v_mfma_f32_16x16x32_bf16 v[60:63], v[148:151], v[132:135], v[60:63]
	v_mfma_f32_16x16x32_bf16 v[56:59], v[148:151], v[140:143], v[56:59]
	v_mfma_f32_16x16x32_bf16 v[52:55], v[156:159], v[132:135], v[52:55]
	v_mfma_f32_16x16x32_bf16 v[48:51], v[156:159], v[140:143], v[48:51]
	v_mfma_f32_16x16x32_bf16 v[44:47], v[164:167], v[132:135], v[44:47]
	v_mfma_f32_16x16x32_bf16 v[40:43], v[164:167], v[140:143], v[40:43]
	v_mfma_f32_16x16x32_bf16 v[36:39], v[172:175], v[132:135], v[36:39]
	v_mfma_f32_16x16x32_bf16 v[32:35], v[172:175], v[140:143], v[32:35]
	s_barrier
	s_add_i32 s25, s69, 0x1c000
	v_lshl_add_u64 v[128:129], v[200:201], 0, s[34:35]
	s_mov_b32 m0, s25
	s_nop 0
	global_load_lds_dwordx4 v[128:129], off
	v_lshl_add_u64 v[128:129], v[200:201], 0, s[14:15]
	s_mov_b32 m0, s16
	s_nop 0
	global_load_lds_dwordx4 v[128:129], off
	s_waitcnt vmcnt(6)
	s_barrier
	v_mfma_f32_16x16x32_bf16 v[28:31], v[144:147], v[176:179], v[28:31]
	v_mfma_f32_16x16x32_bf16 v[24:27], v[144:147], v[184:187], v[24:27]
	v_mfma_f32_16x16x32_bf16 v[20:23], v[152:155], v[176:179], v[20:23]
	v_mfma_f32_16x16x32_bf16 v[16:19], v[152:155], v[184:187], v[16:19]
	v_mfma_f32_16x16x32_bf16 v[12:15], v[160:163], v[176:179], v[12:15]
	v_mfma_f32_16x16x32_bf16 v[8:11], v[160:163], v[184:187], v[8:11]
	v_mfma_f32_16x16x32_bf16 v[4:7], v[168:171], v[176:179], v[4:7]
	v_mfma_f32_16x16x32_bf16 v[0:3], v[168:171], v[184:187], v[0:3]
	v_mfma_f32_16x16x32_bf16 v[28:31], v[148:151], v[180:183], v[28:31]
	v_mfma_f32_16x16x32_bf16 v[24:27], v[148:151], v[188:191], v[24:27]
	v_mfma_f32_16x16x32_bf16 v[20:23], v[156:159], v[180:183], v[20:23]
	v_mfma_f32_16x16x32_bf16 v[16:19], v[156:159], v[188:191], v[16:19]
	v_mfma_f32_16x16x32_bf16 v[12:15], v[164:167], v[180:183], v[12:15]
	v_mfma_f32_16x16x32_bf16 v[8:11], v[164:167], v[188:191], v[8:11]
	v_mfma_f32_16x16x32_bf16 v[4:7], v[172:175], v[180:183], v[4:7]
	v_mfma_f32_16x16x32_bf16 v[0:3], v[172:175], v[188:191], v[0:3]
	s_barrier
	s_add_i32 s8, s8, 2
	s_add_u32 s6, s6, 0x100
	s_addc_u32 s7, s7, 0
	s_add_u32 s10, s10, 0x100
	s_addc_u32 s11, s11, 0
	s_cmp_gt_u32 s8, 27
	s_cbranch_scc0 .LBB0_269
	ds_read_b128 v[128:131], v203 offset:0
	ds_read_b128 v[132:135], v203 offset:0x400
	ds_read_b128 v[136:139], v203 offset:0x800
	ds_read_b128 v[140:143], v203 offset:0xc00
	ds_read_b128 v[144:147], v204 offset:0
	ds_read_b128 v[148:151], v204 offset:0x400
	ds_read_b128 v[152:155], v204 offset:0x800
	ds_read_b128 v[156:159], v204 offset:0xc00
	ds_read_b128 v[160:163], v204 offset:0x1000
	ds_read_b128 v[164:167], v204 offset:0x1400
	v_lshl_add_u64 v[176:177], s[76:77], 0, v[192:193]
	ds_read_b128 v[168:171], v204 offset:0x1800
	s_mov_b64 s[6:7], 0x80f80
	s_mov_b32 m0, s29
	ds_read_b128 v[172:175], v204 offset:0x1c00
	v_lshl_add_u64 v[178:179], v[176:177], 0, s[6:7]
	s_mov_b64 s[6:7], 0xc0f80
	global_load_lds_dwordx4 v[178:179], off
	v_lshl_add_u64 v[176:177], v[176:177], 0, s[6:7]
	s_mov_b32 m0, s17
	s_nop 0
	global_load_lds_dwordx4 v[176:177], off
	s_barrier
	s_waitcnt lgkmcnt(0)
	v_mfma_f32_16x16x32_bf16 v[124:127], v[144:147], v[128:131], v[124:127]
	v_mfma_f32_16x16x32_bf16 v[120:123], v[144:147], v[136:139], v[120:123]
	v_mfma_f32_16x16x32_bf16 v[116:119], v[152:155], v[128:131], v[116:119]
	v_mfma_f32_16x16x32_bf16 v[112:115], v[152:155], v[136:139], v[112:115]
	v_mfma_f32_16x16x32_bf16 v[108:111], v[160:163], v[128:131], v[108:111]
	v_mfma_f32_16x16x32_bf16 v[104:107], v[160:163], v[136:139], v[104:107]
	v_mfma_f32_16x16x32_bf16 v[100:103], v[168:171], v[128:131], v[100:103]
	v_mfma_f32_16x16x32_bf16 v[96:99], v[168:171], v[136:139], v[96:99]
	v_mfma_f32_16x16x32_bf16 v[124:127], v[148:151], v[132:135], v[124:127]
	v_mfma_f32_16x16x32_bf16 v[120:123], v[148:151], v[140:143], v[120:123]
	v_mfma_f32_16x16x32_bf16 v[116:119], v[156:159], v[132:135], v[116:119]
	v_mfma_f32_16x16x32_bf16 v[112:115], v[156:159], v[140:143], v[112:115]
	v_mfma_f32_16x16x32_bf16 v[108:111], v[164:167], v[132:135], v[108:111]
	v_mfma_f32_16x16x32_bf16 v[104:107], v[164:167], v[140:143], v[104:107]
	v_mfma_f32_16x16x32_bf16 v[100:103], v[172:175], v[132:135], v[100:103]
	v_mfma_f32_16x16x32_bf16 v[96:99], v[172:175], v[140:143], v[96:99]
	s_barrier
	ds_read_b128 v[176:179], v205 offset:0
	ds_read_b128 v[180:183], v205 offset:0x400
	ds_read_b128 v[184:187], v205 offset:0x800
	ds_read_b128 v[188:191], v205 offset:0xc00
	s_barrier
	s_waitcnt lgkmcnt(0)
	v_mfma_f32_16x16x32_bf16 v[92:95], v[144:147], v[176:179], v[92:95]
	v_mfma_f32_16x16x32_bf16 v[88:91], v[144:147], v[184:187], v[88:91]
	v_mfma_f32_16x16x32_bf16 v[84:87], v[152:155], v[176:179], v[84:87]
	v_mfma_f32_16x16x32_bf16 v[80:83], v[152:155], v[184:187], v[80:83]
	v_mfma_f32_16x16x32_bf16 v[76:79], v[160:163], v[176:179], v[76:79]
	v_mfma_f32_16x16x32_bf16 v[72:75], v[160:163], v[184:187], v[72:75]
	v_mfma_f32_16x16x32_bf16 v[68:71], v[168:171], v[176:179], v[68:71]
	v_mfma_f32_16x16x32_bf16 v[64:67], v[168:171], v[184:187], v[64:67]
	v_mfma_f32_16x16x32_bf16 v[92:95], v[148:151], v[180:183], v[92:95]
	v_mfma_f32_16x16x32_bf16 v[88:91], v[148:151], v[188:191], v[88:91]
	v_mfma_f32_16x16x32_bf16 v[84:87], v[156:159], v[180:183], v[84:87]
	v_mfma_f32_16x16x32_bf16 v[80:83], v[156:159], v[188:191], v[80:83]
	v_mfma_f32_16x16x32_bf16 v[76:79], v[164:167], v[180:183], v[76:79]
	v_mfma_f32_16x16x32_bf16 v[72:75], v[164:167], v[188:191], v[72:75]
	v_mfma_f32_16x16x32_bf16 v[68:71], v[172:175], v[180:183], v[68:71]
	v_mfma_f32_16x16x32_bf16 v[160:163], v[172:175], v[188:191], v[64:67]
	s_barrier
; #define WAIT_V(n) asm volatile("s_waitcnt vmcnt(%0)" ::"n"(n) : "memory")
; #define SCHED() __builtin_amdgcn_sched_barrier(0)
; #define LGKM(n) asm volatile("s_waitcnt lgkmcnt(%0)" ::"n"(n) : "memory")
; #define STAGE_A(b, h, kt) STAGE_AX(Ag, b, h, kt)
; #define LDA(b, h) do { const unsigned pa_ = lds0 + SLOTA(b, h) + wr * 8192 + laneoff; _Pragma("unroll") for (int m = 0; m < 4; ++m)   \
;       _Pragma("unroll") for (int k = 0; k < 2; ++k) DSR(At[m][k], pa_, m * 2048 + k * 1024); } while (0)
; #define LDB(dst, b, h) do { const unsigned pb_ = lds0 + SLOTB(b, h) + wc * 4096 + laneoff; _Pragma("unroll") for (int n = 0; n < 2; ++n) \
;       _Pragma("unroll") for (int k = 0; k < 2; ++k) DSR(dst[n][k], pb_, n * 2048 + k * 1024); } while (0)
; #define BAR __builtin_amdgcn_s_barrier()
; #define LGKM(n) asm volatile("s_waitcnt lgkmcnt(%0)" ::"n"(n) : "memory")
; template <int EPI, bool SWP> ...
;     ...
;   { LDB(B0, 0, 0); LDA(0, 0); STAGE_A(1, 1, nt - 1);
;     BAR; LGKM(0); SCHED(); MMA(0, 0, B0); BAR; SCHED();
;     LDB(B1, 0, 1); BAR; LGKM(0); SCHED(); MMA(0, 1, B1); BAR; SCHED();
;     LDA(0, 1); WAIT_V(4); BAR; LGKM(0); SCHED(); MMA(1, 0, B0); MMA(1, 1, B1); BAR; SCHED(); }
;   { LDB(B0, 1, 0); LDA(1, 0); WAIT_V(2); BAR; LGKM(0); SCHED(); MMA(0, 0, B0); BAR; SCHED();
;     LDB(B1, 1, 1); WAIT_V(0); BAR; LGKM(0); SCHED(); MMA(0, 1, B1); BAR; SCHED();
	ds_read_b128 v[144:147], v206 offset:0
	ds_read_b128 v[148:151], v206 offset:0x400
	ds_read_b128 v[152:155], v206 offset:0x800
	ds_read_b128 v[156:159], v206 offset:0xc00
	ds_read_b128 v[164:167], v206 offset:0x1000
	ds_read_b128 v[168:171], v206 offset:0x1400
	ds_read_b128 v[172:175], v206 offset:0x1800
	ds_read_b128 v[198:201], v206 offset:0x1c00
	s_waitcnt vmcnt(4)
	s_barrier
	s_waitcnt lgkmcnt(0)
	v_mfma_f32_16x16x32_bf16 v[60:63], v[144:147], v[128:131], v[60:63]
	v_mfma_f32_16x16x32_bf16 v[56:59], v[144:147], v[136:139], v[56:59]
	v_mfma_f32_16x16x32_bf16 v[52:55], v[152:155], v[128:131], v[52:55]
	v_mfma_f32_16x16x32_bf16 v[48:51], v[152:155], v[136:139], v[48:51]
	v_mfma_f32_16x16x32_bf16 v[44:47], v[164:167], v[128:131], v[44:47]
	v_mfma_f32_16x16x32_bf16 v[40:43], v[164:167], v[136:139], v[40:43]
	v_mfma_f32_16x16x32_bf16 v[36:39], v[172:175], v[128:131], v[36:39]
	v_mfma_f32_16x16x32_bf16 v[32:35], v[172:175], v[136:139], v[32:35]
	v_mfma_f32_16x16x32_bf16 v[64:67], v[148:151], v[132:135], v[60:63]
	v_mfma_f32_16x16x32_bf16 v[56:59], v[148:151], v[140:143], v[56:59]
	v_mfma_f32_16x16x32_bf16 v[52:55], v[156:159], v[132:135], v[52:55]
	v_mfma_f32_16x16x32_bf16 v[48:51], v[156:159], v[140:143], v[48:51]
	v_mfma_f32_16x16x32_bf16 v[44:47], v[168:171], v[132:135], v[44:47]
	v_mfma_f32_16x16x32_bf16 v[40:43], v[168:171], v[140:143], v[40:43]
	v_mfma_f32_16x16x32_bf16 v[36:39], v[198:201], v[132:135], v[36:39]
	v_mfma_f32_16x16x32_bf16 v[32:35], v[198:201], v[140:143], v[32:35]
	v_mfma_f32_16x16x32_bf16 v[28:31], v[144:147], v[176:179], v[28:31]
	v_mfma_f32_16x16x32_bf16 v[24:27], v[144:147], v[184:187], v[24:27]
	v_mfma_f32_16x16x32_bf16 v[20:23], v[152:155], v[176:179], v[20:23]
	v_mfma_f32_16x16x32_bf16 v[16:19], v[152:155], v[184:187], v[16:19]
	v_mfma_f32_16x16x32_bf16 v[12:15], v[164:167], v[176:179], v[12:15]
	v_mfma_f32_16x16x32_bf16 v[8:11], v[164:167], v[184:187], v[8:11]
	v_mfma_f32_16x16x32_bf16 v[4:7], v[172:175], v[176:179], v[4:7]
	v_mfma_f32_16x16x32_bf16 v[0:3], v[172:175], v[184:187], v[0:3]
	v_mfma_f32_16x16x32_bf16 v[28:31], v[148:151], v[180:183], v[28:31]
	v_mfma_f32_16x16x32_bf16 v[24:27], v[148:151], v[188:191], v[24:27]
	v_mfma_f32_16x16x32_bf16 v[20:23], v[156:159], v[180:183], v[20:23]
	v_mfma_f32_16x16x32_bf16 v[16:19], v[156:159], v[188:191], v[16:19]
	v_mfma_f32_16x16x32_bf16 v[12:15], v[168:171], v[180:183], v[12:15]
	v_mfma_f32_16x16x32_bf16 v[8:11], v[168:171], v[188:191], v[8:11]
	v_mfma_f32_16x16x32_bf16 v[4:7], v[198:201], v[180:183], v[4:7]
	v_mfma_f32_16x16x32_bf16 v[0:3], v[198:201], v[188:191], v[0:3]
	s_barrier
	ds_read_b128 v[128:131], v207 offset:0
	ds_read_b128 v[132:135], v207 offset:0x400
	ds_read_b128 v[136:139], v207 offset:0x800
	ds_read_b128 v[140:143], v207 offset:0xc00
	ds_read_b128 v[60:63], v208 offset:0
	ds_read_b128 v[164:167], v208 offset:0x400
	ds_read_b128 v[168:171], v208 offset:0x800
	ds_read_b128 v[172:175], v208 offset:0xc00
	ds_read_b128 v[176:179], v208 offset:0x1000
	ds_read_b128 v[180:183], v208 offset:0x1400
	ds_read_b128 v[184:187], v208 offset:0x1800
	ds_read_b128 v[188:191], v208 offset:0x1c00
	s_waitcnt vmcnt(2)
	s_barrier
	s_waitcnt lgkmcnt(0)
	v_mfma_f32_16x16x32_bf16 v[124:127], v[60:63], v[128:131], v[124:127]
	v_mfma_f32_16x16x32_bf16 v[120:123], v[60:63], v[136:139], v[120:123]
	v_mfma_f32_16x16x32_bf16 v[116:119], v[168:171], v[128:131], v[116:119]
	v_mfma_f32_16x16x32_bf16 v[112:115], v[168:171], v[136:139], v[112:115]
	v_mfma_f32_16x16x32_bf16 v[108:111], v[176:179], v[128:131], v[108:111]
	v_mfma_f32_16x16x32_bf16 v[104:107], v[176:179], v[136:139], v[104:107]
	v_mfma_f32_16x16x32_bf16 v[100:103], v[184:187], v[128:131], v[100:103]
	v_mfma_f32_16x16x32_bf16 v[96:99], v[184:187], v[136:139], v[96:99]
	v_mfma_f32_16x16x32_bf16 v[124:127], v[164:167], v[132:135], v[124:127]
	v_mfma_f32_16x16x32_bf16 v[120:123], v[164:167], v[140:143], v[120:123]
	v_mfma_f32_16x16x32_bf16 v[116:119], v[172:175], v[132:135], v[116:119]
	v_mfma_f32_16x16x32_bf16 v[112:115], v[172:175], v[140:143], v[112:115]
	v_mfma_f32_16x16x32_bf16 v[108:111], v[180:183], v[132:135], v[108:111]
	v_mfma_f32_16x16x32_bf16 v[104:107], v[180:183], v[140:143], v[104:107]
	v_mfma_f32_16x16x32_bf16 v[100:103], v[188:191], v[132:135], v[100:103]
	v_mfma_f32_16x16x32_bf16 v[96:99], v[188:191], v[140:143], v[96:99]
	s_barrier
	ds_read_b128 v[144:147], v209 offset:0
	ds_read_b128 v[148:151], v209 offset:0x400
	ds_read_b128 v[152:155], v209 offset:0x800
	ds_read_b128 v[156:159], v209 offset:0xc00
	s_waitcnt vmcnt(0)
	s_barrier
; #define WAIT_V(n) asm volatile("s_waitcnt vmcnt(%0)" ::"n"(n) : "memory")
; #define SCHED() __builtin_amdgcn_sched_barrier(0)
; #define LGKM(n) asm volatile("s_waitcnt lgkmcnt(%0)" ::"n"(n) : "memory")
; #define STAGE_AX(AG, b, h, kt) do { _Pragma("unroll") for (int i = 0; i < 2; ++i)                                    \
;       __builtin_amdgcn_global_load_lds((const unsigned*)(((AG) + ((size_t)(kt) * (BK * 2) + (size_t)((h) * 2 + i) * 128 * lda)) + aoff), \
;                                        (unsigned*)(shm + SLOTA(b, h) + wid * 1024 + i * 8192), 16, 0, 0); } while (0)
; #define STAGE_BX(BG, b, h, kt) do { _Pragma("unroll") for (int i = 0; i < 2; ++i)                                    \
;       __builtin_amdgcn_global_load_lds((const unsigned*)(((BG) + ((size_t)(kt) * (BK * 2) + (size_t)((h) * 2 + i) * 128 * K)) + boff),   \
;                                        (unsigned*)(shm + SLOTB(b, h) + wid * 1024 + i * 8192), 16, 0, 0); } while (0)
; #define LDA(b, h) do { const unsigned pa_ = lds0 + SLOTA(b, h) + wr * 8192 + laneoff; _Pragma("unroll") for (int m = 0; m < 4; ++m)   \
;       _Pragma("unroll") for (int k = 0; k < 2; ++k) DSR(At[m][k], pa_, m * 2048 + k * 1024); } while (0)
; #define LDB(dst, b, h) do { const unsigned pb_ = lds0 + SLOTB(b, h) + wc * 4096 + laneoff; _Pragma("unroll") for (int n = 0; n < 2; ++n) \
;       _Pragma("unroll") for (int k = 0; k < 2; ++k) DSR(dst[n][k], pb_, n * 2048 + k * 1024); } while (0)
; #define BAR __builtin_amdgcn_s_barrier()
; #define LGKM(n) asm volatile("s_waitcnt lgkmcnt(%0)" ::"n"(n) : "memory")
; template <int EPI, bool SWP> ...
;     ...
;     LDB(B1, 1, 1); WAIT_V(0); BAR; LGKM(0); SCHED(); MMA(0, 1, B1); BAR; SCHED();
;     LDA(1, 1);
;     if (has_next) { STAGE_BX(Bg_n, 0, 0, 0); STAGE_AX(Ag_n, 0, 0, 0); STAGE_BX(Bg_n, 0, 1, 0); STAGE_AX(Ag_n, 0, 1, 0); }
;     BAR; LGKM(0); SCHED(); MMA(1, 0, B0); MMA(1, 1, B1); BAR; SCHED(); }
;   if (wr == 0) BAR;
	s_waitcnt lgkmcnt(0)
	v_mfma_f32_16x16x32_bf16 v[92:95], v[60:63], v[144:147], v[92:95]
	v_mfma_f32_16x16x32_bf16 v[60:63], v[60:63], v[152:155], v[88:91]
	v_mfma_f32_16x16x32_bf16 v[88:91], v[164:167], v[156:159], v[60:63]
	v_mfma_f32_16x16x32_bf16 v[60:63], v[168:171], v[144:147], v[84:87]
	v_mfma_f32_16x16x32_bf16 v[84:87], v[172:175], v[148:151], v[60:63]
	v_mfma_f32_16x16x32_bf16 v[60:63], v[168:171], v[152:155], v[80:83]
	v_mfma_f32_16x16x32_bf16 v[80:83], v[172:175], v[156:159], v[60:63]
	v_mfma_f32_16x16x32_bf16 v[60:63], v[176:179], v[144:147], v[76:79]
	v_mfma_f32_16x16x32_bf16 v[76:79], v[180:183], v[148:151], v[60:63]
	v_mfma_f32_16x16x32_bf16 v[60:63], v[176:179], v[152:155], v[72:75]
	v_mfma_f32_16x16x32_bf16 v[72:75], v[180:183], v[156:159], v[60:63]
	v_mfma_f32_16x16x32_bf16 v[60:63], v[184:187], v[144:147], v[68:71]
	v_mfma_f32_16x16x32_bf16 v[68:71], v[188:191], v[148:151], v[60:63]
	v_mfma_f32_16x16x32_bf16 v[60:63], v[184:187], v[152:155], v[160:163]
	v_mfma_f32_16x16x32_bf16 v[92:95], v[164:167], v[148:151], v[92:95]
	v_mfma_f32_16x16x32_bf16 v[60:63], v[188:191], v[156:159], v[60:63]
	s_barrier
	ds_read_b128 v[184:187], v210 offset:0
	ds_read_b128 v[188:191], v210 offset:0x400
	ds_read_b128 v[176:179], v210 offset:0x800
	ds_read_b128 v[180:183], v210 offset:0xc00
	ds_read_b128 v[168:171], v210 offset:0x1000
	ds_read_b128 v[172:175], v210 offset:0x1400
	ds_read_b128 v[160:163], v210 offset:0x1800
	ds_read_b128 v[164:167], v210 offset:0x1c00
	s_and_b64 vcc, exec, s[70:71]
	v_lshl_add_u64 v[198:199], s[74:75], 0, v[192:193]
	v_lshl_add_u64 v[200:201], s[72:73], 0, v[192:193]
	s_cbranch_vccz .LBB0_272
	s_mov_b32 m0, s68
	s_mov_b64 s[6:7], 0x40000
	global_load_lds_dwordx4 v[198:199], off
	v_lshl_add_u64 v[226:227], v[198:199], 0, s[6:7]
	s_mov_b32 m0, s64
	s_nop 0
	global_load_lds_dwordx4 v[226:227], off
	s_mov_b32 m0, s69
	v_lshl_add_u64 v[226:227], v[200:201], 0, s[6:7]
	global_load_lds_dwordx4 v[200:201], off
	s_mov_b32 m0, s65
	s_mov_b64 s[6:7], 0x80000
	global_load_lds_dwordx4 v[226:227], off
	v_lshl_add_u64 v[226:227], v[198:199], 0, s[6:7]
	s_mov_b32 m0, s9
	s_mov_b64 s[8:9], 0xc0000
	global_load_lds_dwordx4 v[226:227], off
	v_lshl_add_u64 v[226:227], v[198:199], 0, s[8:9]
	s_mov_b32 m0, s50
	s_nop 0
	global_load_lds_dwordx4 v[226:227], off
	v_lshl_add_u64 v[226:227], v[200:201], 0, s[6:7]
	s_mov_b32 m0, s13
	s_nop 0
	global_load_lds_dwordx4 v[226:227], off
	v_lshl_add_u64 v[226:227], v[200:201], 0, s[8:9]
	s_mov_b32 m0, s51
	s_nop 0
	global_load_lds_dwordx4 v[226:227], off
.LBB0_272:
	s_barrier
	s_waitcnt lgkmcnt(0)
	v_mfma_f32_16x16x32_bf16 v[64:67], v[184:187], v[128:131], v[64:67]
	v_mfma_f32_16x16x32_bf16 v[56:59], v[184:187], v[136:139], v[56:59]
	v_mfma_f32_16x16x32_bf16 v[52:55], v[176:179], v[128:131], v[52:55]
	v_mfma_f32_16x16x32_bf16 v[48:51], v[176:179], v[136:139], v[48:51]
	v_mfma_f32_16x16x32_bf16 v[44:47], v[168:171], v[128:131], v[44:47]
	v_mfma_f32_16x16x32_bf16 v[40:43], v[168:171], v[136:139], v[40:43]
	v_mfma_f32_16x16x32_bf16 v[36:39], v[160:163], v[128:131], v[36:39]
	v_mfma_f32_16x16x32_bf16 v[32:35], v[160:163], v[136:139], v[32:35]
	v_mfma_f32_16x16x32_bf16 v[64:67], v[188:191], v[132:135], v[64:67]
	v_mfma_f32_16x16x32_bf16 v[56:59], v[188:191], v[140:143], v[56:59]
	v_mfma_f32_16x16x32_bf16 v[52:55], v[180:183], v[132:135], v[52:55]
	v_mfma_f32_16x16x32_bf16 v[48:51], v[180:183], v[140:143], v[48:51]
	v_mfma_f32_16x16x32_bf16 v[44:47], v[172:175], v[132:135], v[44:47]
	v_mfma_f32_16x16x32_bf16 v[40:43], v[172:175], v[140:143], v[40:43]
	v_mfma_f32_16x16x32_bf16 v[36:39], v[164:167], v[132:135], v[36:39]
	v_mfma_f32_16x16x32_bf16 v[32:35], v[164:167], v[140:143], v[32:35]
	v_mfma_f32_16x16x32_bf16 v[28:31], v[184:187], v[144:147], v[28:31]
	v_mfma_f32_16x16x32_bf16 v[24:27], v[184:187], v[152:155], v[24:27]
	v_mfma_f32_16x16x32_bf16 v[20:23], v[176:179], v[144:147], v[20:23]
	v_mfma_f32_16x16x32_bf16 v[16:19], v[176:179], v[152:155], v[16:19]
	v_mfma_f32_16x16x32_bf16 v[12:15], v[168:171], v[144:147], v[12:15]
	v_mfma_f32_16x16x32_bf16 v[8:11], v[168:171], v[152:155], v[8:11]
	v_mfma_f32_16x16x32_bf16 v[4:7], v[160:163], v[144:147], v[4:7]
	v_mfma_f32_16x16x32_bf16 v[0:3], v[160:163], v[152:155], v[0:3]
	v_mfma_f32_16x16x32_bf16 v[28:31], v[188:191], v[148:151], v[28:31]
	v_mfma_f32_16x16x32_bf16 v[24:27], v[188:191], v[156:159], v[24:27]
	v_mfma_f32_16x16x32_bf16 v[20:23], v[180:183], v[148:151], v[20:23]
	v_mfma_f32_16x16x32_bf16 v[16:19], v[180:183], v[156:159], v[16:19]
	v_mfma_f32_16x16x32_bf16 v[12:15], v[172:175], v[148:151], v[12:15]
	v_mfma_f32_16x16x32_bf16 v[8:11], v[172:175], v[156:159], v[8:11]
	v_mfma_f32_16x16x32_bf16 v[4:7], v[164:167], v[148:151], v[4:7]
	v_mfma_f32_16x16x32_bf16 v[0:3], v[164:167], v[156:159], v[0:3]
	s_barrier
	v_readlane_b32 s6, v255, 0
	v_readlane_b32 s7, v255, 1
	s_andn2_b64 vcc, exec, s[6:7]
	s_cbranch_vccnz .LBB0_274
	s_barrier

; #define WAIT_V(n) asm volatile("s_waitcnt vmcnt(%0)" ::"n"(n) : "memory")
; #define SCHED() __builtin_amdgcn_sched_barrier(0)
; #define LGKM(n) asm volatile("s_waitcnt lgkmcnt(%0)" ::"n"(n) : "memory")
; #define STAGE_A(b, h, kt) STAGE_AX(Ag, b, h, kt)
; #define STAGE_B(b, h, kt) STAGE_BX(Bg, b, h, kt)
; #define LDA(b, h) do { const unsigned pa_ = lds0 + SLOTA(b, h) + wr * 8192 + laneoff; _Pragma("unroll") for (int m = 0; m < 4; ++m)   \
;       _Pragma("unroll") for (int k = 0; k < 2; ++k) DSR(At[m][k], pa_, m * 2048 + k * 1024); } while (0)
; #define LDB(dst, b, h) do { const unsigned pb_ = lds0 + SLOTB(b, h) + wc * 4096 + laneoff; _Pragma("unroll") for (int n = 0; n < 2; ++n) \
;       _Pragma("unroll") for (int k = 0; k < 2; ++k) DSR(dst[n][k], pb_, n * 2048 + k * 1024); } while (0)
; #define BAR __builtin_amdgcn_s_barrier()
; #define LGKM(n) asm volatile("s_waitcnt lgkmcnt(%0)" ::"n"(n) : "memory")
; template <int EPI, bool SWP> ...
;     ...
;   for (int t = 0; t < nt - 2; t += 2) {
;     LDB(B0, 0, 0); LDA(0, 0); STAGE_A(1, 1, t + 1);
;     LGKM(8); BAR; LGKM(0); SCHED(); MMA(0, 0, B0); BAR; SCHED();
;     LDB(B1, 0, 1); STAGE_B(0, 0, t + 2);
;     BAR; LGKM(0); SCHED(); MMA(0, 1, B1); BAR; SCHED();
;     LDA(0, 1); STAGE_A(0, 0, t + 2);
;     BAR; LGKM(0); SCHED(); MMA(1, 0, B0); BAR; SCHED();
;     STAGE_B(0, 1, t + 2);
;     WAIT_V(6); BAR; SCHED(); MMA(1, 1, B1); BAR; SCHED();
.LBB0_334:
	ds_read_b128 v[4:7], v229 offset:0
	ds_read_b128 v[8:11], v229 offset:0x400
	s_ashr_i32 s43, s42, 31
	ds_read_b128 v[12:15], v229 offset:0x800
	s_lshl_b64 s[6:7], s[42:43], 19
	ds_read_b128 v[16:19], v229 offset:0xc00
	s_add_u32 s6, s3, s6
	ds_read_b128 v[20:23], v230 offset:0
	s_addc_u32 s7, s16, s7
	ds_read_b128 v[24:27], v230 offset:0x400
	s_add_u32 s60, s6, s60
	ds_read_b128 v[28:31], v230 offset:0x800
	s_addc_u32 s61, s7, s61
	s_lshl_b64 s[6:7], s[62:63], 17
	v_readlane_b32 s62, v254, 36
	ds_read_b128 v[32:35], v230 offset:0xc00
	v_readlane_b32 s63, v254, 37
	s_add_u32 s62, s62, s6
	ds_read_b128 v[36:39], v230 offset:0x1000
	s_addc_u32 s63, s63, s7
	ds_read_b128 v[40:43], v230 offset:0x1400
	s_mov_b64 s[6:7], 0x40080
	ds_read_b128 v[44:47], v230 offset:0x1800
	v_lshl_add_u64 v[52:53], v[0:1], 0, s[6:7]
	s_add_i32 s6, s17, 0xc000
	ds_read_b128 v[48:51], v230 offset:0x1c00
	s_mov_b32 m0, s6
	s_mov_b64 s[66:67], 0x60080
	global_load_lds_dwordx4 v[52:53], off
	v_lshl_add_u64 v[52:53], v[0:1], 0, s[66:67]
	s_mov_b32 m0, s75
	s_nop 0
	global_load_lds_dwordx4 v[52:53], off
	s_waitcnt lgkmcnt(8)
	s_barrier
	s_waitcnt lgkmcnt(0)
	v_mfma_f32_16x16x32_bf16 v[52:55], v[4:7], v[20:23], 0
	v_mfma_f32_16x16x32_bf16 v[64:67], v[12:15], v[28:31], 0
	v_mfma_f32_16x16x32_bf16 v[68:71], v[4:7], v[36:39], 0
	v_mfma_f32_16x16x32_bf16 v[80:83], v[12:15], v[44:47], 0
	v_mfma_f32_16x16x32_bf16 v[52:55], v[8:11], v[24:27], v[52:55]
	v_mfma_f32_16x16x32_bf16 v[56:59], v[12:15], v[20:23], 0
	v_mfma_f32_16x16x32_bf16 v[60:63], v[4:7], v[28:31], 0
	v_mfma_f32_16x16x32_bf16 v[64:67], v[16:19], v[32:35], v[64:67]
	v_mfma_f32_16x16x32_bf16 v[68:71], v[8:11], v[40:43], v[68:71]
	v_mfma_f32_16x16x32_bf16 v[72:75], v[12:15], v[36:39], 0
	v_mfma_f32_16x16x32_bf16 v[76:79], v[4:7], v[44:47], 0
	v_mfma_f32_16x16x32_bf16 v[80:83], v[16:19], v[48:51], v[80:83]
	v_mfma_f32_16x16x32_bf16 v[56:59], v[16:19], v[24:27], v[56:59]
	v_mfma_f32_16x16x32_bf16 v[60:63], v[8:11], v[32:35], v[60:63]
	v_mfma_f32_16x16x32_bf16 v[72:75], v[16:19], v[40:43], v[72:75]
	v_mfma_f32_16x16x32_bf16 v[76:79], v[8:11], v[48:51], v[76:79]
	s_barrier
	ds_read_b128 v[84:87], v231 offset:0
	ds_read_b128 v[88:91], v231 offset:0x400
	ds_read_b128 v[92:95], v231 offset:0x800
	s_mov_b32 m0, s65
	ds_read_b128 v[96:99], v231 offset:0xc00
	v_lshl_add_u64 v[100:101], v[2:3], 0, s[36:37]
	s_mov_b64 s[66:67], 0x8100
	global_load_lds_dwordx4 v[100:101], off
	v_lshl_add_u64 v[100:101], v[2:3], 0, s[66:67]
	s_mov_b32 m0, s68
	s_nop 0
	global_load_lds_dwordx4 v[100:101], off
	s_barrier
	s_waitcnt lgkmcnt(0)
	v_mfma_f32_16x16x32_bf16 v[100:103], v[84:87], v[20:23], 0
	v_mfma_f32_16x16x32_bf16 v[20:23], v[92:95], v[20:23], 0
	v_mfma_f32_16x16x32_bf16 v[100:103], v[88:91], v[24:27], v[100:103]
	v_mfma_f32_16x16x32_bf16 v[20:23], v[96:99], v[24:27], v[20:23]
	v_mfma_f32_16x16x32_bf16 v[24:27], v[84:87], v[28:31], 0
	v_mfma_f32_16x16x32_bf16 v[28:31], v[92:95], v[28:31], 0
	v_mfma_f32_16x16x32_bf16 v[24:27], v[88:91], v[32:35], v[24:27]
	v_mfma_f32_16x16x32_bf16 v[28:31], v[96:99], v[32:35], v[28:31]
	v_mfma_f32_16x16x32_bf16 v[32:35], v[84:87], v[36:39], 0
	v_mfma_f32_16x16x32_bf16 v[36:39], v[92:95], v[36:39], 0
	v_mfma_f32_16x16x32_bf16 v[32:35], v[88:91], v[40:43], v[32:35]
	v_mfma_f32_16x16x32_bf16 v[36:39], v[96:99], v[40:43], v[36:39]
	v_mfma_f32_16x16x32_bf16 v[40:43], v[84:87], v[44:47], 0
	v_mfma_f32_16x16x32_bf16 v[44:47], v[92:95], v[44:47], 0
	v_mfma_f32_16x16x32_bf16 v[40:43], v[88:91], v[48:51], v[40:43]
	v_mfma_f32_16x16x32_bf16 v[44:47], v[96:99], v[48:51], v[44:47]
	s_barrier
	ds_read_b128 v[48:51], v232 offset:0
	ds_read_b128 v[104:107], v232 offset:0x400
	ds_read_b128 v[108:111], v232 offset:0x800
	ds_read_b128 v[112:115], v232 offset:0xc00
	ds_read_b128 v[116:119], v232 offset:0x1000
	ds_read_b128 v[120:123], v232 offset:0x1400
	ds_read_b128 v[124:127], v232 offset:0x1800
	s_mov_b32 m0, s17
	ds_read_b128 v[128:131], v232 offset:0x1c00
	v_lshl_add_u64 v[132:133], v[0:1], 0, s[36:37]
	s_mov_b64 s[66:67], 0x20100
	global_load_lds_dwordx4 v[132:133], off
	v_lshl_add_u64 v[132:133], v[0:1], 0, s[66:67]
	s_mov_b32 m0, s69
	s_nop 0
	global_load_lds_dwordx4 v[132:133], off
	s_barrier
	s_waitcnt lgkmcnt(0)
	v_mfma_f32_16x16x32_bf16 v[132:135], v[4:7], v[48:51], 0
	v_mfma_f32_16x16x32_bf16 v[140:143], v[4:7], v[108:111], 0
	v_mfma_f32_16x16x32_bf16 v[148:151], v[4:7], v[116:119], 0
	v_mfma_f32_16x16x32_bf16 v[4:7], v[4:7], v[124:127], 0
	v_mfma_f32_16x16x32_bf16 v[132:135], v[8:11], v[104:107], v[132:135]
	v_mfma_f32_16x16x32_bf16 v[136:139], v[12:15], v[48:51], 0
	v_mfma_f32_16x16x32_bf16 v[140:143], v[8:11], v[112:115], v[140:143]
	v_mfma_f32_16x16x32_bf16 v[144:147], v[12:15], v[108:111], 0
	v_mfma_f32_16x16x32_bf16 v[148:151], v[8:11], v[120:123], v[148:151]
	v_mfma_f32_16x16x32_bf16 v[152:155], v[12:15], v[116:119], 0
	v_mfma_f32_16x16x32_bf16 v[4:7], v[8:11], v[128:131], v[4:7]
	v_mfma_f32_16x16x32_bf16 v[8:11], v[12:15], v[124:127], 0
	v_mfma_f32_16x16x32_bf16 v[136:139], v[16:19], v[104:107], v[136:139]
	v_mfma_f32_16x16x32_bf16 v[144:147], v[16:19], v[112:115], v[144:147]
	v_mfma_f32_16x16x32_bf16 v[152:155], v[16:19], v[120:123], v[152:155]
	v_mfma_f32_16x16x32_bf16 v[8:11], v[16:19], v[128:131], v[8:11]
	s_barrier
	s_mov_b64 s[66:67], 0x10100
	s_add_i32 s43, s17, 0x14000
	v_lshl_add_u64 v[12:13], v[2:3], 0, s[66:67]
	s_mov_b32 m0, s43
	s_mov_b64 s[66:67], 0x18100
	global_load_lds_dwordx4 v[12:13], off
	v_lshl_add_u64 v[12:13], v[2:3], 0, s[66:67]
	s_mov_b32 m0, s70
	s_nop 0
	global_load_lds_dwordx4 v[12:13], off
	s_waitcnt vmcnt(6)
	s_barrier
; #define WAIT_V(n) asm volatile("s_waitcnt vmcnt(%0)" ::"n"(n) : "memory")
; #define SCHED() __builtin_amdgcn_sched_barrier(0)
; #define LGKM(n) asm volatile("s_waitcnt lgkmcnt(%0)" ::"n"(n) : "memory")
; #define STAGE_A(b, h, kt) STAGE_AX(Ag, b, h, kt)
; #define STAGE_B(b, h, kt) STAGE_BX(Bg, b, h, kt)
; #define LDA(b, h) do { const unsigned pa_ = lds0 + SLOTA(b, h) + wr * 8192 + laneoff; _Pragma("unroll") for (int m = 0; m < 4; ++m)   \
;       _Pragma("unroll") for (int k = 0; k < 2; ++k) DSR(At[m][k], pa_, m * 2048 + k * 1024); } while (0)
; #define LDB(dst, b, h) do { const unsigned pb_ = lds0 + SLOTB(b, h) + wc * 4096 + laneoff; _Pragma("unroll") for (int n = 0; n < 2; ++n) \
;       _Pragma("unroll") for (int k = 0; k < 2; ++k) DSR(dst[n][k], pb_, n * 2048 + k * 1024); } while (0)
; #define BAR __builtin_amdgcn_s_barrier()
; #define LGKM(n) asm volatile("s_waitcnt lgkmcnt(%0)" ::"n"(n) : "memory")
; template <int EPI, bool SWP> ...
;     ...
;     WAIT_V(6); BAR; SCHED(); MMA(1, 1, B1); BAR; SCHED();
;     LDB(B0, 1, 0); LDA(1, 0); STAGE_A(0, 1, t + 2);
;     LGKM(8); BAR; LGKM(0); SCHED(); MMA(0, 0, B0); BAR; SCHED();
;     LDB(B1, 1, 1); STAGE_B(1, 0, t + 3);
;     BAR; LGKM(0); SCHED(); MMA(0, 1, B1); BAR; SCHED();
;     LDA(1, 1); STAGE_A(1, 0, t + 3);
;     BAR; LGKM(0); SCHED(); MMA(1, 0, B0); BAR; SCHED();
	v_mfma_f32_16x16x32_bf16 v[12:15], v[84:87], v[48:51], 0
	v_mfma_f32_16x16x32_bf16 v[16:19], v[92:95], v[48:51], 0
	v_mfma_f32_16x16x32_bf16 v[12:15], v[88:91], v[104:107], v[12:15]
	v_mfma_f32_16x16x32_bf16 v[16:19], v[96:99], v[104:107], v[16:19]
	v_mfma_f32_16x16x32_bf16 v[48:51], v[84:87], v[108:111], 0
	v_mfma_f32_16x16x32_bf16 v[104:107], v[92:95], v[108:111], 0
	v_mfma_f32_16x16x32_bf16 v[108:111], v[84:87], v[116:119], 0
	v_mfma_f32_16x16x32_bf16 v[84:87], v[84:87], v[124:127], 0
	v_mfma_f32_16x16x32_bf16 v[48:51], v[88:91], v[112:115], v[48:51]
	v_mfma_f32_16x16x32_bf16 v[104:107], v[96:99], v[112:115], v[104:107]
	v_mfma_f32_16x16x32_bf16 v[108:111], v[88:91], v[120:123], v[108:111]
	v_mfma_f32_16x16x32_bf16 v[112:115], v[92:95], v[116:119], 0
	v_mfma_f32_16x16x32_bf16 v[84:87], v[88:91], v[128:131], v[84:87]
	v_mfma_f32_16x16x32_bf16 v[88:91], v[92:95], v[124:127], 0
	v_mfma_f32_16x16x32_bf16 v[112:115], v[96:99], v[120:123], v[112:115]
	v_mfma_f32_16x16x32_bf16 v[88:91], v[96:99], v[128:131], v[88:91]
	s_barrier
	ds_read_b128 v[92:95], v233 offset:0
	ds_read_b128 v[96:99], v233 offset:0x400
	ds_read_b128 v[116:119], v233 offset:0x800
	ds_read_b128 v[120:123], v233 offset:0xc00
	ds_read_b128 v[124:127], v234 offset:0
	ds_read_b128 v[128:131], v234 offset:0x400
	ds_read_b128 v[156:159], v234 offset:0x800
	ds_read_b128 v[160:163], v234 offset:0xc00
	ds_read_b128 v[164:167], v234 offset:0x1000
	ds_read_b128 v[168:171], v234 offset:0x1400
	ds_read_b128 v[172:175], v234 offset:0x1800
	s_mov_b64 s[66:67], 0x40100
	s_add_i32 s49, s17, 0x4000
	ds_read_b128 v[176:179], v234 offset:0x1c00
	v_lshl_add_u64 v[180:181], v[0:1], 0, s[66:67]
	s_mov_b32 m0, s49
	s_mov_b64 s[66:67], 0x60100
	global_load_lds_dwordx4 v[180:181], off
	v_lshl_add_u64 v[180:181], v[0:1], 0, s[66:67]
	s_mov_b32 m0, s71
	s_nop 0
	global_load_lds_dwordx4 v[180:181], off
	s_waitcnt lgkmcnt(8)
	s_barrier
	s_waitcnt lgkmcnt(0)
	v_mfma_f32_16x16x32_bf16 v[52:55], v[92:95], v[124:127], v[52:55]
	v_mfma_f32_16x16x32_bf16 v[64:67], v[116:119], v[156:159], v[64:67]
	v_mfma_f32_16x16x32_bf16 v[68:71], v[92:95], v[164:167], v[68:71]
	v_mfma_f32_16x16x32_bf16 v[80:83], v[116:119], v[172:175], v[80:83]
	v_mfma_f32_16x16x32_bf16 v[52:55], v[96:99], v[128:131], v[52:55]
	v_mfma_f32_16x16x32_bf16 v[56:59], v[116:119], v[124:127], v[56:59]
	v_mfma_f32_16x16x32_bf16 v[60:63], v[92:95], v[156:159], v[60:63]
	v_mfma_f32_16x16x32_bf16 v[64:67], v[120:123], v[160:163], v[64:67]
	v_mfma_f32_16x16x32_bf16 v[68:71], v[96:99], v[168:171], v[68:71]
	v_mfma_f32_16x16x32_bf16 v[72:75], v[116:119], v[164:167], v[72:75]
	v_mfma_f32_16x16x32_bf16 v[76:79], v[92:95], v[172:175], v[76:79]
	v_mfma_f32_16x16x32_bf16 v[80:83], v[120:123], v[176:179], v[80:83]
	v_mfma_f32_16x16x32_bf16 v[56:59], v[120:123], v[128:131], v[56:59]
	v_mfma_f32_16x16x32_bf16 v[60:63], v[96:99], v[160:163], v[60:63]
	v_mfma_f32_16x16x32_bf16 v[72:75], v[120:123], v[168:171], v[72:75]
	v_mfma_f32_16x16x32_bf16 v[76:79], v[96:99], v[176:179], v[76:79]
	s_barrier
	ds_read_b128 v[180:183], v235 offset:0
	ds_read_b128 v[184:187], v235 offset:0x400
	ds_read_b128 v[188:191], v235 offset:0x800
	s_add_i32 s45, s17, 0x18000
	ds_read_b128 v[192:195], v235 offset:0xc00
	v_lshl_add_u64 v[196:197], v[2:3], 0, s[38:39]
	s_mov_b32 m0, s45
	s_mov_b64 s[66:67], 0x8180
	global_load_lds_dwordx4 v[196:197], off
	v_lshl_add_u64 v[196:197], v[2:3], 0, s[66:67]
	s_mov_b32 m0, s72
	s_nop 0
	global_load_lds_dwordx4 v[196:197], off
	s_barrier
	s_waitcnt lgkmcnt(0)
	v_mfma_f32_16x16x32_bf16 v[100:103], v[180:183], v[124:127], v[100:103]
	v_mfma_f32_16x16x32_bf16 v[20:23], v[188:191], v[124:127], v[20:23]
	v_mfma_f32_16x16x32_bf16 v[24:27], v[180:183], v[156:159], v[24:27]
	v_mfma_f32_16x16x32_bf16 v[28:31], v[188:191], v[156:159], v[28:31]
	v_mfma_f32_16x16x32_bf16 v[32:35], v[180:183], v[164:167], v[32:35]
	v_mfma_f32_16x16x32_bf16 v[36:39], v[188:191], v[164:167], v[36:39]
	v_mfma_f32_16x16x32_bf16 v[100:103], v[184:187], v[128:131], v[100:103]
	v_mfma_f32_16x16x32_bf16 v[20:23], v[192:195], v[128:131], v[20:23]
	v_mfma_f32_16x16x32_bf16 v[24:27], v[184:187], v[160:163], v[24:27]
	v_mfma_f32_16x16x32_bf16 v[28:31], v[192:195], v[160:163], v[28:31]
	v_mfma_f32_16x16x32_bf16 v[32:35], v[184:187], v[168:171], v[32:35]
	v_mfma_f32_16x16x32_bf16 v[36:39], v[192:195], v[168:171], v[36:39]
	v_mfma_f32_16x16x32_bf16 v[40:43], v[180:183], v[172:175], v[40:43]
	v_mfma_f32_16x16x32_bf16 v[44:47], v[188:191], v[172:175], v[44:47]
	v_mfma_f32_16x16x32_bf16 v[40:43], v[184:187], v[176:179], v[40:43]
	v_mfma_f32_16x16x32_bf16 v[44:47], v[192:195], v[176:179], v[44:47]
	s_barrier
	ds_read_b128 v[124:127], v236 offset:0
	ds_read_b128 v[128:131], v236 offset:0x400
	ds_read_b128 v[156:159], v236 offset:0x800
	ds_read_b128 v[160:163], v236 offset:0xc00
	ds_read_b128 v[164:167], v236 offset:0x1000
	ds_read_b128 v[168:171], v236 offset:0x1400
	ds_read_b128 v[172:175], v236 offset:0x1800
	s_add_i32 s66, s17, 0x8000
	ds_read_b128 v[176:179], v236 offset:0x1c00
	v_lshl_add_u64 v[196:197], v[0:1], 0, s[38:39]
	s_mov_b32 m0, s66
	s_mov_b64 s[78:79], 0x20180
	global_load_lds_dwordx4 v[196:197], off
	v_lshl_add_u64 v[196:197], v[0:1], 0, s[78:79]
	s_mov_b32 m0, s73
	s_nop 0
	global_load_lds_dwordx4 v[196:197], off
	s_barrier
; #define WAIT_V(n) asm volatile("s_waitcnt vmcnt(%0)" ::"n"(n) : "memory")
; #define SCHED() __builtin_amdgcn_sched_barrier(0)
; #define LGKM(n) asm volatile("s_waitcnt lgkmcnt(%0)" ::"n"(n) : "memory")
; #define STAGE_A(b, h, kt) STAGE_AX(Ag, b, h, kt)
; #define STAGE_B(b, h, kt) STAGE_BX(Bg, b, h, kt)
; #define LDA(b, h) do { const unsigned pa_ = lds0 + SLOTA(b, h) + wr * 8192 + laneoff; _Pragma("unroll") for (int m = 0; m < 4; ++m)   \
;       _Pragma("unroll") for (int k = 0; k < 2; ++k) DSR(At[m][k], pa_, m * 2048 + k * 1024); } while (0)
; #define LDB(dst, b, h) do { const unsigned pb_ = lds0 + SLOTB(b, h) + wc * 4096 + laneoff; _Pragma("unroll") for (int n = 0; n < 2; ++n) \
;       _Pragma("unroll") for (int k = 0; k < 2; ++k) DSR(dst[n][k], pb_, n * 2048 + k * 1024); } while (0)
; #define BAR __builtin_amdgcn_s_barrier()
; #define LGKM(n) asm volatile("s_waitcnt lgkmcnt(%0)" ::"n"(n) : "memory")
; template <int EPI, bool SWP> ...
;     ...
;     BAR; LGKM(0); SCHED(); MMA(1, 0, B0); BAR; SCHED();
;     STAGE_B(1, 1, t + 3);
;     WAIT_V(6); BAR; SCHED(); MMA(1, 1, B1); BAR; SCHED();
;   }
;   { LDB(B0, 0, 0); LDA(0, 0); STAGE_A(1, 1, nt - 1);
;     BAR; LGKM(0); SCHED(); MMA(0, 0, B0); BAR; SCHED();
;     LDB(B1, 0, 1); BAR; LGKM(0); SCHED(); MMA(0, 1, B1); BAR; SCHED();
;     LDA(0, 1); WAIT_V(4); BAR; LGKM(0); SCHED(); MMA(1, 0, B0); MMA(1, 1, B1); BAR; SCHED(); }
	s_waitcnt lgkmcnt(0)
	v_mfma_f32_16x16x32_bf16 v[4:7], v[92:95], v[172:175], v[4:7]
	v_mfma_f32_16x16x32_bf16 v[132:135], v[92:95], v[124:127], v[132:135]
	v_mfma_f32_16x16x32_bf16 v[136:139], v[116:119], v[124:127], v[136:139]
	v_mfma_f32_16x16x32_bf16 v[140:143], v[92:95], v[156:159], v[140:143]
	v_mfma_f32_16x16x32_bf16 v[144:147], v[116:119], v[156:159], v[144:147]
	v_mfma_f32_16x16x32_bf16 v[148:151], v[92:95], v[164:167], v[148:151]
	v_mfma_f32_16x16x32_bf16 v[152:155], v[116:119], v[164:167], v[152:155]
	v_mfma_f32_16x16x32_bf16 v[92:95], v[96:99], v[176:179], v[4:7]
	v_mfma_f32_16x16x32_bf16 v[4:7], v[116:119], v[172:175], v[8:11]
	v_mfma_f32_16x16x32_bf16 v[132:135], v[96:99], v[128:131], v[132:135]
	v_mfma_f32_16x16x32_bf16 v[136:139], v[120:123], v[128:131], v[136:139]
	v_mfma_f32_16x16x32_bf16 v[140:143], v[96:99], v[160:163], v[140:143]
	v_mfma_f32_16x16x32_bf16 v[144:147], v[120:123], v[160:163], v[144:147]
	v_mfma_f32_16x16x32_bf16 v[148:151], v[96:99], v[168:171], v[148:151]
	v_mfma_f32_16x16x32_bf16 v[152:155], v[120:123], v[168:171], v[152:155]
	v_mfma_f32_16x16x32_bf16 v[96:99], v[120:123], v[176:179], v[4:7]
	s_barrier
	s_mov_b64 s[78:79], 0x10180
	s_add_i32 s67, s17, 0x1c000
	v_lshl_add_u64 v[4:5], v[2:3], 0, s[78:79]
	s_mov_b32 m0, s67
	s_mov_b64 s[78:79], 0x18180
	global_load_lds_dwordx4 v[4:5], off
	v_lshl_add_u64 v[2:3], v[2:3], 0, s[78:79]
	s_mov_b32 m0, s74
	s_nop 0
	global_load_lds_dwordx4 v[2:3], off
	s_waitcnt vmcnt(6)
	s_barrier
	v_mfma_f32_16x16x32_bf16 v[2:5], v[180:183], v[124:127], v[12:15]
	v_mfma_f32_16x16x32_bf16 v[116:119], v[184:187], v[128:131], v[2:5]
	v_mfma_f32_16x16x32_bf16 v[2:5], v[188:191], v[124:127], v[16:19]
	v_mfma_f32_16x16x32_bf16 v[120:123], v[192:195], v[128:131], v[2:5]
	v_mfma_f32_16x16x32_bf16 v[2:5], v[180:183], v[156:159], v[48:51]
	v_mfma_f32_16x16x32_bf16 v[48:51], v[184:187], v[160:163], v[2:5]
	v_mfma_f32_16x16x32_bf16 v[2:5], v[188:191], v[156:159], v[104:107]
	v_mfma_f32_16x16x32_bf16 v[104:107], v[192:195], v[160:163], v[2:5]
	v_mfma_f32_16x16x32_bf16 v[2:5], v[180:183], v[164:167], v[108:111]
	v_mfma_f32_16x16x32_bf16 v[108:111], v[184:187], v[168:171], v[2:5]
	v_mfma_f32_16x16x32_bf16 v[2:5], v[188:191], v[164:167], v[112:115]
	v_mfma_f32_16x16x32_bf16 v[112:115], v[192:195], v[168:171], v[2:5]
	v_mfma_f32_16x16x32_bf16 v[2:5], v[180:183], v[172:175], v[84:87]
	v_mfma_f32_16x16x32_bf16 v[84:87], v[184:187], v[176:179], v[2:5]
	v_mfma_f32_16x16x32_bf16 v[2:5], v[188:191], v[172:175], v[88:91]
	v_mfma_f32_16x16x32_bf16 v[88:91], v[192:195], v[176:179], v[2:5]
	s_barrier
	ds_read_b128 v[124:127], v229 offset:0
	ds_read_b128 v[128:131], v229 offset:0x400
	ds_read_b128 v[156:159], v229 offset:0x800
	ds_read_b128 v[160:163], v229 offset:0xc00
	ds_read_b128 v[2:5], v230 offset:0
	ds_read_b128 v[6:9], v230 offset:0x400
	ds_read_b128 v[10:13], v230 offset:0x800
	ds_read_b128 v[14:17], v230 offset:0xc00
	ds_read_b128 v[164:167], v230 offset:0x1000
	ds_read_b128 v[168:171], v230 offset:0x1400
	s_mov_b32 m0, s6
	ds_read_b128 v[172:175], v230 offset:0x1800
	s_mov_b64 s[6:7], 0x40180
	ds_read_b128 v[176:179], v230 offset:0x1c00
	v_lshl_add_u64 v[18:19], v[0:1], 0, s[6:7]
	s_mov_b64 s[6:7], 0x60180
	global_load_lds_dwordx4 v[18:19], off
	v_lshl_add_u64 v[0:1], v[0:1], 0, s[6:7]
	s_mov_b32 m0, s75
	s_nop 0
	global_load_lds_dwordx4 v[0:1], off
	s_barrier
	s_waitcnt lgkmcnt(0)
	v_mfma_f32_16x16x32_bf16 v[52:55], v[124:127], v[2:5], v[52:55]
	v_mfma_f32_16x16x32_bf16 v[64:67], v[156:159], v[10:13], v[64:67]
	v_mfma_f32_16x16x32_bf16 v[68:71], v[124:127], v[164:167], v[68:71]
	v_mfma_f32_16x16x32_bf16 v[80:83], v[156:159], v[172:175], v[80:83]
	v_mfma_f32_16x16x32_bf16 v[52:55], v[128:131], v[6:9], v[52:55]
	v_mfma_f32_16x16x32_bf16 v[56:59], v[156:159], v[2:5], v[56:59]
	v_mfma_f32_16x16x32_bf16 v[60:63], v[124:127], v[10:13], v[60:63]
	v_mfma_f32_16x16x32_bf16 v[64:67], v[160:163], v[14:17], v[64:67]
	v_mfma_f32_16x16x32_bf16 v[68:71], v[128:131], v[168:171], v[68:71]
	v_mfma_f32_16x16x32_bf16 v[72:75], v[156:159], v[164:167], v[72:75]
	v_mfma_f32_16x16x32_bf16 v[76:79], v[124:127], v[172:175], v[76:79]
	v_mfma_f32_16x16x32_bf16 v[80:83], v[160:163], v[176:179], v[80:83]
	v_mfma_f32_16x16x32_bf16 v[56:59], v[160:163], v[6:9], v[56:59]
	v_mfma_f32_16x16x32_bf16 v[60:63], v[128:131], v[14:17], v[60:63]
	v_mfma_f32_16x16x32_bf16 v[72:75], v[160:163], v[168:171], v[72:75]
	v_mfma_f32_16x16x32_bf16 v[76:79], v[128:131], v[176:179], v[76:79]
	s_barrier
	ds_read_b128 v[180:183], v231 offset:0
	ds_read_b128 v[184:187], v231 offset:0x400
	ds_read_b128 v[188:191], v231 offset:0x800
	ds_read_b128 v[192:195], v231 offset:0xc00
	s_barrier
	s_waitcnt lgkmcnt(0)
	v_mfma_f32_16x16x32_bf16 v[100:103], v[180:183], v[2:5], v[100:103]
	v_mfma_f32_16x16x32_bf16 v[0:3], v[188:191], v[2:5], v[20:23]
	v_mfma_f32_16x16x32_bf16 v[200:203], v[192:195], v[6:9], v[0:3]
	v_mfma_f32_16x16x32_bf16 v[0:3], v[180:183], v[10:13], v[24:27]
	v_mfma_f32_16x16x32_bf16 v[204:207], v[184:187], v[14:17], v[0:3]
	v_mfma_f32_16x16x32_bf16 v[0:3], v[188:191], v[10:13], v[28:31]
	v_mfma_f32_16x16x32_bf16 v[208:211], v[192:195], v[14:17], v[0:3]
	v_mfma_f32_16x16x32_bf16 v[0:3], v[180:183], v[164:167], v[32:35]
	v_mfma_f32_16x16x32_bf16 v[212:215], v[184:187], v[168:171], v[0:3]
	v_mfma_f32_16x16x32_bf16 v[0:3], v[188:191], v[164:167], v[36:39]
	v_mfma_f32_16x16x32_bf16 v[224:227], v[192:195], v[168:171], v[0:3]
	v_mfma_f32_16x16x32_bf16 v[0:3], v[180:183], v[172:175], v[40:43]
	v_mfma_f32_16x16x32_bf16 v[196:199], v[184:187], v[6:9], v[100:103]
	v_mfma_f32_16x16x32_bf16 v[40:43], v[184:187], v[176:179], v[0:3]
	v_mfma_f32_16x16x32_bf16 v[0:3], v[188:191], v[172:175], v[44:47]
	v_mfma_f32_16x16x32_bf16 v[44:47], v[192:195], v[176:179], v[0:3]
	s_barrier
; #define WAIT_V(n) asm volatile("s_waitcnt vmcnt(%0)" ::"n"(n) : "memory")
; #define SCHED() __builtin_amdgcn_sched_barrier(0)
; #define LGKM(n) asm volatile("s_waitcnt lgkmcnt(%0)" ::"n"(n) : "memory")
; #define LDA(b, h) do { const unsigned pa_ = lds0 + SLOTA(b, h) + wr * 8192 + laneoff; _Pragma("unroll") for (int m = 0; m < 4; ++m)   \
;       _Pragma("unroll") for (int k = 0; k < 2; ++k) DSR(At[m][k], pa_, m * 2048 + k * 1024); } while (0)
; #define LDB(dst, b, h) do { const unsigned pb_ = lds0 + SLOTB(b, h) + wc * 4096 + laneoff; _Pragma("unroll") for (int n = 0; n < 2; ++n) \
;       _Pragma("unroll") for (int k = 0; k < 2; ++k) DSR(dst[n][k], pb_, n * 2048 + k * 1024); } while (0)
; #define BAR __builtin_amdgcn_s_barrier()
; #define LGKM(n) asm volatile("s_waitcnt lgkmcnt(%0)" ::"n"(n) : "memory")
; template <int EPI, bool SWP> ...
;     ...
;     LDA(0, 1); WAIT_V(4); BAR; LGKM(0); SCHED(); MMA(1, 0, B0); MMA(1, 1, B1); BAR; SCHED(); }
;   { LDB(B0, 1, 0); LDA(1, 0); WAIT_V(2); BAR; LGKM(0); SCHED(); MMA(0, 0, B0); BAR; SCHED();
;     LDB(B1, 1, 1); WAIT_V(0); BAR; LGKM(0); SCHED(); MMA(0, 1, B1); BAR; SCHED();
	ds_read_b128 v[32:35], v232 offset:0
	ds_read_b128 v[36:39], v232 offset:0x400
	ds_read_b128 v[100:103], v232 offset:0x800
	ds_read_b128 v[164:167], v232 offset:0xc00
	ds_read_b128 v[168:171], v232 offset:0x1000
	ds_read_b128 v[172:175], v232 offset:0x1400
	ds_read_b128 v[176:179], v232 offset:0x1800
	ds_read_b128 v[242:245], v232 offset:0x1c00
	s_waitcnt vmcnt(4)
	s_barrier
	s_waitcnt lgkmcnt(0)
	v_mfma_f32_16x16x32_bf16 v[0:3], v[124:127], v[32:35], v[132:135]
	v_mfma_f32_16x16x32_bf16 v[4:7], v[156:159], v[32:35], v[136:139]
	v_mfma_f32_16x16x32_bf16 v[8:11], v[124:127], v[100:103], v[140:143]
	v_mfma_f32_16x16x32_bf16 v[12:15], v[156:159], v[100:103], v[144:147]
	v_mfma_f32_16x16x32_bf16 v[16:19], v[124:127], v[168:171], v[148:151]
	v_mfma_f32_16x16x32_bf16 v[20:23], v[156:159], v[168:171], v[152:155]
	v_mfma_f32_16x16x32_bf16 v[24:27], v[124:127], v[176:179], v[92:95]
	v_mfma_f32_16x16x32_bf16 v[28:31], v[156:159], v[176:179], v[96:99]
	v_mfma_f32_16x16x32_bf16 v[0:3], v[128:131], v[36:39], v[0:3]
	v_mfma_f32_16x16x32_bf16 v[4:7], v[160:163], v[36:39], v[4:7]
	v_mfma_f32_16x16x32_bf16 v[8:11], v[128:131], v[164:167], v[8:11]
	v_mfma_f32_16x16x32_bf16 v[12:15], v[160:163], v[164:167], v[12:15]
	v_mfma_f32_16x16x32_bf16 v[16:19], v[128:131], v[172:175], v[16:19]
	v_mfma_f32_16x16x32_bf16 v[20:23], v[160:163], v[172:175], v[20:23]
	v_mfma_f32_16x16x32_bf16 v[24:27], v[128:131], v[242:245], v[24:27]
	v_mfma_f32_16x16x32_bf16 v[28:31], v[160:163], v[242:245], v[28:31]
	v_mfma_f32_16x16x32_bf16 v[92:95], v[180:183], v[32:35], v[116:119]
	v_mfma_f32_16x16x32_bf16 v[32:35], v[188:191], v[32:35], v[120:123]
	v_mfma_f32_16x16x32_bf16 v[132:135], v[192:195], v[36:39], v[32:35]
	v_mfma_f32_16x16x32_bf16 v[32:35], v[180:183], v[100:103], v[48:51]
	v_mfma_f32_16x16x32_bf16 v[136:139], v[184:187], v[164:167], v[32:35]
	v_mfma_f32_16x16x32_bf16 v[32:35], v[188:191], v[100:103], v[104:107]
	v_mfma_f32_16x16x32_bf16 v[140:143], v[192:195], v[164:167], v[32:35]
	v_mfma_f32_16x16x32_bf16 v[32:35], v[180:183], v[168:171], v[108:111]
	v_mfma_f32_16x16x32_bf16 v[144:147], v[184:187], v[172:175], v[32:35]
	v_mfma_f32_16x16x32_bf16 v[32:35], v[188:191], v[168:171], v[112:115]
	v_mfma_f32_16x16x32_bf16 v[148:151], v[192:195], v[172:175], v[32:35]
	v_mfma_f32_16x16x32_bf16 v[32:35], v[180:183], v[176:179], v[84:87]
	v_mfma_f32_16x16x32_bf16 v[152:155], v[184:187], v[242:245], v[32:35]
	v_mfma_f32_16x16x32_bf16 v[32:35], v[188:191], v[176:179], v[88:91]
	v_mfma_f32_16x16x32_bf16 v[128:131], v[184:187], v[36:39], v[92:95]
	v_mfma_f32_16x16x32_bf16 v[156:159], v[192:195], v[242:245], v[32:35]
	s_barrier
	ds_read_b128 v[32:35], v233 offset:0
	ds_read_b128 v[36:39], v233 offset:0x400
	ds_read_b128 v[160:163], v233 offset:0x800
	ds_read_b128 v[164:167], v233 offset:0xc00
	ds_read_b128 v[48:51], v234 offset:0
	ds_read_b128 v[84:87], v234 offset:0x400
	ds_read_b128 v[184:187], v234 offset:0x800
	ds_read_b128 v[188:191], v234 offset:0xc00
	ds_read_b128 v[192:195], v234 offset:0x1000
	ds_read_b128 v[242:245], v234 offset:0x1400
	ds_read_b128 v[246:249], v234 offset:0x1800
	ds_read_b128 v[250:253], v234 offset:0x1c00
	s_waitcnt vmcnt(2)
	s_barrier
	s_waitcnt lgkmcnt(0)
	s_nop 1
	v_mfma_f32_16x16x32_bf16 v[52:55], v[32:35], v[48:51], v[52:55]
	v_mfma_f32_16x16x32_bf16 v[120:123], v[36:39], v[84:87], v[52:55]
	v_mfma_f32_16x16x32_bf16 v[52:55], v[160:163], v[48:51], v[56:59]
	v_mfma_f32_16x16x32_bf16 v[124:127], v[164:167], v[84:87], v[52:55]
	v_mfma_f32_16x16x32_bf16 v[52:55], v[32:35], v[184:187], v[60:63]
	v_mfma_f32_16x16x32_bf16 v[112:115], v[36:39], v[188:191], v[52:55]
	v_mfma_f32_16x16x32_bf16 v[52:55], v[160:163], v[184:187], v[64:67]
	v_mfma_f32_16x16x32_bf16 v[116:119], v[164:167], v[188:191], v[52:55]
	v_mfma_f32_16x16x32_bf16 v[52:55], v[32:35], v[192:195], v[68:71]
	v_mfma_f32_16x16x32_bf16 v[104:107], v[36:39], v[242:245], v[52:55]
	v_mfma_f32_16x16x32_bf16 v[52:55], v[160:163], v[192:195], v[72:75]
	v_mfma_f32_16x16x32_bf16 v[108:111], v[164:167], v[242:245], v[52:55]
	v_mfma_f32_16x16x32_bf16 v[52:55], v[32:35], v[246:249], v[76:79]
	v_mfma_f32_16x16x32_bf16 v[96:99], v[36:39], v[250:253], v[52:55]
	v_mfma_f32_16x16x32_bf16 v[52:55], v[160:163], v[246:249], v[80:83]
	v_mfma_f32_16x16x32_bf16 v[100:103], v[164:167], v[250:253], v[52:55]
	s_barrier
	ds_read_b128 v[168:171], v235 offset:0
	ds_read_b128 v[172:175], v235 offset:0x400
	ds_read_b128 v[176:179], v235 offset:0x800
	ds_read_b128 v[180:183], v235 offset:0xc00
	s_waitcnt vmcnt(0)
	s_barrier
; #define WAIT_V(n) asm volatile("s_waitcnt vmcnt(%0)" ::"n"(n) : "memory")
; #define SCHED() __builtin_amdgcn_sched_barrier(0)
; #define LGKM(n) asm volatile("s_waitcnt lgkmcnt(%0)" ::"n"(n) : "memory")
; #define STAGE_AX(AG, b, h, kt) do { _Pragma("unroll") for (int i = 0; i < 2; ++i)                                    \
;       __builtin_amdgcn_global_load_lds((const unsigned*)(((AG) + ((size_t)(kt) * (BK * 2) + (size_t)((h) * 2 + i) * 128 * lda)) + aoff), \
;                                        (unsigned*)(shm + SLOTA(b, h) + wid * 1024 + i * 8192), 16, 0, 0); } while (0)
; #define STAGE_BX(BG, b, h, kt) do { _Pragma("unroll") for (int i = 0; i < 2; ++i)                                    \
;       __builtin_amdgcn_global_load_lds((const unsigned*)(((BG) + ((size_t)(kt) * (BK * 2) + (size_t)((h) * 2 + i) * 128 * K)) + boff),   \
;                                        (unsigned*)(shm + SLOTB(b, h) + wid * 1024 + i * 8192), 16, 0, 0); } while (0)
; #define LDA(b, h) do { const unsigned pa_ = lds0 + SLOTA(b, h) + wr * 8192 + laneoff; _Pragma("unroll") for (int m = 0; m < 4; ++m)   \
;       _Pragma("unroll") for (int k = 0; k < 2; ++k) DSR(At[m][k], pa_, m * 2048 + k * 1024); } while (0)
; #define LDB(dst, b, h) do { const unsigned pb_ = lds0 + SLOTB(b, h) + wc * 4096 + laneoff; _Pragma("unroll") for (int n = 0; n < 2; ++n) \
;       _Pragma("unroll") for (int k = 0; k < 2; ++k) DSR(dst[n][k], pb_, n * 2048 + k * 1024); } while (0)
; #define BAR __builtin_amdgcn_s_barrier()
; #define LGKM(n) asm volatile("s_waitcnt lgkmcnt(%0)" ::"n"(n) : "memory")
; template <int EPI, bool SWP> ...
;     ...
;     LDB(B1, 1, 1); WAIT_V(0); BAR; LGKM(0); SCHED(); MMA(0, 1, B1); BAR; SCHED();
;     LDA(1, 1);
;     if (has_next) { STAGE_BX(Bg_n, 0, 0, 0); STAGE_AX(Ag_n, 0, 0, 0); STAGE_BX(Bg_n, 0, 1, 0); STAGE_AX(Ag_n, 0, 1, 0); }
;     BAR; LGKM(0); SCHED(); MMA(1, 0, B0); MMA(1, 1, B1); BAR; SCHED(); }
;   if (wr == 0) BAR;
	s_waitcnt lgkmcnt(0)
	v_mfma_f32_16x16x32_bf16 v[52:55], v[168:171], v[48:51], v[196:199]
	v_mfma_f32_16x16x32_bf16 v[48:51], v[176:179], v[48:51], v[200:203]
	v_mfma_f32_16x16x32_bf16 v[92:95], v[180:183], v[84:87], v[48:51]
	v_mfma_f32_16x16x32_bf16 v[48:51], v[168:171], v[184:187], v[204:207]
	v_mfma_f32_16x16x32_bf16 v[80:83], v[172:175], v[188:191], v[48:51]
	v_mfma_f32_16x16x32_bf16 v[48:51], v[176:179], v[184:187], v[208:211]
	v_mfma_f32_16x16x32_bf16 v[88:91], v[172:175], v[84:87], v[52:55]
	v_mfma_f32_16x16x32_bf16 v[84:87], v[180:183], v[188:191], v[48:51]
	v_mfma_f32_16x16x32_bf16 v[48:51], v[168:171], v[192:195], v[212:215]
	v_mfma_f32_16x16x32_bf16 v[64:67], v[172:175], v[242:245], v[48:51]
	v_mfma_f32_16x16x32_bf16 v[48:51], v[176:179], v[192:195], v[224:227]
	v_mfma_f32_16x16x32_bf16 v[40:43], v[168:171], v[246:249], v[40:43]
	v_mfma_f32_16x16x32_bf16 v[68:71], v[180:183], v[242:245], v[48:51]
	v_mfma_f32_16x16x32_bf16 v[48:51], v[172:175], v[250:253], v[40:43]
	v_mfma_f32_16x16x32_bf16 v[40:43], v[176:179], v[246:249], v[44:47]
	v_mfma_f32_16x16x32_bf16 v[52:55], v[180:183], v[250:253], v[40:43]
	s_barrier
	ds_read_b128 v[208:211], v236 offset:0
	ds_read_b128 v[212:215], v236 offset:0x400
	ds_read_b128 v[200:203], v236 offset:0x800
	ds_read_b128 v[204:207], v236 offset:0xc00
	ds_read_b128 v[192:195], v236 offset:0x1000
	ds_read_b128 v[196:199], v236 offset:0x1400
	ds_read_b128 v[184:187], v236 offset:0x1800
	ds_read_b128 v[188:191], v236 offset:0x1c00
	s_nop 4
	v_cndmask_b32_e64 v40, 0, 1, s[58:59]
	v_cmp_ne_u32_e64 s[6:7], 1, v40
	s_andn2_b64 vcc, exec, s[58:59]
	v_lshl_add_u64 v[224:225], s[62:63], 0, v[218:219]
	v_lshl_add_u64 v[226:227], s[60:61], 0, v[220:221]
	s_cbranch_vccnz .LBB0_336
	s_mov_b32 m0, s65
	v_lshl_add_u64 v[40:41], v[224:225], 0, s[4:5]
	global_load_lds_dwordx4 v[224:225], off
	s_mov_b32 m0, s68
	s_nop 0
	global_load_lds_dwordx4 v[40:41], off
	s_mov_b32 m0, s17
	v_lshl_add_u64 v[40:41], v[226:227], 0, s[10:11]
	global_load_lds_dwordx4 v[226:227], off
	s_mov_b32 m0, s69
	s_nop 0
	global_load_lds_dwordx4 v[40:41], off
	v_lshl_add_u64 v[40:41], v[224:225], 0, s[12:13]
	s_mov_b32 m0, s43
	s_nop 0
	global_load_lds_dwordx4 v[40:41], off
	v_lshl_add_u64 v[40:41], v[224:225], 0, s[14:15]
	s_mov_b32 m0, s70
	s_nop 0
	global_load_lds_dwordx4 v[40:41], off
	v_lshl_add_u64 v[40:41], v[226:227], 0, s[20:21]
	s_mov_b32 m0, s49
	s_nop 0
	global_load_lds_dwordx4 v[40:41], off
	v_lshl_add_u64 v[40:41], v[226:227], 0, s[22:23]
	s_mov_b32 m0, s71
	s_nop 0
	global_load_lds_dwordx4 v[40:41], off
.LBB0_336:
	s_barrier
	s_waitcnt lgkmcnt(0)
	v_mfma_f32_16x16x32_bf16 v[0:3], v[32:35], v[208:211], v[0:3]
	v_mfma_f32_16x16x32_bf16 v[72:75], v[36:39], v[212:215], v[0:3]
	v_mfma_f32_16x16x32_bf16 v[0:3], v[160:163], v[208:211], v[4:7]
	v_mfma_f32_16x16x32_bf16 v[76:79], v[164:167], v[212:215], v[0:3]
	v_mfma_f32_16x16x32_bf16 v[0:3], v[32:35], v[200:203], v[8:11]
	v_mfma_f32_16x16x32_bf16 v[56:59], v[36:39], v[204:207], v[0:3]
	v_mfma_f32_16x16x32_bf16 v[0:3], v[160:163], v[200:203], v[12:15]
	v_mfma_f32_16x16x32_bf16 v[60:63], v[164:167], v[204:207], v[0:3]
	v_mfma_f32_16x16x32_bf16 v[0:3], v[32:35], v[192:195], v[16:19]
	v_mfma_f32_16x16x32_bf16 v[40:43], v[36:39], v[196:199], v[0:3]
	v_mfma_f32_16x16x32_bf16 v[0:3], v[160:163], v[192:195], v[20:23]
	v_mfma_f32_16x16x32_bf16 v[44:47], v[164:167], v[196:199], v[0:3]
	v_mfma_f32_16x16x32_bf16 v[0:3], v[32:35], v[184:187], v[24:27]
	v_mfma_f32_16x16x32_bf16 v[32:35], v[36:39], v[188:191], v[0:3]
	v_mfma_f32_16x16x32_bf16 v[0:3], v[160:163], v[184:187], v[28:31]
	v_mfma_f32_16x16x32_bf16 v[36:39], v[164:167], v[188:191], v[0:3]
	v_mfma_f32_16x16x32_bf16 v[0:3], v[168:171], v[208:211], v[128:131]
	v_mfma_f32_16x16x32_bf16 v[24:27], v[172:175], v[212:215], v[0:3]
	v_mfma_f32_16x16x32_bf16 v[0:3], v[176:179], v[208:211], v[132:135]
	v_mfma_f32_16x16x32_bf16 v[28:31], v[180:183], v[212:215], v[0:3]
	v_mfma_f32_16x16x32_bf16 v[0:3], v[168:171], v[200:203], v[136:139]
	v_mfma_f32_16x16x32_bf16 v[16:19], v[172:175], v[204:207], v[0:3]
	v_mfma_f32_16x16x32_bf16 v[0:3], v[176:179], v[200:203], v[140:143]
	v_mfma_f32_16x16x32_bf16 v[20:23], v[180:183], v[204:207], v[0:3]
	v_mfma_f32_16x16x32_bf16 v[0:3], v[168:171], v[192:195], v[144:147]
	v_mfma_f32_16x16x32_bf16 v[8:11], v[172:175], v[196:199], v[0:3]
	v_mfma_f32_16x16x32_bf16 v[0:3], v[176:179], v[192:195], v[148:151]
	v_mfma_f32_16x16x32_bf16 v[12:15], v[180:183], v[196:199], v[0:3]
	v_mfma_f32_16x16x32_bf16 v[0:3], v[168:171], v[184:187], v[152:155]
	v_mfma_f32_16x16x32_bf16 v[4:7], v[176:179], v[184:187], v[156:159]
	v_mfma_f32_16x16x32_bf16 v[0:3], v[172:175], v[188:191], v[0:3]
	v_mfma_f32_16x16x32_bf16 v[4:7], v[180:183], v[188:191], v[4:7]
	s_barrier
	s_andn2_b64 vcc, exec, s[0:1]
	s_cbranch_vccnz .LBB0_338
	s_barrier

; #define SCHED() __builtin_amdgcn_sched_barrier(0)
; #define LGKM(n) asm volatile("s_waitcnt lgkmcnt(%0)" ::"n"(n) : "memory")
; #define STAGE_A(b, h, kt) STAGE_AX(Ag, b, h, kt)
; #define STAGE_B(b, h, kt) STAGE_BX(Bg, b, h, kt)
; #define LDA(b, h) do { const unsigned pa_ = lds0 + SLOTA(b, h) + wr * 8192 + laneoff; _Pragma("unroll") for (int m = 0; m < 4; ++m)   \
;       _Pragma("unroll") for (int k = 0; k < 2; ++k) DSR(At[m][k], pa_, m * 2048 + k * 1024); } while (0)
; #define LDB(dst, b, h) do { const unsigned pb_ = lds0 + SLOTB(b, h) + wc * 4096 + laneoff; _Pragma("unroll") for (int n = 0; n < 2; ++n) \
;       _Pragma("unroll") for (int k = 0; k < 2; ++k) DSR(dst[n][k], pb_, n * 2048 + k * 1024); } while (0)
; #define BAR __builtin_amdgcn_s_barrier()
; #define LGKM(n) asm volatile("s_waitcnt lgkmcnt(%0)" ::"n"(n) : "memory")
; template <int EPI, bool SWP> ...
;     ...
;   for (int t = 0; t < nt - 2; t += 2) {
;     LDB(B0, 0, 0); LDA(0, 0); STAGE_A(1, 1, t + 1);
;     LGKM(8); BAR; LGKM(0); SCHED(); MMA(0, 0, B0); BAR; SCHED();
;     LDB(B1, 0, 1); STAGE_B(0, 0, t + 2);
;     BAR; LGKM(0); SCHED(); MMA(0, 1, B1); BAR; SCHED();
;     LDA(0, 1); STAGE_A(0, 0, t + 2);
;     BAR; LGKM(0); SCHED(); MMA(1, 0, B0); BAR; SCHED();
.LBB0_354:
	ds_read_b128 v[130:133], v222 offset:0
	ds_read_b128 v[134:137], v222 offset:0x400
	ds_read_b128 v[138:141], v222 offset:0x800
	ds_read_b128 v[142:145], v222 offset:0xc00
	ds_read_b128 v[146:149], v223 offset:0
	ds_read_b128 v[150:153], v223 offset:0x400
	ds_read_b128 v[154:157], v223 offset:0x800
	ds_read_b128 v[158:161], v223 offset:0xc00
	ds_read_b128 v[162:165], v223 offset:0x1000
	ds_read_b128 v[166:169], v223 offset:0x1400
	ds_read_b128 v[170:173], v223 offset:0x1800
	v_lshl_add_u64 v[194:195], s[48:49], 0, v[214:215]
	s_mov_b32 m0, s69
	ds_read_b128 v[174:177], v223 offset:0x1c00
	v_lshl_add_u64 v[178:179], v[194:195], 0, s[22:23]
	global_load_lds_dwordx4 v[178:179], off
	v_lshl_add_u64 v[178:179], v[194:195], 0, s[24:25]
	s_mov_b32 m0, s70
	s_nop 0
	global_load_lds_dwordx4 v[178:179], off
	s_waitcnt lgkmcnt(8)
	s_barrier
	s_waitcnt lgkmcnt(0)
	v_mfma_f32_16x16x32_bf16 v[124:127], v[130:133], v[146:149], v[124:127]
	v_mfma_f32_16x16x32_bf16 v[120:123], v[138:141], v[146:149], v[120:123]
	v_mfma_f32_16x16x32_bf16 v[116:119], v[130:133], v[154:157], v[116:119]
	v_mfma_f32_16x16x32_bf16 v[112:115], v[138:141], v[154:157], v[112:115]
	v_mfma_f32_16x16x32_bf16 v[108:111], v[130:133], v[162:165], v[108:111]
	v_mfma_f32_16x16x32_bf16 v[104:107], v[138:141], v[162:165], v[104:107]
	v_mfma_f32_16x16x32_bf16 v[100:103], v[130:133], v[170:173], v[100:103]
	v_mfma_f32_16x16x32_bf16 v[96:99], v[138:141], v[170:173], v[96:99]
	v_mfma_f32_16x16x32_bf16 v[124:127], v[134:137], v[150:153], v[124:127]
	v_mfma_f32_16x16x32_bf16 v[120:123], v[142:145], v[150:153], v[120:123]
	v_mfma_f32_16x16x32_bf16 v[116:119], v[134:137], v[158:161], v[116:119]
	v_mfma_f32_16x16x32_bf16 v[112:115], v[142:145], v[158:161], v[112:115]
	v_mfma_f32_16x16x32_bf16 v[108:111], v[134:137], v[166:169], v[108:111]
	v_mfma_f32_16x16x32_bf16 v[104:107], v[142:145], v[166:169], v[104:107]
	v_mfma_f32_16x16x32_bf16 v[100:103], v[134:137], v[174:177], v[100:103]
	v_mfma_f32_16x16x32_bf16 v[96:99], v[142:145], v[174:177], v[96:99]
	s_barrier
	ds_read_b128 v[178:181], v224 offset:0
	ds_read_b128 v[182:185], v224 offset:0x400
	ds_read_b128 v[186:189], v224 offset:0x800
	v_lshl_add_u64 v[196:197], s[50:51], 0, v[214:215]
	s_mov_b64 s[58:59], 0xe000100
	s_mov_b32 m0, s16
	ds_read_b128 v[190:193], v224 offset:0xc00
	v_lshl_add_u64 v[198:199], v[196:197], 0, s[58:59]
	s_mov_b64 s[58:59], 0xe020100
	global_load_lds_dwordx4 v[198:199], off
	v_lshl_add_u64 v[198:199], v[196:197], 0, s[58:59]
	s_mov_b32 m0, s17
	s_nop 0
	global_load_lds_dwordx4 v[198:199], off
	s_barrier
	s_waitcnt lgkmcnt(0)
	v_mfma_f32_16x16x32_bf16 v[92:95], v[178:181], v[146:149], v[92:95]
	v_mfma_f32_16x16x32_bf16 v[88:91], v[186:189], v[146:149], v[88:91]
	v_mfma_f32_16x16x32_bf16 v[84:87], v[178:181], v[154:157], v[84:87]
	v_mfma_f32_16x16x32_bf16 v[80:83], v[186:189], v[154:157], v[80:83]
	v_mfma_f32_16x16x32_bf16 v[76:79], v[178:181], v[162:165], v[76:79]
	v_mfma_f32_16x16x32_bf16 v[72:75], v[186:189], v[162:165], v[72:75]
	v_mfma_f32_16x16x32_bf16 v[68:71], v[178:181], v[170:173], v[68:71]
	v_mfma_f32_16x16x32_bf16 v[64:67], v[186:189], v[170:173], v[64:67]
	v_mfma_f32_16x16x32_bf16 v[92:95], v[182:185], v[150:153], v[92:95]
	v_mfma_f32_16x16x32_bf16 v[88:91], v[190:193], v[150:153], v[88:91]
	v_mfma_f32_16x16x32_bf16 v[84:87], v[182:185], v[158:161], v[84:87]
	v_mfma_f32_16x16x32_bf16 v[80:83], v[190:193], v[158:161], v[80:83]
	v_mfma_f32_16x16x32_bf16 v[76:79], v[182:185], v[166:169], v[76:79]
	v_mfma_f32_16x16x32_bf16 v[72:75], v[190:193], v[166:169], v[72:75]
	v_mfma_f32_16x16x32_bf16 v[68:71], v[182:185], v[174:177], v[68:71]
	v_mfma_f32_16x16x32_bf16 v[64:67], v[190:193], v[174:177], v[64:67]
	s_barrier
	ds_read_b128 v[146:149], v225 offset:0
	ds_read_b128 v[150:153], v225 offset:0x400
	ds_read_b128 v[154:157], v225 offset:0x800
	ds_read_b128 v[158:161], v225 offset:0xc00
	ds_read_b128 v[162:165], v225 offset:0x1000
	ds_read_b128 v[166:169], v225 offset:0x1400
	ds_read_b128 v[170:173], v225 offset:0x1800
	s_mov_b64 s[58:59], 0x100
	s_mov_b32 m0, s3
	ds_read_b128 v[174:177], v225 offset:0x1c00
	v_lshl_add_u64 v[198:199], v[194:195], 0, s[58:59]
	s_mov_b64 s[58:59], 0x20100
	global_load_lds_dwordx4 v[198:199], off
	v_lshl_add_u64 v[198:199], v[194:195], 0, s[58:59]
	s_mov_b32 m0, s18
	s_nop 0
	global_load_lds_dwordx4 v[198:199], off
	s_barrier
	s_waitcnt lgkmcnt(0)
	v_mfma_f32_16x16x32_bf16 v[60:63], v[130:133], v[146:149], v[60:63]
	v_mfma_f32_16x16x32_bf16 v[56:59], v[138:141], v[146:149], v[56:59]
	v_mfma_f32_16x16x32_bf16 v[52:55], v[130:133], v[154:157], v[52:55]
	v_mfma_f32_16x16x32_bf16 v[48:51], v[138:141], v[154:157], v[48:51]
	v_mfma_f32_16x16x32_bf16 v[44:47], v[130:133], v[162:165], v[44:47]
	v_mfma_f32_16x16x32_bf16 v[40:43], v[138:141], v[162:165], v[40:43]
	v_mfma_f32_16x16x32_bf16 v[36:39], v[130:133], v[170:173], v[36:39]
	v_mfma_f32_16x16x32_bf16 v[32:35], v[138:141], v[170:173], v[32:35]
	v_mfma_f32_16x16x32_bf16 v[60:63], v[134:137], v[150:153], v[60:63]
	v_mfma_f32_16x16x32_bf16 v[56:59], v[142:145], v[150:153], v[56:59]
	v_mfma_f32_16x16x32_bf16 v[52:55], v[134:137], v[158:161], v[52:55]
	v_mfma_f32_16x16x32_bf16 v[48:51], v[142:145], v[158:161], v[48:51]
	v_mfma_f32_16x16x32_bf16 v[44:47], v[134:137], v[166:169], v[44:47]
	v_mfma_f32_16x16x32_bf16 v[40:43], v[142:145], v[166:169], v[40:43]
	v_mfma_f32_16x16x32_bf16 v[36:39], v[134:137], v[174:177], v[36:39]
	v_mfma_f32_16x16x32_bf16 v[32:35], v[142:145], v[174:177], v[32:35]
	s_barrier
; #define WAIT_V(n) asm volatile("s_waitcnt vmcnt(%0)" ::"n"(n) : "memory")
; #define SCHED() __builtin_amdgcn_sched_barrier(0)
; #define LGKM(n) asm volatile("s_waitcnt lgkmcnt(%0)" ::"n"(n) : "memory")
; #define STAGE_A(b, h, kt) STAGE_AX(Ag, b, h, kt)
; #define STAGE_B(b, h, kt) STAGE_BX(Bg, b, h, kt)
; #define LDA(b, h) do { const unsigned pa_ = lds0 + SLOTA(b, h) + wr * 8192 + laneoff; _Pragma("unroll") for (int m = 0; m < 4; ++m)   \
;       _Pragma("unroll") for (int k = 0; k < 2; ++k) DSR(At[m][k], pa_, m * 2048 + k * 1024); } while (0)
; #define LDB(dst, b, h) do { const unsigned pb_ = lds0 + SLOTB(b, h) + wc * 4096 + laneoff; _Pragma("unroll") for (int n = 0; n < 2; ++n) \
;       _Pragma("unroll") for (int k = 0; k < 2; ++k) DSR(dst[n][k], pb_, n * 2048 + k * 1024); } while (0)
; #define BAR __builtin_amdgcn_s_barrier()
; #define LGKM(n) asm volatile("s_waitcnt lgkmcnt(%0)" ::"n"(n) : "memory")
; template <int EPI, bool SWP> ...
;     ...
;     BAR; LGKM(0); SCHED(); MMA(1, 0, B0); BAR; SCHED();
;     STAGE_B(0, 1, t + 2);
;     WAIT_V(6); BAR; SCHED(); MMA(1, 1, B1); BAR; SCHED();
;     LDB(B0, 1, 0); LDA(1, 0); STAGE_A(0, 1, t + 2);
;     LGKM(8); BAR; LGKM(0); SCHED(); MMA(0, 0, B0); BAR; SCHED();
;     LDB(B1, 1, 1); STAGE_B(1, 0, t + 3);
;     BAR; LGKM(0); SCHED(); MMA(0, 1, B1); BAR; SCHED();
;     LDA(1, 1); STAGE_A(1, 0, t + 3);
;     BAR; LGKM(0); SCHED(); MMA(1, 0, B0); BAR; SCHED();
	s_mov_b64 s[58:59], 0xe040100
	s_mov_b32 m0, s19
	v_lshl_add_u64 v[130:131], v[196:197], 0, s[58:59]
	s_mov_b64 s[58:59], 0xe060100
	global_load_lds_dwordx4 v[130:131], off
	v_lshl_add_u64 v[130:131], v[196:197], 0, s[58:59]
	s_mov_b32 m0, s60
	s_nop 0
	global_load_lds_dwordx4 v[130:131], off
	s_waitcnt vmcnt(6)
	s_barrier
	v_mfma_f32_16x16x32_bf16 v[28:31], v[178:181], v[146:149], v[28:31]
	v_mfma_f32_16x16x32_bf16 v[24:27], v[186:189], v[146:149], v[24:27]
	v_mfma_f32_16x16x32_bf16 v[20:23], v[178:181], v[154:157], v[20:23]
	v_mfma_f32_16x16x32_bf16 v[16:19], v[186:189], v[154:157], v[16:19]
	v_mfma_f32_16x16x32_bf16 v[12:15], v[178:181], v[162:165], v[12:15]
	v_mfma_f32_16x16x32_bf16 v[8:11], v[186:189], v[162:165], v[8:11]
	v_mfma_f32_16x16x32_bf16 v[4:7], v[178:181], v[170:173], v[4:7]
	v_mfma_f32_16x16x32_bf16 v[0:3], v[186:189], v[170:173], v[0:3]
	v_mfma_f32_16x16x32_bf16 v[28:31], v[182:185], v[150:153], v[28:31]
	v_mfma_f32_16x16x32_bf16 v[24:27], v[190:193], v[150:153], v[24:27]
	v_mfma_f32_16x16x32_bf16 v[20:23], v[182:185], v[158:161], v[20:23]
	v_mfma_f32_16x16x32_bf16 v[16:19], v[190:193], v[158:161], v[16:19]
	v_mfma_f32_16x16x32_bf16 v[12:15], v[182:185], v[166:169], v[12:15]
	v_mfma_f32_16x16x32_bf16 v[8:11], v[190:193], v[166:169], v[8:11]
	v_mfma_f32_16x16x32_bf16 v[4:7], v[182:185], v[174:177], v[4:7]
	v_mfma_f32_16x16x32_bf16 v[0:3], v[190:193], v[174:177], v[0:3]
	s_barrier
	ds_read_b128 v[130:133], v226 offset:0
	ds_read_b128 v[134:137], v226 offset:0x400
	ds_read_b128 v[138:141], v226 offset:0x800
	ds_read_b128 v[142:145], v226 offset:0xc00
	ds_read_b128 v[146:149], v227 offset:0
	ds_read_b128 v[150:153], v227 offset:0x400
	ds_read_b128 v[154:157], v227 offset:0x800
	ds_read_b128 v[158:161], v227 offset:0xc00
	ds_read_b128 v[162:165], v227 offset:0x1000
	ds_read_b128 v[166:169], v227 offset:0x1400
	ds_read_b128 v[170:173], v227 offset:0x1800
	s_mov_b64 s[58:59], 0x40100
	s_mov_b32 m0, s61
	ds_read_b128 v[174:177], v227 offset:0x1c00
	v_lshl_add_u64 v[178:179], v[194:195], 0, s[58:59]
	s_mov_b64 s[58:59], 0x60100
	global_load_lds_dwordx4 v[178:179], off
	v_lshl_add_u64 v[178:179], v[194:195], 0, s[58:59]
	s_mov_b32 m0, s62
	s_nop 0
	global_load_lds_dwordx4 v[178:179], off
	s_waitcnt lgkmcnt(8)
	s_barrier
	s_waitcnt lgkmcnt(0)
	v_mfma_f32_16x16x32_bf16 v[124:127], v[130:133], v[146:149], v[124:127]
	v_mfma_f32_16x16x32_bf16 v[120:123], v[138:141], v[146:149], v[120:123]
	v_mfma_f32_16x16x32_bf16 v[116:119], v[130:133], v[154:157], v[116:119]
	v_mfma_f32_16x16x32_bf16 v[112:115], v[138:141], v[154:157], v[112:115]
	v_mfma_f32_16x16x32_bf16 v[108:111], v[130:133], v[162:165], v[108:111]
	v_mfma_f32_16x16x32_bf16 v[104:107], v[138:141], v[162:165], v[104:107]
	v_mfma_f32_16x16x32_bf16 v[100:103], v[130:133], v[170:173], v[100:103]
	v_mfma_f32_16x16x32_bf16 v[96:99], v[138:141], v[170:173], v[96:99]
	v_mfma_f32_16x16x32_bf16 v[124:127], v[134:137], v[150:153], v[124:127]
	v_mfma_f32_16x16x32_bf16 v[120:123], v[142:145], v[150:153], v[120:123]
	v_mfma_f32_16x16x32_bf16 v[116:119], v[134:137], v[158:161], v[116:119]
	v_mfma_f32_16x16x32_bf16 v[112:115], v[142:145], v[158:161], v[112:115]
	v_mfma_f32_16x16x32_bf16 v[108:111], v[134:137], v[166:169], v[108:111]
	v_mfma_f32_16x16x32_bf16 v[104:107], v[142:145], v[166:169], v[104:107]
	v_mfma_f32_16x16x32_bf16 v[100:103], v[134:137], v[174:177], v[100:103]
	v_mfma_f32_16x16x32_bf16 v[96:99], v[142:145], v[174:177], v[96:99]
	s_barrier
	ds_read_b128 v[178:181], v229 offset:0
	ds_read_b128 v[182:185], v229 offset:0x400
	ds_read_b128 v[186:189], v229 offset:0x800
	s_mov_b64 s[58:59], 0xe000180
	s_mov_b32 m0, s63
	ds_read_b128 v[190:193], v229 offset:0xc00
	v_lshl_add_u64 v[198:199], v[196:197], 0, s[58:59]
	s_mov_b64 s[58:59], 0xe020180
	global_load_lds_dwordx4 v[198:199], off
	v_lshl_add_u64 v[198:199], v[196:197], 0, s[58:59]
	s_mov_b32 m0, s64
	s_nop 0
	global_load_lds_dwordx4 v[198:199], off
	s_barrier
	s_waitcnt lgkmcnt(0)
	v_mfma_f32_16x16x32_bf16 v[92:95], v[178:181], v[146:149], v[92:95]
	v_mfma_f32_16x16x32_bf16 v[88:91], v[186:189], v[146:149], v[88:91]
	v_mfma_f32_16x16x32_bf16 v[84:87], v[178:181], v[154:157], v[84:87]
	v_mfma_f32_16x16x32_bf16 v[80:83], v[186:189], v[154:157], v[80:83]
	v_mfma_f32_16x16x32_bf16 v[76:79], v[178:181], v[162:165], v[76:79]
	v_mfma_f32_16x16x32_bf16 v[72:75], v[186:189], v[162:165], v[72:75]
	v_mfma_f32_16x16x32_bf16 v[68:71], v[178:181], v[170:173], v[68:71]
	v_mfma_f32_16x16x32_bf16 v[64:67], v[186:189], v[170:173], v[64:67]
	v_mfma_f32_16x16x32_bf16 v[92:95], v[182:185], v[150:153], v[92:95]
	v_mfma_f32_16x16x32_bf16 v[88:91], v[190:193], v[150:153], v[88:91]
	v_mfma_f32_16x16x32_bf16 v[84:87], v[182:185], v[158:161], v[84:87]
	v_mfma_f32_16x16x32_bf16 v[80:83], v[190:193], v[158:161], v[80:83]
	v_mfma_f32_16x16x32_bf16 v[76:79], v[182:185], v[166:169], v[76:79]
	v_mfma_f32_16x16x32_bf16 v[72:75], v[190:193], v[166:169], v[72:75]
	v_mfma_f32_16x16x32_bf16 v[68:71], v[182:185], v[174:177], v[68:71]
	v_mfma_f32_16x16x32_bf16 v[64:67], v[190:193], v[174:177], v[64:67]
	s_barrier
	ds_read_b128 v[146:149], v230 offset:0
	ds_read_b128 v[150:153], v230 offset:0x400
	ds_read_b128 v[154:157], v230 offset:0x800
	ds_read_b128 v[158:161], v230 offset:0xc00
	ds_read_b128 v[162:165], v230 offset:0x1000
	ds_read_b128 v[166:169], v230 offset:0x1400
	ds_read_b128 v[170:173], v230 offset:0x1800
	s_mov_b64 s[58:59], 0x180
	s_mov_b32 m0, s65
	ds_read_b128 v[174:177], v230 offset:0x1c00
	v_lshl_add_u64 v[198:199], v[194:195], 0, s[58:59]
	s_mov_b64 s[58:59], 0x20180
	global_load_lds_dwordx4 v[198:199], off
	v_lshl_add_u64 v[194:195], v[194:195], 0, s[58:59]
	s_mov_b32 m0, s66
	s_nop 0
	global_load_lds_dwordx4 v[194:195], off
	s_barrier
; #define WAIT_V(n) asm volatile("s_waitcnt vmcnt(%0)" ::"n"(n) : "memory")
; #define SCHED() __builtin_amdgcn_sched_barrier(0)
; #define LGKM(n) asm volatile("s_waitcnt lgkmcnt(%0)" ::"n"(n) : "memory")
; #define STAGE_A(b, h, kt) STAGE_AX(Ag, b, h, kt)
; #define STAGE_B(b, h, kt) STAGE_BX(Bg, b, h, kt)
; #define LDA(b, h) do { const unsigned pa_ = lds0 + SLOTA(b, h) + wr * 8192 + laneoff; _Pragma("unroll") for (int m = 0; m < 4; ++m)   \
;       _Pragma("unroll") for (int k = 0; k < 2; ++k) DSR(At[m][k], pa_, m * 2048 + k * 1024); } while (0)
; #define LDB(dst, b, h) do { const unsigned pb_ = lds0 + SLOTB(b, h) + wc * 4096 + laneoff; _Pragma("unroll") for (int n = 0; n < 2; ++n) \
;       _Pragma("unroll") for (int k = 0; k < 2; ++k) DSR(dst[n][k], pb_, n * 2048 + k * 1024); } while (0)
; #define BAR __builtin_amdgcn_s_barrier()
; #define LGKM(n) asm volatile("s_waitcnt lgkmcnt(%0)" ::"n"(n) : "memory")
; template <int EPI, bool SWP> ...
;     ...
;     BAR; LGKM(0); SCHED(); MMA(1, 0, B0); BAR; SCHED();
;     STAGE_B(1, 1, t + 3);
;     WAIT_V(6); BAR; SCHED(); MMA(1, 1, B1); BAR; SCHED();
;   }
;   { LDB(B0, 0, 0); LDA(0, 0); STAGE_A(1, 1, nt - 1);
;     BAR; LGKM(0); SCHED(); MMA(0, 0, B0); BAR; SCHED();
	s_waitcnt lgkmcnt(0)
	v_mfma_f32_16x16x32_bf16 v[60:63], v[130:133], v[146:149], v[60:63]
	v_mfma_f32_16x16x32_bf16 v[56:59], v[138:141], v[146:149], v[56:59]
	v_mfma_f32_16x16x32_bf16 v[52:55], v[130:133], v[154:157], v[52:55]
	v_mfma_f32_16x16x32_bf16 v[48:51], v[138:141], v[154:157], v[48:51]
	v_mfma_f32_16x16x32_bf16 v[44:47], v[130:133], v[162:165], v[44:47]
	v_mfma_f32_16x16x32_bf16 v[40:43], v[138:141], v[162:165], v[40:43]
	v_mfma_f32_16x16x32_bf16 v[36:39], v[130:133], v[170:173], v[36:39]
	v_mfma_f32_16x16x32_bf16 v[32:35], v[138:141], v[170:173], v[32:35]
	v_mfma_f32_16x16x32_bf16 v[60:63], v[134:137], v[150:153], v[60:63]
	v_mfma_f32_16x16x32_bf16 v[56:59], v[142:145], v[150:153], v[56:59]
	v_mfma_f32_16x16x32_bf16 v[52:55], v[134:137], v[158:161], v[52:55]
	v_mfma_f32_16x16x32_bf16 v[48:51], v[142:145], v[158:161], v[48:51]
	v_mfma_f32_16x16x32_bf16 v[44:47], v[134:137], v[166:169], v[44:47]
	v_mfma_f32_16x16x32_bf16 v[40:43], v[142:145], v[166:169], v[40:43]
	v_mfma_f32_16x16x32_bf16 v[36:39], v[134:137], v[174:177], v[36:39]
	v_mfma_f32_16x16x32_bf16 v[32:35], v[142:145], v[174:177], v[32:35]
	s_barrier
	s_mov_b64 s[58:59], 0xe040180
	s_mov_b32 m0, s67
	v_lshl_add_u64 v[130:131], v[196:197], 0, s[58:59]
	s_mov_b64 s[58:59], 0xe060180
	global_load_lds_dwordx4 v[130:131], off
	v_lshl_add_u64 v[130:131], v[196:197], 0, s[58:59]
	s_mov_b32 m0, s68
	s_nop 0
	global_load_lds_dwordx4 v[130:131], off
	s_waitcnt vmcnt(6)
	s_barrier
	v_mfma_f32_16x16x32_bf16 v[28:31], v[178:181], v[146:149], v[28:31]
	v_mfma_f32_16x16x32_bf16 v[24:27], v[186:189], v[146:149], v[24:27]
	v_mfma_f32_16x16x32_bf16 v[20:23], v[178:181], v[154:157], v[20:23]
	v_mfma_f32_16x16x32_bf16 v[16:19], v[186:189], v[154:157], v[16:19]
	v_mfma_f32_16x16x32_bf16 v[12:15], v[178:181], v[162:165], v[12:15]
	v_mfma_f32_16x16x32_bf16 v[8:11], v[186:189], v[162:165], v[8:11]
	v_mfma_f32_16x16x32_bf16 v[4:7], v[178:181], v[170:173], v[4:7]
	v_mfma_f32_16x16x32_bf16 v[0:3], v[186:189], v[170:173], v[0:3]
	v_mfma_f32_16x16x32_bf16 v[28:31], v[182:185], v[150:153], v[28:31]
	v_mfma_f32_16x16x32_bf16 v[24:27], v[190:193], v[150:153], v[24:27]
	v_mfma_f32_16x16x32_bf16 v[20:23], v[182:185], v[158:161], v[20:23]
	v_mfma_f32_16x16x32_bf16 v[16:19], v[190:193], v[158:161], v[16:19]
	v_mfma_f32_16x16x32_bf16 v[12:15], v[182:185], v[166:169], v[12:15]
	v_mfma_f32_16x16x32_bf16 v[8:11], v[190:193], v[166:169], v[8:11]
	v_mfma_f32_16x16x32_bf16 v[4:7], v[182:185], v[174:177], v[4:7]
	v_mfma_f32_16x16x32_bf16 v[0:3], v[190:193], v[174:177], v[0:3]
	s_barrier
	s_add_i32 s35, s35, 2
	s_add_u32 s50, s50, 0x100
	s_addc_u32 s51, s51, 0
	s_add_u32 s48, s48, 0x100
	s_addc_u32 s49, s49, 0
	s_cmp_gt_u32 s35, 11
	s_cbranch_scc0 .LBB0_354
	ds_read_b128 v[140:143], v222 offset:0
	ds_read_b128 v[144:147], v222 offset:0x400
	ds_read_b128 v[148:151], v222 offset:0x800
	ds_read_b128 v[152:155], v222 offset:0xc00
	ds_read_b128 v[130:133], v223 offset:0
	ds_read_b128 v[134:137], v223 offset:0x400
	ds_read_b128 v[156:159], v223 offset:0x800
	ds_read_b128 v[160:163], v223 offset:0xc00
	ds_read_b128 v[164:167], v223 offset:0x1000
	ds_read_b128 v[168:171], v223 offset:0x1400
	ds_read_b128 v[172:175], v223 offset:0x1800
	s_mov_b64 s[48:49], 0x40780
	s_mov_b32 m0, s69
	ds_read_b128 v[176:179], v223 offset:0x1c00
	v_lshl_add_u64 v[138:139], v[128:129], 0, s[48:49]
	global_load_lds_dwordx4 v[138:139], off
	v_lshl_add_u64 v[128:129], v[128:129], 0, s[26:27]
	s_mov_b32 m0, s70
	s_ashr_i32 s39, s38, 31
	global_load_lds_dwordx4 v[128:129], off
	s_lshl_b64 s[48:49], s[38:39], 19
	s_add_u32 s48, s56, s48
	s_addc_u32 s49, s57, s49
	s_ashr_i32 s35, s34, 31
	s_barrier
	s_waitcnt lgkmcnt(0)
	s_lshl_b64 s[50:51], s[34:35], 19
	v_readlane_b32 s58, v254, 30
	v_readlane_b32 s59, v254, 31
	s_add_u32 s50, s58, s50
	s_addc_u32 s51, s59, s51
	v_mfma_f32_16x16x32_bf16 v[124:127], v[140:143], v[130:133], v[124:127]
	v_mfma_f32_16x16x32_bf16 v[120:123], v[148:151], v[130:133], v[120:123]
	v_mfma_f32_16x16x32_bf16 v[116:119], v[140:143], v[156:159], v[116:119]
	v_mfma_f32_16x16x32_bf16 v[112:115], v[148:151], v[156:159], v[112:115]
	v_mfma_f32_16x16x32_bf16 v[108:111], v[140:143], v[164:167], v[108:111]
	v_mfma_f32_16x16x32_bf16 v[104:107], v[148:151], v[164:167], v[104:107]
	v_mfma_f32_16x16x32_bf16 v[100:103], v[140:143], v[172:175], v[100:103]
	v_mfma_f32_16x16x32_bf16 v[96:99], v[148:151], v[172:175], v[96:99]
	v_mfma_f32_16x16x32_bf16 v[124:127], v[144:147], v[134:137], v[124:127]
	v_mfma_f32_16x16x32_bf16 v[180:183], v[152:155], v[134:137], v[120:123]
	v_mfma_f32_16x16x32_bf16 v[116:119], v[144:147], v[160:163], v[116:119]
	v_mfma_f32_16x16x32_bf16 v[184:187], v[152:155], v[160:163], v[112:115]
	v_mfma_f32_16x16x32_bf16 v[108:111], v[144:147], v[168:171], v[108:111]
	v_mfma_f32_16x16x32_bf16 v[188:191], v[152:155], v[168:171], v[104:107]
	v_mfma_f32_16x16x32_bf16 v[100:103], v[144:147], v[176:179], v[100:103]
	v_mfma_f32_16x16x32_bf16 v[192:195], v[152:155], v[176:179], v[96:99]
	s_barrier
	ds_read_b128 v[96:99], v224 offset:0
	ds_read_b128 v[104:107], v224 offset:0x400
	ds_read_b128 v[112:115], v224 offset:0x800
	ds_read_b128 v[120:123], v224 offset:0xc00
	s_barrier
; #define WAIT_V(n) asm volatile("s_waitcnt vmcnt(%0)" ::"n"(n) : "memory")
; #define SCHED() __builtin_amdgcn_sched_barrier(0)
; #define LGKM(n) asm volatile("s_waitcnt lgkmcnt(%0)" ::"n"(n) : "memory")
; #define LDA(b, h) do { const unsigned pa_ = lds0 + SLOTA(b, h) + wr * 8192 + laneoff; _Pragma("unroll") for (int m = 0; m < 4; ++m)   \
;       _Pragma("unroll") for (int k = 0; k < 2; ++k) DSR(At[m][k], pa_, m * 2048 + k * 1024); } while (0)
; #define LDB(dst, b, h) do { const unsigned pb_ = lds0 + SLOTB(b, h) + wc * 4096 + laneoff; _Pragma("unroll") for (int n = 0; n < 2; ++n) \
;       _Pragma("unroll") for (int k = 0; k < 2; ++k) DSR(dst[n][k], pb_, n * 2048 + k * 1024); } while (0)
; #define BAR __builtin_amdgcn_s_barrier()
; #define LGKM(n) asm volatile("s_waitcnt lgkmcnt(%0)" ::"n"(n) : "memory")
; template <int EPI, bool SWP> ...
;     ...
;     BAR; LGKM(0); SCHED(); MMA(0, 0, B0); BAR; SCHED();
;     LDB(B1, 0, 1); BAR; LGKM(0); SCHED(); MMA(0, 1, B1); BAR; SCHED();
;     LDA(0, 1); WAIT_V(4); BAR; LGKM(0); SCHED(); MMA(1, 0, B0); MMA(1, 1, B1); BAR; SCHED(); }
;   { LDB(B0, 1, 0); LDA(1, 0); WAIT_V(2); BAR; LGKM(0); SCHED(); MMA(0, 0, B0); BAR; SCHED();
	s_waitcnt lgkmcnt(0)
	v_mfma_f32_16x16x32_bf16 v[92:95], v[96:99], v[130:133], v[92:95]
	v_mfma_f32_16x16x32_bf16 v[88:91], v[112:115], v[130:133], v[88:91]
	v_mfma_f32_16x16x32_bf16 v[84:87], v[96:99], v[156:159], v[84:87]
	v_mfma_f32_16x16x32_bf16 v[80:83], v[112:115], v[156:159], v[80:83]
	v_mfma_f32_16x16x32_bf16 v[76:79], v[96:99], v[164:167], v[76:79]
	v_mfma_f32_16x16x32_bf16 v[72:75], v[112:115], v[164:167], v[72:75]
	v_mfma_f32_16x16x32_bf16 v[68:71], v[96:99], v[172:175], v[68:71]
	v_mfma_f32_16x16x32_bf16 v[64:67], v[112:115], v[172:175], v[64:67]
	v_mfma_f32_16x16x32_bf16 v[92:95], v[104:107], v[134:137], v[92:95]
	v_mfma_f32_16x16x32_bf16 v[196:199], v[120:123], v[134:137], v[88:91]
	v_mfma_f32_16x16x32_bf16 v[84:87], v[104:107], v[160:163], v[84:87]
	v_mfma_f32_16x16x32_bf16 v[200:203], v[120:123], v[160:163], v[80:83]
	v_mfma_f32_16x16x32_bf16 v[76:79], v[104:107], v[168:171], v[76:79]
	v_mfma_f32_16x16x32_bf16 v[204:207], v[120:123], v[168:171], v[72:75]
	v_mfma_f32_16x16x32_bf16 v[68:71], v[104:107], v[176:179], v[68:71]
	v_mfma_f32_16x16x32_bf16 v[176:179], v[120:123], v[176:179], v[64:67]
	s_barrier
	ds_read_b128 v[64:67], v225 offset:0
	ds_read_b128 v[72:75], v225 offset:0x400
	ds_read_b128 v[80:83], v225 offset:0x800
	ds_read_b128 v[88:91], v225 offset:0xc00
	ds_read_b128 v[156:159], v225 offset:0x1000
	ds_read_b128 v[160:163], v225 offset:0x1400
	ds_read_b128 v[164:167], v225 offset:0x1800
	ds_read_b128 v[168:171], v225 offset:0x1c00
	s_waitcnt vmcnt(4)
	s_barrier
	s_waitcnt lgkmcnt(0)
	v_mfma_f32_16x16x32_bf16 v[60:63], v[140:143], v[64:67], v[60:63]
	v_mfma_f32_16x16x32_bf16 v[56:59], v[148:151], v[64:67], v[56:59]
	v_mfma_f32_16x16x32_bf16 v[52:55], v[140:143], v[80:83], v[52:55]
	v_mfma_f32_16x16x32_bf16 v[48:51], v[148:151], v[80:83], v[48:51]
	v_mfma_f32_16x16x32_bf16 v[44:47], v[140:143], v[156:159], v[44:47]
	v_mfma_f32_16x16x32_bf16 v[40:43], v[148:151], v[156:159], v[40:43]
	v_mfma_f32_16x16x32_bf16 v[36:39], v[140:143], v[164:167], v[36:39]
	v_mfma_f32_16x16x32_bf16 v[32:35], v[148:151], v[164:167], v[32:35]
	v_mfma_f32_16x16x32_bf16 v[60:63], v[144:147], v[72:75], v[60:63]
	v_mfma_f32_16x16x32_bf16 v[128:131], v[152:155], v[72:75], v[56:59]
	v_mfma_f32_16x16x32_bf16 v[52:55], v[144:147], v[88:91], v[52:55]
	v_mfma_f32_16x16x32_bf16 v[132:135], v[152:155], v[88:91], v[48:51]
	v_mfma_f32_16x16x32_bf16 v[44:47], v[144:147], v[160:163], v[44:47]
	v_mfma_f32_16x16x32_bf16 v[136:139], v[152:155], v[160:163], v[40:43]
	v_mfma_f32_16x16x32_bf16 v[36:39], v[144:147], v[168:171], v[36:39]
	v_mfma_f32_16x16x32_bf16 v[140:143], v[152:155], v[168:171], v[32:35]
	v_mfma_f32_16x16x32_bf16 v[28:31], v[96:99], v[64:67], v[28:31]
	v_mfma_f32_16x16x32_bf16 v[24:27], v[112:115], v[64:67], v[24:27]
	v_mfma_f32_16x16x32_bf16 v[20:23], v[96:99], v[80:83], v[20:23]
	v_mfma_f32_16x16x32_bf16 v[16:19], v[112:115], v[80:83], v[16:19]
	v_mfma_f32_16x16x32_bf16 v[12:15], v[96:99], v[156:159], v[12:15]
	v_mfma_f32_16x16x32_bf16 v[8:11], v[112:115], v[156:159], v[8:11]
	v_mfma_f32_16x16x32_bf16 v[4:7], v[96:99], v[164:167], v[4:7]
	v_mfma_f32_16x16x32_bf16 v[0:3], v[112:115], v[164:167], v[0:3]
	v_mfma_f32_16x16x32_bf16 v[28:31], v[104:107], v[72:75], v[28:31]
	v_mfma_f32_16x16x32_bf16 v[144:147], v[120:123], v[72:75], v[24:27]
	v_mfma_f32_16x16x32_bf16 v[20:23], v[104:107], v[88:91], v[20:23]
	v_mfma_f32_16x16x32_bf16 v[148:151], v[120:123], v[88:91], v[16:19]
	v_mfma_f32_16x16x32_bf16 v[12:15], v[104:107], v[160:163], v[12:15]
	v_mfma_f32_16x16x32_bf16 v[152:155], v[120:123], v[160:163], v[8:11]
	v_mfma_f32_16x16x32_bf16 v[4:7], v[104:107], v[168:171], v[4:7]
	v_mfma_f32_16x16x32_bf16 v[156:159], v[120:123], v[168:171], v[0:3]
	s_barrier
	ds_read_b128 v[0:3], v226 offset:0
	ds_read_b128 v[8:11], v226 offset:0x400
	ds_read_b128 v[16:19], v226 offset:0x800
	ds_read_b128 v[24:27], v226 offset:0xc00
	ds_read_b128 v[32:35], v227 offset:0
	ds_read_b128 v[40:43], v227 offset:0x400
	ds_read_b128 v[48:51], v227 offset:0x800
	ds_read_b128 v[56:59], v227 offset:0xc00
	ds_read_b128 v[64:67], v227 offset:0x1000
	ds_read_b128 v[218:221], v227 offset:0x1400
	ds_read_b128 v[236:239], v227 offset:0x1800
	ds_read_b128 v[240:243], v227 offset:0x1c00
	s_waitcnt vmcnt(2)
	s_barrier
	s_waitcnt lgkmcnt(0)
	v_mfma_f32_16x16x32_bf16 v[72:75], v[0:3], v[32:35], v[124:127]
	v_mfma_f32_16x16x32_bf16 v[120:123], v[8:11], v[40:43], v[72:75]
	v_mfma_f32_16x16x32_bf16 v[72:75], v[16:19], v[32:35], v[180:183]
	v_mfma_f32_16x16x32_bf16 v[124:127], v[24:27], v[40:43], v[72:75]
	v_mfma_f32_16x16x32_bf16 v[72:75], v[0:3], v[48:51], v[116:119]
	v_mfma_f32_16x16x32_bf16 v[112:115], v[8:11], v[56:59], v[72:75]
	v_mfma_f32_16x16x32_bf16 v[72:75], v[16:19], v[48:51], v[184:187]
	v_mfma_f32_16x16x32_bf16 v[116:119], v[24:27], v[56:59], v[72:75]
	v_mfma_f32_16x16x32_bf16 v[72:75], v[0:3], v[64:67], v[108:111]
	v_mfma_f32_16x16x32_bf16 v[104:107], v[8:11], v[218:221], v[72:75]
	v_mfma_f32_16x16x32_bf16 v[72:75], v[16:19], v[64:67], v[188:191]
	v_mfma_f32_16x16x32_bf16 v[108:111], v[24:27], v[218:221], v[72:75]
	v_mfma_f32_16x16x32_bf16 v[72:75], v[0:3], v[236:239], v[100:103]
	v_mfma_f32_16x16x32_bf16 v[96:99], v[8:11], v[240:243], v[72:75]
	v_mfma_f32_16x16x32_bf16 v[72:75], v[16:19], v[236:239], v[192:195]
	v_mfma_f32_16x16x32_bf16 v[100:103], v[24:27], v[240:243], v[72:75]
	s_barrier
; #define WAIT_V(n) asm volatile("s_waitcnt vmcnt(%0)" ::"n"(n) : "memory")
; #define SCHED() __builtin_amdgcn_sched_barrier(0)
; #define LGKM(n) asm volatile("s_waitcnt lgkmcnt(%0)" ::"n"(n) : "memory")
; #define STAGE_AX(AG, b, h, kt) do { _Pragma("unroll") for (int i = 0; i < 2; ++i)                                    \
;       __builtin_amdgcn_global_load_lds((const unsigned*)(((AG) + ((size_t)(kt) * (BK * 2) + (size_t)((h) * 2 + i) * 128 * lda)) + aoff), \
;                                        (unsigned*)(shm + SLOTA(b, h) + wid * 1024 + i * 8192), 16, 0, 0); } while (0)
; #define STAGE_BX(BG, b, h, kt) do { _Pragma("unroll") for (int i = 0; i < 2; ++i)                                    \
;       __builtin_amdgcn_global_load_lds((const unsigned*)(((BG) + ((size_t)(kt) * (BK * 2) + (size_t)((h) * 2 + i) * 128 * K)) + boff),   \
;                                        (unsigned*)(shm + SLOTB(b, h) + wid * 1024 + i * 8192), 16, 0, 0); } while (0)
; #define LDA(b, h) do { const unsigned pa_ = lds0 + SLOTA(b, h) + wr * 8192 + laneoff; _Pragma("unroll") for (int m = 0; m < 4; ++m)   \
;       _Pragma("unroll") for (int k = 0; k < 2; ++k) DSR(At[m][k], pa_, m * 2048 + k * 1024); } while (0)
; #define LDB(dst, b, h) do { const unsigned pb_ = lds0 + SLOTB(b, h) + wc * 4096 + laneoff; _Pragma("unroll") for (int n = 0; n < 2; ++n) \
;       _Pragma("unroll") for (int k = 0; k < 2; ++k) DSR(dst[n][k], pb_, n * 2048 + k * 1024); } while (0)
; #define BAR __builtin_amdgcn_s_barrier()
; #define LGKM(n) asm volatile("s_waitcnt lgkmcnt(%0)" ::"n"(n) : "memory")
; template <int EPI, bool SWP> ...
;     ...
;   { LDB(B0, 1, 0); LDA(1, 0); WAIT_V(2); BAR; LGKM(0); SCHED(); MMA(0, 0, B0); BAR; SCHED();
;     LDB(B1, 1, 1); WAIT_V(0); BAR; LGKM(0); SCHED(); MMA(0, 1, B1); BAR; SCHED();
;     LDA(1, 1);
;     if (has_next) { STAGE_BX(Bg_n, 0, 0, 0); STAGE_AX(Ag_n, 0, 0, 0); STAGE_BX(Bg_n, 0, 1, 0); STAGE_AX(Ag_n, 0, 1, 0); }
;     BAR; LGKM(0); SCHED(); MMA(1, 0, B0); MMA(1, 1, B1); BAR; SCHED(); }
;   if (wr == 0) BAR;
	ds_read_b128 v[160:163], v229 offset:0
	ds_read_b128 v[164:167], v229 offset:0x400
	ds_read_b128 v[168:171], v229 offset:0x800
	ds_read_b128 v[172:175], v229 offset:0xc00
	s_waitcnt vmcnt(0)
	s_barrier
	s_waitcnt lgkmcnt(0)
	v_mfma_f32_16x16x32_bf16 v[72:75], v[160:163], v[32:35], v[92:95]
	v_mfma_f32_16x16x32_bf16 v[32:35], v[168:171], v[32:35], v[196:199]
	v_mfma_f32_16x16x32_bf16 v[92:95], v[172:175], v[40:43], v[32:35]
	v_mfma_f32_16x16x32_bf16 v[32:35], v[160:163], v[48:51], v[84:87]
	v_mfma_f32_16x16x32_bf16 v[80:83], v[164:167], v[56:59], v[32:35]
	v_mfma_f32_16x16x32_bf16 v[32:35], v[168:171], v[48:51], v[200:203]
	v_mfma_f32_16x16x32_bf16 v[84:87], v[172:175], v[56:59], v[32:35]
	v_mfma_f32_16x16x32_bf16 v[32:35], v[160:163], v[64:67], v[76:79]
	v_mfma_f32_16x16x32_bf16 v[88:91], v[164:167], v[40:43], v[72:75]
	v_mfma_f32_16x16x32_bf16 v[72:75], v[164:167], v[218:221], v[32:35]
	v_mfma_f32_16x16x32_bf16 v[32:35], v[168:171], v[64:67], v[204:207]
	v_mfma_f32_16x16x32_bf16 v[76:79], v[172:175], v[218:221], v[32:35]
	v_mfma_f32_16x16x32_bf16 v[32:35], v[160:163], v[236:239], v[68:71]
	v_mfma_f32_16x16x32_bf16 v[64:67], v[164:167], v[240:243], v[32:35]
	v_mfma_f32_16x16x32_bf16 v[32:35], v[168:171], v[236:239], v[176:179]
	v_mfma_f32_16x16x32_bf16 v[68:71], v[172:175], v[240:243], v[32:35]
	s_barrier
	ds_read_b128 v[200:203], v230 offset:0
	ds_read_b128 v[204:207], v230 offset:0x400
	ds_read_b128 v[192:195], v230 offset:0x800
	ds_read_b128 v[196:199], v230 offset:0xc00
	ds_read_b128 v[184:187], v230 offset:0x1000
	ds_read_b128 v[188:191], v230 offset:0x1400
	ds_read_b128 v[176:179], v230 offset:0x1800
	ds_read_b128 v[180:183], v230 offset:0x1c00
	s_and_b64 vcc, exec, s[44:45]
	v_lshl_add_u64 v[218:219], s[50:51], 0, v[208:209]
	v_lshl_add_u64 v[220:221], s[48:49], 0, v[208:209]
	s_cbranch_vccz .LBB0_357
	s_mov_b32 m0, s16
	v_lshl_add_u64 v[32:33], v[218:219], 0, s[4:5]
	global_load_lds_dwordx4 v[218:219], off
	s_mov_b32 m0, s17
	s_nop 0
	global_load_lds_dwordx4 v[32:33], off
	s_mov_b32 m0, s3
	v_lshl_add_u64 v[32:33], v[220:221], 0, s[4:5]
	global_load_lds_dwordx4 v[220:221], off
	s_mov_b32 m0, s18
	s_nop 0
	global_load_lds_dwordx4 v[32:33], off
	v_lshl_add_u64 v[32:33], v[218:219], 0, s[10:11]
	s_mov_b32 m0, s19
	s_nop 0
	global_load_lds_dwordx4 v[32:33], off
	v_lshl_add_u64 v[32:33], v[218:219], 0, s[12:13]
	s_mov_b32 m0, s60
	s_nop 0
	global_load_lds_dwordx4 v[32:33], off
	v_lshl_add_u64 v[32:33], v[220:221], 0, s[10:11]
	s_mov_b32 m0, s61
	s_nop 0
	global_load_lds_dwordx4 v[32:33], off
	v_lshl_add_u64 v[32:33], v[220:221], 0, s[12:13]
	s_mov_b32 m0, s62
	s_nop 0
	global_load_lds_dwordx4 v[32:33], off
.LBB0_357:
	s_barrier
	s_waitcnt lgkmcnt(0)
	v_mfma_f32_16x16x32_bf16 v[32:35], v[0:3], v[200:203], v[60:63]
	v_mfma_f32_16x16x32_bf16 v[56:59], v[8:11], v[204:207], v[32:35]
	v_mfma_f32_16x16x32_bf16 v[32:35], v[16:19], v[200:203], v[128:131]
	v_mfma_f32_16x16x32_bf16 v[60:63], v[24:27], v[204:207], v[32:35]
	v_mfma_f32_16x16x32_bf16 v[32:35], v[0:3], v[192:195], v[52:55]
	v_mfma_f32_16x16x32_bf16 v[48:51], v[8:11], v[196:199], v[32:35]
	v_mfma_f32_16x16x32_bf16 v[32:35], v[16:19], v[192:195], v[132:135]
	v_mfma_f32_16x16x32_bf16 v[52:55], v[24:27], v[196:199], v[32:35]
	v_mfma_f32_16x16x32_bf16 v[32:35], v[0:3], v[184:187], v[44:47]
	v_mfma_f32_16x16x32_bf16 v[40:43], v[8:11], v[188:191], v[32:35]
	v_mfma_f32_16x16x32_bf16 v[32:35], v[16:19], v[184:187], v[136:139]
	v_mfma_f32_16x16x32_bf16 v[0:3], v[0:3], v[176:179], v[36:39]
	v_mfma_f32_16x16x32_bf16 v[44:47], v[24:27], v[188:191], v[32:35]
	v_mfma_f32_16x16x32_bf16 v[32:35], v[8:11], v[180:183], v[0:3]
	v_mfma_f32_16x16x32_bf16 v[0:3], v[16:19], v[176:179], v[140:143]
	v_mfma_f32_16x16x32_bf16 v[36:39], v[24:27], v[180:183], v[0:3]
	v_mfma_f32_16x16x32_bf16 v[0:3], v[160:163], v[200:203], v[28:31]
	v_mfma_f32_16x16x32_bf16 v[24:27], v[164:167], v[204:207], v[0:3]
	v_mfma_f32_16x16x32_bf16 v[0:3], v[168:171], v[200:203], v[144:147]
	v_mfma_f32_16x16x32_bf16 v[28:31], v[172:175], v[204:207], v[0:3]
	v_mfma_f32_16x16x32_bf16 v[0:3], v[160:163], v[192:195], v[20:23]
	v_mfma_f32_16x16x32_bf16 v[16:19], v[164:167], v[196:199], v[0:3]
	v_mfma_f32_16x16x32_bf16 v[0:3], v[168:171], v[192:195], v[148:151]
	v_mfma_f32_16x16x32_bf16 v[20:23], v[172:175], v[196:199], v[0:3]
	v_mfma_f32_16x16x32_bf16 v[0:3], v[160:163], v[184:187], v[12:15]
	v_mfma_f32_16x16x32_bf16 v[8:11], v[164:167], v[188:191], v[0:3]
	v_mfma_f32_16x16x32_bf16 v[0:3], v[168:171], v[184:187], v[152:155]
	v_mfma_f32_16x16x32_bf16 v[12:15], v[172:175], v[188:191], v[0:3]
	v_mfma_f32_16x16x32_bf16 v[0:3], v[160:163], v[176:179], v[4:7]
	v_mfma_f32_16x16x32_bf16 v[4:7], v[168:171], v[176:179], v[156:159]
	v_mfma_f32_16x16x32_bf16 v[0:3], v[164:167], v[180:183], v[0:3]
	v_mfma_f32_16x16x32_bf16 v[4:7], v[172:175], v[180:183], v[4:7]
	s_barrier
	s_andn2_b64 vcc, exec, s[0:1]
	s_cbranch_vccnz .LBB0_359
	s_barrier

; #define SCHED() __builtin_amdgcn_sched_barrier(0)
; #define LGKM(n) asm volatile("s_waitcnt lgkmcnt(%0)" ::"n"(n) : "memory")
; #define STAGE_A(b, h, kt) STAGE_AX(Ag, b, h, kt)
; #define STAGE_B(b, h, kt) STAGE_BX(Bg, b, h, kt)
; #define LDA(b, h) do { const unsigned pa_ = lds0 + SLOTA(b, h) + wr * 8192 + laneoff; _Pragma("unroll") for (int m = 0; m < 4; ++m)   \
;       _Pragma("unroll") for (int k = 0; k < 2; ++k) DSR(At[m][k], pa_, m * 2048 + k * 1024); } while (0)
; #define LDB(dst, b, h) do { const unsigned pb_ = lds0 + SLOTB(b, h) + wc * 4096 + laneoff; _Pragma("unroll") for (int n = 0; n < 2; ++n) \
;       _Pragma("unroll") for (int k = 0; k < 2; ++k) DSR(dst[n][k], pb_, n * 2048 + k * 1024); } while (0)
; #define BAR __builtin_amdgcn_s_barrier()
; #define LGKM(n) asm volatile("s_waitcnt lgkmcnt(%0)" ::"n"(n) : "memory")
; template <int EPI, bool SWP> ...
;     ...
;   for (int t = 0; t < nt - 2; t += 2) {
;     LDB(B0, 0, 0); LDA(0, 0); STAGE_A(1, 1, t + 1);
;     LGKM(8); BAR; LGKM(0); SCHED(); MMA(0, 0, B0); BAR; SCHED();
;     LDB(B1, 0, 1); STAGE_B(0, 0, t + 2);
;     BAR; LGKM(0); SCHED(); MMA(0, 1, B1); BAR; SCHED();
;     LDA(0, 1); STAGE_A(0, 0, t + 2);
;     BAR; LGKM(0); SCHED(); MMA(1, 0, B0); BAR; SCHED();
.LBB0_385:
	ds_read_b128 v[130:133], v224 offset:0
	ds_read_b128 v[134:137], v224 offset:0x400
	ds_read_b128 v[138:141], v224 offset:0x800
	ds_read_b128 v[142:145], v224 offset:0xc00
	ds_read_b128 v[146:149], v225 offset:0
	ds_read_b128 v[150:153], v225 offset:0x400
	ds_read_b128 v[154:157], v225 offset:0x800
	ds_read_b128 v[158:161], v225 offset:0xc00
	ds_read_b128 v[162:165], v225 offset:0x1000
	ds_read_b128 v[166:169], v225 offset:0x1400
	ds_read_b128 v[170:173], v225 offset:0x1800
	v_lshl_add_u64 v[194:195], s[50:51], 0, v[218:219]
	s_mov_b64 s[58:59], 0xf140080
	s_mov_b32 m0, s69
	ds_read_b128 v[174:177], v225 offset:0x1c00
	v_lshl_add_u64 v[178:179], v[194:195], 0, s[58:59]
	s_mov_b64 s[58:59], 0xf160080
	global_load_lds_dwordx4 v[178:179], off
	v_lshl_add_u64 v[178:179], v[194:195], 0, s[58:59]
	s_mov_b32 m0, s70
	s_nop 0
	global_load_lds_dwordx4 v[178:179], off
	s_waitcnt lgkmcnt(8)
	s_barrier
	s_waitcnt lgkmcnt(0)
	v_mfma_f32_16x16x32_bf16 v[124:127], v[130:133], v[146:149], v[124:127]
	v_mfma_f32_16x16x32_bf16 v[120:123], v[138:141], v[146:149], v[120:123]
	v_mfma_f32_16x16x32_bf16 v[116:119], v[130:133], v[154:157], v[116:119]
	v_mfma_f32_16x16x32_bf16 v[112:115], v[138:141], v[154:157], v[112:115]
	v_mfma_f32_16x16x32_bf16 v[108:111], v[130:133], v[162:165], v[108:111]
	v_mfma_f32_16x16x32_bf16 v[104:107], v[138:141], v[162:165], v[104:107]
	v_mfma_f32_16x16x32_bf16 v[100:103], v[130:133], v[170:173], v[100:103]
	v_mfma_f32_16x16x32_bf16 v[96:99], v[138:141], v[170:173], v[96:99]
	v_mfma_f32_16x16x32_bf16 v[124:127], v[134:137], v[150:153], v[124:127]
	v_mfma_f32_16x16x32_bf16 v[120:123], v[142:145], v[150:153], v[120:123]
	v_mfma_f32_16x16x32_bf16 v[116:119], v[134:137], v[158:161], v[116:119]
	v_mfma_f32_16x16x32_bf16 v[112:115], v[142:145], v[158:161], v[112:115]
	v_mfma_f32_16x16x32_bf16 v[108:111], v[134:137], v[166:169], v[108:111]
	v_mfma_f32_16x16x32_bf16 v[104:107], v[142:145], v[166:169], v[104:107]
	v_mfma_f32_16x16x32_bf16 v[100:103], v[134:137], v[174:177], v[100:103]
	v_mfma_f32_16x16x32_bf16 v[96:99], v[142:145], v[174:177], v[96:99]
	s_barrier
	ds_read_b128 v[178:181], v226 offset:0
	ds_read_b128 v[182:185], v226 offset:0x400
	ds_read_b128 v[186:189], v226 offset:0x800
	v_lshl_add_u64 v[196:197], s[48:49], 0, v[218:219]
	s_mov_b64 s[58:59], 0xe400100
	s_mov_b32 m0, s16
	ds_read_b128 v[190:193], v226 offset:0xc00
	v_lshl_add_u64 v[198:199], v[196:197], 0, s[58:59]
	s_mov_b64 s[58:59], 0xe420100
	global_load_lds_dwordx4 v[198:199], off
	v_lshl_add_u64 v[198:199], v[196:197], 0, s[58:59]
	s_mov_b32 m0, s17
	s_nop 0
	global_load_lds_dwordx4 v[198:199], off
	s_barrier
	s_waitcnt lgkmcnt(0)
	v_mfma_f32_16x16x32_bf16 v[92:95], v[178:181], v[146:149], v[92:95]
	v_mfma_f32_16x16x32_bf16 v[88:91], v[186:189], v[146:149], v[88:91]
	v_mfma_f32_16x16x32_bf16 v[84:87], v[178:181], v[154:157], v[84:87]
	v_mfma_f32_16x16x32_bf16 v[80:83], v[186:189], v[154:157], v[80:83]
	v_mfma_f32_16x16x32_bf16 v[76:79], v[178:181], v[162:165], v[76:79]
	v_mfma_f32_16x16x32_bf16 v[72:75], v[186:189], v[162:165], v[72:75]
	v_mfma_f32_16x16x32_bf16 v[68:71], v[178:181], v[170:173], v[68:71]
	v_mfma_f32_16x16x32_bf16 v[64:67], v[186:189], v[170:173], v[64:67]
	v_mfma_f32_16x16x32_bf16 v[92:95], v[182:185], v[150:153], v[92:95]
	v_mfma_f32_16x16x32_bf16 v[88:91], v[190:193], v[150:153], v[88:91]
	v_mfma_f32_16x16x32_bf16 v[84:87], v[182:185], v[158:161], v[84:87]
	v_mfma_f32_16x16x32_bf16 v[80:83], v[190:193], v[158:161], v[80:83]
	v_mfma_f32_16x16x32_bf16 v[76:79], v[182:185], v[166:169], v[76:79]
	v_mfma_f32_16x16x32_bf16 v[72:75], v[190:193], v[166:169], v[72:75]
	v_mfma_f32_16x16x32_bf16 v[68:71], v[182:185], v[174:177], v[68:71]
	v_mfma_f32_16x16x32_bf16 v[64:67], v[190:193], v[174:177], v[64:67]
	s_barrier
	ds_read_b128 v[146:149], v227 offset:0
	ds_read_b128 v[150:153], v227 offset:0x400
	ds_read_b128 v[154:157], v227 offset:0x800
	ds_read_b128 v[158:161], v227 offset:0xc00
	ds_read_b128 v[162:165], v227 offset:0x1000
	ds_read_b128 v[166:169], v227 offset:0x1400
	ds_read_b128 v[170:173], v227 offset:0x1800
	s_mov_b64 s[58:59], 0xf100100
	s_mov_b32 m0, s3
	ds_read_b128 v[174:177], v227 offset:0x1c00
	v_lshl_add_u64 v[198:199], v[194:195], 0, s[58:59]
	s_mov_b64 s[58:59], 0xf120100
	global_load_lds_dwordx4 v[198:199], off
	v_lshl_add_u64 v[198:199], v[194:195], 0, s[58:59]
	s_mov_b32 m0, s18
	s_nop 0
	global_load_lds_dwordx4 v[198:199], off
	s_barrier
	s_waitcnt lgkmcnt(0)
	v_mfma_f32_16x16x32_bf16 v[60:63], v[130:133], v[146:149], v[60:63]
	v_mfma_f32_16x16x32_bf16 v[56:59], v[138:141], v[146:149], v[56:59]
	v_mfma_f32_16x16x32_bf16 v[52:55], v[130:133], v[154:157], v[52:55]
	v_mfma_f32_16x16x32_bf16 v[48:51], v[138:141], v[154:157], v[48:51]
	v_mfma_f32_16x16x32_bf16 v[44:47], v[130:133], v[162:165], v[44:47]
	v_mfma_f32_16x16x32_bf16 v[40:43], v[138:141], v[162:165], v[40:43]
	v_mfma_f32_16x16x32_bf16 v[36:39], v[130:133], v[170:173], v[36:39]
	v_mfma_f32_16x16x32_bf16 v[32:35], v[138:141], v[170:173], v[32:35]
	v_mfma_f32_16x16x32_bf16 v[60:63], v[134:137], v[150:153], v[60:63]
	v_mfma_f32_16x16x32_bf16 v[56:59], v[142:145], v[150:153], v[56:59]
	v_mfma_f32_16x16x32_bf16 v[52:55], v[134:137], v[158:161], v[52:55]
	v_mfma_f32_16x16x32_bf16 v[48:51], v[142:145], v[158:161], v[48:51]
	v_mfma_f32_16x16x32_bf16 v[44:47], v[134:137], v[166:169], v[44:47]
	v_mfma_f32_16x16x32_bf16 v[40:43], v[142:145], v[166:169], v[40:43]
	v_mfma_f32_16x16x32_bf16 v[36:39], v[134:137], v[174:177], v[36:39]
	v_mfma_f32_16x16x32_bf16 v[32:35], v[142:145], v[174:177], v[32:35]
	s_barrier
; #define WAIT_V(n) asm volatile("s_waitcnt vmcnt(%0)" ::"n"(n) : "memory")
; #define SCHED() __builtin_amdgcn_sched_barrier(0)
; #define LGKM(n) asm volatile("s_waitcnt lgkmcnt(%0)" ::"n"(n) : "memory")
; #define STAGE_A(b, h, kt) STAGE_AX(Ag, b, h, kt)
; #define STAGE_B(b, h, kt) STAGE_BX(Bg, b, h, kt)
; #define LDA(b, h) do { const unsigned pa_ = lds0 + SLOTA(b, h) + wr * 8192 + laneoff; _Pragma("unroll") for (int m = 0; m < 4; ++m)   \
;       _Pragma("unroll") for (int k = 0; k < 2; ++k) DSR(At[m][k], pa_, m * 2048 + k * 1024); } while (0)
; #define LDB(dst, b, h) do { const unsigned pb_ = lds0 + SLOTB(b, h) + wc * 4096 + laneoff; _Pragma("unroll") for (int n = 0; n < 2; ++n) \
;       _Pragma("unroll") for (int k = 0; k < 2; ++k) DSR(dst[n][k], pb_, n * 2048 + k * 1024); } while (0)
; #define BAR __builtin_amdgcn_s_barrier()
; #define LGKM(n) asm volatile("s_waitcnt lgkmcnt(%0)" ::"n"(n) : "memory")
; template <int EPI, bool SWP> ...
;     ...
;     BAR; LGKM(0); SCHED(); MMA(1, 0, B0); BAR; SCHED();
;     STAGE_B(0, 1, t + 2);
;     WAIT_V(6); BAR; SCHED(); MMA(1, 1, B1); BAR; SCHED();
;     LDB(B0, 1, 0); LDA(1, 0); STAGE_A(0, 1, t + 2);
;     LGKM(8); BAR; LGKM(0); SCHED(); MMA(0, 0, B0); BAR; SCHED();
;     LDB(B1, 1, 1); STAGE_B(1, 0, t + 3);
;     BAR; LGKM(0); SCHED(); MMA(0, 1, B1); BAR; SCHED();
;     LDA(1, 1); STAGE_A(1, 0, t + 3);
;     BAR; LGKM(0); SCHED(); MMA(1, 0, B0); BAR; SCHED();
	s_mov_b64 s[58:59], 0xe440100
	s_mov_b32 m0, s19
	v_lshl_add_u64 v[130:131], v[196:197], 0, s[58:59]
	s_mov_b64 s[58:59], 0xe460100
	global_load_lds_dwordx4 v[130:131], off
	v_lshl_add_u64 v[130:131], v[196:197], 0, s[58:59]
	s_mov_b32 m0, s60
	s_nop 0
	global_load_lds_dwordx4 v[130:131], off
	s_waitcnt vmcnt(6)
	s_barrier
	v_mfma_f32_16x16x32_bf16 v[28:31], v[178:181], v[146:149], v[28:31]
	v_mfma_f32_16x16x32_bf16 v[24:27], v[186:189], v[146:149], v[24:27]
	v_mfma_f32_16x16x32_bf16 v[20:23], v[178:181], v[154:157], v[20:23]
	v_mfma_f32_16x16x32_bf16 v[16:19], v[186:189], v[154:157], v[16:19]
	v_mfma_f32_16x16x32_bf16 v[12:15], v[178:181], v[162:165], v[12:15]
	v_mfma_f32_16x16x32_bf16 v[8:11], v[186:189], v[162:165], v[8:11]
	v_mfma_f32_16x16x32_bf16 v[4:7], v[178:181], v[170:173], v[4:7]
	v_mfma_f32_16x16x32_bf16 v[0:3], v[186:189], v[170:173], v[0:3]
	v_mfma_f32_16x16x32_bf16 v[28:31], v[182:185], v[150:153], v[28:31]
	v_mfma_f32_16x16x32_bf16 v[24:27], v[190:193], v[150:153], v[24:27]
	v_mfma_f32_16x16x32_bf16 v[20:23], v[182:185], v[158:161], v[20:23]
	v_mfma_f32_16x16x32_bf16 v[16:19], v[190:193], v[158:161], v[16:19]
	v_mfma_f32_16x16x32_bf16 v[12:15], v[182:185], v[166:169], v[12:15]
	v_mfma_f32_16x16x32_bf16 v[8:11], v[190:193], v[166:169], v[8:11]
	v_mfma_f32_16x16x32_bf16 v[4:7], v[182:185], v[174:177], v[4:7]
	v_mfma_f32_16x16x32_bf16 v[0:3], v[190:193], v[174:177], v[0:3]
	s_barrier
	ds_read_b128 v[130:133], v229 offset:0
	ds_read_b128 v[134:137], v229 offset:0x400
	ds_read_b128 v[138:141], v229 offset:0x800
	ds_read_b128 v[142:145], v229 offset:0xc00
	ds_read_b128 v[146:149], v230 offset:0
	ds_read_b128 v[150:153], v230 offset:0x400
	ds_read_b128 v[154:157], v230 offset:0x800
	ds_read_b128 v[158:161], v230 offset:0xc00
	ds_read_b128 v[162:165], v230 offset:0x1000
	ds_read_b128 v[166:169], v230 offset:0x1400
	ds_read_b128 v[170:173], v230 offset:0x1800
	s_mov_b64 s[58:59], 0xf140100
	s_mov_b32 m0, s61
	ds_read_b128 v[174:177], v230 offset:0x1c00
	v_lshl_add_u64 v[178:179], v[194:195], 0, s[58:59]
	s_mov_b64 s[58:59], 0xf160100
	global_load_lds_dwordx4 v[178:179], off
	v_lshl_add_u64 v[178:179], v[194:195], 0, s[58:59]
	s_mov_b32 m0, s62
	s_nop 0
	global_load_lds_dwordx4 v[178:179], off
	s_waitcnt lgkmcnt(8)
	s_barrier
	s_waitcnt lgkmcnt(0)
	v_mfma_f32_16x16x32_bf16 v[124:127], v[130:133], v[146:149], v[124:127]
	v_mfma_f32_16x16x32_bf16 v[120:123], v[138:141], v[146:149], v[120:123]
	v_mfma_f32_16x16x32_bf16 v[116:119], v[130:133], v[154:157], v[116:119]
	v_mfma_f32_16x16x32_bf16 v[112:115], v[138:141], v[154:157], v[112:115]
	v_mfma_f32_16x16x32_bf16 v[108:111], v[130:133], v[162:165], v[108:111]
	v_mfma_f32_16x16x32_bf16 v[104:107], v[138:141], v[162:165], v[104:107]
	v_mfma_f32_16x16x32_bf16 v[100:103], v[130:133], v[170:173], v[100:103]
	v_mfma_f32_16x16x32_bf16 v[96:99], v[138:141], v[170:173], v[96:99]
	v_mfma_f32_16x16x32_bf16 v[124:127], v[134:137], v[150:153], v[124:127]
	v_mfma_f32_16x16x32_bf16 v[120:123], v[142:145], v[150:153], v[120:123]
	v_mfma_f32_16x16x32_bf16 v[116:119], v[134:137], v[158:161], v[116:119]
	v_mfma_f32_16x16x32_bf16 v[112:115], v[142:145], v[158:161], v[112:115]
	v_mfma_f32_16x16x32_bf16 v[108:111], v[134:137], v[166:169], v[108:111]
	v_mfma_f32_16x16x32_bf16 v[104:107], v[142:145], v[166:169], v[104:107]
	v_mfma_f32_16x16x32_bf16 v[100:103], v[134:137], v[174:177], v[100:103]
	v_mfma_f32_16x16x32_bf16 v[96:99], v[142:145], v[174:177], v[96:99]
	s_barrier
	ds_read_b128 v[178:181], v231 offset:0
	ds_read_b128 v[182:185], v231 offset:0x400
	ds_read_b128 v[186:189], v231 offset:0x800
	s_mov_b64 s[58:59], 0xe400180
	s_mov_b32 m0, s63
	ds_read_b128 v[190:193], v231 offset:0xc00
	v_lshl_add_u64 v[198:199], v[196:197], 0, s[58:59]
	s_mov_b64 s[58:59], 0xe420180
	global_load_lds_dwordx4 v[198:199], off
	v_lshl_add_u64 v[198:199], v[196:197], 0, s[58:59]
	s_mov_b32 m0, s64
	s_nop 0
	global_load_lds_dwordx4 v[198:199], off
	s_barrier
	s_waitcnt lgkmcnt(0)
	v_mfma_f32_16x16x32_bf16 v[92:95], v[178:181], v[146:149], v[92:95]
	v_mfma_f32_16x16x32_bf16 v[88:91], v[186:189], v[146:149], v[88:91]
	v_mfma_f32_16x16x32_bf16 v[84:87], v[178:181], v[154:157], v[84:87]
	v_mfma_f32_16x16x32_bf16 v[80:83], v[186:189], v[154:157], v[80:83]
	v_mfma_f32_16x16x32_bf16 v[76:79], v[178:181], v[162:165], v[76:79]
	v_mfma_f32_16x16x32_bf16 v[72:75], v[186:189], v[162:165], v[72:75]
	v_mfma_f32_16x16x32_bf16 v[68:71], v[178:181], v[170:173], v[68:71]
	v_mfma_f32_16x16x32_bf16 v[64:67], v[186:189], v[170:173], v[64:67]
	v_mfma_f32_16x16x32_bf16 v[92:95], v[182:185], v[150:153], v[92:95]
	v_mfma_f32_16x16x32_bf16 v[88:91], v[190:193], v[150:153], v[88:91]
	v_mfma_f32_16x16x32_bf16 v[84:87], v[182:185], v[158:161], v[84:87]
	v_mfma_f32_16x16x32_bf16 v[80:83], v[190:193], v[158:161], v[80:83]
	v_mfma_f32_16x16x32_bf16 v[76:79], v[182:185], v[166:169], v[76:79]
	v_mfma_f32_16x16x32_bf16 v[72:75], v[190:193], v[166:169], v[72:75]
	v_mfma_f32_16x16x32_bf16 v[68:71], v[182:185], v[174:177], v[68:71]
	v_mfma_f32_16x16x32_bf16 v[64:67], v[190:193], v[174:177], v[64:67]
	s_barrier
	ds_read_b128 v[146:149], v232 offset:0
	ds_read_b128 v[150:153], v232 offset:0x400
	ds_read_b128 v[154:157], v232 offset:0x800
	ds_read_b128 v[158:161], v232 offset:0xc00
	ds_read_b128 v[162:165], v232 offset:0x1000
	ds_read_b128 v[166:169], v232 offset:0x1400
	ds_read_b128 v[170:173], v232 offset:0x1800
	s_mov_b64 s[58:59], 0xf100180
	s_mov_b32 m0, s65
	ds_read_b128 v[174:177], v232 offset:0x1c00
	v_lshl_add_u64 v[198:199], v[194:195], 0, s[58:59]
	s_mov_b64 s[58:59], 0xf120180
	global_load_lds_dwordx4 v[198:199], off
	v_lshl_add_u64 v[194:195], v[194:195], 0, s[58:59]
	s_mov_b32 m0, s66
	s_nop 0
	global_load_lds_dwordx4 v[194:195], off
	s_barrier
; #define WAIT_V(n) asm volatile("s_waitcnt vmcnt(%0)" ::"n"(n) : "memory")
; #define SCHED() __builtin_amdgcn_sched_barrier(0)
; #define LGKM(n) asm volatile("s_waitcnt lgkmcnt(%0)" ::"n"(n) : "memory")
; #define STAGE_A(b, h, kt) STAGE_AX(Ag, b, h, kt)
; #define STAGE_B(b, h, kt) STAGE_BX(Bg, b, h, kt)
; #define LDA(b, h) do { const unsigned pa_ = lds0 + SLOTA(b, h) + wr * 8192 + laneoff; _Pragma("unroll") for (int m = 0; m < 4; ++m)   \
;       _Pragma("unroll") for (int k = 0; k < 2; ++k) DSR(At[m][k], pa_, m * 2048 + k * 1024); } while (0)
; #define LDB(dst, b, h) do { const unsigned pb_ = lds0 + SLOTB(b, h) + wc * 4096 + laneoff; _Pragma("unroll") for (int n = 0; n < 2; ++n) \
;       _Pragma("unroll") for (int k = 0; k < 2; ++k) DSR(dst[n][k], pb_, n * 2048 + k * 1024); } while (0)
; #define BAR __builtin_amdgcn_s_barrier()
; #define LGKM(n) asm volatile("s_waitcnt lgkmcnt(%0)" ::"n"(n) : "memory")
; template <int EPI, bool SWP> ...
;     ...
;     BAR; LGKM(0); SCHED(); MMA(1, 0, B0); BAR; SCHED();
;     STAGE_B(1, 1, t + 3);
;     WAIT_V(6); BAR; SCHED(); MMA(1, 1, B1); BAR; SCHED();
;   }
;   { LDB(B0, 0, 0); LDA(0, 0); STAGE_A(1, 1, nt - 1);
;     BAR; LGKM(0); SCHED(); MMA(0, 0, B0); BAR; SCHED();
	s_waitcnt lgkmcnt(0)
	v_mfma_f32_16x16x32_bf16 v[60:63], v[130:133], v[146:149], v[60:63]
	v_mfma_f32_16x16x32_bf16 v[56:59], v[138:141], v[146:149], v[56:59]
	v_mfma_f32_16x16x32_bf16 v[52:55], v[130:133], v[154:157], v[52:55]
	v_mfma_f32_16x16x32_bf16 v[48:51], v[138:141], v[154:157], v[48:51]
	v_mfma_f32_16x16x32_bf16 v[44:47], v[130:133], v[162:165], v[44:47]
	v_mfma_f32_16x16x32_bf16 v[40:43], v[138:141], v[162:165], v[40:43]
	v_mfma_f32_16x16x32_bf16 v[36:39], v[130:133], v[170:173], v[36:39]
	v_mfma_f32_16x16x32_bf16 v[32:35], v[138:141], v[170:173], v[32:35]
	v_mfma_f32_16x16x32_bf16 v[60:63], v[134:137], v[150:153], v[60:63]
	v_mfma_f32_16x16x32_bf16 v[56:59], v[142:145], v[150:153], v[56:59]
	v_mfma_f32_16x16x32_bf16 v[52:55], v[134:137], v[158:161], v[52:55]
	v_mfma_f32_16x16x32_bf16 v[48:51], v[142:145], v[158:161], v[48:51]
	v_mfma_f32_16x16x32_bf16 v[44:47], v[134:137], v[166:169], v[44:47]
	v_mfma_f32_16x16x32_bf16 v[40:43], v[142:145], v[166:169], v[40:43]
	v_mfma_f32_16x16x32_bf16 v[36:39], v[134:137], v[174:177], v[36:39]
	v_mfma_f32_16x16x32_bf16 v[32:35], v[142:145], v[174:177], v[32:35]
	s_barrier
	s_mov_b64 s[58:59], 0xe440180
	s_mov_b32 m0, s67
	v_lshl_add_u64 v[130:131], v[196:197], 0, s[58:59]
	s_mov_b64 s[58:59], 0xe460180
	global_load_lds_dwordx4 v[130:131], off
	v_lshl_add_u64 v[130:131], v[196:197], 0, s[58:59]
	s_mov_b32 m0, s68
	s_nop 0
	global_load_lds_dwordx4 v[130:131], off
	s_waitcnt vmcnt(6)
	s_barrier
	v_mfma_f32_16x16x32_bf16 v[28:31], v[178:181], v[146:149], v[28:31]
	v_mfma_f32_16x16x32_bf16 v[24:27], v[186:189], v[146:149], v[24:27]
	v_mfma_f32_16x16x32_bf16 v[20:23], v[178:181], v[154:157], v[20:23]
	v_mfma_f32_16x16x32_bf16 v[16:19], v[186:189], v[154:157], v[16:19]
	v_mfma_f32_16x16x32_bf16 v[12:15], v[178:181], v[162:165], v[12:15]
	v_mfma_f32_16x16x32_bf16 v[8:11], v[186:189], v[162:165], v[8:11]
	v_mfma_f32_16x16x32_bf16 v[4:7], v[178:181], v[170:173], v[4:7]
	v_mfma_f32_16x16x32_bf16 v[0:3], v[186:189], v[170:173], v[0:3]
	v_mfma_f32_16x16x32_bf16 v[28:31], v[182:185], v[150:153], v[28:31]
	v_mfma_f32_16x16x32_bf16 v[24:27], v[190:193], v[150:153], v[24:27]
	v_mfma_f32_16x16x32_bf16 v[20:23], v[182:185], v[158:161], v[20:23]
	v_mfma_f32_16x16x32_bf16 v[16:19], v[190:193], v[158:161], v[16:19]
	v_mfma_f32_16x16x32_bf16 v[12:15], v[182:185], v[166:169], v[12:15]
	v_mfma_f32_16x16x32_bf16 v[8:11], v[190:193], v[166:169], v[8:11]
	v_mfma_f32_16x16x32_bf16 v[4:7], v[182:185], v[174:177], v[4:7]
	v_mfma_f32_16x16x32_bf16 v[0:3], v[190:193], v[174:177], v[0:3]
	s_barrier
	s_add_i32 s35, s35, 2
	s_add_u32 s48, s48, 0x100
	s_addc_u32 s49, s49, 0
	s_add_u32 s50, s50, 0x100
	s_addc_u32 s51, s51, 0
	s_cmp_gt_u32 s35, 11
	s_cbranch_scc0 .LBB0_385
	ds_read_b128 v[140:143], v224 offset:0
	ds_read_b128 v[144:147], v224 offset:0x400
	ds_read_b128 v[148:151], v224 offset:0x800
	ds_read_b128 v[152:155], v224 offset:0xc00
	ds_read_b128 v[130:133], v225 offset:0
	ds_read_b128 v[134:137], v225 offset:0x400
	ds_read_b128 v[156:159], v225 offset:0x800
	ds_read_b128 v[160:163], v225 offset:0xc00
	ds_read_b128 v[164:167], v225 offset:0x1000
	ds_read_b128 v[168:171], v225 offset:0x1400
	ds_read_b128 v[172:175], v225 offset:0x1800
	s_mov_b32 m0, s69
	ds_read_b128 v[176:179], v225 offset:0x1c00
	v_lshl_add_u64 v[138:139], v[128:129], 0, s[24:25]
	global_load_lds_dwordx4 v[138:139], off
	v_lshl_add_u64 v[128:129], v[128:129], 0, s[26:27]
	s_mov_b32 m0, s70
	s_ashr_i32 s39, s38, 31
	global_load_lds_dwordx4 v[128:129], off
	s_lshl_b64 s[48:49], s[38:39], 19
	s_add_u32 s48, s46, s48
	s_addc_u32 s49, s47, s49
	s_ashr_i32 s35, s34, 31
	s_barrier
	s_waitcnt lgkmcnt(0)
	s_lshl_b64 s[50:51], s[34:35], 19
	v_readlane_b32 s58, v254, 32
	v_readlane_b32 s59, v254, 33
	s_add_u32 s50, s58, s50
	s_addc_u32 s51, s59, s51
	v_mfma_f32_16x16x32_bf16 v[124:127], v[140:143], v[130:133], v[124:127]
	v_mfma_f32_16x16x32_bf16 v[120:123], v[148:151], v[130:133], v[120:123]
	v_mfma_f32_16x16x32_bf16 v[116:119], v[140:143], v[156:159], v[116:119]
	v_mfma_f32_16x16x32_bf16 v[112:115], v[148:151], v[156:159], v[112:115]
	v_mfma_f32_16x16x32_bf16 v[108:111], v[140:143], v[164:167], v[108:111]
	v_mfma_f32_16x16x32_bf16 v[104:107], v[148:151], v[164:167], v[104:107]
	v_mfma_f32_16x16x32_bf16 v[100:103], v[140:143], v[172:175], v[100:103]
	v_mfma_f32_16x16x32_bf16 v[96:99], v[148:151], v[172:175], v[96:99]
	v_mfma_f32_16x16x32_bf16 v[124:127], v[144:147], v[134:137], v[124:127]
	v_mfma_f32_16x16x32_bf16 v[180:183], v[152:155], v[134:137], v[120:123]
	v_mfma_f32_16x16x32_bf16 v[116:119], v[144:147], v[160:163], v[116:119]
	v_mfma_f32_16x16x32_bf16 v[184:187], v[152:155], v[160:163], v[112:115]
	v_mfma_f32_16x16x32_bf16 v[108:111], v[144:147], v[168:171], v[108:111]
	v_mfma_f32_16x16x32_bf16 v[188:191], v[152:155], v[168:171], v[104:107]
	v_mfma_f32_16x16x32_bf16 v[100:103], v[144:147], v[176:179], v[100:103]
	v_mfma_f32_16x16x32_bf16 v[192:195], v[152:155], v[176:179], v[96:99]
	s_barrier
	ds_read_b128 v[96:99], v226 offset:0
	ds_read_b128 v[104:107], v226 offset:0x400
	ds_read_b128 v[112:115], v226 offset:0x800
	ds_read_b128 v[120:123], v226 offset:0xc00
	s_barrier
; #define WAIT_V(n) asm volatile("s_waitcnt vmcnt(%0)" ::"n"(n) : "memory")
; #define SCHED() __builtin_amdgcn_sched_barrier(0)
; #define LGKM(n) asm volatile("s_waitcnt lgkmcnt(%0)" ::"n"(n) : "memory")
; #define LDA(b, h) do { const unsigned pa_ = lds0 + SLOTA(b, h) + wr * 8192 + laneoff; _Pragma("unroll") for (int m = 0; m < 4; ++m)   \
;       _Pragma("unroll") for (int k = 0; k < 2; ++k) DSR(At[m][k], pa_, m * 2048 + k * 1024); } while (0)
; #define LDB(dst, b, h) do { const unsigned pb_ = lds0 + SLOTB(b, h) + wc * 4096 + laneoff; _Pragma("unroll") for (int n = 0; n < 2; ++n) \
;       _Pragma("unroll") for (int k = 0; k < 2; ++k) DSR(dst[n][k], pb_, n * 2048 + k * 1024); } while (0)
; #define BAR __builtin_amdgcn_s_barrier()
; #define LGKM(n) asm volatile("s_waitcnt lgkmcnt(%0)" ::"n"(n) : "memory")
; template <int EPI, bool SWP> ...
;     ...
;     BAR; LGKM(0); SCHED(); MMA(0, 0, B0); BAR; SCHED();
;     LDB(B1, 0, 1); BAR; LGKM(0); SCHED(); MMA(0, 1, B1); BAR; SCHED();
;     LDA(0, 1); WAIT_V(4); BAR; LGKM(0); SCHED(); MMA(1, 0, B0); MMA(1, 1, B1); BAR; SCHED(); }
;   { LDB(B0, 1, 0); LDA(1, 0); WAIT_V(2); BAR; LGKM(0); SCHED(); MMA(0, 0, B0); BAR; SCHED();
	s_waitcnt lgkmcnt(0)
	v_mfma_f32_16x16x32_bf16 v[92:95], v[96:99], v[130:133], v[92:95]
	v_mfma_f32_16x16x32_bf16 v[88:91], v[112:115], v[130:133], v[88:91]
	v_mfma_f32_16x16x32_bf16 v[84:87], v[96:99], v[156:159], v[84:87]
	v_mfma_f32_16x16x32_bf16 v[80:83], v[112:115], v[156:159], v[80:83]
	v_mfma_f32_16x16x32_bf16 v[76:79], v[96:99], v[164:167], v[76:79]
	v_mfma_f32_16x16x32_bf16 v[72:75], v[112:115], v[164:167], v[72:75]
	v_mfma_f32_16x16x32_bf16 v[68:71], v[96:99], v[172:175], v[68:71]
	v_mfma_f32_16x16x32_bf16 v[64:67], v[112:115], v[172:175], v[64:67]
	v_mfma_f32_16x16x32_bf16 v[92:95], v[104:107], v[134:137], v[92:95]
	v_mfma_f32_16x16x32_bf16 v[196:199], v[120:123], v[134:137], v[88:91]
	v_mfma_f32_16x16x32_bf16 v[84:87], v[104:107], v[160:163], v[84:87]
	v_mfma_f32_16x16x32_bf16 v[200:203], v[120:123], v[160:163], v[80:83]
	v_mfma_f32_16x16x32_bf16 v[76:79], v[104:107], v[168:171], v[76:79]
	v_mfma_f32_16x16x32_bf16 v[204:207], v[120:123], v[168:171], v[72:75]
	v_mfma_f32_16x16x32_bf16 v[68:71], v[104:107], v[176:179], v[68:71]
	v_mfma_f32_16x16x32_bf16 v[176:179], v[120:123], v[176:179], v[64:67]
	s_barrier
	ds_read_b128 v[64:67], v227 offset:0
	ds_read_b128 v[72:75], v227 offset:0x400
	ds_read_b128 v[80:83], v227 offset:0x800
	ds_read_b128 v[88:91], v227 offset:0xc00
	ds_read_b128 v[156:159], v227 offset:0x1000
	ds_read_b128 v[160:163], v227 offset:0x1400
	ds_read_b128 v[164:167], v227 offset:0x1800
	ds_read_b128 v[168:171], v227 offset:0x1c00
	s_waitcnt vmcnt(4)
	s_barrier
	s_waitcnt lgkmcnt(0)
	v_mfma_f32_16x16x32_bf16 v[60:63], v[140:143], v[64:67], v[60:63]
	v_mfma_f32_16x16x32_bf16 v[56:59], v[148:151], v[64:67], v[56:59]
	v_mfma_f32_16x16x32_bf16 v[52:55], v[140:143], v[80:83], v[52:55]
	v_mfma_f32_16x16x32_bf16 v[48:51], v[148:151], v[80:83], v[48:51]
	v_mfma_f32_16x16x32_bf16 v[44:47], v[140:143], v[156:159], v[44:47]
	v_mfma_f32_16x16x32_bf16 v[40:43], v[148:151], v[156:159], v[40:43]
	v_mfma_f32_16x16x32_bf16 v[36:39], v[140:143], v[164:167], v[36:39]
	v_mfma_f32_16x16x32_bf16 v[32:35], v[148:151], v[164:167], v[32:35]
	v_mfma_f32_16x16x32_bf16 v[60:63], v[144:147], v[72:75], v[60:63]
	v_mfma_f32_16x16x32_bf16 v[128:131], v[152:155], v[72:75], v[56:59]
	v_mfma_f32_16x16x32_bf16 v[52:55], v[144:147], v[88:91], v[52:55]
	v_mfma_f32_16x16x32_bf16 v[132:135], v[152:155], v[88:91], v[48:51]
	v_mfma_f32_16x16x32_bf16 v[44:47], v[144:147], v[160:163], v[44:47]
	v_mfma_f32_16x16x32_bf16 v[136:139], v[152:155], v[160:163], v[40:43]
	v_mfma_f32_16x16x32_bf16 v[36:39], v[144:147], v[168:171], v[36:39]
	v_mfma_f32_16x16x32_bf16 v[140:143], v[152:155], v[168:171], v[32:35]
	v_mfma_f32_16x16x32_bf16 v[28:31], v[96:99], v[64:67], v[28:31]
	v_mfma_f32_16x16x32_bf16 v[24:27], v[112:115], v[64:67], v[24:27]
	v_mfma_f32_16x16x32_bf16 v[20:23], v[96:99], v[80:83], v[20:23]
	v_mfma_f32_16x16x32_bf16 v[16:19], v[112:115], v[80:83], v[16:19]
	v_mfma_f32_16x16x32_bf16 v[12:15], v[96:99], v[156:159], v[12:15]
	v_mfma_f32_16x16x32_bf16 v[8:11], v[112:115], v[156:159], v[8:11]
	v_mfma_f32_16x16x32_bf16 v[4:7], v[96:99], v[164:167], v[4:7]
	v_mfma_f32_16x16x32_bf16 v[0:3], v[112:115], v[164:167], v[0:3]
	v_mfma_f32_16x16x32_bf16 v[28:31], v[104:107], v[72:75], v[28:31]
	v_mfma_f32_16x16x32_bf16 v[144:147], v[120:123], v[72:75], v[24:27]
	v_mfma_f32_16x16x32_bf16 v[20:23], v[104:107], v[88:91], v[20:23]
	v_mfma_f32_16x16x32_bf16 v[148:151], v[120:123], v[88:91], v[16:19]
	v_mfma_f32_16x16x32_bf16 v[12:15], v[104:107], v[160:163], v[12:15]
	v_mfma_f32_16x16x32_bf16 v[152:155], v[120:123], v[160:163], v[8:11]
	v_mfma_f32_16x16x32_bf16 v[4:7], v[104:107], v[168:171], v[4:7]
	v_mfma_f32_16x16x32_bf16 v[156:159], v[120:123], v[168:171], v[0:3]
	s_barrier
	ds_read_b128 v[0:3], v229 offset:0
	ds_read_b128 v[8:11], v229 offset:0x400
	ds_read_b128 v[16:19], v229 offset:0x800
	ds_read_b128 v[24:27], v229 offset:0xc00
	ds_read_b128 v[32:35], v230 offset:0
	ds_read_b128 v[40:43], v230 offset:0x400
	ds_read_b128 v[48:51], v230 offset:0x800
	ds_read_b128 v[56:59], v230 offset:0xc00
	ds_read_b128 v[64:67], v230 offset:0x1000
	ds_read_b128 v[220:223], v230 offset:0x1400
	ds_read_b128 v[238:241], v230 offset:0x1800
	ds_read_b128 v[242:245], v230 offset:0x1c00
	s_waitcnt vmcnt(2)
	s_barrier
; #define WAIT_V(n) asm volatile("s_waitcnt vmcnt(%0)" ::"n"(n) : "memory")
; #define SCHED() __builtin_amdgcn_sched_barrier(0)
; #define LGKM(n) asm volatile("s_waitcnt lgkmcnt(%0)" ::"n"(n) : "memory")
; #define STAGE_AX(AG, b, h, kt) do { _Pragma("unroll") for (int i = 0; i < 2; ++i)                                    \
;       __builtin_amdgcn_global_load_lds((const unsigned*)(((AG) + ((size_t)(kt) * (BK * 2) + (size_t)((h) * 2 + i) * 128 * lda)) + aoff), \
;                                        (unsigned*)(shm + SLOTA(b, h) + wid * 1024 + i * 8192), 16, 0, 0); } while (0)
; #define STAGE_BX(BG, b, h, kt) do { _Pragma("unroll") for (int i = 0; i < 2; ++i)                                    \
;       __builtin_amdgcn_global_load_lds((const unsigned*)(((BG) + ((size_t)(kt) * (BK * 2) + (size_t)((h) * 2 + i) * 128 * K)) + boff),   \
;                                        (unsigned*)(shm + SLOTB(b, h) + wid * 1024 + i * 8192), 16, 0, 0); } while (0)
; #define LDA(b, h) do { const unsigned pa_ = lds0 + SLOTA(b, h) + wr * 8192 + laneoff; _Pragma("unroll") for (int m = 0; m < 4; ++m)   \
;       _Pragma("unroll") for (int k = 0; k < 2; ++k) DSR(At[m][k], pa_, m * 2048 + k * 1024); } while (0)
; #define LDB(dst, b, h) do { const unsigned pb_ = lds0 + SLOTB(b, h) + wc * 4096 + laneoff; _Pragma("unroll") for (int n = 0; n < 2; ++n) \
;       _Pragma("unroll") for (int k = 0; k < 2; ++k) DSR(dst[n][k], pb_, n * 2048 + k * 1024); } while (0)
; #define BAR __builtin_amdgcn_s_barrier()
; #define LGKM(n) asm volatile("s_waitcnt lgkmcnt(%0)" ::"n"(n) : "memory")
; template <int EPI, bool SWP> ...
;     ...
;   { LDB(B0, 1, 0); LDA(1, 0); WAIT_V(2); BAR; LGKM(0); SCHED(); MMA(0, 0, B0); BAR; SCHED();
;     LDB(B1, 1, 1); WAIT_V(0); BAR; LGKM(0); SCHED(); MMA(0, 1, B1); BAR; SCHED();
;     LDA(1, 1);
;     if (has_next) { STAGE_BX(Bg_n, 0, 0, 0); STAGE_AX(Ag_n, 0, 0, 0); STAGE_BX(Bg_n, 0, 1, 0); STAGE_AX(Ag_n, 0, 1, 0); }
	s_waitcnt lgkmcnt(0)
	v_mfma_f32_16x16x32_bf16 v[72:75], v[0:3], v[32:35], v[124:127]
	v_mfma_f32_16x16x32_bf16 v[120:123], v[8:11], v[40:43], v[72:75]
	v_mfma_f32_16x16x32_bf16 v[72:75], v[16:19], v[32:35], v[180:183]
	v_mfma_f32_16x16x32_bf16 v[124:127], v[24:27], v[40:43], v[72:75]
	v_mfma_f32_16x16x32_bf16 v[72:75], v[0:3], v[48:51], v[116:119]
	v_mfma_f32_16x16x32_bf16 v[112:115], v[8:11], v[56:59], v[72:75]
	v_mfma_f32_16x16x32_bf16 v[72:75], v[16:19], v[48:51], v[184:187]
	v_mfma_f32_16x16x32_bf16 v[116:119], v[24:27], v[56:59], v[72:75]
	v_mfma_f32_16x16x32_bf16 v[72:75], v[0:3], v[64:67], v[108:111]
	v_mfma_f32_16x16x32_bf16 v[104:107], v[8:11], v[220:223], v[72:75]
	v_mfma_f32_16x16x32_bf16 v[72:75], v[16:19], v[64:67], v[188:191]
	v_mfma_f32_16x16x32_bf16 v[108:111], v[24:27], v[220:223], v[72:75]
	v_mfma_f32_16x16x32_bf16 v[72:75], v[0:3], v[238:241], v[100:103]
	v_mfma_f32_16x16x32_bf16 v[96:99], v[8:11], v[242:245], v[72:75]
	v_mfma_f32_16x16x32_bf16 v[72:75], v[16:19], v[238:241], v[192:195]
	v_mfma_f32_16x16x32_bf16 v[100:103], v[24:27], v[242:245], v[72:75]
	s_barrier
	ds_read_b128 v[160:163], v231 offset:0
	ds_read_b128 v[164:167], v231 offset:0x400
	ds_read_b128 v[168:171], v231 offset:0x800
	ds_read_b128 v[172:175], v231 offset:0xc00
	s_waitcnt vmcnt(0)
	s_barrier
	s_waitcnt lgkmcnt(0)
	v_mfma_f32_16x16x32_bf16 v[72:75], v[160:163], v[32:35], v[92:95]
	v_mfma_f32_16x16x32_bf16 v[32:35], v[168:171], v[32:35], v[196:199]
	v_mfma_f32_16x16x32_bf16 v[92:95], v[172:175], v[40:43], v[32:35]
	v_mfma_f32_16x16x32_bf16 v[32:35], v[160:163], v[48:51], v[84:87]
	v_mfma_f32_16x16x32_bf16 v[80:83], v[164:167], v[56:59], v[32:35]
	v_mfma_f32_16x16x32_bf16 v[32:35], v[168:171], v[48:51], v[200:203]
	v_mfma_f32_16x16x32_bf16 v[84:87], v[172:175], v[56:59], v[32:35]
	v_mfma_f32_16x16x32_bf16 v[32:35], v[160:163], v[64:67], v[76:79]
	v_mfma_f32_16x16x32_bf16 v[88:91], v[164:167], v[40:43], v[72:75]
	v_mfma_f32_16x16x32_bf16 v[72:75], v[164:167], v[220:223], v[32:35]
	v_mfma_f32_16x16x32_bf16 v[32:35], v[168:171], v[64:67], v[204:207]
	v_mfma_f32_16x16x32_bf16 v[76:79], v[172:175], v[220:223], v[32:35]
	v_mfma_f32_16x16x32_bf16 v[32:35], v[160:163], v[238:241], v[68:71]
	v_mfma_f32_16x16x32_bf16 v[64:67], v[164:167], v[242:245], v[32:35]
	v_mfma_f32_16x16x32_bf16 v[32:35], v[168:171], v[238:241], v[176:179]
	v_mfma_f32_16x16x32_bf16 v[68:71], v[172:175], v[242:245], v[32:35]
	s_barrier
	ds_read_b128 v[200:203], v232 offset:0
	ds_read_b128 v[204:207], v232 offset:0x400
	ds_read_b128 v[192:195], v232 offset:0x800
	ds_read_b128 v[196:199], v232 offset:0xc00
	ds_read_b128 v[184:187], v232 offset:0x1000
	ds_read_b128 v[188:191], v232 offset:0x1400
	ds_read_b128 v[176:179], v232 offset:0x1800
	ds_read_b128 v[180:183], v232 offset:0x1c00
	s_and_b64 vcc, exec, s[44:45]
	v_lshl_add_u64 v[220:221], s[50:51], 0, v[208:209]
	v_lshl_add_u64 v[222:223], s[48:49], 0, v[208:209]
	s_cbranch_vccz .LBB0_388
	s_mov_b32 m0, s16
	v_lshl_add_u64 v[32:33], v[220:221], 0, s[4:5]
	global_load_lds_dwordx4 v[220:221], off
	s_mov_b32 m0, s17
	s_nop 0
	global_load_lds_dwordx4 v[32:33], off
	s_mov_b32 m0, s3
	v_lshl_add_u64 v[32:33], v[222:223], 0, s[4:5]
	global_load_lds_dwordx4 v[222:223], off
	s_mov_b32 m0, s18
	s_nop 0
	global_load_lds_dwordx4 v[32:33], off
	v_lshl_add_u64 v[32:33], v[220:221], 0, s[8:9]
	s_mov_b32 m0, s19
	s_nop 0
	global_load_lds_dwordx4 v[32:33], off
	v_lshl_add_u64 v[32:33], v[220:221], 0, s[10:11]
	s_mov_b32 m0, s60
	s_nop 0
	global_load_lds_dwordx4 v[32:33], off
	v_lshl_add_u64 v[32:33], v[222:223], 0, s[8:9]
	s_mov_b32 m0, s61
	s_nop 0
	global_load_lds_dwordx4 v[32:33], off
	v_lshl_add_u64 v[32:33], v[222:223], 0, s[10:11]
	s_mov_b32 m0, s62
	s_nop 0
	global_load_lds_dwordx4 v[32:33], off

; #define SCHED() __builtin_amdgcn_sched_barrier(0)
; #define LGKM(n) asm volatile("s_waitcnt lgkmcnt(%0)" ::"n"(n) : "memory")
; #define STAGE_A(b, h, kt) STAGE_AX(Ag, b, h, kt)
; #define STAGE_B(b, h, kt) STAGE_BX(Bg, b, h, kt)
; #define LDA(b, h) do { const unsigned pa_ = lds0 + SLOTA(b, h) + wr * 8192 + laneoff; _Pragma("unroll") for (int m = 0; m < 4; ++m)   \
;       _Pragma("unroll") for (int k = 0; k < 2; ++k) DSR(At[m][k], pa_, m * 2048 + k * 1024); } while (0)
; #define LDB(dst, b, h) do { const unsigned pb_ = lds0 + SLOTB(b, h) + wc * 4096 + laneoff; _Pragma("unroll") for (int n = 0; n < 2; ++n) \
;       _Pragma("unroll") for (int k = 0; k < 2; ++k) DSR(dst[n][k], pb_, n * 2048 + k * 1024); } while (0)
; #define BAR __builtin_amdgcn_s_barrier()
; #define LGKM(n) asm volatile("s_waitcnt lgkmcnt(%0)" ::"n"(n) : "memory")
; template <int EPI, bool SWP> ...
;     ...
;   for (int t = 0; t < nt - 2; t += 2) {
;     LDB(B0, 0, 0); LDA(0, 0); STAGE_A(1, 1, t + 1);
;     LGKM(8); BAR; LGKM(0); SCHED(); MMA(0, 0, B0); BAR; SCHED();
;     LDB(B1, 0, 1); STAGE_B(0, 0, t + 2);
;     BAR; LGKM(0); SCHED(); MMA(0, 1, B1); BAR; SCHED();
;     LDA(0, 1); STAGE_A(0, 0, t + 2);
;     BAR; LGKM(0); SCHED(); MMA(1, 0, B0); BAR; SCHED();
.LBB0_428:
	ds_read_b128 v[130:133], v201 offset:0
	ds_read_b128 v[134:137], v201 offset:0x400
	ds_read_b128 v[138:141], v201 offset:0x800
	ds_read_b128 v[142:145], v201 offset:0xc00
	ds_read_b128 v[146:149], v202 offset:0
	ds_read_b128 v[150:153], v202 offset:0x400
	ds_read_b128 v[154:157], v202 offset:0x800
	ds_read_b128 v[158:161], v202 offset:0xc00
	ds_read_b128 v[162:165], v202 offset:0x1000
	ds_read_b128 v[166:169], v202 offset:0x1400
	ds_read_b128 v[170:173], v202 offset:0x1800
	v_lshl_add_u64 v[198:199], s[68:69], 0, v[196:197]
	s_add_i32 s63, s3, 0xc000
	ds_read_b128 v[174:177], v202 offset:0x1c00
	v_lshl_add_u64 v[178:179], v[198:199], 0, s[40:41]
	s_mov_b32 m0, s63
	s_nop 0
	global_load_lds_dwordx4 v[178:179], off
	v_lshl_add_u64 v[178:179], v[198:199], 0, s[42:43]
	s_mov_b32 m0, s81
	s_nop 0
	global_load_lds_dwordx4 v[178:179], off
	s_waitcnt lgkmcnt(8)
	s_barrier
	s_waitcnt lgkmcnt(0)
	v_mfma_f32_16x16x32_bf16 v[124:127], v[130:133], v[146:149], v[124:127]
	v_mfma_f32_16x16x32_bf16 v[120:123], v[138:141], v[146:149], v[120:123]
	v_mfma_f32_16x16x32_bf16 v[116:119], v[130:133], v[154:157], v[116:119]
	v_mfma_f32_16x16x32_bf16 v[112:115], v[138:141], v[154:157], v[112:115]
	v_mfma_f32_16x16x32_bf16 v[108:111], v[130:133], v[162:165], v[108:111]
	v_mfma_f32_16x16x32_bf16 v[104:107], v[138:141], v[162:165], v[104:107]
	v_mfma_f32_16x16x32_bf16 v[100:103], v[130:133], v[170:173], v[100:103]
	v_mfma_f32_16x16x32_bf16 v[96:99], v[138:141], v[170:173], v[96:99]
	v_mfma_f32_16x16x32_bf16 v[124:127], v[134:137], v[150:153], v[124:127]
	v_mfma_f32_16x16x32_bf16 v[120:123], v[142:145], v[150:153], v[120:123]
	v_mfma_f32_16x16x32_bf16 v[116:119], v[134:137], v[158:161], v[116:119]
	v_mfma_f32_16x16x32_bf16 v[112:115], v[142:145], v[158:161], v[112:115]
	v_mfma_f32_16x16x32_bf16 v[108:111], v[134:137], v[166:169], v[108:111]
	v_mfma_f32_16x16x32_bf16 v[104:107], v[142:145], v[166:169], v[104:107]
	v_mfma_f32_16x16x32_bf16 v[100:103], v[134:137], v[174:177], v[100:103]
	v_mfma_f32_16x16x32_bf16 v[96:99], v[142:145], v[174:177], v[96:99]
	s_barrier
	ds_read_b128 v[178:181], v203 offset:0
	ds_read_b128 v[182:185], v203 offset:0x400
	ds_read_b128 v[186:189], v203 offset:0x800
	v_lshl_add_u64 v[218:219], s[70:71], 0, v[196:197]
	s_mov_b64 s[72:73], 0xe800100
	s_mov_b32 m0, s17
	ds_read_b128 v[190:193], v203 offset:0xc00
	v_lshl_add_u64 v[220:221], v[218:219], 0, s[72:73]
	s_mov_b64 s[72:73], 0xe840100
	global_load_lds_dwordx4 v[220:221], off
	v_lshl_add_u64 v[220:221], v[218:219], 0, s[72:73]
	s_mov_b32 m0, s18
	s_nop 0
	global_load_lds_dwordx4 v[220:221], off
	s_barrier
	s_waitcnt lgkmcnt(0)
	v_mfma_f32_16x16x32_bf16 v[92:95], v[178:181], v[146:149], v[92:95]
	v_mfma_f32_16x16x32_bf16 v[88:91], v[186:189], v[146:149], v[88:91]
	v_mfma_f32_16x16x32_bf16 v[84:87], v[178:181], v[154:157], v[84:87]
	v_mfma_f32_16x16x32_bf16 v[80:83], v[186:189], v[154:157], v[80:83]
	v_mfma_f32_16x16x32_bf16 v[76:79], v[178:181], v[162:165], v[76:79]
	v_mfma_f32_16x16x32_bf16 v[72:75], v[186:189], v[162:165], v[72:75]
	v_mfma_f32_16x16x32_bf16 v[68:71], v[178:181], v[170:173], v[68:71]
	v_mfma_f32_16x16x32_bf16 v[64:67], v[186:189], v[170:173], v[64:67]
	v_mfma_f32_16x16x32_bf16 v[92:95], v[182:185], v[150:153], v[92:95]
	v_mfma_f32_16x16x32_bf16 v[88:91], v[190:193], v[150:153], v[88:91]
	v_mfma_f32_16x16x32_bf16 v[84:87], v[182:185], v[158:161], v[84:87]
	v_mfma_f32_16x16x32_bf16 v[80:83], v[190:193], v[158:161], v[80:83]
	v_mfma_f32_16x16x32_bf16 v[76:79], v[182:185], v[166:169], v[76:79]
	v_mfma_f32_16x16x32_bf16 v[72:75], v[190:193], v[166:169], v[72:75]
	v_mfma_f32_16x16x32_bf16 v[68:71], v[182:185], v[174:177], v[68:71]
	v_mfma_f32_16x16x32_bf16 v[64:67], v[190:193], v[174:177], v[64:67]
	s_barrier
	ds_read_b128 v[146:149], v204 offset:0
	ds_read_b128 v[150:153], v204 offset:0x400
	ds_read_b128 v[154:157], v204 offset:0x800
	ds_read_b128 v[158:161], v204 offset:0xc00
	ds_read_b128 v[162:165], v204 offset:0x1000
	ds_read_b128 v[166:169], v204 offset:0x1400
	ds_read_b128 v[170:173], v204 offset:0x1800
	s_mov_b64 s[72:73], 0x100
	s_mov_b32 m0, s3
	ds_read_b128 v[174:177], v204 offset:0x1c00
	v_lshl_add_u64 v[220:221], v[198:199], 0, s[72:73]
	s_mov_b64 s[72:73], 0x40100
	global_load_lds_dwordx4 v[220:221], off
	v_lshl_add_u64 v[220:221], v[198:199], 0, s[72:73]
	s_mov_b32 m0, s19
	s_nop 0
	global_load_lds_dwordx4 v[220:221], off
	s_barrier
	s_waitcnt lgkmcnt(0)
	v_mfma_f32_16x16x32_bf16 v[60:63], v[130:133], v[146:149], v[60:63]
	v_mfma_f32_16x16x32_bf16 v[56:59], v[138:141], v[146:149], v[56:59]
	v_mfma_f32_16x16x32_bf16 v[52:55], v[130:133], v[154:157], v[52:55]
	v_mfma_f32_16x16x32_bf16 v[48:51], v[138:141], v[154:157], v[48:51]
	v_mfma_f32_16x16x32_bf16 v[44:47], v[130:133], v[162:165], v[44:47]
	v_mfma_f32_16x16x32_bf16 v[40:43], v[138:141], v[162:165], v[40:43]
	v_mfma_f32_16x16x32_bf16 v[36:39], v[130:133], v[170:173], v[36:39]
	v_mfma_f32_16x16x32_bf16 v[32:35], v[138:141], v[170:173], v[32:35]
	v_mfma_f32_16x16x32_bf16 v[60:63], v[134:137], v[150:153], v[60:63]
	v_mfma_f32_16x16x32_bf16 v[56:59], v[142:145], v[150:153], v[56:59]
	v_mfma_f32_16x16x32_bf16 v[52:55], v[134:137], v[158:161], v[52:55]
	v_mfma_f32_16x16x32_bf16 v[48:51], v[142:145], v[158:161], v[48:51]
	v_mfma_f32_16x16x32_bf16 v[44:47], v[134:137], v[166:169], v[44:47]
	v_mfma_f32_16x16x32_bf16 v[40:43], v[142:145], v[166:169], v[40:43]
	v_mfma_f32_16x16x32_bf16 v[36:39], v[134:137], v[174:177], v[36:39]
	v_mfma_f32_16x16x32_bf16 v[32:35], v[142:145], v[174:177], v[32:35]
	s_barrier
; #define WAIT_V(n) asm volatile("s_waitcnt vmcnt(%0)" ::"n"(n) : "memory")
; #define SCHED() __builtin_amdgcn_sched_barrier(0)
; #define LGKM(n) asm volatile("s_waitcnt lgkmcnt(%0)" ::"n"(n) : "memory")
; #define STAGE_A(b, h, kt) STAGE_AX(Ag, b, h, kt)
; #define STAGE_B(b, h, kt) STAGE_BX(Bg, b, h, kt)
; #define LDA(b, h) do { const unsigned pa_ = lds0 + SLOTA(b, h) + wr * 8192 + laneoff; _Pragma("unroll") for (int m = 0; m < 4; ++m)   \
;       _Pragma("unroll") for (int k = 0; k < 2; ++k) DSR(At[m][k], pa_, m * 2048 + k * 1024); } while (0)
; #define LDB(dst, b, h) do { const unsigned pb_ = lds0 + SLOTB(b, h) + wc * 4096 + laneoff; _Pragma("unroll") for (int n = 0; n < 2; ++n) \
;       _Pragma("unroll") for (int k = 0; k < 2; ++k) DSR(dst[n][k], pb_, n * 2048 + k * 1024); } while (0)
; #define BAR __builtin_amdgcn_s_barrier()
; #define LGKM(n) asm volatile("s_waitcnt lgkmcnt(%0)" ::"n"(n) : "memory")
; template <int EPI, bool SWP> ...
;     ...
;     BAR; LGKM(0); SCHED(); MMA(1, 0, B0); BAR; SCHED();
;     STAGE_B(0, 1, t + 2);
;     WAIT_V(6); BAR; SCHED(); MMA(1, 1, B1); BAR; SCHED();
;     LDB(B0, 1, 0); LDA(1, 0); STAGE_A(0, 1, t + 2);
;     LGKM(8); BAR; LGKM(0); SCHED(); MMA(0, 0, B0); BAR; SCHED();
;     LDB(B1, 1, 1); STAGE_B(1, 0, t + 3);
;     BAR; LGKM(0); SCHED(); MMA(0, 1, B1); BAR; SCHED();
;     LDA(1, 1); STAGE_A(1, 0, t + 3);
;     BAR; LGKM(0); SCHED(); MMA(1, 0, B0); BAR; SCHED();
	s_mov_b64 s[72:73], 0xe880100
	s_mov_b32 m0, s74
	v_lshl_add_u64 v[130:131], v[218:219], 0, s[72:73]
	s_mov_b64 s[72:73], 0xe8c0100
	global_load_lds_dwordx4 v[130:131], off
	v_lshl_add_u64 v[130:131], v[218:219], 0, s[72:73]
	s_mov_b32 m0, s75
	s_nop 0
	global_load_lds_dwordx4 v[130:131], off
	s_waitcnt vmcnt(6)
	s_barrier
	v_mfma_f32_16x16x32_bf16 v[28:31], v[178:181], v[146:149], v[28:31]
	v_mfma_f32_16x16x32_bf16 v[24:27], v[186:189], v[146:149], v[24:27]
	v_mfma_f32_16x16x32_bf16 v[20:23], v[178:181], v[154:157], v[20:23]
	v_mfma_f32_16x16x32_bf16 v[16:19], v[186:189], v[154:157], v[16:19]
	v_mfma_f32_16x16x32_bf16 v[12:15], v[178:181], v[162:165], v[12:15]
	v_mfma_f32_16x16x32_bf16 v[8:11], v[186:189], v[162:165], v[8:11]
	v_mfma_f32_16x16x32_bf16 v[4:7], v[178:181], v[170:173], v[4:7]
	v_mfma_f32_16x16x32_bf16 v[0:3], v[186:189], v[170:173], v[0:3]
	v_mfma_f32_16x16x32_bf16 v[28:31], v[182:185], v[150:153], v[28:31]
	v_mfma_f32_16x16x32_bf16 v[24:27], v[190:193], v[150:153], v[24:27]
	v_mfma_f32_16x16x32_bf16 v[20:23], v[182:185], v[158:161], v[20:23]
	v_mfma_f32_16x16x32_bf16 v[16:19], v[190:193], v[158:161], v[16:19]
	v_mfma_f32_16x16x32_bf16 v[12:15], v[182:185], v[166:169], v[12:15]
	v_mfma_f32_16x16x32_bf16 v[8:11], v[190:193], v[166:169], v[8:11]
	v_mfma_f32_16x16x32_bf16 v[4:7], v[182:185], v[174:177], v[4:7]
	v_mfma_f32_16x16x32_bf16 v[0:3], v[190:193], v[174:177], v[0:3]
	s_barrier
	ds_read_b128 v[130:133], v205 offset:0
	ds_read_b128 v[134:137], v205 offset:0x400
	ds_read_b128 v[138:141], v205 offset:0x800
	ds_read_b128 v[142:145], v205 offset:0xc00
	ds_read_b128 v[146:149], v206 offset:0
	ds_read_b128 v[150:153], v206 offset:0x400
	ds_read_b128 v[154:157], v206 offset:0x800
	ds_read_b128 v[158:161], v206 offset:0xc00
	ds_read_b128 v[162:165], v206 offset:0x1000
	ds_read_b128 v[166:169], v206 offset:0x1400
	ds_read_b128 v[170:173], v206 offset:0x1800
	s_mov_b64 s[72:73], 0x80100
	s_mov_b32 m0, s76
	ds_read_b128 v[174:177], v206 offset:0x1c00
	v_lshl_add_u64 v[178:179], v[198:199], 0, s[72:73]
	s_mov_b64 s[72:73], 0xc0100
	global_load_lds_dwordx4 v[178:179], off
	v_lshl_add_u64 v[178:179], v[198:199], 0, s[72:73]
	s_mov_b32 m0, s77
	s_nop 0
	global_load_lds_dwordx4 v[178:179], off
	s_waitcnt lgkmcnt(8)
	s_barrier
	s_waitcnt lgkmcnt(0)
	v_mfma_f32_16x16x32_bf16 v[124:127], v[130:133], v[146:149], v[124:127]
	v_mfma_f32_16x16x32_bf16 v[120:123], v[138:141], v[146:149], v[120:123]
	v_mfma_f32_16x16x32_bf16 v[116:119], v[130:133], v[154:157], v[116:119]
	v_mfma_f32_16x16x32_bf16 v[112:115], v[138:141], v[154:157], v[112:115]
	v_mfma_f32_16x16x32_bf16 v[108:111], v[130:133], v[162:165], v[108:111]
	v_mfma_f32_16x16x32_bf16 v[104:107], v[138:141], v[162:165], v[104:107]
	v_mfma_f32_16x16x32_bf16 v[100:103], v[130:133], v[170:173], v[100:103]
	v_mfma_f32_16x16x32_bf16 v[96:99], v[138:141], v[170:173], v[96:99]
	v_mfma_f32_16x16x32_bf16 v[124:127], v[134:137], v[150:153], v[124:127]
	v_mfma_f32_16x16x32_bf16 v[120:123], v[142:145], v[150:153], v[120:123]
	v_mfma_f32_16x16x32_bf16 v[116:119], v[134:137], v[158:161], v[116:119]
	v_mfma_f32_16x16x32_bf16 v[112:115], v[142:145], v[158:161], v[112:115]
	v_mfma_f32_16x16x32_bf16 v[108:111], v[134:137], v[166:169], v[108:111]
	v_mfma_f32_16x16x32_bf16 v[104:107], v[142:145], v[166:169], v[104:107]
	v_mfma_f32_16x16x32_bf16 v[100:103], v[134:137], v[174:177], v[100:103]
	v_mfma_f32_16x16x32_bf16 v[96:99], v[142:145], v[174:177], v[96:99]
	s_barrier
	ds_read_b128 v[178:181], v207 offset:0
	ds_read_b128 v[182:185], v207 offset:0x400
	ds_read_b128 v[186:189], v207 offset:0x800
	s_mov_b64 s[72:73], 0xe800180
	s_add_i32 s67, s3, 0x18000
	ds_read_b128 v[190:193], v207 offset:0xc00
	v_lshl_add_u64 v[220:221], v[218:219], 0, s[72:73]
	s_mov_b32 m0, s67
	s_mov_b64 s[72:73], 0xe840180
	global_load_lds_dwordx4 v[220:221], off
	v_lshl_add_u64 v[220:221], v[218:219], 0, s[72:73]
	s_mov_b32 m0, s78
	s_nop 0
	global_load_lds_dwordx4 v[220:221], off
	s_barrier
	s_waitcnt lgkmcnt(0)
	v_mfma_f32_16x16x32_bf16 v[92:95], v[178:181], v[146:149], v[92:95]
	v_mfma_f32_16x16x32_bf16 v[88:91], v[186:189], v[146:149], v[88:91]
	v_mfma_f32_16x16x32_bf16 v[84:87], v[178:181], v[154:157], v[84:87]
	v_mfma_f32_16x16x32_bf16 v[80:83], v[186:189], v[154:157], v[80:83]
	v_mfma_f32_16x16x32_bf16 v[76:79], v[178:181], v[162:165], v[76:79]
	v_mfma_f32_16x16x32_bf16 v[72:75], v[186:189], v[162:165], v[72:75]
	v_mfma_f32_16x16x32_bf16 v[68:71], v[178:181], v[170:173], v[68:71]
	v_mfma_f32_16x16x32_bf16 v[64:67], v[186:189], v[170:173], v[64:67]
	v_mfma_f32_16x16x32_bf16 v[92:95], v[182:185], v[150:153], v[92:95]
	v_mfma_f32_16x16x32_bf16 v[88:91], v[190:193], v[150:153], v[88:91]
	v_mfma_f32_16x16x32_bf16 v[84:87], v[182:185], v[158:161], v[84:87]
	v_mfma_f32_16x16x32_bf16 v[80:83], v[190:193], v[158:161], v[80:83]
	v_mfma_f32_16x16x32_bf16 v[76:79], v[182:185], v[166:169], v[76:79]
	v_mfma_f32_16x16x32_bf16 v[72:75], v[190:193], v[166:169], v[72:75]
	v_mfma_f32_16x16x32_bf16 v[68:71], v[182:185], v[174:177], v[68:71]
	v_mfma_f32_16x16x32_bf16 v[64:67], v[190:193], v[174:177], v[64:67]
	s_barrier
	ds_read_b128 v[146:149], v208 offset:0
	ds_read_b128 v[150:153], v208 offset:0x400
	ds_read_b128 v[154:157], v208 offset:0x800
	ds_read_b128 v[158:161], v208 offset:0xc00
	ds_read_b128 v[162:165], v208 offset:0x1000
	ds_read_b128 v[166:169], v208 offset:0x1400
	s_mov_b64 s[72:73], 0x180
	ds_read_b128 v[170:173], v208 offset:0x1800
	v_lshl_add_u64 v[220:221], v[198:199], 0, s[72:73]
	s_add_i32 s72, s3, 0x8000
	ds_read_b128 v[174:177], v208 offset:0x1c00
	s_mov_b32 m0, s72
	s_mov_b64 s[84:85], 0x40180
	global_load_lds_dwordx4 v[220:221], off
	v_lshl_add_u64 v[198:199], v[198:199], 0, s[84:85]
	s_mov_b32 m0, s79
	s_nop 0
	global_load_lds_dwordx4 v[198:199], off
	s_barrier
; #define WAIT_V(n) asm volatile("s_waitcnt vmcnt(%0)" ::"n"(n) : "memory")
; #define SCHED() __builtin_amdgcn_sched_barrier(0)
; #define LGKM(n) asm volatile("s_waitcnt lgkmcnt(%0)" ::"n"(n) : "memory")
; #define STAGE_A(b, h, kt) STAGE_AX(Ag, b, h, kt)
; #define STAGE_B(b, h, kt) STAGE_BX(Bg, b, h, kt)
; #define LDA(b, h) do { const unsigned pa_ = lds0 + SLOTA(b, h) + wr * 8192 + laneoff; _Pragma("unroll") for (int m = 0; m < 4; ++m)   \
;       _Pragma("unroll") for (int k = 0; k < 2; ++k) DSR(At[m][k], pa_, m * 2048 + k * 1024); } while (0)
; #define LDB(dst, b, h) do { const unsigned pb_ = lds0 + SLOTB(b, h) + wc * 4096 + laneoff; _Pragma("unroll") for (int n = 0; n < 2; ++n) \
;       _Pragma("unroll") for (int k = 0; k < 2; ++k) DSR(dst[n][k], pb_, n * 2048 + k * 1024); } while (0)
; #define BAR __builtin_amdgcn_s_barrier()
; #define LGKM(n) asm volatile("s_waitcnt lgkmcnt(%0)" ::"n"(n) : "memory")
; template <int EPI, bool SWP> ...
;     ...
;     BAR; LGKM(0); SCHED(); MMA(1, 0, B0); BAR; SCHED();
;     STAGE_B(1, 1, t + 3);
;     WAIT_V(6); BAR; SCHED(); MMA(1, 1, B1); BAR; SCHED();
;   }
;   { LDB(B0, 0, 0); LDA(0, 0); STAGE_A(1, 1, nt - 1);
;     BAR; LGKM(0); SCHED(); MMA(0, 0, B0); BAR; SCHED();
	s_waitcnt lgkmcnt(0)
	v_mfma_f32_16x16x32_bf16 v[60:63], v[130:133], v[146:149], v[60:63]
	v_mfma_f32_16x16x32_bf16 v[56:59], v[138:141], v[146:149], v[56:59]
	v_mfma_f32_16x16x32_bf16 v[52:55], v[130:133], v[154:157], v[52:55]
	v_mfma_f32_16x16x32_bf16 v[48:51], v[138:141], v[154:157], v[48:51]
	v_mfma_f32_16x16x32_bf16 v[44:47], v[130:133], v[162:165], v[44:47]
	v_mfma_f32_16x16x32_bf16 v[40:43], v[138:141], v[162:165], v[40:43]
	v_mfma_f32_16x16x32_bf16 v[36:39], v[130:133], v[170:173], v[36:39]
	v_mfma_f32_16x16x32_bf16 v[32:35], v[138:141], v[170:173], v[32:35]
	v_mfma_f32_16x16x32_bf16 v[60:63], v[134:137], v[150:153], v[60:63]
	v_mfma_f32_16x16x32_bf16 v[56:59], v[142:145], v[150:153], v[56:59]
	v_mfma_f32_16x16x32_bf16 v[52:55], v[134:137], v[158:161], v[52:55]
	v_mfma_f32_16x16x32_bf16 v[48:51], v[142:145], v[158:161], v[48:51]
	v_mfma_f32_16x16x32_bf16 v[44:47], v[134:137], v[166:169], v[44:47]
	v_mfma_f32_16x16x32_bf16 v[40:43], v[142:145], v[166:169], v[40:43]
	v_mfma_f32_16x16x32_bf16 v[36:39], v[134:137], v[174:177], v[36:39]
	v_mfma_f32_16x16x32_bf16 v[32:35], v[142:145], v[174:177], v[32:35]
	s_barrier
	s_add_i32 s73, s3, 0x1c000
	v_lshl_add_u64 v[130:131], v[218:219], 0, s[44:45]
	s_mov_b32 m0, s73
	s_nop 0
	global_load_lds_dwordx4 v[130:131], off
	v_lshl_add_u64 v[130:131], v[218:219], 0, s[46:47]
	s_mov_b32 m0, s80
	s_nop 0
	global_load_lds_dwordx4 v[130:131], off
	s_waitcnt vmcnt(6)
	s_barrier
	v_mfma_f32_16x16x32_bf16 v[28:31], v[178:181], v[146:149], v[28:31]
	v_mfma_f32_16x16x32_bf16 v[24:27], v[186:189], v[146:149], v[24:27]
	v_mfma_f32_16x16x32_bf16 v[20:23], v[178:181], v[154:157], v[20:23]
	v_mfma_f32_16x16x32_bf16 v[16:19], v[186:189], v[154:157], v[16:19]
	v_mfma_f32_16x16x32_bf16 v[12:15], v[178:181], v[162:165], v[12:15]
	v_mfma_f32_16x16x32_bf16 v[8:11], v[186:189], v[162:165], v[8:11]
	v_mfma_f32_16x16x32_bf16 v[4:7], v[178:181], v[170:173], v[4:7]
	v_mfma_f32_16x16x32_bf16 v[0:3], v[186:189], v[170:173], v[0:3]
	v_mfma_f32_16x16x32_bf16 v[28:31], v[182:185], v[150:153], v[28:31]
	v_mfma_f32_16x16x32_bf16 v[24:27], v[190:193], v[150:153], v[24:27]
	v_mfma_f32_16x16x32_bf16 v[20:23], v[182:185], v[158:161], v[20:23]
	v_mfma_f32_16x16x32_bf16 v[16:19], v[190:193], v[158:161], v[16:19]
	v_mfma_f32_16x16x32_bf16 v[12:15], v[182:185], v[166:169], v[12:15]
	v_mfma_f32_16x16x32_bf16 v[8:11], v[190:193], v[166:169], v[8:11]
	v_mfma_f32_16x16x32_bf16 v[4:7], v[182:185], v[174:177], v[4:7]
	v_mfma_f32_16x16x32_bf16 v[0:3], v[190:193], v[174:177], v[0:3]
	s_barrier
	s_add_i32 s61, s61, 2
	s_add_u32 s70, s70, 0x100
	s_addc_u32 s71, s71, 0
	s_add_u32 s68, s68, 0x100
	s_addc_u32 s69, s69, 0
	s_cmp_gt_u32 s61, 27
	s_cbranch_scc0 .LBB0_428
	ds_read_b128 v[130:133], v201 offset:0
	ds_read_b128 v[134:137], v201 offset:0x400
	ds_read_b128 v[138:141], v201 offset:0x800
	ds_read_b128 v[142:145], v201 offset:0xc00
	ds_read_b128 v[146:149], v202 offset:0
	ds_read_b128 v[150:153], v202 offset:0x400
	ds_read_b128 v[154:157], v202 offset:0x800
	ds_read_b128 v[158:161], v202 offset:0xc00
	ds_read_b128 v[162:165], v202 offset:0x1000
	ds_read_b128 v[166:169], v202 offset:0x1400
	ds_read_b128 v[170:173], v202 offset:0x1800
	s_mov_b32 m0, s63
	ds_read_b128 v[174:177], v202 offset:0x1c00
	v_lshl_add_u64 v[178:179], v[128:129], 0, s[88:89]
	global_load_lds_dwordx4 v[178:179], off
	v_lshl_add_u64 v[128:129], v[128:129], 0, s[90:91]
	s_mov_b32 m0, s81
	s_ashr_i32 s95, s94, 31
	global_load_lds_dwordx4 v[128:129], off
	s_lshl_b64 s[68:69], s[94:95], 20
	s_add_u32 s68, s56, s68
	s_addc_u32 s69, s57, s69
	s_ashr_i32 s87, s86, 31
	s_barrier
	s_waitcnt lgkmcnt(0)
	s_lshl_b64 s[70:71], s[86:87], 20
	v_readlane_b32 s48, v254, 34
	v_readlane_b32 s49, v254, 35
	s_add_u32 s70, s48, s70
	s_addc_u32 s71, s49, s71
	v_mfma_f32_16x16x32_bf16 v[124:127], v[130:133], v[146:149], v[124:127]
	v_mfma_f32_16x16x32_bf16 v[120:123], v[138:141], v[146:149], v[120:123]
	v_mfma_f32_16x16x32_bf16 v[116:119], v[130:133], v[154:157], v[116:119]
	v_mfma_f32_16x16x32_bf16 v[112:115], v[138:141], v[154:157], v[112:115]
	v_mfma_f32_16x16x32_bf16 v[108:111], v[130:133], v[162:165], v[108:111]
	v_mfma_f32_16x16x32_bf16 v[104:107], v[138:141], v[162:165], v[104:107]
	v_mfma_f32_16x16x32_bf16 v[100:103], v[130:133], v[170:173], v[100:103]
	v_mfma_f32_16x16x32_bf16 v[96:99], v[138:141], v[170:173], v[96:99]
	v_mfma_f32_16x16x32_bf16 v[124:127], v[134:137], v[150:153], v[124:127]
	v_mfma_f32_16x16x32_bf16 v[120:123], v[142:145], v[150:153], v[120:123]
	v_mfma_f32_16x16x32_bf16 v[116:119], v[134:137], v[158:161], v[116:119]
	v_mfma_f32_16x16x32_bf16 v[178:181], v[142:145], v[158:161], v[112:115]
	v_mfma_f32_16x16x32_bf16 v[108:111], v[134:137], v[166:169], v[108:111]
	v_mfma_f32_16x16x32_bf16 v[104:107], v[142:145], v[166:169], v[104:107]
	v_mfma_f32_16x16x32_bf16 v[100:103], v[134:137], v[174:177], v[100:103]
	v_mfma_f32_16x16x32_bf16 v[96:99], v[142:145], v[174:177], v[96:99]
	s_barrier
	ds_read_b128 v[112:115], v203 offset:0
	ds_read_b128 v[182:185], v203 offset:0x400
	ds_read_b128 v[186:189], v203 offset:0x800
	ds_read_b128 v[190:193], v203 offset:0xc00
	s_barrier
; #define WAIT_V(n) asm volatile("s_waitcnt vmcnt(%0)" ::"n"(n) : "memory")
; #define SCHED() __builtin_amdgcn_sched_barrier(0)
; #define LGKM(n) asm volatile("s_waitcnt lgkmcnt(%0)" ::"n"(n) : "memory")
; #define LDA(b, h) do { const unsigned pa_ = lds0 + SLOTA(b, h) + wr * 8192 + laneoff; _Pragma("unroll") for (int m = 0; m < 4; ++m)   \
;       _Pragma("unroll") for (int k = 0; k < 2; ++k) DSR(At[m][k], pa_, m * 2048 + k * 1024); } while (0)
; #define LDB(dst, b, h) do { const unsigned pb_ = lds0 + SLOTB(b, h) + wc * 4096 + laneoff; _Pragma("unroll") for (int n = 0; n < 2; ++n) \
;       _Pragma("unroll") for (int k = 0; k < 2; ++k) DSR(dst[n][k], pb_, n * 2048 + k * 1024); } while (0)
; #define BAR __builtin_amdgcn_s_barrier()
; #define LGKM(n) asm volatile("s_waitcnt lgkmcnt(%0)" ::"n"(n) : "memory")
; template <int EPI, bool SWP> ...
;     ...
;     BAR; LGKM(0); SCHED(); MMA(0, 0, B0); BAR; SCHED();
;     LDB(B1, 0, 1); BAR; LGKM(0); SCHED(); MMA(0, 1, B1); BAR; SCHED();
;     LDA(0, 1); WAIT_V(4); BAR; LGKM(0); SCHED(); MMA(1, 0, B0); MMA(1, 1, B1); BAR; SCHED(); }
;   { LDB(B0, 1, 0); LDA(1, 0); WAIT_V(2); BAR; LGKM(0); SCHED(); MMA(0, 0, B0); BAR; SCHED();
	s_waitcnt lgkmcnt(0)
	v_mfma_f32_16x16x32_bf16 v[92:95], v[112:115], v[146:149], v[92:95]
	v_mfma_f32_16x16x32_bf16 v[88:91], v[186:189], v[146:149], v[88:91]
	v_mfma_f32_16x16x32_bf16 v[84:87], v[112:115], v[154:157], v[84:87]
	v_mfma_f32_16x16x32_bf16 v[80:83], v[186:189], v[154:157], v[80:83]
	v_mfma_f32_16x16x32_bf16 v[76:79], v[112:115], v[162:165], v[76:79]
	v_mfma_f32_16x16x32_bf16 v[72:75], v[186:189], v[162:165], v[72:75]
	v_mfma_f32_16x16x32_bf16 v[68:71], v[112:115], v[170:173], v[68:71]
	v_mfma_f32_16x16x32_bf16 v[64:67], v[186:189], v[170:173], v[64:67]
	v_mfma_f32_16x16x32_bf16 v[92:95], v[182:185], v[150:153], v[92:95]
	v_mfma_f32_16x16x32_bf16 v[88:91], v[190:193], v[150:153], v[88:91]
	v_mfma_f32_16x16x32_bf16 v[84:87], v[182:185], v[158:161], v[84:87]
	v_mfma_f32_16x16x32_bf16 v[80:83], v[190:193], v[158:161], v[80:83]
	v_mfma_f32_16x16x32_bf16 v[76:79], v[182:185], v[166:169], v[76:79]
	v_mfma_f32_16x16x32_bf16 v[72:75], v[190:193], v[166:169], v[72:75]
	v_mfma_f32_16x16x32_bf16 v[68:71], v[182:185], v[174:177], v[68:71]
	v_mfma_f32_16x16x32_bf16 v[64:67], v[190:193], v[174:177], v[64:67]
	s_barrier
	ds_read_b128 v[146:149], v204 offset:0
	ds_read_b128 v[150:153], v204 offset:0x400
	ds_read_b128 v[154:157], v204 offset:0x800
	ds_read_b128 v[158:161], v204 offset:0xc00
	ds_read_b128 v[162:165], v204 offset:0x1000
	ds_read_b128 v[166:169], v204 offset:0x1400
	ds_read_b128 v[170:173], v204 offset:0x1800
	ds_read_b128 v[174:177], v204 offset:0x1c00
	s_waitcnt vmcnt(4)
	s_barrier
	s_waitcnt lgkmcnt(0)
	v_mfma_f32_16x16x32_bf16 v[60:63], v[130:133], v[146:149], v[60:63]
	v_mfma_f32_16x16x32_bf16 v[56:59], v[138:141], v[146:149], v[56:59]
	v_mfma_f32_16x16x32_bf16 v[52:55], v[130:133], v[154:157], v[52:55]
	v_mfma_f32_16x16x32_bf16 v[48:51], v[138:141], v[154:157], v[48:51]
	v_mfma_f32_16x16x32_bf16 v[44:47], v[130:133], v[162:165], v[44:47]
	v_mfma_f32_16x16x32_bf16 v[40:43], v[138:141], v[162:165], v[40:43]
	v_mfma_f32_16x16x32_bf16 v[36:39], v[130:133], v[170:173], v[36:39]
	v_mfma_f32_16x16x32_bf16 v[32:35], v[138:141], v[170:173], v[32:35]
	v_mfma_f32_16x16x32_bf16 v[60:63], v[134:137], v[150:153], v[60:63]
	v_mfma_f32_16x16x32_bf16 v[56:59], v[142:145], v[150:153], v[56:59]
	v_mfma_f32_16x16x32_bf16 v[52:55], v[134:137], v[158:161], v[52:55]
	v_mfma_f32_16x16x32_bf16 v[48:51], v[142:145], v[158:161], v[48:51]
	v_mfma_f32_16x16x32_bf16 v[44:47], v[134:137], v[166:169], v[44:47]
	v_mfma_f32_16x16x32_bf16 v[40:43], v[142:145], v[166:169], v[40:43]
	v_mfma_f32_16x16x32_bf16 v[36:39], v[134:137], v[174:177], v[36:39]
	v_mfma_f32_16x16x32_bf16 v[32:35], v[142:145], v[174:177], v[32:35]
	v_mfma_f32_16x16x32_bf16 v[28:31], v[112:115], v[146:149], v[28:31]
	v_mfma_f32_16x16x32_bf16 v[24:27], v[186:189], v[146:149], v[24:27]
	v_mfma_f32_16x16x32_bf16 v[20:23], v[112:115], v[154:157], v[20:23]
	v_mfma_f32_16x16x32_bf16 v[16:19], v[186:189], v[154:157], v[16:19]
	v_mfma_f32_16x16x32_bf16 v[12:15], v[112:115], v[162:165], v[12:15]
	v_mfma_f32_16x16x32_bf16 v[8:11], v[186:189], v[162:165], v[8:11]
	v_mfma_f32_16x16x32_bf16 v[4:7], v[112:115], v[170:173], v[4:7]
	v_mfma_f32_16x16x32_bf16 v[0:3], v[186:189], v[170:173], v[0:3]
	v_mfma_f32_16x16x32_bf16 v[28:31], v[182:185], v[150:153], v[28:31]
	v_mfma_f32_16x16x32_bf16 v[24:27], v[190:193], v[150:153], v[24:27]
	v_mfma_f32_16x16x32_bf16 v[20:23], v[182:185], v[158:161], v[20:23]
	v_mfma_f32_16x16x32_bf16 v[16:19], v[190:193], v[158:161], v[16:19]
	v_mfma_f32_16x16x32_bf16 v[12:15], v[182:185], v[166:169], v[12:15]
	v_mfma_f32_16x16x32_bf16 v[8:11], v[190:193], v[166:169], v[8:11]
	v_mfma_f32_16x16x32_bf16 v[4:7], v[182:185], v[174:177], v[4:7]
	v_mfma_f32_16x16x32_bf16 v[0:3], v[190:193], v[174:177], v[0:3]
	s_barrier
	ds_read_b128 v[112:115], v205 offset:0
	ds_read_b128 v[134:137], v205 offset:0x400
	ds_read_b128 v[138:141], v205 offset:0x800
	ds_read_b128 v[142:145], v205 offset:0xc00
	ds_read_b128 v[162:165], v206 offset:0
	ds_read_b128 v[166:169], v206 offset:0x400
	ds_read_b128 v[170:173], v206 offset:0x800
	ds_read_b128 v[174:177], v206 offset:0xc00
	ds_read_b128 v[182:185], v206 offset:0x1000
	ds_read_b128 v[186:189], v206 offset:0x1400
	ds_read_b128 v[190:193], v206 offset:0x1800
	ds_read_b128 v[218:221], v206 offset:0x1c00
	s_waitcnt vmcnt(2)
	s_barrier
	s_waitcnt lgkmcnt(0)
	v_mfma_f32_16x16x32_bf16 v[124:127], v[112:115], v[162:165], v[124:127]
	v_mfma_f32_16x16x32_bf16 v[120:123], v[138:141], v[162:165], v[120:123]
	v_mfma_f32_16x16x32_bf16 v[116:119], v[112:115], v[170:173], v[116:119]
	v_mfma_f32_16x16x32_bf16 v[130:133], v[134:137], v[166:169], v[124:127]
	v_mfma_f32_16x16x32_bf16 v[126:129], v[142:145], v[166:169], v[120:123]
	v_mfma_f32_16x16x32_bf16 v[122:125], v[134:137], v[174:177], v[116:119]
	v_mfma_f32_16x16x32_bf16 v[116:119], v[138:141], v[170:173], v[178:181]
	v_mfma_f32_16x16x32_bf16 v[108:111], v[112:115], v[182:185], v[108:111]
	v_mfma_f32_16x16x32_bf16 v[104:107], v[138:141], v[182:185], v[104:107]
	v_mfma_f32_16x16x32_bf16 v[100:103], v[112:115], v[190:193], v[100:103]
	v_mfma_f32_16x16x32_bf16 v[96:99], v[138:141], v[190:193], v[96:99]
	v_mfma_f32_16x16x32_bf16 v[118:121], v[142:145], v[174:177], v[116:119]
	v_mfma_f32_16x16x32_bf16 v[108:111], v[134:137], v[186:189], v[108:111]
	v_mfma_f32_16x16x32_bf16 v[104:107], v[142:145], v[186:189], v[104:107]
	v_mfma_f32_16x16x32_bf16 v[100:103], v[134:137], v[218:221], v[100:103]
	v_mfma_f32_16x16x32_bf16 v[96:99], v[142:145], v[218:221], v[96:99]
	s_barrier
; #define WAIT_V(n) asm volatile("s_waitcnt vmcnt(%0)" ::"n"(n) : "memory")
; #define SCHED() __builtin_amdgcn_sched_barrier(0)
; #define LGKM(n) asm volatile("s_waitcnt lgkmcnt(%0)" ::"n"(n) : "memory")
; #define STAGE_AX(AG, b, h, kt) do { _Pragma("unroll") for (int i = 0; i < 2; ++i)                                    \
;       __builtin_amdgcn_global_load_lds((const unsigned*)(((AG) + ((size_t)(kt) * (BK * 2) + (size_t)((h) * 2 + i) * 128 * lda)) + aoff), \
;                                        (unsigned*)(shm + SLOTA(b, h) + wid * 1024 + i * 8192), 16, 0, 0); } while (0)
; #define STAGE_BX(BG, b, h, kt) do { _Pragma("unroll") for (int i = 0; i < 2; ++i)                                    \
;       __builtin_amdgcn_global_load_lds((const unsigned*)(((BG) + ((size_t)(kt) * (BK * 2) + (size_t)((h) * 2 + i) * 128 * K)) + boff),   \
;                                        (unsigned*)(shm + SLOTB(b, h) + wid * 1024 + i * 8192), 16, 0, 0); } while (0)
; #define LDA(b, h) do { const unsigned pa_ = lds0 + SLOTA(b, h) + wr * 8192 + laneoff; _Pragma("unroll") for (int m = 0; m < 4; ++m)   \
;       _Pragma("unroll") for (int k = 0; k < 2; ++k) DSR(At[m][k], pa_, m * 2048 + k * 1024); } while (0)
; #define LDB(dst, b, h) do { const unsigned pb_ = lds0 + SLOTB(b, h) + wc * 4096 + laneoff; _Pragma("unroll") for (int n = 0; n < 2; ++n) \
;       _Pragma("unroll") for (int k = 0; k < 2; ++k) DSR(dst[n][k], pb_, n * 2048 + k * 1024); } while (0)
; #define BAR __builtin_amdgcn_s_barrier()
; #define LGKM(n) asm volatile("s_waitcnt lgkmcnt(%0)" ::"n"(n) : "memory")
; template <int EPI, bool SWP> ...
;     ...
;   { LDB(B0, 1, 0); LDA(1, 0); WAIT_V(2); BAR; LGKM(0); SCHED(); MMA(0, 0, B0); BAR; SCHED();
;     LDB(B1, 1, 1); WAIT_V(0); BAR; LGKM(0); SCHED(); MMA(0, 1, B1); BAR; SCHED();
;     LDA(1, 1);
;     if (has_next) { STAGE_BX(Bg_n, 0, 0, 0); STAGE_AX(Ag_n, 0, 0, 0); STAGE_BX(Bg_n, 0, 1, 0); STAGE_AX(Ag_n, 0, 1, 0); }
;     BAR; LGKM(0); SCHED(); MMA(1, 0, B0); MMA(1, 1, B1); BAR; SCHED(); }
;   if (wr == 0) BAR;
	ds_read_b128 v[146:149], v207 offset:0
	ds_read_b128 v[150:153], v207 offset:0x400
	ds_read_b128 v[154:157], v207 offset:0x800
	ds_read_b128 v[158:161], v207 offset:0xc00
	s_waitcnt vmcnt(0)
	s_barrier
	s_waitcnt lgkmcnt(0)
	v_mfma_f32_16x16x32_bf16 v[92:95], v[146:149], v[162:165], v[92:95]
	v_mfma_f32_16x16x32_bf16 v[88:91], v[154:157], v[162:165], v[88:91]
	v_mfma_f32_16x16x32_bf16 v[84:87], v[146:149], v[170:173], v[84:87]
	v_mfma_f32_16x16x32_bf16 v[80:83], v[154:157], v[170:173], v[80:83]
	v_mfma_f32_16x16x32_bf16 v[76:79], v[146:149], v[182:185], v[76:79]
	v_mfma_f32_16x16x32_bf16 v[72:75], v[154:157], v[182:185], v[72:75]
	v_mfma_f32_16x16x32_bf16 v[68:71], v[146:149], v[190:193], v[68:71]
	v_mfma_f32_16x16x32_bf16 v[64:67], v[154:157], v[190:193], v[64:67]
	v_mfma_f32_16x16x32_bf16 v[92:95], v[150:153], v[166:169], v[92:95]
	v_mfma_f32_16x16x32_bf16 v[88:91], v[158:161], v[166:169], v[88:91]
	v_mfma_f32_16x16x32_bf16 v[84:87], v[150:153], v[174:177], v[84:87]
	v_mfma_f32_16x16x32_bf16 v[80:83], v[158:161], v[174:177], v[80:83]
	v_mfma_f32_16x16x32_bf16 v[76:79], v[150:153], v[186:189], v[76:79]
	v_mfma_f32_16x16x32_bf16 v[72:75], v[158:161], v[186:189], v[72:75]
	v_mfma_f32_16x16x32_bf16 v[68:71], v[150:153], v[218:221], v[68:71]
	v_mfma_f32_16x16x32_bf16 v[64:67], v[158:161], v[218:221], v[64:67]
	s_barrier
	ds_read_b128 v[186:189], v208 offset:0
	ds_read_b128 v[190:193], v208 offset:0x400
	ds_read_b128 v[178:181], v208 offset:0x800
	ds_read_b128 v[182:185], v208 offset:0xc00
	ds_read_b128 v[170:173], v208 offset:0x1000
	ds_read_b128 v[174:177], v208 offset:0x1400
	ds_read_b128 v[162:165], v208 offset:0x1800
	ds_read_b128 v[166:169], v208 offset:0x1c00
	s_and_b64 vcc, exec, s[12:13]
	v_lshl_add_u64 v[116:117], s[70:71], 0, v[194:195]
	v_lshl_add_u64 v[198:199], s[68:69], 0, v[194:195]
	s_cbranch_vccz .LBB0_431
	s_mov_b32 m0, s17
	v_lshl_add_u64 v[218:219], v[116:117], 0, s[20:21]
	global_load_lds_dwordx4 v[116:117], off
	s_mov_b32 m0, s18
	s_nop 0
	global_load_lds_dwordx4 v[218:219], off
	s_mov_b32 m0, s3
	v_lshl_add_u64 v[218:219], v[198:199], 0, s[20:21]
	global_load_lds_dwordx4 v[198:199], off
	s_mov_b32 m0, s19
	s_nop 0
	global_load_lds_dwordx4 v[218:219], off
	v_lshl_add_u64 v[218:219], v[116:117], 0, s[28:29]
	s_mov_b32 m0, s74
	s_nop 0
	global_load_lds_dwordx4 v[218:219], off
	v_lshl_add_u64 v[218:219], v[116:117], 0, s[34:35]
	s_mov_b32 m0, s75
	s_nop 0
	global_load_lds_dwordx4 v[218:219], off
	v_lshl_add_u64 v[218:219], v[198:199], 0, s[28:29]
	s_mov_b32 m0, s76
	s_nop 0
	global_load_lds_dwordx4 v[218:219], off
	v_lshl_add_u64 v[218:219], v[198:199], 0, s[34:35]
	s_mov_b32 m0, s77
	s_nop 0
	global_load_lds_dwordx4 v[218:219], off
.LBB0_431:
	s_barrier
	s_waitcnt lgkmcnt(0)
	v_mfma_f32_16x16x32_bf16 v[60:63], v[112:115], v[186:189], v[60:63]
	v_mfma_f32_16x16x32_bf16 v[56:59], v[138:141], v[186:189], v[56:59]
	v_mfma_f32_16x16x32_bf16 v[52:55], v[112:115], v[178:181], v[52:55]
	v_mfma_f32_16x16x32_bf16 v[48:51], v[138:141], v[178:181], v[48:51]
	v_mfma_f32_16x16x32_bf16 v[44:47], v[112:115], v[170:173], v[44:47]
	v_mfma_f32_16x16x32_bf16 v[40:43], v[138:141], v[170:173], v[40:43]
	v_mfma_f32_16x16x32_bf16 v[36:39], v[112:115], v[162:165], v[36:39]
	v_mfma_f32_16x16x32_bf16 v[32:35], v[138:141], v[162:165], v[32:35]
	v_mfma_f32_16x16x32_bf16 v[60:63], v[134:137], v[190:193], v[60:63]
	v_mfma_f32_16x16x32_bf16 v[56:59], v[142:145], v[190:193], v[56:59]
	v_mfma_f32_16x16x32_bf16 v[52:55], v[134:137], v[182:185], v[52:55]
	v_mfma_f32_16x16x32_bf16 v[48:51], v[142:145], v[182:185], v[48:51]
	v_mfma_f32_16x16x32_bf16 v[44:47], v[134:137], v[174:177], v[44:47]
	v_mfma_f32_16x16x32_bf16 v[40:43], v[142:145], v[174:177], v[40:43]
	v_mfma_f32_16x16x32_bf16 v[36:39], v[134:137], v[166:169], v[36:39]
	v_mfma_f32_16x16x32_bf16 v[32:35], v[142:145], v[166:169], v[32:35]
	v_mfma_f32_16x16x32_bf16 v[28:31], v[146:149], v[186:189], v[28:31]
	v_mfma_f32_16x16x32_bf16 v[24:27], v[154:157], v[186:189], v[24:27]
	v_mfma_f32_16x16x32_bf16 v[20:23], v[146:149], v[178:181], v[20:23]
	v_mfma_f32_16x16x32_bf16 v[16:19], v[154:157], v[178:181], v[16:19]
	v_mfma_f32_16x16x32_bf16 v[12:15], v[146:149], v[170:173], v[12:15]
	v_mfma_f32_16x16x32_bf16 v[8:11], v[154:157], v[170:173], v[8:11]
	v_mfma_f32_16x16x32_bf16 v[4:7], v[146:149], v[162:165], v[4:7]
	v_mfma_f32_16x16x32_bf16 v[0:3], v[154:157], v[162:165], v[0:3]
	v_mfma_f32_16x16x32_bf16 v[28:31], v[150:153], v[190:193], v[28:31]
	v_mfma_f32_16x16x32_bf16 v[24:27], v[158:161], v[190:193], v[24:27]
	v_mfma_f32_16x16x32_bf16 v[20:23], v[150:153], v[182:185], v[20:23]
	v_mfma_f32_16x16x32_bf16 v[16:19], v[158:161], v[182:185], v[16:19]
	v_mfma_f32_16x16x32_bf16 v[12:15], v[150:153], v[174:177], v[12:15]
	v_mfma_f32_16x16x32_bf16 v[8:11], v[158:161], v[174:177], v[8:11]
	v_mfma_f32_16x16x32_bf16 v[4:7], v[150:153], v[166:169], v[4:7]
	v_mfma_f32_16x16x32_bf16 v[0:3], v[158:161], v[166:169], v[0:3]
	s_barrier
	s_andn2_b64 vcc, exec, s[4:5]
	s_cbranch_vccnz .LBB0_433
	s_barrier

; #define SCHED() __builtin_amdgcn_sched_barrier(0)
; #define LGKM(n) asm volatile("s_waitcnt lgkmcnt(%0)" ::"n"(n) : "memory")
; #define STAGE_A(b, h, kt) STAGE_AX(Ag, b, h, kt)
; #define STAGE_B(b, h, kt) STAGE_BX(Bg, b, h, kt)
; #define LDA(b, h) do { const unsigned pa_ = lds0 + SLOTA(b, h) + wr * 8192 + laneoff; _Pragma("unroll") for (int m = 0; m < 4; ++m)   \
;       _Pragma("unroll") for (int k = 0; k < 2; ++k) DSR(At[m][k], pa_, m * 2048 + k * 1024); } while (0)
; #define LDB(dst, b, h) do { const unsigned pb_ = lds0 + SLOTB(b, h) + wc * 4096 + laneoff; _Pragma("unroll") for (int n = 0; n < 2; ++n) \
;       _Pragma("unroll") for (int k = 0; k < 2; ++k) DSR(dst[n][k], pb_, n * 2048 + k * 1024); } while (0)
; #define BAR __builtin_amdgcn_s_barrier()
; #define LGKM(n) asm volatile("s_waitcnt lgkmcnt(%0)" ::"n"(n) : "memory")
; template <int EPI, bool SWP> ...
;     ...
;   for (int t = 0; t < nt - 2; t += 2) {
;     LDB(B0, 0, 0); LDA(0, 0); STAGE_A(1, 1, t + 1);
;     LGKM(8); BAR; LGKM(0); SCHED(); MMA(0, 0, B0); BAR; SCHED();
;     LDB(B1, 0, 1); STAGE_B(0, 0, t + 2);
;     BAR; LGKM(0); SCHED(); MMA(0, 1, B1); BAR; SCHED();
;     LDA(0, 1); STAGE_A(0, 0, t + 2);
;     BAR; LGKM(0); SCHED(); MMA(1, 0, B0); BAR; SCHED();
.LBB0_667:
	ds_read_b128 v[128:131], v219 offset:0
	ds_read_b128 v[132:135], v219 offset:0x400
	ds_read_b128 v[136:139], v219 offset:0x800
	ds_read_b128 v[140:143], v219 offset:0xc00
	ds_read_b128 v[144:147], v220 offset:0
	ds_read_b128 v[148:151], v220 offset:0x400
	ds_read_b128 v[152:155], v220 offset:0x800
	ds_read_b128 v[156:159], v220 offset:0xc00
	ds_read_b128 v[160:163], v220 offset:0x1000
	ds_read_b128 v[164:167], v220 offset:0x1400
	ds_read_b128 v[168:171], v220 offset:0x1800
	v_lshl_add_u64 v[192:193], s[68:69], 0, v[210:211]
	s_mov_b64 s[70:71], 0xc080080
	s_mov_b32 m0, s87
	ds_read_b128 v[172:175], v220 offset:0x1c00
	v_lshl_add_u64 v[176:177], v[192:193], 0, s[70:71]
	s_mov_b64 s[70:71], 0xc0c0080
	global_load_lds_dwordx4 v[176:177], off
	v_lshl_add_u64 v[176:177], v[192:193], 0, s[70:71]
	s_mov_b32 m0, s88
	s_nop 0
	global_load_lds_dwordx4 v[176:177], off
	s_waitcnt lgkmcnt(8)
	s_barrier
	s_waitcnt lgkmcnt(0)
	v_mfma_f32_16x16x32_bf16 v[124:127], v[128:131], v[144:147], v[124:127]
	v_mfma_f32_16x16x32_bf16 v[120:123], v[136:139], v[144:147], v[120:123]
	v_mfma_f32_16x16x32_bf16 v[116:119], v[128:131], v[152:155], v[116:119]
	v_mfma_f32_16x16x32_bf16 v[112:115], v[136:139], v[152:155], v[112:115]
	v_mfma_f32_16x16x32_bf16 v[108:111], v[128:131], v[160:163], v[108:111]
	v_mfma_f32_16x16x32_bf16 v[104:107], v[136:139], v[160:163], v[104:107]
	v_mfma_f32_16x16x32_bf16 v[100:103], v[128:131], v[168:171], v[100:103]
	v_mfma_f32_16x16x32_bf16 v[96:99], v[136:139], v[168:171], v[96:99]
	v_mfma_f32_16x16x32_bf16 v[124:127], v[132:135], v[148:151], v[124:127]
	v_mfma_f32_16x16x32_bf16 v[120:123], v[140:143], v[148:151], v[120:123]
	v_mfma_f32_16x16x32_bf16 v[116:119], v[132:135], v[156:159], v[116:119]
	v_mfma_f32_16x16x32_bf16 v[112:115], v[140:143], v[156:159], v[112:115]
	v_mfma_f32_16x16x32_bf16 v[108:111], v[132:135], v[164:167], v[108:111]
	v_mfma_f32_16x16x32_bf16 v[104:107], v[140:143], v[164:167], v[104:107]
	v_mfma_f32_16x16x32_bf16 v[100:103], v[132:135], v[172:175], v[100:103]
	v_mfma_f32_16x16x32_bf16 v[96:99], v[140:143], v[172:175], v[96:99]
	s_barrier
	ds_read_b128 v[176:179], v221 offset:0
	ds_read_b128 v[180:183], v221 offset:0x400
	ds_read_b128 v[184:187], v221 offset:0x800
	v_lshl_add_u64 v[194:195], s[66:67], 0, v[210:211]
	s_mov_b64 s[70:71], 0x2d100100
	s_mov_b32 m0, s75
	ds_read_b128 v[188:191], v221 offset:0xc00
	v_lshl_add_u64 v[196:197], v[194:195], 0, s[70:71]
	s_mov_b64 s[70:71], 0x2d140100
	global_load_lds_dwordx4 v[196:197], off
	v_lshl_add_u64 v[196:197], v[194:195], 0, s[70:71]
	s_mov_b32 m0, s76
	s_nop 0
	global_load_lds_dwordx4 v[196:197], off
	s_barrier
	s_waitcnt lgkmcnt(0)
	v_mfma_f32_16x16x32_bf16 v[92:95], v[176:179], v[144:147], v[92:95]
	v_mfma_f32_16x16x32_bf16 v[88:91], v[184:187], v[144:147], v[88:91]
	v_mfma_f32_16x16x32_bf16 v[84:87], v[176:179], v[152:155], v[84:87]
	v_mfma_f32_16x16x32_bf16 v[80:83], v[184:187], v[152:155], v[80:83]
	v_mfma_f32_16x16x32_bf16 v[76:79], v[176:179], v[160:163], v[76:79]
	v_mfma_f32_16x16x32_bf16 v[72:75], v[184:187], v[160:163], v[72:75]
	v_mfma_f32_16x16x32_bf16 v[68:71], v[176:179], v[168:171], v[68:71]
	v_mfma_f32_16x16x32_bf16 v[64:67], v[184:187], v[168:171], v[64:67]
	v_mfma_f32_16x16x32_bf16 v[92:95], v[180:183], v[148:151], v[92:95]
	v_mfma_f32_16x16x32_bf16 v[88:91], v[188:191], v[148:151], v[88:91]
	v_mfma_f32_16x16x32_bf16 v[84:87], v[180:183], v[156:159], v[84:87]
	v_mfma_f32_16x16x32_bf16 v[80:83], v[188:191], v[156:159], v[80:83]
	v_mfma_f32_16x16x32_bf16 v[76:79], v[180:183], v[164:167], v[76:79]
	v_mfma_f32_16x16x32_bf16 v[72:75], v[188:191], v[164:167], v[72:75]
	v_mfma_f32_16x16x32_bf16 v[68:71], v[180:183], v[172:175], v[68:71]
	v_mfma_f32_16x16x32_bf16 v[64:67], v[188:191], v[172:175], v[64:67]
	s_barrier
	ds_read_b128 v[144:147], v222 offset:0
	ds_read_b128 v[148:151], v222 offset:0x400
	ds_read_b128 v[152:155], v222 offset:0x800
	ds_read_b128 v[156:159], v222 offset:0xc00
	ds_read_b128 v[160:163], v222 offset:0x1000
	ds_read_b128 v[164:167], v222 offset:0x1400
	ds_read_b128 v[168:171], v222 offset:0x1800
	s_mov_b64 s[70:71], 0xc000100
	s_mov_b32 m0, s3
	ds_read_b128 v[172:175], v222 offset:0x1c00
	v_lshl_add_u64 v[196:197], v[192:193], 0, s[70:71]
	s_mov_b64 s[70:71], 0xc040100
	global_load_lds_dwordx4 v[196:197], off
	v_lshl_add_u64 v[196:197], v[192:193], 0, s[70:71]
	s_mov_b32 m0, s77
	s_nop 0
	global_load_lds_dwordx4 v[196:197], off
	s_barrier
	s_waitcnt lgkmcnt(0)
	v_mfma_f32_16x16x32_bf16 v[60:63], v[128:131], v[144:147], v[60:63]
	v_mfma_f32_16x16x32_bf16 v[56:59], v[136:139], v[144:147], v[56:59]
	v_mfma_f32_16x16x32_bf16 v[52:55], v[128:131], v[152:155], v[52:55]
	v_mfma_f32_16x16x32_bf16 v[48:51], v[136:139], v[152:155], v[48:51]
	v_mfma_f32_16x16x32_bf16 v[44:47], v[128:131], v[160:163], v[44:47]
	v_mfma_f32_16x16x32_bf16 v[40:43], v[136:139], v[160:163], v[40:43]
	v_mfma_f32_16x16x32_bf16 v[36:39], v[128:131], v[168:171], v[36:39]
	v_mfma_f32_16x16x32_bf16 v[32:35], v[136:139], v[168:171], v[32:35]
	v_mfma_f32_16x16x32_bf16 v[60:63], v[132:135], v[148:151], v[60:63]
	v_mfma_f32_16x16x32_bf16 v[56:59], v[140:143], v[148:151], v[56:59]
	v_mfma_f32_16x16x32_bf16 v[52:55], v[132:135], v[156:159], v[52:55]
	v_mfma_f32_16x16x32_bf16 v[48:51], v[140:143], v[156:159], v[48:51]
	v_mfma_f32_16x16x32_bf16 v[44:47], v[132:135], v[164:167], v[44:47]
	v_mfma_f32_16x16x32_bf16 v[40:43], v[140:143], v[164:167], v[40:43]
	v_mfma_f32_16x16x32_bf16 v[36:39], v[132:135], v[172:175], v[36:39]
	v_mfma_f32_16x16x32_bf16 v[32:35], v[140:143], v[172:175], v[32:35]
	s_barrier
; #define WAIT_V(n) asm volatile("s_waitcnt vmcnt(%0)" ::"n"(n) : "memory")
; #define SCHED() __builtin_amdgcn_sched_barrier(0)
; #define LGKM(n) asm volatile("s_waitcnt lgkmcnt(%0)" ::"n"(n) : "memory")
; #define STAGE_A(b, h, kt) STAGE_AX(Ag, b, h, kt)
; #define STAGE_B(b, h, kt) STAGE_BX(Bg, b, h, kt)
; #define LDA(b, h) do { const unsigned pa_ = lds0 + SLOTA(b, h) + wr * 8192 + laneoff; _Pragma("unroll") for (int m = 0; m < 4; ++m)   \
;       _Pragma("unroll") for (int k = 0; k < 2; ++k) DSR(At[m][k], pa_, m * 2048 + k * 1024); } while (0)
; #define LDB(dst, b, h) do { const unsigned pb_ = lds0 + SLOTB(b, h) + wc * 4096 + laneoff; _Pragma("unroll") for (int n = 0; n < 2; ++n) \
;       _Pragma("unroll") for (int k = 0; k < 2; ++k) DSR(dst[n][k], pb_, n * 2048 + k * 1024); } while (0)
; #define BAR __builtin_amdgcn_s_barrier()
; #define LGKM(n) asm volatile("s_waitcnt lgkmcnt(%0)" ::"n"(n) : "memory")
; template <int EPI, bool SWP> ...
;     ...
;     STAGE_B(0, 1, t + 2);
;     WAIT_V(6); BAR; SCHED(); MMA(1, 1, B1); BAR; SCHED();
;     LDB(B0, 1, 0); LDA(1, 0); STAGE_A(0, 1, t + 2);
;     LGKM(8); BAR; LGKM(0); SCHED(); MMA(0, 0, B0); BAR; SCHED();
;     LDB(B1, 1, 1); STAGE_B(1, 0, t + 3);
;     BAR; LGKM(0); SCHED(); MMA(0, 1, B1); BAR; SCHED();
;     LDA(1, 1); STAGE_A(1, 0, t + 3);
	s_mov_b64 s[70:71], 0x2d180100
	s_mov_b32 m0, s78
	v_lshl_add_u64 v[128:129], v[194:195], 0, s[70:71]
	s_mov_b64 s[70:71], 0x2d1c0100
	global_load_lds_dwordx4 v[128:129], off
	v_lshl_add_u64 v[128:129], v[194:195], 0, s[70:71]
	s_mov_b32 m0, s79
	s_nop 0
	global_load_lds_dwordx4 v[128:129], off
	s_waitcnt vmcnt(6)
	s_barrier
	v_mfma_f32_16x16x32_bf16 v[28:31], v[176:179], v[144:147], v[28:31]
	v_mfma_f32_16x16x32_bf16 v[24:27], v[184:187], v[144:147], v[24:27]
	v_mfma_f32_16x16x32_bf16 v[20:23], v[176:179], v[152:155], v[20:23]
	v_mfma_f32_16x16x32_bf16 v[16:19], v[184:187], v[152:155], v[16:19]
	v_mfma_f32_16x16x32_bf16 v[12:15], v[176:179], v[160:163], v[12:15]
	v_mfma_f32_16x16x32_bf16 v[8:11], v[184:187], v[160:163], v[8:11]
	v_mfma_f32_16x16x32_bf16 v[4:7], v[176:179], v[168:171], v[4:7]
	v_mfma_f32_16x16x32_bf16 v[0:3], v[184:187], v[168:171], v[0:3]
	v_mfma_f32_16x16x32_bf16 v[28:31], v[180:183], v[148:151], v[28:31]
	v_mfma_f32_16x16x32_bf16 v[24:27], v[188:191], v[148:151], v[24:27]
	v_mfma_f32_16x16x32_bf16 v[20:23], v[180:183], v[156:159], v[20:23]
	v_mfma_f32_16x16x32_bf16 v[16:19], v[188:191], v[156:159], v[16:19]
	v_mfma_f32_16x16x32_bf16 v[12:15], v[180:183], v[164:167], v[12:15]
	v_mfma_f32_16x16x32_bf16 v[8:11], v[188:191], v[164:167], v[8:11]
	v_mfma_f32_16x16x32_bf16 v[4:7], v[180:183], v[172:175], v[4:7]
	v_mfma_f32_16x16x32_bf16 v[0:3], v[188:191], v[172:175], v[0:3]
	s_barrier
	ds_read_b128 v[128:131], v223 offset:0
	ds_read_b128 v[132:135], v223 offset:0x400
	ds_read_b128 v[136:139], v223 offset:0x800
	ds_read_b128 v[140:143], v223 offset:0xc00
	ds_read_b128 v[144:147], v224 offset:0
	ds_read_b128 v[148:151], v224 offset:0x400
	ds_read_b128 v[152:155], v224 offset:0x800
	ds_read_b128 v[156:159], v224 offset:0xc00
	ds_read_b128 v[160:163], v224 offset:0x1000
	ds_read_b128 v[164:167], v224 offset:0x1400
	ds_read_b128 v[168:171], v224 offset:0x1800
	s_mov_b64 s[70:71], 0xc080100
	s_mov_b32 m0, s80
	ds_read_b128 v[172:175], v224 offset:0x1c00
	v_lshl_add_u64 v[176:177], v[192:193], 0, s[70:71]
	s_mov_b64 s[70:71], 0xc0c0100
	global_load_lds_dwordx4 v[176:177], off
	v_lshl_add_u64 v[176:177], v[192:193], 0, s[70:71]
	s_mov_b32 m0, s81
	s_nop 0
	global_load_lds_dwordx4 v[176:177], off
	s_waitcnt lgkmcnt(8)
	s_barrier
	s_waitcnt lgkmcnt(0)
	v_mfma_f32_16x16x32_bf16 v[124:127], v[128:131], v[144:147], v[124:127]
	v_mfma_f32_16x16x32_bf16 v[120:123], v[136:139], v[144:147], v[120:123]
	v_mfma_f32_16x16x32_bf16 v[116:119], v[128:131], v[152:155], v[116:119]
	v_mfma_f32_16x16x32_bf16 v[112:115], v[136:139], v[152:155], v[112:115]
	v_mfma_f32_16x16x32_bf16 v[108:111], v[128:131], v[160:163], v[108:111]
	v_mfma_f32_16x16x32_bf16 v[104:107], v[136:139], v[160:163], v[104:107]
	v_mfma_f32_16x16x32_bf16 v[100:103], v[128:131], v[168:171], v[100:103]
	v_mfma_f32_16x16x32_bf16 v[96:99], v[136:139], v[168:171], v[96:99]
	v_mfma_f32_16x16x32_bf16 v[124:127], v[132:135], v[148:151], v[124:127]
	v_mfma_f32_16x16x32_bf16 v[120:123], v[140:143], v[148:151], v[120:123]
	v_mfma_f32_16x16x32_bf16 v[116:119], v[132:135], v[156:159], v[116:119]
	v_mfma_f32_16x16x32_bf16 v[112:115], v[140:143], v[156:159], v[112:115]
	v_mfma_f32_16x16x32_bf16 v[108:111], v[132:135], v[164:167], v[108:111]
	v_mfma_f32_16x16x32_bf16 v[104:107], v[140:143], v[164:167], v[104:107]
	v_mfma_f32_16x16x32_bf16 v[100:103], v[132:135], v[172:175], v[100:103]
	v_mfma_f32_16x16x32_bf16 v[96:99], v[140:143], v[172:175], v[96:99]
	s_barrier
	ds_read_b128 v[176:179], v225 offset:0
	ds_read_b128 v[180:183], v225 offset:0x400
	ds_read_b128 v[184:187], v225 offset:0x800
	s_mov_b64 s[70:71], 0x2d100180
	s_mov_b32 m0, s82
	ds_read_b128 v[188:191], v225 offset:0xc00
	v_lshl_add_u64 v[196:197], v[194:195], 0, s[70:71]
	s_mov_b64 s[70:71], 0x2d140180
	global_load_lds_dwordx4 v[196:197], off
	v_lshl_add_u64 v[196:197], v[194:195], 0, s[70:71]
	s_mov_b32 m0, s83
	s_nop 0
	global_load_lds_dwordx4 v[196:197], off
	s_barrier
	s_waitcnt lgkmcnt(0)
	v_mfma_f32_16x16x32_bf16 v[92:95], v[176:179], v[144:147], v[92:95]
	v_mfma_f32_16x16x32_bf16 v[88:91], v[184:187], v[144:147], v[88:91]
	v_mfma_f32_16x16x32_bf16 v[84:87], v[176:179], v[152:155], v[84:87]
	v_mfma_f32_16x16x32_bf16 v[80:83], v[184:187], v[152:155], v[80:83]
	v_mfma_f32_16x16x32_bf16 v[76:79], v[176:179], v[160:163], v[76:79]
	v_mfma_f32_16x16x32_bf16 v[72:75], v[184:187], v[160:163], v[72:75]
	v_mfma_f32_16x16x32_bf16 v[68:71], v[176:179], v[168:171], v[68:71]
	v_mfma_f32_16x16x32_bf16 v[64:67], v[184:187], v[168:171], v[64:67]
	v_mfma_f32_16x16x32_bf16 v[92:95], v[180:183], v[148:151], v[92:95]
	v_mfma_f32_16x16x32_bf16 v[88:91], v[188:191], v[148:151], v[88:91]
	v_mfma_f32_16x16x32_bf16 v[84:87], v[180:183], v[156:159], v[84:87]
	v_mfma_f32_16x16x32_bf16 v[80:83], v[188:191], v[156:159], v[80:83]
	v_mfma_f32_16x16x32_bf16 v[76:79], v[180:183], v[164:167], v[76:79]
	v_mfma_f32_16x16x32_bf16 v[72:75], v[188:191], v[164:167], v[72:75]
	v_mfma_f32_16x16x32_bf16 v[68:71], v[180:183], v[172:175], v[68:71]
	v_mfma_f32_16x16x32_bf16 v[64:67], v[188:191], v[172:175], v[64:67]
	s_barrier
	ds_read_b128 v[144:147], v226 offset:0
	ds_read_b128 v[148:151], v226 offset:0x400
	ds_read_b128 v[152:155], v226 offset:0x800
	ds_read_b128 v[156:159], v226 offset:0xc00
	ds_read_b128 v[160:163], v226 offset:0x1000
	ds_read_b128 v[164:167], v226 offset:0x1400
	ds_read_b128 v[168:171], v226 offset:0x1800
	s_mov_b32 m0, s84
	ds_read_b128 v[172:175], v226 offset:0x1c00
	v_lshl_add_u64 v[196:197], v[192:193], 0, s[36:37]
	global_load_lds_dwordx4 v[196:197], off
	v_lshl_add_u64 v[192:193], v[192:193], 0, s[38:39]
	s_mov_b32 m0, s85
	s_nop 0
	global_load_lds_dwordx4 v[192:193], off
	s_barrier
; #define WAIT_V(n) asm volatile("s_waitcnt vmcnt(%0)" ::"n"(n) : "memory")
; #define SCHED() __builtin_amdgcn_sched_barrier(0)
; #define LGKM(n) asm volatile("s_waitcnt lgkmcnt(%0)" ::"n"(n) : "memory")
; #define STAGE_A(b, h, kt) STAGE_AX(Ag, b, h, kt)
; #define STAGE_B(b, h, kt) STAGE_BX(Bg, b, h, kt)
; #define LDA(b, h) do { const unsigned pa_ = lds0 + SLOTA(b, h) + wr * 8192 + laneoff; _Pragma("unroll") for (int m = 0; m < 4; ++m)   \
;       _Pragma("unroll") for (int k = 0; k < 2; ++k) DSR(At[m][k], pa_, m * 2048 + k * 1024); } while (0)
; #define LDB(dst, b, h) do { const unsigned pb_ = lds0 + SLOTB(b, h) + wc * 4096 + laneoff; _Pragma("unroll") for (int n = 0; n < 2; ++n) \
;       _Pragma("unroll") for (int k = 0; k < 2; ++k) DSR(dst[n][k], pb_, n * 2048 + k * 1024); } while (0)
; #define BAR __builtin_amdgcn_s_barrier()
; #define LGKM(n) asm volatile("s_waitcnt lgkmcnt(%0)" ::"n"(n) : "memory")
; template <int EPI, bool SWP> ...
;     ...
;     LDA(1, 1); STAGE_A(1, 0, t + 3);
;     BAR; LGKM(0); SCHED(); MMA(1, 0, B0); BAR; SCHED();
;     STAGE_B(1, 1, t + 3);
;     WAIT_V(6); BAR; SCHED(); MMA(1, 1, B1); BAR; SCHED();
;   }
;   { LDB(B0, 0, 0); LDA(0, 0); STAGE_A(1, 1, nt - 1);
;     BAR; LGKM(0); SCHED(); MMA(0, 0, B0); BAR; SCHED();
;     LDB(B1, 0, 1); BAR; LGKM(0); SCHED(); MMA(0, 1, B1); BAR; SCHED();
	s_waitcnt lgkmcnt(0)
	v_mfma_f32_16x16x32_bf16 v[60:63], v[128:131], v[144:147], v[60:63]
	v_mfma_f32_16x16x32_bf16 v[56:59], v[136:139], v[144:147], v[56:59]
	v_mfma_f32_16x16x32_bf16 v[52:55], v[128:131], v[152:155], v[52:55]
	v_mfma_f32_16x16x32_bf16 v[48:51], v[136:139], v[152:155], v[48:51]
	v_mfma_f32_16x16x32_bf16 v[44:47], v[128:131], v[160:163], v[44:47]
	v_mfma_f32_16x16x32_bf16 v[40:43], v[136:139], v[160:163], v[40:43]
	v_mfma_f32_16x16x32_bf16 v[36:39], v[128:131], v[168:171], v[36:39]
	v_mfma_f32_16x16x32_bf16 v[32:35], v[136:139], v[168:171], v[32:35]
	v_mfma_f32_16x16x32_bf16 v[60:63], v[132:135], v[148:151], v[60:63]
	v_mfma_f32_16x16x32_bf16 v[56:59], v[140:143], v[148:151], v[56:59]
	v_mfma_f32_16x16x32_bf16 v[52:55], v[132:135], v[156:159], v[52:55]
	v_mfma_f32_16x16x32_bf16 v[48:51], v[140:143], v[156:159], v[48:51]
	v_mfma_f32_16x16x32_bf16 v[44:47], v[132:135], v[164:167], v[44:47]
	v_mfma_f32_16x16x32_bf16 v[40:43], v[140:143], v[164:167], v[40:43]
	v_mfma_f32_16x16x32_bf16 v[36:39], v[132:135], v[172:175], v[36:39]
	v_mfma_f32_16x16x32_bf16 v[32:35], v[140:143], v[172:175], v[32:35]
	s_barrier
	s_add_i32 s70, s3, 0x1c000
	v_lshl_add_u64 v[128:129], v[194:195], 0, s[40:41]
	s_mov_b32 m0, s70
	s_nop 0
	global_load_lds_dwordx4 v[128:129], off
	v_lshl_add_u64 v[128:129], v[194:195], 0, s[42:43]
	s_mov_b32 m0, s86
	s_nop 0
	global_load_lds_dwordx4 v[128:129], off
	s_waitcnt vmcnt(6)
	s_barrier
	v_mfma_f32_16x16x32_bf16 v[28:31], v[176:179], v[144:147], v[28:31]
	v_mfma_f32_16x16x32_bf16 v[24:27], v[184:187], v[144:147], v[24:27]
	v_mfma_f32_16x16x32_bf16 v[20:23], v[176:179], v[152:155], v[20:23]
	v_mfma_f32_16x16x32_bf16 v[16:19], v[184:187], v[152:155], v[16:19]
	v_mfma_f32_16x16x32_bf16 v[12:15], v[176:179], v[160:163], v[12:15]
	v_mfma_f32_16x16x32_bf16 v[8:11], v[184:187], v[160:163], v[8:11]
	v_mfma_f32_16x16x32_bf16 v[4:7], v[176:179], v[168:171], v[4:7]
	v_mfma_f32_16x16x32_bf16 v[0:3], v[184:187], v[168:171], v[0:3]
	v_mfma_f32_16x16x32_bf16 v[28:31], v[180:183], v[148:151], v[28:31]
	v_mfma_f32_16x16x32_bf16 v[24:27], v[188:191], v[148:151], v[24:27]
	v_mfma_f32_16x16x32_bf16 v[20:23], v[180:183], v[156:159], v[20:23]
	v_mfma_f32_16x16x32_bf16 v[16:19], v[188:191], v[156:159], v[16:19]
	v_mfma_f32_16x16x32_bf16 v[12:15], v[180:183], v[164:167], v[12:15]
	v_mfma_f32_16x16x32_bf16 v[8:11], v[188:191], v[164:167], v[8:11]
	v_mfma_f32_16x16x32_bf16 v[4:7], v[180:183], v[172:175], v[4:7]
	v_mfma_f32_16x16x32_bf16 v[0:3], v[188:191], v[172:175], v[0:3]
	s_barrier
	s_add_i32 s1, s1, 2
	s_add_u32 s66, s66, 0x100
	s_addc_u32 s67, s67, 0
	s_add_u32 s68, s68, 0x100
	s_addc_u32 s69, s69, 0
	s_cmp_gt_u32 s1, 27
	s_cbranch_scc0 .LBB0_667
	ds_read_b128 v[136:139], v219 offset:0
	ds_read_b128 v[140:143], v219 offset:0x400
	ds_read_b128 v[144:147], v219 offset:0x800
	ds_read_b128 v[148:151], v219 offset:0xc00
	ds_read_b128 v[128:131], v220 offset:0
	ds_read_b128 v[132:135], v220 offset:0x400
	ds_read_b128 v[152:155], v220 offset:0x800
	ds_read_b128 v[156:159], v220 offset:0xc00
	ds_read_b128 v[160:163], v220 offset:0x1000
	ds_read_b128 v[164:167], v220 offset:0x1400
	v_lshl_add_u64 v[176:177], s[64:65], 0, v[208:209]
	ds_read_b128 v[168:171], v220 offset:0x1800
	s_mov_b32 m0, s87
	ds_read_b128 v[172:175], v220 offset:0x1c00
	v_lshl_add_u64 v[178:179], v[176:177], 0, s[44:45]
	global_load_lds_dwordx4 v[178:179], off
	v_lshl_add_u64 v[176:177], v[176:177], 0, s[46:47]
	s_mov_b32 m0, s88
	s_ashr_i32 s1, s0, 31
	global_load_lds_dwordx4 v[176:177], off
	s_lshl_b64 s[64:65], s[0:1], 20
	s_add_u32 s64, s24, s64
	s_addc_u32 s65, s25, s65
	s_ashr_i32 s51, s50, 31
	s_barrier
	s_waitcnt lgkmcnt(0)
	s_lshl_b64 s[66:67], s[50:51], 20
	s_add_u32 s66, s30, s66
	s_addc_u32 s67, s31, s67
	v_mfma_f32_16x16x32_bf16 v[124:127], v[136:139], v[128:131], v[124:127]
	v_mfma_f32_16x16x32_bf16 v[120:123], v[144:147], v[128:131], v[120:123]
	v_mfma_f32_16x16x32_bf16 v[116:119], v[136:139], v[152:155], v[116:119]
	v_mfma_f32_16x16x32_bf16 v[112:115], v[144:147], v[152:155], v[112:115]
	v_mfma_f32_16x16x32_bf16 v[108:111], v[136:139], v[160:163], v[108:111]
	v_mfma_f32_16x16x32_bf16 v[104:107], v[144:147], v[160:163], v[104:107]
	v_mfma_f32_16x16x32_bf16 v[100:103], v[136:139], v[168:171], v[100:103]
	v_mfma_f32_16x16x32_bf16 v[96:99], v[144:147], v[168:171], v[96:99]
	v_mfma_f32_16x16x32_bf16 v[124:127], v[140:143], v[132:135], v[124:127]
	v_mfma_f32_16x16x32_bf16 v[120:123], v[148:151], v[132:135], v[120:123]
	v_mfma_f32_16x16x32_bf16 v[116:119], v[140:143], v[156:159], v[116:119]
	v_mfma_f32_16x16x32_bf16 v[112:115], v[148:151], v[156:159], v[112:115]
	v_mfma_f32_16x16x32_bf16 v[176:179], v[140:143], v[164:167], v[108:111]
	v_mfma_f32_16x16x32_bf16 v[180:183], v[148:151], v[164:167], v[104:107]
	v_mfma_f32_16x16x32_bf16 v[100:103], v[140:143], v[172:175], v[100:103]
	v_mfma_f32_16x16x32_bf16 v[96:99], v[148:151], v[172:175], v[96:99]
	s_barrier
	ds_read_b128 v[104:107], v221 offset:0
	ds_read_b128 v[108:111], v221 offset:0x400
	ds_read_b128 v[184:187], v221 offset:0x800
	ds_read_b128 v[188:191], v221 offset:0xc00
	s_barrier
; #define WAIT_V(n) asm volatile("s_waitcnt vmcnt(%0)" ::"n"(n) : "memory")
; #define SCHED() __builtin_amdgcn_sched_barrier(0)
; #define LGKM(n) asm volatile("s_waitcnt lgkmcnt(%0)" ::"n"(n) : "memory")
; #define LDA(b, h) do { const unsigned pa_ = lds0 + SLOTA(b, h) + wr * 8192 + laneoff; _Pragma("unroll") for (int m = 0; m < 4; ++m)   \
;       _Pragma("unroll") for (int k = 0; k < 2; ++k) DSR(At[m][k], pa_, m * 2048 + k * 1024); } while (0)
; #define LDB(dst, b, h) do { const unsigned pb_ = lds0 + SLOTB(b, h) + wc * 4096 + laneoff; _Pragma("unroll") for (int n = 0; n < 2; ++n) \
;       _Pragma("unroll") for (int k = 0; k < 2; ++k) DSR(dst[n][k], pb_, n * 2048 + k * 1024); } while (0)
; #define BAR __builtin_amdgcn_s_barrier()
; #define LGKM(n) asm volatile("s_waitcnt lgkmcnt(%0)" ::"n"(n) : "memory")
; template <int EPI, bool SWP> ...
;     ...
;     LDB(B1, 0, 1); BAR; LGKM(0); SCHED(); MMA(0, 1, B1); BAR; SCHED();
;     LDA(0, 1); WAIT_V(4); BAR; LGKM(0); SCHED(); MMA(1, 0, B0); MMA(1, 1, B1); BAR; SCHED(); }
;   { LDB(B0, 1, 0); LDA(1, 0); WAIT_V(2); BAR; LGKM(0); SCHED(); MMA(0, 0, B0); BAR; SCHED();
	s_waitcnt lgkmcnt(0)
	v_mfma_f32_16x16x32_bf16 v[92:95], v[104:107], v[128:131], v[92:95]
	v_mfma_f32_16x16x32_bf16 v[88:91], v[184:187], v[128:131], v[88:91]
	v_mfma_f32_16x16x32_bf16 v[84:87], v[104:107], v[152:155], v[84:87]
	v_mfma_f32_16x16x32_bf16 v[80:83], v[184:187], v[152:155], v[80:83]
	v_mfma_f32_16x16x32_bf16 v[76:79], v[104:107], v[160:163], v[76:79]
	v_mfma_f32_16x16x32_bf16 v[72:75], v[184:187], v[160:163], v[72:75]
	v_mfma_f32_16x16x32_bf16 v[68:71], v[104:107], v[168:171], v[68:71]
	v_mfma_f32_16x16x32_bf16 v[64:67], v[184:187], v[168:171], v[64:67]
	v_mfma_f32_16x16x32_bf16 v[192:195], v[108:111], v[132:135], v[92:95]
	v_mfma_f32_16x16x32_bf16 v[196:199], v[188:191], v[132:135], v[88:91]
	v_mfma_f32_16x16x32_bf16 v[84:87], v[108:111], v[156:159], v[84:87]
	v_mfma_f32_16x16x32_bf16 v[80:83], v[188:191], v[156:159], v[80:83]
	v_mfma_f32_16x16x32_bf16 v[200:203], v[108:111], v[164:167], v[76:79]
	v_mfma_f32_16x16x32_bf16 v[204:207], v[188:191], v[164:167], v[72:75]
	v_mfma_f32_16x16x32_bf16 v[68:71], v[108:111], v[172:175], v[68:71]
	v_mfma_f32_16x16x32_bf16 v[64:67], v[188:191], v[172:175], v[64:67]
	s_barrier
	ds_read_b128 v[72:75], v222 offset:0
	ds_read_b128 v[76:79], v222 offset:0x400
	ds_read_b128 v[88:91], v222 offset:0x800
	ds_read_b128 v[92:95], v222 offset:0xc00
	ds_read_b128 v[152:155], v222 offset:0x1000
	ds_read_b128 v[156:159], v222 offset:0x1400
	ds_read_b128 v[160:163], v222 offset:0x1800
	ds_read_b128 v[164:167], v222 offset:0x1c00
	s_waitcnt vmcnt(4)
	s_barrier
	s_waitcnt lgkmcnt(0)
	v_mfma_f32_16x16x32_bf16 v[60:63], v[136:139], v[72:75], v[60:63]
	v_mfma_f32_16x16x32_bf16 v[56:59], v[144:147], v[72:75], v[56:59]
	v_mfma_f32_16x16x32_bf16 v[52:55], v[136:139], v[88:91], v[52:55]
	v_mfma_f32_16x16x32_bf16 v[48:51], v[144:147], v[88:91], v[48:51]
	v_mfma_f32_16x16x32_bf16 v[44:47], v[136:139], v[152:155], v[44:47]
	v_mfma_f32_16x16x32_bf16 v[40:43], v[144:147], v[152:155], v[40:43]
	v_mfma_f32_16x16x32_bf16 v[36:39], v[136:139], v[160:163], v[36:39]
	v_mfma_f32_16x16x32_bf16 v[32:35], v[144:147], v[160:163], v[32:35]
	v_mfma_f32_16x16x32_bf16 v[60:63], v[140:143], v[76:79], v[60:63]
	v_mfma_f32_16x16x32_bf16 v[56:59], v[148:151], v[76:79], v[56:59]
	v_mfma_f32_16x16x32_bf16 v[52:55], v[140:143], v[92:95], v[52:55]
	v_mfma_f32_16x16x32_bf16 v[48:51], v[148:151], v[92:95], v[48:51]
	v_mfma_f32_16x16x32_bf16 v[128:131], v[140:143], v[156:159], v[44:47]
	v_mfma_f32_16x16x32_bf16 v[132:135], v[148:151], v[156:159], v[40:43]
	v_mfma_f32_16x16x32_bf16 v[36:39], v[140:143], v[164:167], v[36:39]
	v_mfma_f32_16x16x32_bf16 v[32:35], v[148:151], v[164:167], v[32:35]
	v_mfma_f32_16x16x32_bf16 v[28:31], v[104:107], v[72:75], v[28:31]
	v_mfma_f32_16x16x32_bf16 v[24:27], v[184:187], v[72:75], v[24:27]
	v_mfma_f32_16x16x32_bf16 v[20:23], v[104:107], v[88:91], v[20:23]
	v_mfma_f32_16x16x32_bf16 v[16:19], v[184:187], v[88:91], v[16:19]
	v_mfma_f32_16x16x32_bf16 v[12:15], v[104:107], v[152:155], v[12:15]
	v_mfma_f32_16x16x32_bf16 v[8:11], v[184:187], v[152:155], v[8:11]
	v_mfma_f32_16x16x32_bf16 v[4:7], v[104:107], v[160:163], v[4:7]
	v_mfma_f32_16x16x32_bf16 v[0:3], v[184:187], v[160:163], v[0:3]
	v_mfma_f32_16x16x32_bf16 v[136:139], v[108:111], v[76:79], v[28:31]
	v_mfma_f32_16x16x32_bf16 v[140:143], v[188:191], v[76:79], v[24:27]
	v_mfma_f32_16x16x32_bf16 v[20:23], v[108:111], v[92:95], v[20:23]
	v_mfma_f32_16x16x32_bf16 v[16:19], v[188:191], v[92:95], v[16:19]
	v_mfma_f32_16x16x32_bf16 v[144:147], v[108:111], v[156:159], v[12:15]
	v_mfma_f32_16x16x32_bf16 v[148:151], v[188:191], v[156:159], v[8:11]
	v_mfma_f32_16x16x32_bf16 v[4:7], v[108:111], v[164:167], v[4:7]
	v_mfma_f32_16x16x32_bf16 v[0:3], v[188:191], v[164:167], v[0:3]
	s_barrier
	ds_read_b128 v[8:11], v223 offset:0
	ds_read_b128 v[12:15], v223 offset:0x400
	ds_read_b128 v[152:155], v223 offset:0x800
	ds_read_b128 v[156:159], v223 offset:0xc00
	ds_read_b128 v[24:27], v224 offset:0
	ds_read_b128 v[28:31], v224 offset:0x400
	ds_read_b128 v[40:43], v224 offset:0x800
	ds_read_b128 v[44:47], v224 offset:0xc00
	ds_read_b128 v[184:187], v224 offset:0x1000
	ds_read_b128 v[188:191], v224 offset:0x1400
	ds_read_b128 v[212:215], v224 offset:0x1800
	ds_read_b128 v[236:239], v224 offset:0x1c00
	s_waitcnt vmcnt(2)
	s_barrier
	s_waitcnt lgkmcnt(0)
	v_mfma_f32_16x16x32_bf16 v[72:75], v[8:11], v[24:27], v[124:127]
	v_mfma_f32_16x16x32_bf16 v[124:127], v[12:15], v[28:31], v[72:75]
	v_mfma_f32_16x16x32_bf16 v[72:75], v[152:155], v[24:27], v[120:123]
	v_mfma_f32_16x16x32_bf16 v[120:123], v[156:159], v[28:31], v[72:75]
	v_mfma_f32_16x16x32_bf16 v[72:75], v[8:11], v[40:43], v[116:119]
	v_mfma_f32_16x16x32_bf16 v[108:111], v[12:15], v[44:47], v[72:75]
	v_mfma_f32_16x16x32_bf16 v[72:75], v[152:155], v[40:43], v[112:115]
	v_mfma_f32_16x16x32_bf16 v[104:107], v[156:159], v[44:47], v[72:75]
	v_mfma_f32_16x16x32_bf16 v[72:75], v[8:11], v[184:187], v[176:179]
	v_mfma_f32_16x16x32_bf16 v[92:95], v[12:15], v[188:191], v[72:75]
	v_mfma_f32_16x16x32_bf16 v[72:75], v[152:155], v[184:187], v[180:183]
	v_mfma_f32_16x16x32_bf16 v[88:91], v[156:159], v[188:191], v[72:75]
	v_mfma_f32_16x16x32_bf16 v[72:75], v[8:11], v[212:215], v[100:103]
	v_mfma_f32_16x16x32_bf16 v[76:79], v[12:15], v[236:239], v[72:75]
	v_mfma_f32_16x16x32_bf16 v[72:75], v[152:155], v[212:215], v[96:99]
	v_mfma_f32_16x16x32_bf16 v[72:75], v[156:159], v[236:239], v[72:75]
	s_barrier
; #define WAIT_V(n) asm volatile("s_waitcnt vmcnt(%0)" ::"n"(n) : "memory")
; #define SCHED() __builtin_amdgcn_sched_barrier(0)
; #define LGKM(n) asm volatile("s_waitcnt lgkmcnt(%0)" ::"n"(n) : "memory")
; #define STAGE_AX(AG, b, h, kt) do { _Pragma("unroll") for (int i = 0; i < 2; ++i)                                    \
;       __builtin_amdgcn_global_load_lds((const unsigned*)(((AG) + ((size_t)(kt) * (BK * 2) + (size_t)((h) * 2 + i) * 128 * lda)) + aoff), \
;                                        (unsigned*)(shm + SLOTA(b, h) + wid * 1024 + i * 8192), 16, 0, 0); } while (0)
; #define STAGE_BX(BG, b, h, kt) do { _Pragma("unroll") for (int i = 0; i < 2; ++i)                                    \
;       __builtin_amdgcn_global_load_lds((const unsigned*)(((BG) + ((size_t)(kt) * (BK * 2) + (size_t)((h) * 2 + i) * 128 * K)) + boff),   \
;                                        (unsigned*)(shm + SLOTB(b, h) + wid * 1024 + i * 8192), 16, 0, 0); } while (0)
; #define LDA(b, h) do { const unsigned pa_ = lds0 + SLOTA(b, h) + wr * 8192 + laneoff; _Pragma("unroll") for (int m = 0; m < 4; ++m)   \
;       _Pragma("unroll") for (int k = 0; k < 2; ++k) DSR(At[m][k], pa_, m * 2048 + k * 1024); } while (0)
; #define LDB(dst, b, h) do { const unsigned pb_ = lds0 + SLOTB(b, h) + wc * 4096 + laneoff; _Pragma("unroll") for (int n = 0; n < 2; ++n) \
;       _Pragma("unroll") for (int k = 0; k < 2; ++k) DSR(dst[n][k], pb_, n * 2048 + k * 1024); } while (0)
; #define BAR __builtin_amdgcn_s_barrier()
; #define LGKM(n) asm volatile("s_waitcnt lgkmcnt(%0)" ::"n"(n) : "memory")
; template <int EPI, bool SWP> ...
;     ...
;     LDB(B1, 1, 1); WAIT_V(0); BAR; LGKM(0); SCHED(); MMA(0, 1, B1); BAR; SCHED();
;     LDA(1, 1);
;     if (has_next) { STAGE_BX(Bg_n, 0, 0, 0); STAGE_AX(Ag_n, 0, 0, 0); STAGE_BX(Bg_n, 0, 1, 0); STAGE_AX(Ag_n, 0, 1, 0); }
;     BAR; LGKM(0); SCHED(); MMA(1, 0, B0); MMA(1, 1, B1); BAR; SCHED(); }
;   if (wr == 0) BAR;
	ds_read_b128 v[160:163], v225 offset:0
	ds_read_b128 v[164:167], v225 offset:0x400
	ds_read_b128 v[168:171], v225 offset:0x800
	ds_read_b128 v[172:175], v225 offset:0xc00
	s_waitcnt vmcnt(0)
	s_barrier
	s_waitcnt lgkmcnt(0)
	v_mfma_f32_16x16x32_bf16 v[96:99], v[160:163], v[24:27], v[192:195]
	v_mfma_f32_16x16x32_bf16 v[24:27], v[168:171], v[24:27], v[196:199]
	v_mfma_f32_16x16x32_bf16 v[112:115], v[172:175], v[28:31], v[24:27]
	v_mfma_f32_16x16x32_bf16 v[24:27], v[160:163], v[40:43], v[84:87]
	v_mfma_f32_16x16x32_bf16 v[100:103], v[164:167], v[44:47], v[24:27]
	v_mfma_f32_16x16x32_bf16 v[24:27], v[168:171], v[40:43], v[80:83]
	v_mfma_f32_16x16x32_bf16 v[116:119], v[164:167], v[28:31], v[96:99]
	v_mfma_f32_16x16x32_bf16 v[96:99], v[172:175], v[44:47], v[24:27]
	v_mfma_f32_16x16x32_bf16 v[24:27], v[160:163], v[184:187], v[200:203]
	v_mfma_f32_16x16x32_bf16 v[84:87], v[164:167], v[188:191], v[24:27]
	v_mfma_f32_16x16x32_bf16 v[24:27], v[168:171], v[184:187], v[204:207]
	v_mfma_f32_16x16x32_bf16 v[80:83], v[172:175], v[188:191], v[24:27]
	v_mfma_f32_16x16x32_bf16 v[24:27], v[160:163], v[212:215], v[68:71]
	v_mfma_f32_16x16x32_bf16 v[68:71], v[164:167], v[236:239], v[24:27]
	v_mfma_f32_16x16x32_bf16 v[24:27], v[168:171], v[212:215], v[64:67]
	v_mfma_f32_16x16x32_bf16 v[64:67], v[172:175], v[236:239], v[24:27]
	s_barrier
	ds_read_b128 v[200:203], v226 offset:0
	ds_read_b128 v[204:207], v226 offset:0x400
	ds_read_b128 v[192:195], v226 offset:0x800
	ds_read_b128 v[196:199], v226 offset:0xc00
	ds_read_b128 v[184:187], v226 offset:0x1000
	ds_read_b128 v[188:191], v226 offset:0x1400
	ds_read_b128 v[176:179], v226 offset:0x1800
	ds_read_b128 v[180:183], v226 offset:0x1c00
	s_and_b64 vcc, exec, s[62:63]
	v_lshl_add_u64 v[212:213], s[66:67], 0, v[208:209]
	v_lshl_add_u64 v[214:215], s[64:65], 0, v[208:209]
	s_cbranch_vccz .LBB0_670
	s_mov_b32 m0, s75
	v_lshl_add_u64 v[24:25], v[212:213], 0, s[12:13]
	global_load_lds_dwordx4 v[212:213], off
	s_mov_b32 m0, s76
	s_nop 0
	global_load_lds_dwordx4 v[24:25], off
	s_mov_b32 m0, s3
	v_lshl_add_u64 v[24:25], v[214:215], 0, s[12:13]
	global_load_lds_dwordx4 v[214:215], off
	s_mov_b32 m0, s77
	s_nop 0
	global_load_lds_dwordx4 v[24:25], off
	v_lshl_add_u64 v[24:25], v[212:213], 0, s[14:15]
	s_mov_b32 m0, s78
	s_nop 0
	global_load_lds_dwordx4 v[24:25], off
	v_lshl_add_u64 v[24:25], v[212:213], 0, s[16:17]
	s_mov_b32 m0, s79
	s_nop 0
	global_load_lds_dwordx4 v[24:25], off
	v_lshl_add_u64 v[24:25], v[214:215], 0, s[14:15]
	s_mov_b32 m0, s80
	s_nop 0
	global_load_lds_dwordx4 v[24:25], off
	v_lshl_add_u64 v[24:25], v[214:215], 0, s[16:17]
	s_mov_b32 m0, s81
	s_nop 0
	global_load_lds_dwordx4 v[24:25], off
.LBB0_670:
	s_barrier
	s_waitcnt lgkmcnt(0)
	v_mfma_f32_16x16x32_bf16 v[24:27], v[8:11], v[200:203], v[60:63]
	v_mfma_f32_16x16x32_bf16 v[60:63], v[12:15], v[204:207], v[24:27]
	v_mfma_f32_16x16x32_bf16 v[24:27], v[152:155], v[200:203], v[56:59]
	v_mfma_f32_16x16x32_bf16 v[56:59], v[156:159], v[204:207], v[24:27]
	v_mfma_f32_16x16x32_bf16 v[24:27], v[8:11], v[192:195], v[52:55]
	v_mfma_f32_16x16x32_bf16 v[44:47], v[12:15], v[196:199], v[24:27]
	v_mfma_f32_16x16x32_bf16 v[24:27], v[152:155], v[192:195], v[48:51]
	v_mfma_f32_16x16x32_bf16 v[40:43], v[156:159], v[196:199], v[24:27]
	v_mfma_f32_16x16x32_bf16 v[24:27], v[8:11], v[184:187], v[128:131]
	v_mfma_f32_16x16x32_bf16 v[8:11], v[8:11], v[176:179], v[36:39]
	v_mfma_f32_16x16x32_bf16 v[28:31], v[12:15], v[188:191], v[24:27]
	v_mfma_f32_16x16x32_bf16 v[24:27], v[152:155], v[184:187], v[132:135]
	v_mfma_f32_16x16x32_bf16 v[12:15], v[12:15], v[180:183], v[8:11]
	v_mfma_f32_16x16x32_bf16 v[8:11], v[152:155], v[176:179], v[32:35]
	v_mfma_f32_16x16x32_bf16 v[24:27], v[156:159], v[188:191], v[24:27]
	v_mfma_f32_16x16x32_bf16 v[8:11], v[156:159], v[180:183], v[8:11]
	v_mfma_f32_16x16x32_bf16 v[32:35], v[160:163], v[200:203], v[136:139]
	v_mfma_f32_16x16x32_bf16 v[52:55], v[164:167], v[204:207], v[32:35]
	v_mfma_f32_16x16x32_bf16 v[32:35], v[168:171], v[200:203], v[140:143]
	v_mfma_f32_16x16x32_bf16 v[16:19], v[168:171], v[192:195], v[16:19]
	v_mfma_f32_16x16x32_bf16 v[48:51], v[172:175], v[204:207], v[32:35]
	v_mfma_f32_16x16x32_bf16 v[20:23], v[160:163], v[192:195], v[20:23]
	v_mfma_f32_16x16x32_bf16 v[32:35], v[172:175], v[196:199], v[16:19]
	v_mfma_f32_16x16x32_bf16 v[16:19], v[160:163], v[184:187], v[144:147]
	v_mfma_f32_16x16x32_bf16 v[36:39], v[164:167], v[196:199], v[20:23]
	v_mfma_f32_16x16x32_bf16 v[20:23], v[164:167], v[188:191], v[16:19]
	v_mfma_f32_16x16x32_bf16 v[16:19], v[168:171], v[184:187], v[148:151]
	v_mfma_f32_16x16x32_bf16 v[4:7], v[160:163], v[176:179], v[4:7]
	v_mfma_f32_16x16x32_bf16 v[0:3], v[168:171], v[176:179], v[0:3]
	v_mfma_f32_16x16x32_bf16 v[16:19], v[172:175], v[188:191], v[16:19]
	v_mfma_f32_16x16x32_bf16 v[4:7], v[164:167], v[180:183], v[4:7]
	v_mfma_f32_16x16x32_bf16 v[0:3], v[172:175], v[180:183], v[0:3]
	s_barrier
	s_andn2_b64 vcc, exec, s[4:5]
	s_cbranch_vccnz .LBB0_672
	s_barrier

; #define WAIT_V(n) asm volatile("s_waitcnt vmcnt(%0)" ::"n"(n) : "memory")
; #define SCHED() __builtin_amdgcn_sched_barrier(0)
; #define LGKM(n) asm volatile("s_waitcnt lgkmcnt(%0)" ::"n"(n) : "memory")
; #define STAGE_A(b, h, kt) STAGE_AX(Ag, b, h, kt)
; #define STAGE_B(b, h, kt) STAGE_BX(Bg, b, h, kt)
; #define LDA(b, h) do { const unsigned pa_ = lds0 + SLOTA(b, h) + wr * 8192 + laneoff; _Pragma("unroll") for (int m = 0; m < 4; ++m)   \
;       _Pragma("unroll") for (int k = 0; k < 2; ++k) DSR(At[m][k], pa_, m * 2048 + k * 1024); } while (0)
; #define LDB(dst, b, h) do { const unsigned pb_ = lds0 + SLOTB(b, h) + wc * 4096 + laneoff; _Pragma("unroll") for (int n = 0; n < 2; ++n) \
;       _Pragma("unroll") for (int k = 0; k < 2; ++k) DSR(dst[n][k], pb_, n * 2048 + k * 1024); } while (0)
; #define BAR __builtin_amdgcn_s_barrier()
; #define LGKM(n) asm volatile("s_waitcnt lgkmcnt(%0)" ::"n"(n) : "memory")
; template <int EPI, bool SWP> ...
;     ...
;     LDB(B0, 0, 0); LDA(0, 0); STAGE_A(1, 1, t + 1);
;     LGKM(8); BAR; LGKM(0); SCHED(); MMA(0, 0, B0); BAR; SCHED();
;     LDB(B1, 0, 1); STAGE_B(0, 0, t + 2);
;     BAR; LGKM(0); SCHED(); MMA(0, 1, B1); BAR; SCHED();
;     LDA(0, 1); STAGE_A(0, 0, t + 2);
;     BAR; LGKM(0); SCHED(); MMA(1, 0, B0); BAR; SCHED();
;     STAGE_B(0, 1, t + 2);
;     WAIT_V(6); BAR; SCHED(); MMA(1, 1, B1); BAR; SCHED();
.LBB0_709:
	ds_read_b128 v[130:133], v201 offset:0
	ds_read_b128 v[134:137], v201 offset:0x400
	ds_read_b128 v[138:141], v201 offset:0x800
	ds_read_b128 v[142:145], v201 offset:0xc00
	ds_read_b128 v[146:149], v202 offset:0
	ds_read_b128 v[150:153], v202 offset:0x400
	ds_read_b128 v[154:157], v202 offset:0x800
	ds_read_b128 v[158:161], v202 offset:0xc00
	ds_read_b128 v[162:165], v202 offset:0x1000
	ds_read_b128 v[166:169], v202 offset:0x1400
	ds_read_b128 v[170:173], v202 offset:0x1800
	v_lshl_add_u64 v[190:191], s[68:69], 0, v[194:195]
	s_mov_b32 m0, s86
	ds_read_b128 v[174:177], v202 offset:0x1c00
	v_lshl_add_u64 v[178:179], v[190:191], 0, s[28:29]
	global_load_lds_dwordx4 v[178:179], off
	v_lshl_add_u64 v[178:179], v[190:191], 0, s[30:31]
	s_mov_b32 m0, s87
	s_nop 0
	global_load_lds_dwordx4 v[178:179], off
	s_waitcnt lgkmcnt(8)
	s_barrier
	s_waitcnt lgkmcnt(0)
	v_mfma_f32_16x16x32_bf16 v[124:127], v[130:133], v[146:149], v[124:127]
	v_mfma_f32_16x16x32_bf16 v[120:123], v[138:141], v[146:149], v[120:123]
	v_mfma_f32_16x16x32_bf16 v[116:119], v[130:133], v[154:157], v[116:119]
	v_mfma_f32_16x16x32_bf16 v[112:115], v[138:141], v[154:157], v[112:115]
	v_mfma_f32_16x16x32_bf16 v[108:111], v[130:133], v[162:165], v[108:111]
	v_mfma_f32_16x16x32_bf16 v[104:107], v[138:141], v[162:165], v[104:107]
	v_mfma_f32_16x16x32_bf16 v[100:103], v[130:133], v[170:173], v[100:103]
	v_mfma_f32_16x16x32_bf16 v[96:99], v[138:141], v[170:173], v[96:99]
	v_mfma_f32_16x16x32_bf16 v[124:127], v[134:137], v[150:153], v[124:127]
	v_mfma_f32_16x16x32_bf16 v[120:123], v[142:145], v[150:153], v[120:123]
	v_mfma_f32_16x16x32_bf16 v[116:119], v[134:137], v[158:161], v[116:119]
	v_mfma_f32_16x16x32_bf16 v[112:115], v[142:145], v[158:161], v[112:115]
	v_mfma_f32_16x16x32_bf16 v[108:111], v[134:137], v[166:169], v[108:111]
	v_mfma_f32_16x16x32_bf16 v[104:107], v[142:145], v[166:169], v[104:107]
	v_mfma_f32_16x16x32_bf16 v[100:103], v[134:137], v[174:177], v[100:103]
	v_mfma_f32_16x16x32_bf16 v[96:99], v[142:145], v[174:177], v[96:99]
	s_barrier
	ds_read_b128 v[178:181], v203 offset:0
	ds_read_b128 v[182:185], v203 offset:0x400
	ds_read_b128 v[186:189], v203 offset:0x800
	v_lshl_add_u64 v[218:219], s[70:71], 0, v[194:195]
	s_mov_b64 s[92:93], 0x2fd00100
	s_mov_b32 m0, s73
	ds_read_b128 v[196:199], v203 offset:0xc00
	v_lshl_add_u64 v[220:221], v[218:219], 0, s[92:93]
	s_mov_b64 s[92:93], 0x2fdb0100
	global_load_lds_dwordx4 v[220:221], off
	v_lshl_add_u64 v[220:221], v[218:219], 0, s[92:93]
	s_mov_b32 m0, s74
	s_nop 0
	global_load_lds_dwordx4 v[220:221], off
	s_barrier
	s_waitcnt lgkmcnt(0)
	v_mfma_f32_16x16x32_bf16 v[92:95], v[178:181], v[146:149], v[92:95]
	v_mfma_f32_16x16x32_bf16 v[88:91], v[186:189], v[146:149], v[88:91]
	v_mfma_f32_16x16x32_bf16 v[84:87], v[178:181], v[154:157], v[84:87]
	v_mfma_f32_16x16x32_bf16 v[80:83], v[186:189], v[154:157], v[80:83]
	v_mfma_f32_16x16x32_bf16 v[76:79], v[178:181], v[162:165], v[76:79]
	v_mfma_f32_16x16x32_bf16 v[72:75], v[186:189], v[162:165], v[72:75]
	v_mfma_f32_16x16x32_bf16 v[68:71], v[178:181], v[170:173], v[68:71]
	v_mfma_f32_16x16x32_bf16 v[64:67], v[186:189], v[170:173], v[64:67]
	v_mfma_f32_16x16x32_bf16 v[92:95], v[182:185], v[150:153], v[92:95]
	v_mfma_f32_16x16x32_bf16 v[88:91], v[196:199], v[150:153], v[88:91]
	v_mfma_f32_16x16x32_bf16 v[84:87], v[182:185], v[158:161], v[84:87]
	v_mfma_f32_16x16x32_bf16 v[80:83], v[196:199], v[158:161], v[80:83]
	v_mfma_f32_16x16x32_bf16 v[76:79], v[182:185], v[166:169], v[76:79]
	v_mfma_f32_16x16x32_bf16 v[72:75], v[196:199], v[166:169], v[72:75]
	v_mfma_f32_16x16x32_bf16 v[68:71], v[182:185], v[174:177], v[68:71]
	v_mfma_f32_16x16x32_bf16 v[64:67], v[196:199], v[174:177], v[64:67]
	s_barrier
	ds_read_b128 v[146:149], v204 offset:0
	ds_read_b128 v[150:153], v204 offset:0x400
	ds_read_b128 v[154:157], v204 offset:0x800
	ds_read_b128 v[158:161], v204 offset:0xc00
	ds_read_b128 v[162:165], v204 offset:0x1000
	ds_read_b128 v[166:169], v204 offset:0x1400
	ds_read_b128 v[170:173], v204 offset:0x1800
	s_mov_b64 s[92:93], 0x100
	s_mov_b32 m0, s3
	ds_read_b128 v[174:177], v204 offset:0x1c00
	v_lshl_add_u64 v[220:221], v[190:191], 0, s[92:93]
	s_mov_b64 s[92:93], 0xb0100
	global_load_lds_dwordx4 v[220:221], off
	v_lshl_add_u64 v[220:221], v[190:191], 0, s[92:93]
	s_mov_b32 m0, s75
	s_nop 0
	global_load_lds_dwordx4 v[220:221], off
	s_barrier
	s_waitcnt lgkmcnt(0)
	v_mfma_f32_16x16x32_bf16 v[60:63], v[130:133], v[146:149], v[60:63]
	v_mfma_f32_16x16x32_bf16 v[56:59], v[138:141], v[146:149], v[56:59]
	v_mfma_f32_16x16x32_bf16 v[52:55], v[130:133], v[154:157], v[52:55]
	v_mfma_f32_16x16x32_bf16 v[48:51], v[138:141], v[154:157], v[48:51]
	v_mfma_f32_16x16x32_bf16 v[44:47], v[130:133], v[162:165], v[44:47]
	v_mfma_f32_16x16x32_bf16 v[40:43], v[138:141], v[162:165], v[40:43]
	v_mfma_f32_16x16x32_bf16 v[36:39], v[130:133], v[170:173], v[36:39]
	v_mfma_f32_16x16x32_bf16 v[32:35], v[138:141], v[170:173], v[32:35]
	v_mfma_f32_16x16x32_bf16 v[60:63], v[134:137], v[150:153], v[60:63]
	v_mfma_f32_16x16x32_bf16 v[56:59], v[142:145], v[150:153], v[56:59]
	v_mfma_f32_16x16x32_bf16 v[52:55], v[134:137], v[158:161], v[52:55]
	v_mfma_f32_16x16x32_bf16 v[48:51], v[142:145], v[158:161], v[48:51]
	v_mfma_f32_16x16x32_bf16 v[44:47], v[134:137], v[166:169], v[44:47]
	v_mfma_f32_16x16x32_bf16 v[40:43], v[142:145], v[166:169], v[40:43]
	v_mfma_f32_16x16x32_bf16 v[36:39], v[134:137], v[174:177], v[36:39]
	v_mfma_f32_16x16x32_bf16 v[32:35], v[142:145], v[174:177], v[32:35]
	s_barrier
	s_mov_b32 m0, s76
	v_lshl_add_u64 v[130:131], v[218:219], 0, s[34:35]
	global_load_lds_dwordx4 v[130:131], off
	v_lshl_add_u64 v[130:131], v[218:219], 0, s[36:37]
	s_mov_b32 m0, s77
	s_nop 0
	global_load_lds_dwordx4 v[130:131], off
	s_waitcnt vmcnt(6)
	s_barrier
; #define WAIT_V(n) asm volatile("s_waitcnt vmcnt(%0)" ::"n"(n) : "memory")
; #define SCHED() __builtin_amdgcn_sched_barrier(0)
; #define LGKM(n) asm volatile("s_waitcnt lgkmcnt(%0)" ::"n"(n) : "memory")
; #define STAGE_A(b, h, kt) STAGE_AX(Ag, b, h, kt)
; #define STAGE_B(b, h, kt) STAGE_BX(Bg, b, h, kt)
; #define LDA(b, h) do { const unsigned pa_ = lds0 + SLOTA(b, h) + wr * 8192 + laneoff; _Pragma("unroll") for (int m = 0; m < 4; ++m)   \
;       _Pragma("unroll") for (int k = 0; k < 2; ++k) DSR(At[m][k], pa_, m * 2048 + k * 1024); } while (0)
; #define LDB(dst, b, h) do { const unsigned pb_ = lds0 + SLOTB(b, h) + wc * 4096 + laneoff; _Pragma("unroll") for (int n = 0; n < 2; ++n) \
;       _Pragma("unroll") for (int k = 0; k < 2; ++k) DSR(dst[n][k], pb_, n * 2048 + k * 1024); } while (0)
; #define BAR __builtin_amdgcn_s_barrier()
; #define LGKM(n) asm volatile("s_waitcnt lgkmcnt(%0)" ::"n"(n) : "memory")
; template <int EPI, bool SWP> ...
;     ...
;     WAIT_V(6); BAR; SCHED(); MMA(1, 1, B1); BAR; SCHED();
;     LDB(B0, 1, 0); LDA(1, 0); STAGE_A(0, 1, t + 2);
;     LGKM(8); BAR; LGKM(0); SCHED(); MMA(0, 0, B0); BAR; SCHED();
;     LDB(B1, 1, 1); STAGE_B(1, 0, t + 3);
;     BAR; LGKM(0); SCHED(); MMA(0, 1, B1); BAR; SCHED();
;     LDA(1, 1); STAGE_A(1, 0, t + 3);
	v_mfma_f32_16x16x32_bf16 v[28:31], v[178:181], v[146:149], v[28:31]
	v_mfma_f32_16x16x32_bf16 v[24:27], v[186:189], v[146:149], v[24:27]
	v_mfma_f32_16x16x32_bf16 v[20:23], v[178:181], v[154:157], v[20:23]
	v_mfma_f32_16x16x32_bf16 v[16:19], v[186:189], v[154:157], v[16:19]
	v_mfma_f32_16x16x32_bf16 v[12:15], v[178:181], v[162:165], v[12:15]
	v_mfma_f32_16x16x32_bf16 v[8:11], v[186:189], v[162:165], v[8:11]
	v_mfma_f32_16x16x32_bf16 v[4:7], v[178:181], v[170:173], v[4:7]
	v_mfma_f32_16x16x32_bf16 v[0:3], v[186:189], v[170:173], v[0:3]
	v_mfma_f32_16x16x32_bf16 v[28:31], v[182:185], v[150:153], v[28:31]
	v_mfma_f32_16x16x32_bf16 v[24:27], v[196:199], v[150:153], v[24:27]
	v_mfma_f32_16x16x32_bf16 v[20:23], v[182:185], v[158:161], v[20:23]
	v_mfma_f32_16x16x32_bf16 v[16:19], v[196:199], v[158:161], v[16:19]
	v_mfma_f32_16x16x32_bf16 v[12:15], v[182:185], v[166:169], v[12:15]
	v_mfma_f32_16x16x32_bf16 v[8:11], v[196:199], v[166:169], v[8:11]
	v_mfma_f32_16x16x32_bf16 v[4:7], v[182:185], v[174:177], v[4:7]
	v_mfma_f32_16x16x32_bf16 v[0:3], v[196:199], v[174:177], v[0:3]
	s_barrier
	ds_read_b128 v[130:133], v205 offset:0
	ds_read_b128 v[134:137], v205 offset:0x400
	ds_read_b128 v[138:141], v205 offset:0x800
	ds_read_b128 v[142:145], v205 offset:0xc00
	ds_read_b128 v[146:149], v206 offset:0
	ds_read_b128 v[150:153], v206 offset:0x400
	ds_read_b128 v[154:157], v206 offset:0x800
	ds_read_b128 v[158:161], v206 offset:0xc00
	ds_read_b128 v[162:165], v206 offset:0x1000
	ds_read_b128 v[166:169], v206 offset:0x1400
	ds_read_b128 v[170:173], v206 offset:0x1800
	s_mov_b32 m0, s78
	ds_read_b128 v[174:177], v206 offset:0x1c00
	v_lshl_add_u64 v[178:179], v[190:191], 0, s[38:39]
	global_load_lds_dwordx4 v[178:179], off
	v_lshl_add_u64 v[178:179], v[190:191], 0, s[40:41]
	s_mov_b32 m0, s79
	s_nop 0
	global_load_lds_dwordx4 v[178:179], off
	s_waitcnt lgkmcnt(8)
	s_barrier
	s_waitcnt lgkmcnt(0)
	v_mfma_f32_16x16x32_bf16 v[124:127], v[130:133], v[146:149], v[124:127]
	v_mfma_f32_16x16x32_bf16 v[120:123], v[138:141], v[146:149], v[120:123]
	v_mfma_f32_16x16x32_bf16 v[116:119], v[130:133], v[154:157], v[116:119]
	v_mfma_f32_16x16x32_bf16 v[112:115], v[138:141], v[154:157], v[112:115]
	v_mfma_f32_16x16x32_bf16 v[108:111], v[130:133], v[162:165], v[108:111]
	v_mfma_f32_16x16x32_bf16 v[104:107], v[138:141], v[162:165], v[104:107]
	v_mfma_f32_16x16x32_bf16 v[100:103], v[130:133], v[170:173], v[100:103]
	v_mfma_f32_16x16x32_bf16 v[96:99], v[138:141], v[170:173], v[96:99]
	v_mfma_f32_16x16x32_bf16 v[124:127], v[134:137], v[150:153], v[124:127]
	v_mfma_f32_16x16x32_bf16 v[120:123], v[142:145], v[150:153], v[120:123]
	v_mfma_f32_16x16x32_bf16 v[116:119], v[134:137], v[158:161], v[116:119]
	v_mfma_f32_16x16x32_bf16 v[112:115], v[142:145], v[158:161], v[112:115]
	v_mfma_f32_16x16x32_bf16 v[108:111], v[134:137], v[166:169], v[108:111]
	v_mfma_f32_16x16x32_bf16 v[104:107], v[142:145], v[166:169], v[104:107]
	v_mfma_f32_16x16x32_bf16 v[100:103], v[134:137], v[174:177], v[100:103]
	v_mfma_f32_16x16x32_bf16 v[96:99], v[142:145], v[174:177], v[96:99]
	s_barrier
	ds_read_b128 v[178:181], v207 offset:0
	ds_read_b128 v[182:185], v207 offset:0x400
	ds_read_b128 v[186:189], v207 offset:0x800
	s_mov_b32 m0, s80
	ds_read_b128 v[196:199], v207 offset:0xc00
	v_lshl_add_u64 v[220:221], v[218:219], 0, s[42:43]
	global_load_lds_dwordx4 v[220:221], off
	v_lshl_add_u64 v[220:221], v[218:219], 0, s[44:45]
	s_mov_b32 m0, s81
	s_nop 0
	global_load_lds_dwordx4 v[220:221], off
	s_barrier
	s_waitcnt lgkmcnt(0)
	v_mfma_f32_16x16x32_bf16 v[92:95], v[178:181], v[146:149], v[92:95]
	v_mfma_f32_16x16x32_bf16 v[88:91], v[186:189], v[146:149], v[88:91]
	v_mfma_f32_16x16x32_bf16 v[84:87], v[178:181], v[154:157], v[84:87]
	v_mfma_f32_16x16x32_bf16 v[80:83], v[186:189], v[154:157], v[80:83]
	v_mfma_f32_16x16x32_bf16 v[76:79], v[178:181], v[162:165], v[76:79]
	v_mfma_f32_16x16x32_bf16 v[72:75], v[186:189], v[162:165], v[72:75]
	v_mfma_f32_16x16x32_bf16 v[68:71], v[178:181], v[170:173], v[68:71]
	v_mfma_f32_16x16x32_bf16 v[64:67], v[186:189], v[170:173], v[64:67]
	v_mfma_f32_16x16x32_bf16 v[92:95], v[182:185], v[150:153], v[92:95]
	v_mfma_f32_16x16x32_bf16 v[88:91], v[196:199], v[150:153], v[88:91]
	v_mfma_f32_16x16x32_bf16 v[84:87], v[182:185], v[158:161], v[84:87]
	v_mfma_f32_16x16x32_bf16 v[80:83], v[196:199], v[158:161], v[80:83]
	v_mfma_f32_16x16x32_bf16 v[76:79], v[182:185], v[166:169], v[76:79]
	v_mfma_f32_16x16x32_bf16 v[72:75], v[196:199], v[166:169], v[72:75]
	v_mfma_f32_16x16x32_bf16 v[68:71], v[182:185], v[174:177], v[68:71]
	v_mfma_f32_16x16x32_bf16 v[64:67], v[196:199], v[174:177], v[64:67]
	s_barrier
	ds_read_b128 v[146:149], v208 offset:0
	ds_read_b128 v[150:153], v208 offset:0x400
	ds_read_b128 v[154:157], v208 offset:0x800
	ds_read_b128 v[158:161], v208 offset:0xc00
	ds_read_b128 v[162:165], v208 offset:0x1000
	ds_read_b128 v[166:169], v208 offset:0x1400
	ds_read_b128 v[170:173], v208 offset:0x1800
	s_mov_b32 m0, s82
	ds_read_b128 v[174:177], v208 offset:0x1c00
	v_lshl_add_u64 v[220:221], v[190:191], 0, s[46:47]
	global_load_lds_dwordx4 v[220:221], off
	v_lshl_add_u64 v[190:191], v[190:191], 0, s[48:49]
	s_mov_b32 m0, s83
	s_nop 0
	global_load_lds_dwordx4 v[190:191], off
	s_barrier
; #define WAIT_V(n) asm volatile("s_waitcnt vmcnt(%0)" ::"n"(n) : "memory")
; #define SCHED() __builtin_amdgcn_sched_barrier(0)
; #define LGKM(n) asm volatile("s_waitcnt lgkmcnt(%0)" ::"n"(n) : "memory")
; #define STAGE_A(b, h, kt) STAGE_AX(Ag, b, h, kt)
; #define STAGE_B(b, h, kt) STAGE_BX(Bg, b, h, kt)
; #define LDA(b, h) do { const unsigned pa_ = lds0 + SLOTA(b, h) + wr * 8192 + laneoff; _Pragma("unroll") for (int m = 0; m < 4; ++m)   \
;       _Pragma("unroll") for (int k = 0; k < 2; ++k) DSR(At[m][k], pa_, m * 2048 + k * 1024); } while (0)
; #define LDB(dst, b, h) do { const unsigned pb_ = lds0 + SLOTB(b, h) + wc * 4096 + laneoff; _Pragma("unroll") for (int n = 0; n < 2; ++n) \
;       _Pragma("unroll") for (int k = 0; k < 2; ++k) DSR(dst[n][k], pb_, n * 2048 + k * 1024); } while (0)
; #define BAR __builtin_amdgcn_s_barrier()
; #define LGKM(n) asm volatile("s_waitcnt lgkmcnt(%0)" ::"n"(n) : "memory")
; template <int EPI, bool SWP> ...
;     ...
;     BAR; LGKM(0); SCHED(); MMA(1, 0, B0); BAR; SCHED();
;     STAGE_B(1, 1, t + 3);
;     WAIT_V(6); BAR; SCHED(); MMA(1, 1, B1); BAR; SCHED();
;   }
;   { LDB(B0, 0, 0); LDA(0, 0); STAGE_A(1, 1, nt - 1);
;     BAR; LGKM(0); SCHED(); MMA(0, 0, B0); BAR; SCHED();
;     LDB(B1, 0, 1); BAR; LGKM(0); SCHED(); MMA(0, 1, B1); BAR; SCHED();
	s_waitcnt lgkmcnt(0)
	v_mfma_f32_16x16x32_bf16 v[60:63], v[130:133], v[146:149], v[60:63]
	v_mfma_f32_16x16x32_bf16 v[56:59], v[138:141], v[146:149], v[56:59]
	v_mfma_f32_16x16x32_bf16 v[52:55], v[130:133], v[154:157], v[52:55]
	v_mfma_f32_16x16x32_bf16 v[48:51], v[138:141], v[154:157], v[48:51]
	v_mfma_f32_16x16x32_bf16 v[44:47], v[130:133], v[162:165], v[44:47]
	v_mfma_f32_16x16x32_bf16 v[40:43], v[138:141], v[162:165], v[40:43]
	v_mfma_f32_16x16x32_bf16 v[36:39], v[130:133], v[170:173], v[36:39]
	v_mfma_f32_16x16x32_bf16 v[32:35], v[138:141], v[170:173], v[32:35]
	v_mfma_f32_16x16x32_bf16 v[60:63], v[134:137], v[150:153], v[60:63]
	v_mfma_f32_16x16x32_bf16 v[56:59], v[142:145], v[150:153], v[56:59]
	v_mfma_f32_16x16x32_bf16 v[52:55], v[134:137], v[158:161], v[52:55]
	v_mfma_f32_16x16x32_bf16 v[48:51], v[142:145], v[158:161], v[48:51]
	v_mfma_f32_16x16x32_bf16 v[44:47], v[134:137], v[166:169], v[44:47]
	v_mfma_f32_16x16x32_bf16 v[40:43], v[142:145], v[166:169], v[40:43]
	v_mfma_f32_16x16x32_bf16 v[36:39], v[134:137], v[174:177], v[36:39]
	v_mfma_f32_16x16x32_bf16 v[32:35], v[142:145], v[174:177], v[32:35]
	s_barrier
	s_mov_b32 m0, s84
	v_lshl_add_u64 v[130:131], v[218:219], 0, s[50:51]
	global_load_lds_dwordx4 v[130:131], off
	v_lshl_add_u64 v[130:131], v[218:219], 0, s[58:59]
	s_mov_b32 m0, s85
	s_nop 0
	global_load_lds_dwordx4 v[130:131], off
	s_waitcnt vmcnt(6)
	s_barrier
	v_mfma_f32_16x16x32_bf16 v[28:31], v[178:181], v[146:149], v[28:31]
	v_mfma_f32_16x16x32_bf16 v[24:27], v[186:189], v[146:149], v[24:27]
	v_mfma_f32_16x16x32_bf16 v[20:23], v[178:181], v[154:157], v[20:23]
	v_mfma_f32_16x16x32_bf16 v[16:19], v[186:189], v[154:157], v[16:19]
	v_mfma_f32_16x16x32_bf16 v[12:15], v[178:181], v[162:165], v[12:15]
	v_mfma_f32_16x16x32_bf16 v[8:11], v[186:189], v[162:165], v[8:11]
	v_mfma_f32_16x16x32_bf16 v[4:7], v[178:181], v[170:173], v[4:7]
	v_mfma_f32_16x16x32_bf16 v[0:3], v[186:189], v[170:173], v[0:3]
	v_mfma_f32_16x16x32_bf16 v[28:31], v[182:185], v[150:153], v[28:31]
	v_mfma_f32_16x16x32_bf16 v[24:27], v[196:199], v[150:153], v[24:27]
	v_mfma_f32_16x16x32_bf16 v[20:23], v[182:185], v[158:161], v[20:23]
	v_mfma_f32_16x16x32_bf16 v[16:19], v[196:199], v[158:161], v[16:19]
	v_mfma_f32_16x16x32_bf16 v[12:15], v[182:185], v[166:169], v[12:15]
	v_mfma_f32_16x16x32_bf16 v[8:11], v[196:199], v[166:169], v[8:11]
	v_mfma_f32_16x16x32_bf16 v[4:7], v[182:185], v[174:177], v[4:7]
	v_mfma_f32_16x16x32_bf16 v[0:3], v[196:199], v[174:177], v[0:3]
	s_barrier
	s_add_i32 s91, s91, 2
	s_add_u32 s70, s70, 0x100
	s_addc_u32 s71, s71, 0
	s_add_u32 s68, s68, 0x100
	s_addc_u32 s69, s69, 0
	s_cmpk_gt_u32 s91, 0x53
	s_cbranch_scc0 .LBB0_709
	ds_read_b128 v[130:133], v201 offset:0
	ds_read_b128 v[134:137], v201 offset:0x400
	ds_read_b128 v[138:141], v201 offset:0x800
	ds_read_b128 v[142:145], v201 offset:0xc00
	ds_read_b128 v[146:149], v202 offset:0
	ds_read_b128 v[150:153], v202 offset:0x400
	ds_read_b128 v[154:157], v202 offset:0x800
	ds_read_b128 v[158:161], v202 offset:0xc00
	ds_read_b128 v[162:165], v202 offset:0x1000
	ds_read_b128 v[166:169], v202 offset:0x1400
	ds_read_b128 v[170:173], v202 offset:0x1800
	s_mov_b32 m0, s86
	ds_read_b128 v[174:177], v202 offset:0x1c00
	v_lshl_add_u64 v[178:179], v[128:129], 0, s[60:61]
	global_load_lds_dwordx4 v[178:179], off
	v_lshl_add_u64 v[128:129], v[128:129], 0, s[62:63]
	s_mov_b32 m0, s87
	s_mul_i32 s68, s88, 0x2c0000
	global_load_lds_dwordx4 v[128:129], off
	s_mul_hi_i32 s69, s88, 0x2c0000
	s_add_u32 s68, s56, s68
	s_barrier
	s_waitcnt lgkmcnt(0)
	s_addc_u32 s69, s57, s69
	s_mul_i32 s70, s89, 0x2c0000
	s_mul_hi_i32 s71, s89, 0x2c0000
	s_add_u32 s70, s22, s70
	s_addc_u32 s71, s23, s71
	v_mfma_f32_16x16x32_bf16 v[124:127], v[130:133], v[146:149], v[124:127]
	v_mfma_f32_16x16x32_bf16 v[120:123], v[138:141], v[146:149], v[120:123]
	v_mfma_f32_16x16x32_bf16 v[116:119], v[130:133], v[154:157], v[116:119]
	v_mfma_f32_16x16x32_bf16 v[112:115], v[138:141], v[154:157], v[112:115]
	v_mfma_f32_16x16x32_bf16 v[108:111], v[130:133], v[162:165], v[108:111]
	v_mfma_f32_16x16x32_bf16 v[104:107], v[138:141], v[162:165], v[104:107]
	v_mfma_f32_16x16x32_bf16 v[100:103], v[130:133], v[170:173], v[100:103]
	v_mfma_f32_16x16x32_bf16 v[96:99], v[138:141], v[170:173], v[96:99]
	v_mfma_f32_16x16x32_bf16 v[124:127], v[134:137], v[150:153], v[124:127]
	v_mfma_f32_16x16x32_bf16 v[120:123], v[142:145], v[150:153], v[120:123]
	v_mfma_f32_16x16x32_bf16 v[116:119], v[134:137], v[158:161], v[116:119]
	v_mfma_f32_16x16x32_bf16 v[112:115], v[142:145], v[158:161], v[112:115]
	v_mfma_f32_16x16x32_bf16 v[108:111], v[134:137], v[166:169], v[108:111]
	v_mfma_f32_16x16x32_bf16 v[104:107], v[142:145], v[166:169], v[104:107]
	v_mfma_f32_16x16x32_bf16 v[100:103], v[134:137], v[174:177], v[100:103]
	v_mfma_f32_16x16x32_bf16 v[96:99], v[142:145], v[174:177], v[96:99]
	s_barrier
	ds_read_b128 v[178:181], v203 offset:0
	ds_read_b128 v[182:185], v203 offset:0x400
	ds_read_b128 v[186:189], v203 offset:0x800
	ds_read_b128 v[196:199], v203 offset:0xc00
	s_barrier
	s_waitcnt lgkmcnt(0)
	v_mfma_f32_16x16x32_bf16 v[92:95], v[178:181], v[146:149], v[92:95]
	v_mfma_f32_16x16x32_bf16 v[88:91], v[186:189], v[146:149], v[88:91]
	v_mfma_f32_16x16x32_bf16 v[84:87], v[178:181], v[154:157], v[84:87]
	v_mfma_f32_16x16x32_bf16 v[80:83], v[186:189], v[154:157], v[80:83]
	v_mfma_f32_16x16x32_bf16 v[76:79], v[178:181], v[162:165], v[76:79]
	v_mfma_f32_16x16x32_bf16 v[72:75], v[186:189], v[162:165], v[72:75]
	v_mfma_f32_16x16x32_bf16 v[68:71], v[178:181], v[170:173], v[68:71]
	v_mfma_f32_16x16x32_bf16 v[64:67], v[186:189], v[170:173], v[64:67]
	v_mfma_f32_16x16x32_bf16 v[92:95], v[182:185], v[150:153], v[92:95]
	v_mfma_f32_16x16x32_bf16 v[88:91], v[196:199], v[150:153], v[88:91]
	v_mfma_f32_16x16x32_bf16 v[84:87], v[182:185], v[158:161], v[84:87]
	v_mfma_f32_16x16x32_bf16 v[80:83], v[196:199], v[158:161], v[80:83]
	v_mfma_f32_16x16x32_bf16 v[76:79], v[182:185], v[166:169], v[76:79]
	v_mfma_f32_16x16x32_bf16 v[72:75], v[196:199], v[166:169], v[72:75]
	v_mfma_f32_16x16x32_bf16 v[68:71], v[182:185], v[174:177], v[68:71]
	v_mfma_f32_16x16x32_bf16 v[64:67], v[196:199], v[174:177], v[64:67]
	s_barrier
; #define WAIT_V(n) asm volatile("s_waitcnt vmcnt(%0)" ::"n"(n) : "memory")
; #define SCHED() __builtin_amdgcn_sched_barrier(0)
; #define LGKM(n) asm volatile("s_waitcnt lgkmcnt(%0)" ::"n"(n) : "memory")
; #define STAGE_AX(AG, b, h, kt) do { _Pragma("unroll") for (int i = 0; i < 2; ++i)                                    \
;       __builtin_amdgcn_global_load_lds((const unsigned*)(((AG) + ((size_t)(kt) * (BK * 2) + (size_t)((h) * 2 + i) * 128 * lda)) + aoff), \
;                                        (unsigned*)(shm + SLOTA(b, h) + wid * 1024 + i * 8192), 16, 0, 0); } while (0)
; #define STAGE_BX(BG, b, h, kt) do { _Pragma("unroll") for (int i = 0; i < 2; ++i)                                    \
;       __builtin_amdgcn_global_load_lds((const unsigned*)(((BG) + ((size_t)(kt) * (BK * 2) + (size_t)((h) * 2 + i) * 128 * K)) + boff),   \
;                                        (unsigned*)(shm + SLOTB(b, h) + wid * 1024 + i * 8192), 16, 0, 0); } while (0)
; #define LDA(b, h) do { const unsigned pa_ = lds0 + SLOTA(b, h) + wr * 8192 + laneoff; _Pragma("unroll") for (int m = 0; m < 4; ++m)   \
;       _Pragma("unroll") for (int k = 0; k < 2; ++k) DSR(At[m][k], pa_, m * 2048 + k * 1024); } while (0)
; #define LDB(dst, b, h) do { const unsigned pb_ = lds0 + SLOTB(b, h) + wc * 4096 + laneoff; _Pragma("unroll") for (int n = 0; n < 2; ++n) \
;       _Pragma("unroll") for (int k = 0; k < 2; ++k) DSR(dst[n][k], pb_, n * 2048 + k * 1024); } while (0)
; #define BAR __builtin_amdgcn_s_barrier()
; #define LGKM(n) asm volatile("s_waitcnt lgkmcnt(%0)" ::"n"(n) : "memory")
; template <int EPI, bool SWP> ...
;     ...
;     LDA(0, 1); WAIT_V(4); BAR; LGKM(0); SCHED(); MMA(1, 0, B0); MMA(1, 1, B1); BAR; SCHED(); }
;   { LDB(B0, 1, 0); LDA(1, 0); WAIT_V(2); BAR; LGKM(0); SCHED(); MMA(0, 0, B0); BAR; SCHED();
;     LDB(B1, 1, 1); WAIT_V(0); BAR; LGKM(0); SCHED(); MMA(0, 1, B1); BAR; SCHED();
;     LDA(1, 1);
;     if (has_next) { STAGE_BX(Bg_n, 0, 0, 0); STAGE_AX(Ag_n, 0, 0, 0); STAGE_BX(Bg_n, 0, 1, 0); STAGE_AX(Ag_n, 0, 1, 0); }
	ds_read_b128 v[146:149], v204 offset:0
	ds_read_b128 v[150:153], v204 offset:0x400
	ds_read_b128 v[154:157], v204 offset:0x800
	ds_read_b128 v[158:161], v204 offset:0xc00
	ds_read_b128 v[162:165], v204 offset:0x1000
	ds_read_b128 v[166:169], v204 offset:0x1400
	ds_read_b128 v[170:173], v204 offset:0x1800
	ds_read_b128 v[174:177], v204 offset:0x1c00
	s_waitcnt vmcnt(4)
	s_barrier
	s_waitcnt lgkmcnt(0)
	v_mfma_f32_16x16x32_bf16 v[60:63], v[130:133], v[146:149], v[60:63]
	v_mfma_f32_16x16x32_bf16 v[56:59], v[138:141], v[146:149], v[56:59]
	v_mfma_f32_16x16x32_bf16 v[52:55], v[130:133], v[154:157], v[52:55]
	v_mfma_f32_16x16x32_bf16 v[48:51], v[138:141], v[154:157], v[48:51]
	v_mfma_f32_16x16x32_bf16 v[44:47], v[130:133], v[162:165], v[44:47]
	v_mfma_f32_16x16x32_bf16 v[40:43], v[138:141], v[162:165], v[40:43]
	v_mfma_f32_16x16x32_bf16 v[36:39], v[130:133], v[170:173], v[36:39]
	v_mfma_f32_16x16x32_bf16 v[32:35], v[138:141], v[170:173], v[32:35]
	v_mfma_f32_16x16x32_bf16 v[60:63], v[134:137], v[150:153], v[60:63]
	v_mfma_f32_16x16x32_bf16 v[56:59], v[142:145], v[150:153], v[56:59]
	v_mfma_f32_16x16x32_bf16 v[52:55], v[134:137], v[158:161], v[52:55]
	v_mfma_f32_16x16x32_bf16 v[48:51], v[142:145], v[158:161], v[48:51]
	v_mfma_f32_16x16x32_bf16 v[44:47], v[134:137], v[166:169], v[44:47]
	v_mfma_f32_16x16x32_bf16 v[40:43], v[142:145], v[166:169], v[40:43]
	v_mfma_f32_16x16x32_bf16 v[36:39], v[134:137], v[174:177], v[36:39]
	v_mfma_f32_16x16x32_bf16 v[32:35], v[142:145], v[174:177], v[32:35]
	v_mfma_f32_16x16x32_bf16 v[28:31], v[178:181], v[146:149], v[28:31]
	v_mfma_f32_16x16x32_bf16 v[24:27], v[186:189], v[146:149], v[24:27]
	v_mfma_f32_16x16x32_bf16 v[20:23], v[178:181], v[154:157], v[20:23]
	v_mfma_f32_16x16x32_bf16 v[16:19], v[186:189], v[154:157], v[16:19]
	v_mfma_f32_16x16x32_bf16 v[12:15], v[178:181], v[162:165], v[12:15]
	v_mfma_f32_16x16x32_bf16 v[8:11], v[186:189], v[162:165], v[8:11]
	v_mfma_f32_16x16x32_bf16 v[4:7], v[178:181], v[170:173], v[4:7]
	v_mfma_f32_16x16x32_bf16 v[0:3], v[186:189], v[170:173], v[0:3]
	v_mfma_f32_16x16x32_bf16 v[28:31], v[182:185], v[150:153], v[28:31]
	v_mfma_f32_16x16x32_bf16 v[24:27], v[196:199], v[150:153], v[24:27]
	v_mfma_f32_16x16x32_bf16 v[20:23], v[182:185], v[158:161], v[20:23]
	v_mfma_f32_16x16x32_bf16 v[16:19], v[196:199], v[158:161], v[16:19]
	v_mfma_f32_16x16x32_bf16 v[12:15], v[182:185], v[166:169], v[12:15]
	v_mfma_f32_16x16x32_bf16 v[8:11], v[196:199], v[166:169], v[8:11]
	v_mfma_f32_16x16x32_bf16 v[4:7], v[182:185], v[174:177], v[4:7]
	v_mfma_f32_16x16x32_bf16 v[0:3], v[196:199], v[174:177], v[0:3]
	s_barrier
	ds_read_b128 v[128:131], v205 offset:0
	ds_read_b128 v[132:135], v205 offset:0x400
	ds_read_b128 v[136:139], v205 offset:0x800
	ds_read_b128 v[140:143], v205 offset:0xc00
	ds_read_b128 v[160:163], v206 offset:0
	ds_read_b128 v[164:167], v206 offset:0x400
	ds_read_b128 v[168:171], v206 offset:0x800
	ds_read_b128 v[172:175], v206 offset:0xc00
	ds_read_b128 v[176:179], v206 offset:0x1000
	ds_read_b128 v[180:183], v206 offset:0x1400
	ds_read_b128 v[184:187], v206 offset:0x1800
	ds_read_b128 v[188:191], v206 offset:0x1c00
	s_waitcnt vmcnt(2)
	s_barrier
	s_waitcnt lgkmcnt(0)
	v_mfma_f32_16x16x32_bf16 v[124:127], v[128:131], v[160:163], v[124:127]
	v_mfma_f32_16x16x32_bf16 v[120:123], v[136:139], v[160:163], v[120:123]
	v_mfma_f32_16x16x32_bf16 v[116:119], v[128:131], v[168:171], v[116:119]
	v_mfma_f32_16x16x32_bf16 v[112:115], v[136:139], v[168:171], v[112:115]
	v_mfma_f32_16x16x32_bf16 v[108:111], v[128:131], v[176:179], v[108:111]
	v_mfma_f32_16x16x32_bf16 v[104:107], v[136:139], v[176:179], v[104:107]
	v_mfma_f32_16x16x32_bf16 v[100:103], v[128:131], v[184:187], v[100:103]
	v_mfma_f32_16x16x32_bf16 v[96:99], v[136:139], v[184:187], v[96:99]
	v_mfma_f32_16x16x32_bf16 v[124:127], v[132:135], v[164:167], v[124:127]
	v_mfma_f32_16x16x32_bf16 v[120:123], v[140:143], v[164:167], v[120:123]
	v_mfma_f32_16x16x32_bf16 v[116:119], v[132:135], v[172:175], v[116:119]
	v_mfma_f32_16x16x32_bf16 v[112:115], v[140:143], v[172:175], v[112:115]
	v_mfma_f32_16x16x32_bf16 v[108:111], v[132:135], v[180:183], v[108:111]
	v_mfma_f32_16x16x32_bf16 v[104:107], v[140:143], v[180:183], v[104:107]
	v_mfma_f32_16x16x32_bf16 v[100:103], v[132:135], v[188:191], v[100:103]
	v_mfma_f32_16x16x32_bf16 v[96:99], v[140:143], v[188:191], v[96:99]
	s_barrier
	ds_read_b128 v[144:147], v207 offset:0
	ds_read_b128 v[148:151], v207 offset:0x400
	ds_read_b128 v[152:155], v207 offset:0x800
	ds_read_b128 v[156:159], v207 offset:0xc00
	s_waitcnt vmcnt(0)
	s_barrier
	s_waitcnt lgkmcnt(0)
	v_mfma_f32_16x16x32_bf16 v[92:95], v[144:147], v[160:163], v[92:95]
	v_mfma_f32_16x16x32_bf16 v[88:91], v[152:155], v[160:163], v[88:91]
	v_mfma_f32_16x16x32_bf16 v[84:87], v[144:147], v[168:171], v[84:87]
	v_mfma_f32_16x16x32_bf16 v[80:83], v[152:155], v[168:171], v[80:83]
	v_mfma_f32_16x16x32_bf16 v[76:79], v[144:147], v[176:179], v[76:79]
	v_mfma_f32_16x16x32_bf16 v[72:75], v[152:155], v[176:179], v[72:75]
	v_mfma_f32_16x16x32_bf16 v[68:71], v[144:147], v[184:187], v[68:71]
	v_mfma_f32_16x16x32_bf16 v[64:67], v[152:155], v[184:187], v[64:67]
	v_mfma_f32_16x16x32_bf16 v[92:95], v[148:151], v[164:167], v[92:95]
	v_mfma_f32_16x16x32_bf16 v[88:91], v[156:159], v[164:167], v[88:91]
	v_mfma_f32_16x16x32_bf16 v[84:87], v[148:151], v[172:175], v[84:87]
	v_mfma_f32_16x16x32_bf16 v[80:83], v[156:159], v[172:175], v[80:83]
	v_mfma_f32_16x16x32_bf16 v[76:79], v[148:151], v[180:183], v[76:79]
	v_mfma_f32_16x16x32_bf16 v[72:75], v[156:159], v[180:183], v[72:75]
	v_mfma_f32_16x16x32_bf16 v[68:71], v[148:151], v[188:191], v[68:71]
	v_mfma_f32_16x16x32_bf16 v[64:67], v[156:159], v[188:191], v[64:67]
	s_barrier
	ds_read_b128 v[184:187], v208 offset:0
	ds_read_b128 v[188:191], v208 offset:0x400
	ds_read_b128 v[176:179], v208 offset:0x800
	ds_read_b128 v[180:183], v208 offset:0xc00
	ds_read_b128 v[168:171], v208 offset:0x1000
	ds_read_b128 v[172:175], v208 offset:0x1400
	ds_read_b128 v[160:163], v208 offset:0x1800
	ds_read_b128 v[164:167], v208 offset:0x1c00
	s_and_b64 vcc, exec, s[66:67]
	v_lshl_add_u64 v[196:197], s[70:71], 0, v[192:193]
	v_lshl_add_u64 v[198:199], s[68:69], 0, v[192:193]
	s_cbranch_vccz .LBB0_712
	s_mov_b32 m0, s73
	v_lshl_add_u64 v[218:219], v[196:197], 0, s[14:15]
	global_load_lds_dwordx4 v[196:197], off
	s_mov_b32 m0, s74
	s_nop 0
	global_load_lds_dwordx4 v[218:219], off
	s_mov_b32 m0, s3
	v_lshl_add_u64 v[218:219], v[198:199], 0, s[14:15]
	global_load_lds_dwordx4 v[198:199], off
	s_mov_b32 m0, s75
	s_nop 0
	global_load_lds_dwordx4 v[218:219], off
	v_lshl_add_u64 v[218:219], v[196:197], 0, s[16:17]
	s_mov_b32 m0, s76
	s_nop 0
	global_load_lds_dwordx4 v[218:219], off
	v_lshl_add_u64 v[218:219], v[196:197], 0, s[18:19]
	s_mov_b32 m0, s77
	s_nop 0
	global_load_lds_dwordx4 v[218:219], off
	v_lshl_add_u64 v[218:219], v[198:199], 0, s[16:17]
	s_mov_b32 m0, s78
	s_nop 0
	global_load_lds_dwordx4 v[218:219], off
	v_lshl_add_u64 v[218:219], v[198:199], 0, s[18:19]
	s_mov_b32 m0, s79
	s_nop 0
	global_load_lds_dwordx4 v[218:219], off
; #define SCHED() __builtin_amdgcn_sched_barrier(0)
; #define LGKM(n) asm volatile("s_waitcnt lgkmcnt(%0)" ::"n"(n) : "memory")
; #define BAR __builtin_amdgcn_s_barrier()
; #define LGKM(n) asm volatile("s_waitcnt lgkmcnt(%0)" ::"n"(n) : "memory")
; template <int EPI, bool SWP> ...
;     ...
;     BAR; LGKM(0); SCHED(); MMA(1, 0, B0); MMA(1, 1, B1); BAR; SCHED(); }
;   if (wr == 0) BAR;
.LBB0_712:
	s_barrier
	s_waitcnt lgkmcnt(0)
	v_mfma_f32_16x16x32_bf16 v[60:63], v[128:131], v[184:187], v[60:63]
	v_mfma_f32_16x16x32_bf16 v[56:59], v[136:139], v[184:187], v[56:59]
	v_mfma_f32_16x16x32_bf16 v[52:55], v[128:131], v[176:179], v[52:55]
	v_mfma_f32_16x16x32_bf16 v[48:51], v[136:139], v[176:179], v[48:51]
	v_mfma_f32_16x16x32_bf16 v[44:47], v[128:131], v[168:171], v[44:47]
	v_mfma_f32_16x16x32_bf16 v[40:43], v[136:139], v[168:171], v[40:43]
	v_mfma_f32_16x16x32_bf16 v[36:39], v[128:131], v[160:163], v[36:39]
	v_mfma_f32_16x16x32_bf16 v[32:35], v[136:139], v[160:163], v[32:35]
	v_mfma_f32_16x16x32_bf16 v[60:63], v[132:135], v[188:191], v[60:63]
	v_mfma_f32_16x16x32_bf16 v[56:59], v[140:143], v[188:191], v[56:59]
	v_mfma_f32_16x16x32_bf16 v[52:55], v[132:135], v[180:183], v[52:55]
	v_mfma_f32_16x16x32_bf16 v[48:51], v[140:143], v[180:183], v[48:51]
	v_mfma_f32_16x16x32_bf16 v[44:47], v[132:135], v[172:175], v[44:47]
	v_mfma_f32_16x16x32_bf16 v[40:43], v[140:143], v[172:175], v[40:43]
	v_mfma_f32_16x16x32_bf16 v[36:39], v[132:135], v[164:167], v[36:39]
	v_mfma_f32_16x16x32_bf16 v[32:35], v[140:143], v[164:167], v[32:35]
	v_mfma_f32_16x16x32_bf16 v[28:31], v[144:147], v[184:187], v[28:31]
	v_mfma_f32_16x16x32_bf16 v[24:27], v[152:155], v[184:187], v[24:27]
	v_mfma_f32_16x16x32_bf16 v[20:23], v[144:147], v[176:179], v[20:23]
	v_mfma_f32_16x16x32_bf16 v[16:19], v[152:155], v[176:179], v[16:19]
	v_mfma_f32_16x16x32_bf16 v[12:15], v[144:147], v[168:171], v[12:15]
	v_mfma_f32_16x16x32_bf16 v[8:11], v[152:155], v[168:171], v[8:11]
	v_mfma_f32_16x16x32_bf16 v[4:7], v[144:147], v[160:163], v[4:7]
	v_mfma_f32_16x16x32_bf16 v[0:3], v[152:155], v[160:163], v[0:3]
	v_mfma_f32_16x16x32_bf16 v[28:31], v[148:151], v[188:191], v[28:31]
	v_mfma_f32_16x16x32_bf16 v[24:27], v[156:159], v[188:191], v[24:27]
	v_mfma_f32_16x16x32_bf16 v[20:23], v[148:151], v[180:183], v[20:23]
	v_mfma_f32_16x16x32_bf16 v[16:19], v[156:159], v[180:183], v[16:19]
	v_mfma_f32_16x16x32_bf16 v[12:15], v[148:151], v[172:175], v[12:15]
	v_mfma_f32_16x16x32_bf16 v[8:11], v[156:159], v[172:175], v[8:11]
	v_mfma_f32_16x16x32_bf16 v[4:7], v[148:151], v[164:167], v[4:7]
	v_mfma_f32_16x16x32_bf16 v[0:3], v[156:159], v[164:167], v[0:3]
	s_barrier
	s_andn2_b64 vcc, exec, s[12:13]
	s_cbranch_vccnz .LBB0_714
	s_barrier
